# batch-slab layout for T1/T2 and HID (no bytes shared between batches): XCD pipelines fully independent after prep, weights published at end of FFN-out; 4 us per XCD one-time shift
# speedup vs baseline: 1.0220x; 1.0220x over previous
; DI unsigned pk_bf16(float a, float b) { f32x2_t v = {a, b}; bf16x2_t r = __builtin_convertvector(v, bf16x2_t); return __builtin_bit_cast(unsigned, r); }
; DI float silu_f(float x) { return x * __builtin_amdgcn_rcpf(1.f + __expf(-x)); }
; template <int EPI>
; DI void gemm_phase(const bf16_t* __restrict__ A, const bf16_t* __restrict__ Bt, const int K, const int N, const Params& p, const int layer_j, char* lds) {
;     ...
;         } else if (EPI == EPI_FFN_IN) {
;             bf16_t* HID = (bf16_t*)(ws + OFF_P) + (size_t)(pm * 256 + wr * 64 + fr) * FFN_H + (col0 >> 1) + 8 * fq;
; #pragma unroll
;             for (int ai = 0; ai < 2; ++ai)
; #pragma unroll
;                 for (int m = 0; m < 4; ++m) {
;                     u32x4 o;
; #pragma unroll
;                     for (int n = 0; n < 2; ++n) {
;                         o[2 * n] = pk_bf16(silu_f(acc[ai][0][m][n][0]) * acc[ai][1][m][n][0], silu_f(acc[ai][0][m][n][1]) * acc[ai][1][m][n][1]);
;                         o[2 * n + 1] = pk_bf16(silu_f(acc[ai][0][m][n][2]) * acc[ai][1][m][n][2], silu_f(acc[ai][0][m][n][3]) * acc[ai][1][m][n][3]); }
;                     *(u32x4*)(HID + (size_t)(ai * 128 + m * 16) * FFN_H) = o;
;                 }
.LBB0_46:
	s_lshl_b32 s6, s26, 8
	v_readlane_b32 s7, v254, 7
	v_mbcnt_lo_u32_b32 v32, -1, 0
	v_mbcnt_hi_u32_b32 v32, -1, v32
	s_add_i32 s6, s6, s7
	s_lshl_b32 s7, s24, 8
	v_readlane_b32 s10, v254, 14
	v_and_or_b32 v132, v32, 15, s6
	s_lshr_b32 s98, s26, 3
	s_lshl_b32 s98, s98, 20
	s_add_u32 s98, s8, s98
	s_addc_u32 s99, s9, 0
	v_mov_b64_e32 v[130:131], s[98:99]
	s_movk_i32 s6, 0x1600
	v_ashrrev_i32_e32 v32, 1, v32
	s_or_b32 s10, s7, s10
	v_mad_i64_i32 v[130:131], s[6:7], v132, s6, v[130:131]
	v_and_b32_e32 v132, -8, v32
	v_mul_f32_e32 v32, 0xbfb8aa3b, v126
	v_exp_f32_e32 v32, v32
	s_ashr_i32 s6, s10, 1
	s_ashr_i32 s7, s6, 31
	v_lshl_add_u64 v[130:131], s[6:7], 1, v[130:131]
	v_ashrrev_i32_e32 v133, 31, v132
	v_add_f32_e32 v32, 1.0, v32
	v_lshl_add_u64 v[130:131], v[132:133], 1, v[130:131]
	v_rcp_f32_e32 v132, v32
	v_mul_f32_e32 v32, 0xbfb8aa3b, v127
	v_exp_f32_e32 v32, v32
	s_mov_b32 s6, 0x16000
	s_mov_b64 s[24:25], -1
	s_mov_b32 s39, 0x2e8ba2e9
	v_add_f32_e32 v32, 1.0, v32
	v_rcp_f32_e32 v133, v32
	v_mul_f32_e32 v32, 0xbfb8aa3b, v128
	v_exp_f32_e32 v32, v32
	s_movk_i32 s37, 0x580
	v_pk_mul_f32 v[126:127], v[126:127], v[132:133]
	v_add_f32_e32 v32, 1.0, v32
	v_pk_mul_f32 v[122:123], v[126:127], v[122:123]
	v_rcp_f32_e32 v126, v32
	v_mul_f32_e32 v32, 0xbfb8aa3b, v129
	v_exp_f32_e32 v32, v32
	v_cvt_pk_bf16_f32 v122, v122, v123
	v_add_f32_e32 v32, 1.0, v32
	v_rcp_f32_e32 v127, v32
	v_mul_f32_e32 v32, 0xbfb8aa3b, v118
	v_exp_f32_e32 v32, v32
	v_pk_mul_f32 v[126:127], v[128:129], v[126:127]
	s_nop 0
	v_pk_mul_f32 v[124:125], v[126:127], v[124:125]
	v_add_f32_e32 v32, 1.0, v32
	v_cvt_pk_bf16_f32 v123, v124, v125
	v_rcp_f32_e32 v124, v32
	v_mul_f32_e32 v32, 0xbfb8aa3b, v119
	v_exp_f32_e32 v32, v32
	s_nop 0
	v_add_f32_e32 v32, 1.0, v32
	v_rcp_f32_e32 v125, v32
	v_mul_f32_e32 v32, 0xbfb8aa3b, v120
	v_exp_f32_e32 v32, v32
	v_pk_mul_f32 v[118:119], v[118:119], v[124:125]
	s_nop 0
	v_pk_mul_f32 v[114:115], v[118:119], v[114:115]
	v_add_f32_e32 v32, 1.0, v32
	v_cvt_pk_bf16_f32 v124, v114, v115
	v_rcp_f32_e32 v114, v32
	v_mul_f32_e32 v32, 0xbfb8aa3b, v121
	v_exp_f32_e32 v32, v32
	s_nop 0
	v_add_f32_e32 v32, 1.0, v32
	v_rcp_f32_e32 v115, v32
	v_mul_f32_e32 v32, 0xbfb8aa3b, v110
	v_exp_f32_e32 v32, v32
	v_pk_mul_f32 v[114:115], v[120:121], v[114:115]
	s_nop 0
	v_pk_mul_f32 v[114:115], v[114:115], v[116:117]
	v_add_f32_e32 v32, 1.0, v32
	v_cvt_pk_bf16_f32 v125, v114, v115
	v_rcp_f32_e32 v114, v32
	v_mul_f32_e32 v32, 0xbfb8aa3b, v111
	v_exp_f32_e32 v32, v32
	s_waitcnt vmcnt(0)
	flat_store_dwordx4 v[130:131], v[122:125]
	v_add_f32_e32 v32, 1.0, v32
	v_rcp_f32_e32 v115, v32
	v_mul_f32_e32 v32, 0xbfb8aa3b, v112
	v_exp_f32_e32 v32, v32
	v_pk_mul_f32 v[110:111], v[110:111], v[114:115]
	s_nop 0
	v_pk_mul_f32 v[106:107], v[110:111], v[106:107]
	v_add_f32_e32 v32, 1.0, v32
	v_rcp_f32_e32 v110, v32
	v_mul_f32_e32 v32, 0xbfb8aa3b, v113
	v_exp_f32_e32 v32, v32
	v_cvt_pk_bf16_f32 v106, v106, v107
	v_add_f32_e32 v32, 1.0, v32
	v_rcp_f32_e32 v111, v32
	v_mul_f32_e32 v32, 0xbfb8aa3b, v102
	v_exp_f32_e32 v32, v32
	v_pk_mul_f32 v[110:111], v[112:113], v[110:111]
	s_nop 0
	v_pk_mul_f32 v[108:109], v[110:111], v[108:109]
	v_add_f32_e32 v32, 1.0, v32
	v_cvt_pk_bf16_f32 v107, v108, v109
	v_rcp_f32_e32 v108, v32
	v_mul_f32_e32 v32, 0xbfb8aa3b, v103
	v_exp_f32_e32 v32, v32
	s_nop 0
	v_add_f32_e32 v32, 1.0, v32
	v_rcp_f32_e32 v109, v32
	v_mul_f32_e32 v32, 0xbfb8aa3b, v104
	v_exp_f32_e32 v32, v32
	v_pk_mul_f32 v[102:103], v[102:103], v[108:109]
	s_nop 0
	v_pk_mul_f32 v[98:99], v[102:103], v[98:99]
	v_add_f32_e32 v32, 1.0, v32
	v_cvt_pk_bf16_f32 v108, v98, v99
	v_rcp_f32_e32 v98, v32
	v_mul_f32_e32 v32, 0xbfb8aa3b, v105
	v_exp_f32_e32 v32, v32
	s_nop 0
	v_add_f32_e32 v32, 1.0, v32
	v_rcp_f32_e32 v99, v32
	v_mul_f32_e32 v32, 0xbfb8aa3b, v94
	v_exp_f32_e32 v32, v32
	v_pk_mul_f32 v[98:99], v[104:105], v[98:99]
	s_nop 0
	v_pk_mul_f32 v[98:99], v[98:99], v[100:101]
	v_add_f32_e32 v32, 1.0, v32
	v_cvt_pk_bf16_f32 v109, v98, v99
	v_add_co_u32_e32 v98, vcc, s6, v130
	s_mov_b32 s6, 0x2c000
	s_nop 0
	v_addc_co_u32_e32 v99, vcc, 0, v131, vcc
	flat_store_dwordx4 v[98:99], v[106:109]
	v_rcp_f32_e32 v98, v32
	v_mul_f32_e32 v32, 0xbfb8aa3b, v95
	v_exp_f32_e32 v32, v32
	s_nop 0
	v_add_f32_e32 v32, 1.0, v32
	v_rcp_f32_e32 v99, v32
	v_mul_f32_e32 v32, 0xbfb8aa3b, v96
	v_exp_f32_e32 v32, v32
	v_pk_mul_f32 v[94:95], v[94:95], v[98:99]
	s_nop 0
	v_pk_mul_f32 v[90:91], v[94:95], v[90:91]
	v_add_f32_e32 v32, 1.0, v32
	v_rcp_f32_e32 v94, v32
	v_mul_f32_e32 v32, 0xbfb8aa3b, v97
	v_exp_f32_e32 v32, v32
	v_cvt_pk_bf16_f32 v90, v90, v91
	v_add_f32_e32 v32, 1.0, v32
	v_rcp_f32_e32 v95, v32
	v_mul_f32_e32 v32, 0xbfb8aa3b, v86
	v_exp_f32_e32 v32, v32
	v_pk_mul_f32 v[94:95], v[96:97], v[94:95]
	s_nop 0
	v_pk_mul_f32 v[92:93], v[94:95], v[92:93]
	v_add_f32_e32 v32, 1.0, v32
	v_cvt_pk_bf16_f32 v91, v92, v93
	v_rcp_f32_e32 v92, v32
	v_mul_f32_e32 v32, 0xbfb8aa3b, v87
	v_exp_f32_e32 v32, v32
	s_nop 0
	v_add_f32_e32 v32, 1.0, v32
	v_rcp_f32_e32 v93, v32
	v_mul_f32_e32 v32, 0xbfb8aa3b, v88
	v_exp_f32_e32 v32, v32
	v_pk_mul_f32 v[86:87], v[86:87], v[92:93]
	s_nop 0
	v_pk_mul_f32 v[82:83], v[86:87], v[82:83]
	v_add_f32_e32 v32, 1.0, v32
	v_cvt_pk_bf16_f32 v92, v82, v83
	v_rcp_f32_e32 v82, v32
	v_mul_f32_e32 v32, 0xbfb8aa3b, v89
	v_exp_f32_e32 v32, v32
	s_nop 0
	v_add_f32_e32 v32, 1.0, v32
	v_rcp_f32_e32 v83, v32
	v_mul_f32_e32 v32, 0xbfb8aa3b, v78
	v_exp_f32_e32 v32, v32
	v_pk_mul_f32 v[82:83], v[88:89], v[82:83]
	s_nop 0
	v_pk_mul_f32 v[82:83], v[82:83], v[84:85]
	v_add_f32_e32 v32, 1.0, v32
	v_cvt_pk_bf16_f32 v93, v82, v83
	v_add_co_u32_e32 v82, vcc, s6, v130
	s_mov_b32 s6, 0x42000
	s_nop 0
	v_addc_co_u32_e32 v83, vcc, 0, v131, vcc
; DI unsigned pk_bf16(float a, float b) { f32x2_t v = {a, b}; bf16x2_t r = __builtin_convertvector(v, bf16x2_t); return __builtin_bit_cast(unsigned, r); }
; DI float silu_f(float x) { return x * __builtin_amdgcn_rcpf(1.f + __expf(-x)); }
; template <int EPI>
; DI void gemm_phase(const bf16_t* __restrict__ A, const bf16_t* __restrict__ Bt, const int K, const int N, const Params& p, const int layer_j, char* lds) {
;     ...
;         } else if (EPI == EPI_FFN_IN) {
;             bf16_t* HID = (bf16_t*)(ws + OFF_P) + (size_t)(pm * 256 + wr * 64 + fr) * FFN_H + (col0 >> 1) + 8 * fq;
; #pragma unroll
;             for (int ai = 0; ai < 2; ++ai)
; #pragma unroll
;                 for (int m = 0; m < 4; ++m) {
;                     u32x4 o;
; #pragma unroll
;                     for (int n = 0; n < 2; ++n) {
;                         o[2 * n] = pk_bf16(silu_f(acc[ai][0][m][n][0]) * acc[ai][1][m][n][0], silu_f(acc[ai][0][m][n][1]) * acc[ai][1][m][n][1]);
;                         o[2 * n + 1] = pk_bf16(silu_f(acc[ai][0][m][n][2]) * acc[ai][1][m][n][2], silu_f(acc[ai][0][m][n][3]) * acc[ai][1][m][n][3]); }
;                     *(u32x4*)(HID + (size_t)(ai * 128 + m * 16) * FFN_H) = o;
;                 }
	flat_store_dwordx4 v[82:83], v[90:93]
	v_rcp_f32_e32 v82, v32
	v_mul_f32_e32 v32, 0xbfb8aa3b, v79
	v_exp_f32_e32 v32, v32
	s_nop 0
	v_add_f32_e32 v32, 1.0, v32
	v_rcp_f32_e32 v83, v32
	v_mul_f32_e32 v32, 0xbfb8aa3b, v80
	v_exp_f32_e32 v32, v32
	v_pk_mul_f32 v[78:79], v[78:79], v[82:83]
	s_nop 0
	v_pk_mul_f32 v[74:75], v[78:79], v[74:75]
	v_add_f32_e32 v32, 1.0, v32
	v_rcp_f32_e32 v78, v32
	v_mul_f32_e32 v32, 0xbfb8aa3b, v81
	v_exp_f32_e32 v32, v32
	v_cvt_pk_bf16_f32 v74, v74, v75
	v_add_f32_e32 v32, 1.0, v32
	v_rcp_f32_e32 v79, v32
	v_mul_f32_e32 v32, 0xbfb8aa3b, v70
	v_exp_f32_e32 v32, v32
	v_pk_mul_f32 v[78:79], v[80:81], v[78:79]
	s_nop 0
	v_pk_mul_f32 v[76:77], v[78:79], v[76:77]
	v_add_f32_e32 v32, 1.0, v32
	v_cvt_pk_bf16_f32 v75, v76, v77
	v_rcp_f32_e32 v76, v32
	v_mul_f32_e32 v32, 0xbfb8aa3b, v71
	v_exp_f32_e32 v32, v32
	s_nop 0
	v_add_f32_e32 v32, 1.0, v32
	v_rcp_f32_e32 v77, v32
	v_mul_f32_e32 v32, 0xbfb8aa3b, v72
	v_exp_f32_e32 v32, v32
	v_pk_mul_f32 v[70:71], v[70:71], v[76:77]
	s_nop 0
	v_pk_mul_f32 v[66:67], v[70:71], v[66:67]
	v_add_f32_e32 v32, 1.0, v32
	v_cvt_pk_bf16_f32 v76, v66, v67
	v_rcp_f32_e32 v66, v32
	v_mul_f32_e32 v32, 0xbfb8aa3b, v73
	v_exp_f32_e32 v32, v32
	s_nop 0
	v_add_f32_e32 v32, 1.0, v32
	v_rcp_f32_e32 v67, v32
	v_mul_f32_e32 v32, 0xbfb8aa3b, v62
	v_exp_f32_e32 v32, v32
	v_pk_mul_f32 v[66:67], v[72:73], v[66:67]
	s_nop 0
	v_pk_mul_f32 v[66:67], v[66:67], v[68:69]
	v_add_f32_e32 v32, 1.0, v32
	v_cvt_pk_bf16_f32 v77, v66, v67
	v_add_co_u32_e32 v66, vcc, s6, v130
	s_mov_b32 s6, 0xb0000
	s_nop 0
	v_addc_co_u32_e32 v67, vcc, 0, v131, vcc
	flat_store_dwordx4 v[66:67], v[74:77]
	v_rcp_f32_e32 v66, v32
	v_mul_f32_e32 v32, 0xbfb8aa3b, v63
	v_exp_f32_e32 v32, v32
	s_nop 0
	v_add_f32_e32 v32, 1.0, v32
	v_rcp_f32_e32 v67, v32
	v_mul_f32_e32 v32, 0xbfb8aa3b, v64
	v_exp_f32_e32 v32, v32
	v_pk_mul_f32 v[62:63], v[62:63], v[66:67]
	s_nop 0
	v_pk_mul_f32 v[58:59], v[62:63], v[58:59]
	v_add_f32_e32 v32, 1.0, v32
	v_rcp_f32_e32 v62, v32
	v_mul_f32_e32 v32, 0xbfb8aa3b, v65
	v_exp_f32_e32 v32, v32
	v_cvt_pk_bf16_f32 v58, v58, v59
	v_add_f32_e32 v32, 1.0, v32
	v_rcp_f32_e32 v63, v32
	v_mul_f32_e32 v32, 0xbfb8aa3b, v54
	v_exp_f32_e32 v32, v32
	v_pk_mul_f32 v[62:63], v[64:65], v[62:63]
	s_nop 0
	v_pk_mul_f32 v[60:61], v[62:63], v[60:61]
	v_add_f32_e32 v32, 1.0, v32
	v_cvt_pk_bf16_f32 v59, v60, v61
	v_rcp_f32_e32 v60, v32
	v_mul_f32_e32 v32, 0xbfb8aa3b, v55
	v_exp_f32_e32 v32, v32
	s_nop 0
	v_add_f32_e32 v32, 1.0, v32
	v_rcp_f32_e32 v61, v32
	v_mul_f32_e32 v32, 0xbfb8aa3b, v56
	v_exp_f32_e32 v32, v32
	v_pk_mul_f32 v[54:55], v[54:55], v[60:61]
	s_nop 0
	v_pk_mul_f32 v[50:51], v[54:55], v[50:51]
	v_add_f32_e32 v32, 1.0, v32
	v_cvt_pk_bf16_f32 v60, v50, v51
	v_rcp_f32_e32 v50, v32
	v_mul_f32_e32 v32, 0xbfb8aa3b, v57
	v_exp_f32_e32 v32, v32
	s_nop 0
	v_add_f32_e32 v32, 1.0, v32
	v_rcp_f32_e32 v51, v32
	v_mul_f32_e32 v32, 0xbfb8aa3b, v46
	v_exp_f32_e32 v32, v32
	v_pk_mul_f32 v[50:51], v[56:57], v[50:51]
	s_nop 0
	v_pk_mul_f32 v[50:51], v[50:51], v[52:53]
	v_add_f32_e32 v32, 1.0, v32
	v_cvt_pk_bf16_f32 v61, v50, v51
	v_add_co_u32_e32 v50, vcc, s6, v130
	s_mov_b32 s6, 0xc6000
	s_nop 0
	v_addc_co_u32_e32 v51, vcc, 0, v131, vcc
	flat_store_dwordx4 v[50:51], v[58:61]
	v_rcp_f32_e32 v50, v32
	v_mul_f32_e32 v32, 0xbfb8aa3b, v47
	v_exp_f32_e32 v32, v32
	s_nop 0
	v_add_f32_e32 v32, 1.0, v32
	v_rcp_f32_e32 v51, v32
	v_mul_f32_e32 v32, 0xbfb8aa3b, v48
	v_exp_f32_e32 v32, v32
	v_pk_mul_f32 v[46:47], v[46:47], v[50:51]
	s_nop 0
	v_pk_mul_f32 v[42:43], v[46:47], v[42:43]
	v_add_f32_e32 v32, 1.0, v32
	v_rcp_f32_e32 v46, v32
	v_mul_f32_e32 v32, 0xbfb8aa3b, v49
	v_exp_f32_e32 v32, v32
	v_cvt_pk_bf16_f32 v42, v42, v43
	v_add_f32_e32 v32, 1.0, v32
	v_rcp_f32_e32 v47, v32
	v_mul_f32_e32 v32, 0xbfb8aa3b, v38
	v_exp_f32_e32 v32, v32
	v_pk_mul_f32 v[46:47], v[48:49], v[46:47]
	s_nop 0
	v_pk_mul_f32 v[44:45], v[46:47], v[44:45]
	v_add_f32_e32 v32, 1.0, v32
	v_cvt_pk_bf16_f32 v43, v44, v45
	v_rcp_f32_e32 v44, v32
	v_mul_f32_e32 v32, 0xbfb8aa3b, v39
	v_exp_f32_e32 v32, v32
	s_nop 0
; DI unsigned pk_bf16(float a, float b) { f32x2_t v = {a, b}; bf16x2_t r = __builtin_convertvector(v, bf16x2_t); return __builtin_bit_cast(unsigned, r); }
; DI float silu_f(float x) { return x * __builtin_amdgcn_rcpf(1.f + __expf(-x)); }
; #define BAR __builtin_amdgcn_s_barrier()
; template <int EPI>
; DI void gemm_phase(const bf16_t* __restrict__ A, const bf16_t* __restrict__ Bt, const int K, const int N, const Params& p, const int layer_j, char* lds) {
;     ...
;         } else if (EPI == EPI_FFN_IN) {
;             bf16_t* HID = (bf16_t*)(ws + OFF_P) + (size_t)(pm * 256 + wr * 64 + fr) * FFN_H + (col0 >> 1) + 8 * fq;
; #pragma unroll
;             for (int ai = 0; ai < 2; ++ai)
; #pragma unroll
;                 for (int m = 0; m < 4; ++m) {
;                     u32x4 o;
; #pragma unroll
;                     for (int n = 0; n < 2; ++n) {
;                         o[2 * n] = pk_bf16(silu_f(acc[ai][0][m][n][0]) * acc[ai][1][m][n][0], silu_f(acc[ai][0][m][n][1]) * acc[ai][1][m][n][1]);
;                         o[2 * n + 1] = pk_bf16(silu_f(acc[ai][0][m][n][2]) * acc[ai][1][m][n][2], silu_f(acc[ai][0][m][n][3]) * acc[ai][1][m][n][3]); }
;                     *(u32x4*)(HID + (size_t)(ai * 128 + m * 16) * FFN_H) = o;
;                 }
;     ...
;         if (!has_next) break;
; #pragma unroll
;         for (int a = 0; a < 2; ++a)
; #pragma unroll
;             for (int b = 0; b < 2; ++b)
; #pragma unroll
;                 for (int m = 0; m < 4; ++m)
; #pragma unroll
;                     for (int n = 0; n < 2; ++n) acc[a][b][m][n] = (f32x4){0.f, 0.f, 0.f, 0.f};
;         pm = pm2; pn = pn2; cA = nA; cB = nB;
;         if (wr == 1) BAR;
;     }
	v_add_f32_e32 v32, 1.0, v32
	v_rcp_f32_e32 v45, v32
	s_nop 0
	v_pk_mul_f32 v[38:39], v[38:39], v[44:45]
	s_nop 0
	v_pk_mul_f32 v[28:29], v[38:39], v[28:29]
	s_nop 0
	v_cvt_pk_bf16_f32 v44, v28, v29
	v_mul_f32_e32 v28, 0xbfb8aa3b, v40
	v_mul_f32_e32 v29, 0xbfb8aa3b, v41
	v_exp_f32_e32 v28, v28
	v_exp_f32_e32 v29, v29
	v_add_f32_e32 v28, 1.0, v28
	v_add_f32_e32 v29, 1.0, v29
	v_rcp_f32_e32 v28, v28
	v_rcp_f32_e32 v29, v29
	s_nop 0
	v_pk_mul_f32 v[28:29], v[40:41], v[28:29]
	s_nop 0
	v_pk_mul_f32 v[28:29], v[28:29], v[30:31]
	s_nop 0
	v_cvt_pk_bf16_f32 v45, v28, v29
	v_add_co_u32_e32 v28, vcc, s6, v130
	s_mov_b32 s6, 0xdc000
	s_nop 0
	v_addc_co_u32_e32 v29, vcc, 0, v131, vcc
	flat_store_dwordx4 v[28:29], v[42:45]
	v_mul_f32_e32 v28, 0xbfb8aa3b, v24
	v_mul_f32_e32 v29, 0xbfb8aa3b, v25
	v_exp_f32_e32 v28, v28
	v_exp_f32_e32 v29, v29
	v_add_f32_e32 v28, 1.0, v28
	v_add_f32_e32 v29, 1.0, v29
	v_rcp_f32_e32 v28, v28
	v_rcp_f32_e32 v29, v29
	s_nop 0
	v_pk_mul_f32 v[24:25], v[24:25], v[28:29]
	s_nop 0
	v_pk_mul_f32 v[24:25], v[24:25], v[34:35]
	s_nop 0
	v_cvt_pk_bf16_f32 v24, v24, v25
	v_mul_f32_e32 v25, 0xbfb8aa3b, v26
	v_exp_f32_e32 v25, v25
	s_nop 0
	v_add_f32_e32 v25, 1.0, v25
	v_rcp_f32_e32 v28, v25
	v_mul_f32_e32 v25, 0xbfb8aa3b, v27
	v_exp_f32_e32 v25, v25
	s_nop 0
	v_add_f32_e32 v25, 1.0, v25
	v_rcp_f32_e32 v29, v25
	s_nop 0
	v_pk_mul_f32 v[26:27], v[26:27], v[28:29]
	s_nop 0
	v_pk_mul_f32 v[26:27], v[26:27], v[36:37]
	s_nop 0
	v_cvt_pk_bf16_f32 v25, v26, v27
	v_mul_f32_e32 v26, 0xbfb8aa3b, v16
	v_mul_f32_e32 v27, 0xbfb8aa3b, v17
	v_exp_f32_e32 v26, v26
	v_exp_f32_e32 v27, v27
	v_add_f32_e32 v26, 1.0, v26
	v_add_f32_e32 v27, 1.0, v27
	v_rcp_f32_e32 v26, v26
	v_rcp_f32_e32 v27, v27
	s_nop 0
	v_pk_mul_f32 v[16:17], v[16:17], v[26:27]
	s_nop 0
	v_pk_mul_f32 v[16:17], v[16:17], v[20:21]
	s_nop 0
	v_cvt_pk_bf16_f32 v26, v16, v17
	v_mul_f32_e32 v16, 0xbfb8aa3b, v18
	v_mul_f32_e32 v17, 0xbfb8aa3b, v19
	v_exp_f32_e32 v16, v16
	v_exp_f32_e32 v17, v17
	v_add_f32_e32 v16, 1.0, v16
	v_add_f32_e32 v17, 1.0, v17
	v_rcp_f32_e32 v16, v16
	v_rcp_f32_e32 v17, v17
	s_nop 0
	v_pk_mul_f32 v[16:17], v[18:19], v[16:17]
	s_nop 0
	v_pk_mul_f32 v[16:17], v[16:17], v[22:23]
	s_nop 0
	v_cvt_pk_bf16_f32 v27, v16, v17
	v_add_co_u32_e32 v16, vcc, s6, v130
	s_nop 1
	v_addc_co_u32_e32 v17, vcc, 0, v131, vcc
	flat_store_dwordx4 v[16:17], v[24:27]
	v_mul_f32_e32 v16, 0xbfb8aa3b, v8
	v_mul_f32_e32 v17, 0xbfb8aa3b, v9
	v_exp_f32_e32 v16, v16
	v_exp_f32_e32 v17, v17
	v_add_f32_e32 v16, 1.0, v16
	v_add_f32_e32 v17, 1.0, v17
	v_rcp_f32_e32 v16, v16
	v_rcp_f32_e32 v17, v17
	s_nop 0
	v_pk_mul_f32 v[8:9], v[8:9], v[16:17]
	s_nop 0
	v_pk_mul_f32 v[8:9], v[8:9], v[12:13]
	s_nop 0
	v_cvt_pk_bf16_f32 v8, v8, v9
	v_mul_f32_e32 v9, 0xbfb8aa3b, v10
	v_exp_f32_e32 v9, v9
	s_nop 0
	v_add_f32_e32 v9, 1.0, v9
	v_rcp_f32_e32 v12, v9
	v_mul_f32_e32 v9, 0xbfb8aa3b, v11
	v_exp_f32_e32 v9, v9
	s_nop 0
	v_add_f32_e32 v9, 1.0, v9
	v_rcp_f32_e32 v13, v9
	s_nop 0
	v_pk_mul_f32 v[10:11], v[10:11], v[12:13]
	s_nop 0
	v_pk_mul_f32 v[10:11], v[10:11], v[14:15]
	s_nop 0
	v_cvt_pk_bf16_f32 v9, v10, v11
	v_mul_f32_e32 v10, 0xbfb8aa3b, v0
	v_mul_f32_e32 v11, 0xbfb8aa3b, v1
	v_exp_f32_e32 v10, v10
	v_exp_f32_e32 v11, v11
	v_add_f32_e32 v10, 1.0, v10
	v_add_f32_e32 v11, 1.0, v11
	v_rcp_f32_e32 v10, v10
	v_rcp_f32_e32 v11, v11
	s_nop 0
	v_pk_mul_f32 v[0:1], v[0:1], v[10:11]
	s_nop 0
	v_pk_mul_f32 v[0:1], v[0:1], v[4:5]
	s_nop 0
	v_cvt_pk_bf16_f32 v10, v0, v1
	v_mul_f32_e32 v0, 0xbfb8aa3b, v2
	v_mul_f32_e32 v1, 0xbfb8aa3b, v3
	v_exp_f32_e32 v0, v0
	v_exp_f32_e32 v1, v1
	v_add_f32_e32 v0, 1.0, v0
	v_add_f32_e32 v1, 1.0, v1
	v_rcp_f32_e32 v0, v0
	v_rcp_f32_e32 v1, v1
	s_nop 0
	v_pk_mul_f32 v[0:1], v[2:3], v[0:1]
	s_nop 0
	v_pk_mul_f32 v[0:1], v[0:1], v[6:7]
	s_nop 0
	v_cvt_pk_bf16_f32 v11, v0, v1
	v_add_co_u32_e32 v0, vcc, 0xf2000, v130
	s_nop 1
	v_addc_co_u32_e32 v1, vcc, 0, v131, vcc
	s_andn2_b64 vcc, exec, s[18:19]
	flat_store_dwordx4 v[0:1], v[8:11]
	s_cbranch_vccnz .LBB0_39
	s_and_b64 vcc, exec, s[4:5]
	s_cbranch_vccnz .LBB0_38
	s_barrier
	s_branch .LBB0_38

; DI int obid() { int b = blockIdx.x; asm volatile("" : "+s"(b)); return b; }
; DI int ogrid() { int g = gridDim.x; asm volatile("" : "+s"(g)); return g; }
; DI int otid_w(int gw) { return (gw << 6) | olane(); }
; DI float shx(float v, int mask) { const int l = olane(); return __builtin_bit_cast(float, __builtin_amdgcn_ds_bpermute(((l ^ mask) & 63) << 2, __builtin_bit_cast(int, v))); }
; DI void row_phase(const bf16_t* msrc, const float* xsrc, float* xdst, const float* g_post, const float* g_next, bf16_t* hdst, const int gw) {
;     ...
;     const int tid = otid_w(gw); const int lane = tid & 63, w = tid >> 6;
;     const int wg = obid() * 8 + w, nw = ogrid() * 8;
;     for (int rowb = wg * RB; rowb < M_TOK; rowb += nw * RB) {
;         f32x4 xv[RB][4], mv[RB][4];
; #pragma unroll
;         for (int r = 0; r < RB; ++r)
; #pragma unroll
;             for (int j = 0; j < 4; ++j) xv[r][j] = *(const f32x4*)(xsrc + (size_t)(rowb + r) * DM + lane * 4 + 256 * j);
;         if (msrc) {
; #pragma unroll
;             for (int r = 0; r < RB; ++r)
; #pragma unroll
;                 for (int j = 0; j < 4; ++j) { const u32x2 mw = *(const u32x2*)(msrc + (size_t)(rowb + r) * DM + lane * 4 + 256 * j);
;                     mv[r][j] = (f32x4){__uint_as_float(mw[0] << 16), __uint_as_float(mw[0] & 0xffff0000u), __uint_as_float(mw[1] << 16), __uint_as_float(mw[1] & 0xffff0000u)}; }
;             float ss[RB];
; #pragma unroll
;             for (int r = 0; r < RB; ++r) { ss[r] = 0.f;
; #pragma unroll
;                 for (int j = 0; j < 4; ++j) ss[r] += mv[r][j][0] * mv[r][j][0] + mv[r][j][1] * mv[r][j][1] + mv[r][j][2] * mv[r][j][2] + mv[r][j][3] * mv[r][j][3]; }
; #pragma unroll
;             for (int o = 32; o >= 1; o >>= 1)
; #pragma unroll
;                 for (int r = 0; r < RB; ++r) ss[r] += shx(ss[r], o);
; #pragma unroll
;             for (int j = 0; j < 4; ++j) { const f32x4 g = *(const f32x4*)(g_post + lane * 4 + 256 * j);
; #pragma unroll
;                 for (int r = 0; r < RB; ++r) { const float r1 = rsqrtf(ss[r] * (1.f / DM) + EPS); xv[r][j] = xv[r][j] + mv[r][j] * r1 * g; *(f32x4*)(xdst + (size_t)(rowb + r) * DM + lane * 4 + 256 * j) = xv[r][j]; } }
.Lrow_r1:
	v_writelane_b32 v3, s4, 0
	v_writelane_b32 v3, s5, 1
	v_writelane_b32 v3, s6, 2
	v_writelane_b32 v3, s7, 3
	v_writelane_b32 v3, s8, 4
	v_writelane_b32 v3, s9, 5
	v_writelane_b32 v3, s10, 6
	v_writelane_b32 v3, s11, 7
	v_writelane_b32 v3, s12, 8
	v_writelane_b32 v3, s13, 9
	v_writelane_b32 v3, s14, 10
	v_writelane_b32 v3, s15, 11
	v_writelane_b32 v3, s16, 12
	v_writelane_b32 v3, s17, 13
	v_writelane_b32 v3, s18, 14
	v_writelane_b32 v3, s19, 15
	v_writelane_b32 v3, s20, 16
	v_writelane_b32 v3, s21, 17
	v_writelane_b32 v3, s22, 18
	v_writelane_b32 v3, s23, 19
	v_writelane_b32 v3, s24, 20
	v_writelane_b32 v3, s25, 21
	s_waitcnt vmcnt(0) lgkmcnt(0)
	v_mbcnt_lo_u32_b32 v0, -1, 0
	v_mbcnt_hi_u32_b32 v0, -1, v0
	v_lshlrev_b32_e32 v1, 5, v0
	v_lshlrev_b32_e32 v2, 4, v0
	s_lshr_b32 s4, s71, 6
	s_and_b32 s5, s2, 7
	s_lshl_b32 s5, s5, 8
	s_lshr_b32 s24, s2, 3
	s_lshl_b32 s24, s24, 3
	s_add_i32 s5, s5, s24
	s_add_i32 s5, s5, s4
	s_lshl_b32 s24, s5, 15
	s_lshl_b32 s25, s5, 14
	v_readlane_b32 s8, v254, 62
	v_readlane_b32 s9, v254, 63
	v_readlane_b32 s6, v255, 2
	v_readlane_b32 s7, v255, 3
	v_readlane_b32 s4, v255, 6
	v_readlane_b32 s16, v255, 10
	v_readlane_b32 s17, v255, 11
	s_nop 1
	s_cmp_eq_u32 s4, 0
	s_cselect_b32 s6, s6, s8
	s_cselect_b32 s7, s7, s9
	s_add_u32 s6, s6, s24
	s_addc_u32 s7, s7, 0
	s_add_u32 s8, s8, s24
	s_addc_u32 s9, s9, 0
	s_add_u32 s10, s68, 0x10681000
	s_addc_u32 s11, s69, 0
	s_add_u32 s10, s10, s25
	s_addc_u32 s11, s11, 0
	s_and_b32 s12, s2, 7
	s_lshl_b32 s12, s12, 22
	s_add_u32 s10, s10, s12
	s_addc_u32 s11, s11, 0
	s_add_u32 s12, s10, 0x400000
	s_addc_u32 s13, s11, 0
	s_add_u32 s14, s82, s25
	s_addc_u32 s15, s83, 0
	s_add_u32 s18, s16, 0x1000
	s_addc_u32 s19, s17, 0
	global_load_dwordx4 v[40:43], v1, s[18:19] offset:0
	global_load_dwordx4 v[44:47], v1, s[18:19] offset:16
	global_load_dwordx4 v[48:51], v1, s[18:19] offset:2048
	global_load_dwordx4 v[52:55], v1, s[18:19] offset:2064
	s_add_u32 s18, s16, 0x2000
	s_addc_u32 s19, s17, 0
	global_load_dwordx4 v[56:59], v1, s[18:19] offset:0
	global_load_dwordx4 v[60:63], v1, s[18:19] offset:16
	global_load_dwordx4 v[64:67], v1, s[18:19] offset:2048
	global_load_dwordx4 v[68:71], v1, s[18:19] offset:2064
	global_load_dwordx4 v[96:99], v1, s[6:7] offset:0
	global_load_dwordx4 v[100:103], v1, s[6:7] offset:16
	global_load_dwordx4 v[104:107], v1, s[6:7] offset:2048
	global_load_dwordx4 v[108:111], v1, s[6:7] offset:2064
	global_load_dwordx4 v[112:115], v2, s[10:11]
	global_load_dwordx4 v[116:119], v2, s[10:11] offset:1024
	s_add_u32 s6, s6, 0x1000
	s_addc_u32 s7, s7, 0
	s_add_u32 s10, s10, 0x800
	s_addc_u32 s11, s11, 0
	global_load_dwordx4 v[128:131], v1, s[6:7] offset:0
	global_load_dwordx4 v[132:135], v1, s[6:7] offset:16
	global_load_dwordx4 v[136:139], v1, s[6:7] offset:2048
	global_load_dwordx4 v[140:143], v1, s[6:7] offset:2064
	global_load_dwordx4 v[144:147], v2, s[10:11]
	global_load_dwordx4 v[148:151], v2, s[10:11] offset:1024
	s_add_u32 s6, s6, 0x1000
	s_addc_u32 s7, s7, 0
	s_add_u32 s10, s10, 0x800
	s_addc_u32 s11, s11, 0
	global_load_dwordx4 v[160:163], v1, s[6:7] offset:0
	global_load_dwordx4 v[164:167], v1, s[6:7] offset:16
	global_load_dwordx4 v[168:171], v1, s[6:7] offset:2048
	global_load_dwordx4 v[172:175], v1, s[6:7] offset:2064
	global_load_dwordx4 v[176:179], v2, s[10:11]
	global_load_dwordx4 v[180:183], v2, s[10:11] offset:1024
	s_add_u32 s6, s6, 0x1000
	s_addc_u32 s7, s7, 0
	s_add_u32 s10, s10, 0x800
	s_addc_u32 s11, s11, 0
	s_waitcnt vmcnt(12)
	v_lshlrev_b32_e32 v208, 16, v112
	v_and_b32_e32 v209, 0xffff0000, v112
	v_lshlrev_b32_e32 v210, 16, v113
	v_and_b32_e32 v211, 0xffff0000, v113
	v_lshlrev_b32_e32 v212, 16, v114
	v_and_b32_e32 v213, 0xffff0000, v114
	v_lshlrev_b32_e32 v214, 16, v115
	v_and_b32_e32 v215, 0xffff0000, v115
	v_lshlrev_b32_e32 v216, 16, v116
	v_and_b32_e32 v217, 0xffff0000, v116
	v_lshlrev_b32_e32 v218, 16, v117
	v_and_b32_e32 v219, 0xffff0000, v117
	v_lshlrev_b32_e32 v220, 16, v118
	v_and_b32_e32 v221, 0xffff0000, v118
	v_lshlrev_b32_e32 v222, 16, v119
	v_and_b32_e32 v223, 0xffff0000, v119
	v_mul_f32_e32 v224, v208, v208
	v_fmac_f32_e32 v224, v209, v209
	v_fmac_f32_e32 v224, v210, v210
	v_fmac_f32_e32 v224, v211, v211
	v_fmac_f32_e32 v224, v212, v212
	v_fmac_f32_e32 v224, v213, v213
	v_fmac_f32_e32 v224, v214, v214
	v_fmac_f32_e32 v224, v215, v215
	v_fmac_f32_e32 v224, v216, v216
	v_fmac_f32_e32 v224, v217, v217
	v_fmac_f32_e32 v224, v218, v218
	v_fmac_f32_e32 v224, v219, v219
	v_fmac_f32_e32 v224, v220, v220
	v_fmac_f32_e32 v224, v221, v221
	v_fmac_f32_e32 v224, v222, v222
	v_fmac_f32_e32 v224, v223, v223
	s_nop 1
	v_add_f32_dpp v224, v224, v224 quad_perm:[1,0,3,2] row_mask:0xf bank_mask:0xf
	s_nop 1
	v_add_f32_dpp v224, v224, v224 quad_perm:[2,3,0,1] row_mask:0xf bank_mask:0xf
	s_nop 1
	v_add_f32_dpp v224, v224, v224 row_ror:4 row_mask:0xf bank_mask:0xf
	s_nop 1
	v_add_f32_dpp v224, v224, v224 row_ror:8 row_mask:0xf bank_mask:0xf
	s_nop 1
	v_readlane_b32 s20, v224, 0
	v_readlane_b32 s21, v224, 16
	v_readlane_b32 s22, v224, 32
	v_readlane_b32 s23, v224, 48
	s_nop 1
	v_mov_b32_e32 v225, s20
	v_add_f32_e32 v225, s21, v225
	v_add_f32_e32 v225, s22, v225
	v_add_f32_e32 v225, s23, v225
	v_mov_b32_e32 v226, 0x358637bd
	v_fmac_f32_e32 v226, 0x3a800000, v225
	v_rsq_f32_e32 v226, v226
	s_nop 0
	v_mul_f32_e32 v208, v208, v226
	v_mul_f32_e32 v209, v209, v226
	v_mul_f32_e32 v210, v210, v226
	v_mul_f32_e32 v211, v211, v226
	v_mul_f32_e32 v212, v212, v226
	v_mul_f32_e32 v213, v213, v226
	v_mul_f32_e32 v214, v214, v226
	v_mul_f32_e32 v215, v215, v226
	v_mul_f32_e32 v216, v216, v226
	v_mul_f32_e32 v217, v217, v226
	v_mul_f32_e32 v218, v218, v226
; DI unsigned pk_bf16(float a, float b) { f32x2_t v = {a, b}; bf16x2_t r = __builtin_convertvector(v, bf16x2_t); return __builtin_bit_cast(unsigned, r); }
; DI float shx(float v, int mask) { const int l = olane(); return __builtin_bit_cast(float, __builtin_amdgcn_ds_bpermute(((l ^ mask) & 63) << 2, __builtin_bit_cast(int, v))); }
; DI void row_phase(const bf16_t* msrc, const float* xsrc, float* xdst, const float* g_post, const float* g_next, bf16_t* hdst, const int gw) {
;     ...
;             for (int j = 0; j < 4; ++j) { const f32x4 g = *(const f32x4*)(g_post + lane * 4 + 256 * j);
; #pragma unroll
;                 for (int r = 0; r < RB; ++r) { const float r1 = rsqrtf(ss[r] * (1.f / DM) + EPS); xv[r][j] = xv[r][j] + mv[r][j] * r1 * g; *(f32x4*)(xdst + (size_t)(rowb + r) * DM + lane * 4 + 256 * j) = xv[r][j]; } }
;         }
;         if (hdst) {
;             float ss[RB];
; #pragma unroll
;             for (int r = 0; r < RB; ++r) { ss[r] = 0.f;
; #pragma unroll
;                 for (int j = 0; j < 4; ++j) ss[r] += xv[r][j][0] * xv[r][j][0] + xv[r][j][1] * xv[r][j][1] + xv[r][j][2] * xv[r][j][2] + xv[r][j][3] * xv[r][j][3]; }
; #pragma unroll
;             for (int o = 32; o >= 1; o >>= 1)
; #pragma unroll
;                 for (int r = 0; r < RB; ++r) ss[r] += shx(ss[r], o);
; #pragma unroll
;             for (int j = 0; j < 4; ++j) { const f32x4 g = *(const f32x4*)(g_next + lane * 4 + 256 * j);
; #pragma unroll
;                 for (int r = 0; r < RB; ++r) { const float r2 = rsqrtf(ss[r] * (1.f / DM) + EPS); const f32x4 hv = xv[r][j] * r2 * g;
;                     u32x2 o; o[0] = pk_bf16(hv[0], hv[1]); o[1] = pk_bf16(hv[2], hv[3]); *(u32x2*)(hdst + (size_t)(rowb + r) * DM + lane * 4 + 256 * j) = o; } }
	v_mul_f32_e32 v219, v219, v226
	v_mul_f32_e32 v220, v220, v226
	v_mul_f32_e32 v221, v221, v226
	v_mul_f32_e32 v222, v222, v226
	v_mul_f32_e32 v223, v223, v226
	v_fmac_f32_e32 v96, v208, v40
	v_fmac_f32_e32 v97, v209, v41
	v_fmac_f32_e32 v98, v210, v42
	v_fmac_f32_e32 v99, v211, v43
	v_fmac_f32_e32 v100, v212, v44
	v_fmac_f32_e32 v101, v213, v45
	v_fmac_f32_e32 v102, v214, v46
	v_fmac_f32_e32 v103, v215, v47
	v_fmac_f32_e32 v104, v216, v48
	v_fmac_f32_e32 v105, v217, v49
	v_fmac_f32_e32 v106, v218, v50
	v_fmac_f32_e32 v107, v219, v51
	v_fmac_f32_e32 v108, v220, v52
	v_fmac_f32_e32 v109, v221, v53
	v_fmac_f32_e32 v110, v222, v54
	v_fmac_f32_e32 v111, v223, v55
	v_mul_f32_e32 v224, v96, v96
	v_fmac_f32_e32 v224, v97, v97
	v_fmac_f32_e32 v224, v98, v98
	v_fmac_f32_e32 v224, v99, v99
	v_fmac_f32_e32 v224, v100, v100
	v_fmac_f32_e32 v224, v101, v101
	v_fmac_f32_e32 v224, v102, v102
	v_fmac_f32_e32 v224, v103, v103
	v_fmac_f32_e32 v224, v104, v104
	v_fmac_f32_e32 v224, v105, v105
	v_fmac_f32_e32 v224, v106, v106
	v_fmac_f32_e32 v224, v107, v107
	v_fmac_f32_e32 v224, v108, v108
	v_fmac_f32_e32 v224, v109, v109
	v_fmac_f32_e32 v224, v110, v110
	v_fmac_f32_e32 v224, v111, v111
	s_nop 1
	v_add_f32_dpp v224, v224, v224 quad_perm:[1,0,3,2] row_mask:0xf bank_mask:0xf
	s_nop 1
	v_add_f32_dpp v224, v224, v224 quad_perm:[2,3,0,1] row_mask:0xf bank_mask:0xf
	s_nop 1
	v_add_f32_dpp v224, v224, v224 row_ror:4 row_mask:0xf bank_mask:0xf
	s_nop 1
	v_add_f32_dpp v224, v224, v224 row_ror:8 row_mask:0xf bank_mask:0xf
	s_nop 1
	v_readlane_b32 s20, v224, 0
	v_readlane_b32 s21, v224, 16
	v_readlane_b32 s22, v224, 32
	v_readlane_b32 s23, v224, 48
	s_nop 1
	v_mov_b32_e32 v225, s20
	v_add_f32_e32 v225, s21, v225
	v_add_f32_e32 v225, s22, v225
	v_add_f32_e32 v225, s23, v225
	v_mov_b32_e32 v226, 0x358637bd
	v_fmac_f32_e32 v226, 0x3a800000, v225
	v_rsq_f32_e32 v226, v226
	s_nop 0
	v_mul_f32_e32 v208, v96, v226
	v_mul_f32_e32 v209, v97, v226
	v_mul_f32_e32 v210, v98, v226
	v_mul_f32_e32 v211, v99, v226
	v_mul_f32_e32 v212, v100, v226
	v_mul_f32_e32 v213, v101, v226
	v_mul_f32_e32 v214, v102, v226
	v_mul_f32_e32 v215, v103, v226
	v_mul_f32_e32 v216, v104, v226
	v_mul_f32_e32 v217, v105, v226
	v_mul_f32_e32 v218, v106, v226
	v_mul_f32_e32 v219, v107, v226
	v_mul_f32_e32 v220, v108, v226
	v_mul_f32_e32 v221, v109, v226
	v_mul_f32_e32 v222, v110, v226
	v_mul_f32_e32 v223, v111, v226
	v_mul_f32_e32 v208, v208, v56
	v_mul_f32_e32 v209, v209, v57
	v_mul_f32_e32 v210, v210, v58
	v_mul_f32_e32 v211, v211, v59
	v_mul_f32_e32 v212, v212, v60
	v_mul_f32_e32 v213, v213, v61
	v_mul_f32_e32 v214, v214, v62
	v_mul_f32_e32 v215, v215, v63
	v_mul_f32_e32 v216, v216, v64
	v_mul_f32_e32 v217, v217, v65
	v_mul_f32_e32 v218, v218, v66
	v_mul_f32_e32 v219, v219, v67
	v_mul_f32_e32 v220, v220, v68
	v_mul_f32_e32 v221, v221, v69
	v_mul_f32_e32 v222, v222, v70
	v_mul_f32_e32 v223, v223, v71
	v_cvt_pk_bf16_f32 v112, v208, v209
	v_cvt_pk_bf16_f32 v113, v210, v211
	v_cvt_pk_bf16_f32 v114, v212, v213
	v_cvt_pk_bf16_f32 v115, v214, v215
	v_cvt_pk_bf16_f32 v116, v216, v217
	v_cvt_pk_bf16_f32 v117, v218, v219
	v_cvt_pk_bf16_f32 v118, v220, v221
	v_cvt_pk_bf16_f32 v119, v222, v223
	global_store_dwordx4 v2, v[112:115], s[14:15]
	global_store_dwordx4 v2, v[116:119], s[14:15] offset:1024
	s_add_u32 s14, s14, 0x800
	s_addc_u32 s15, s15, 0
	global_load_dwordx4 v[96:99], v1, s[6:7] offset:0
	global_load_dwordx4 v[100:103], v1, s[6:7] offset:16
	global_load_dwordx4 v[104:107], v1, s[6:7] offset:2048
	global_load_dwordx4 v[108:111], v1, s[6:7] offset:2064
	global_load_dwordx4 v[112:115], v2, s[10:11]
	global_load_dwordx4 v[116:119], v2, s[10:11] offset:1024
	s_add_u32 s6, s6, 0x1000
	s_addc_u32 s7, s7, 0
	s_add_u32 s10, s10, 0x800
	s_addc_u32 s11, s11, 0
	s_waitcnt vmcnt(14)
	v_lshlrev_b32_e32 v208, 16, v144
	v_and_b32_e32 v209, 0xffff0000, v144
	v_lshlrev_b32_e32 v210, 16, v145
	v_and_b32_e32 v211, 0xffff0000, v145
	v_lshlrev_b32_e32 v212, 16, v146
	v_and_b32_e32 v213, 0xffff0000, v146
	v_lshlrev_b32_e32 v214, 16, v147
	v_and_b32_e32 v215, 0xffff0000, v147
	v_lshlrev_b32_e32 v216, 16, v148
	v_and_b32_e32 v217, 0xffff0000, v148
	v_lshlrev_b32_e32 v218, 16, v149
	v_and_b32_e32 v219, 0xffff0000, v149
	v_lshlrev_b32_e32 v220, 16, v150
	v_and_b32_e32 v221, 0xffff0000, v150
	v_lshlrev_b32_e32 v222, 16, v151
	v_and_b32_e32 v223, 0xffff0000, v151
	v_mul_f32_e32 v224, v208, v208
	v_fmac_f32_e32 v224, v209, v209
	v_fmac_f32_e32 v224, v210, v210
	v_fmac_f32_e32 v224, v211, v211
	v_fmac_f32_e32 v224, v212, v212
	v_fmac_f32_e32 v224, v213, v213
	v_fmac_f32_e32 v224, v214, v214
	v_fmac_f32_e32 v224, v215, v215
	v_fmac_f32_e32 v224, v216, v216
	v_fmac_f32_e32 v224, v217, v217
	v_fmac_f32_e32 v224, v218, v218
	v_fmac_f32_e32 v224, v219, v219
	v_fmac_f32_e32 v224, v220, v220
	v_fmac_f32_e32 v224, v221, v221
	v_fmac_f32_e32 v224, v222, v222
	v_fmac_f32_e32 v224, v223, v223
	s_nop 1
	v_add_f32_dpp v224, v224, v224 quad_perm:[1,0,3,2] row_mask:0xf bank_mask:0xf
	s_nop 1
	v_add_f32_dpp v224, v224, v224 quad_perm:[2,3,0,1] row_mask:0xf bank_mask:0xf
	s_nop 1
	v_add_f32_dpp v224, v224, v224 row_ror:4 row_mask:0xf bank_mask:0xf
	s_nop 1
	v_add_f32_dpp v224, v224, v224 row_ror:8 row_mask:0xf bank_mask:0xf
	s_nop 1
	v_readlane_b32 s20, v224, 0
	v_readlane_b32 s21, v224, 16
	v_readlane_b32 s22, v224, 32
	v_readlane_b32 s23, v224, 48
	s_nop 1
	v_mov_b32_e32 v225, s20
	v_add_f32_e32 v225, s21, v225
	v_add_f32_e32 v225, s22, v225
	v_add_f32_e32 v225, s23, v225
	v_mov_b32_e32 v226, 0x358637bd
	v_fmac_f32_e32 v226, 0x3a800000, v225
	v_rsq_f32_e32 v226, v226
	s_nop 0
	v_mul_f32_e32 v208, v208, v226
	v_mul_f32_e32 v209, v209, v226
; DI unsigned pk_bf16(float a, float b) { f32x2_t v = {a, b}; bf16x2_t r = __builtin_convertvector(v, bf16x2_t); return __builtin_bit_cast(unsigned, r); }
; DI float shx(float v, int mask) { const int l = olane(); return __builtin_bit_cast(float, __builtin_amdgcn_ds_bpermute(((l ^ mask) & 63) << 2, __builtin_bit_cast(int, v))); }
; DI void row_phase(const bf16_t* msrc, const float* xsrc, float* xdst, const float* g_post, const float* g_next, bf16_t* hdst, const int gw) {
;     ...
;             for (int j = 0; j < 4; ++j) { const f32x4 g = *(const f32x4*)(g_post + lane * 4 + 256 * j);
; #pragma unroll
;                 for (int r = 0; r < RB; ++r) { const float r1 = rsqrtf(ss[r] * (1.f / DM) + EPS); xv[r][j] = xv[r][j] + mv[r][j] * r1 * g; *(f32x4*)(xdst + (size_t)(rowb + r) * DM + lane * 4 + 256 * j) = xv[r][j]; } }
;         }
;         if (hdst) {
;             float ss[RB];
; #pragma unroll
;             for (int r = 0; r < RB; ++r) { ss[r] = 0.f;
; #pragma unroll
;                 for (int j = 0; j < 4; ++j) ss[r] += xv[r][j][0] * xv[r][j][0] + xv[r][j][1] * xv[r][j][1] + xv[r][j][2] * xv[r][j][2] + xv[r][j][3] * xv[r][j][3]; }
; #pragma unroll
;             for (int o = 32; o >= 1; o >>= 1)
; #pragma unroll
;                 for (int r = 0; r < RB; ++r) ss[r] += shx(ss[r], o);
; #pragma unroll
;             for (int j = 0; j < 4; ++j) { const f32x4 g = *(const f32x4*)(g_next + lane * 4 + 256 * j);
; #pragma unroll
;                 for (int r = 0; r < RB; ++r) { const float r2 = rsqrtf(ss[r] * (1.f / DM) + EPS); const f32x4 hv = xv[r][j] * r2 * g;
;                     u32x2 o; o[0] = pk_bf16(hv[0], hv[1]); o[1] = pk_bf16(hv[2], hv[3]); *(u32x2*)(hdst + (size_t)(rowb + r) * DM + lane * 4 + 256 * j) = o; } }
	v_mul_f32_e32 v210, v210, v226
	v_mul_f32_e32 v211, v211, v226
	v_mul_f32_e32 v212, v212, v226
	v_mul_f32_e32 v213, v213, v226
	v_mul_f32_e32 v214, v214, v226
	v_mul_f32_e32 v215, v215, v226
	v_mul_f32_e32 v216, v216, v226
	v_mul_f32_e32 v217, v217, v226
	v_mul_f32_e32 v218, v218, v226
	v_mul_f32_e32 v219, v219, v226
	v_mul_f32_e32 v220, v220, v226
	v_mul_f32_e32 v221, v221, v226
	v_mul_f32_e32 v222, v222, v226
	v_mul_f32_e32 v223, v223, v226
	v_fmac_f32_e32 v128, v208, v40
	v_fmac_f32_e32 v129, v209, v41
	v_fmac_f32_e32 v130, v210, v42
	v_fmac_f32_e32 v131, v211, v43
	v_fmac_f32_e32 v132, v212, v44
	v_fmac_f32_e32 v133, v213, v45
	v_fmac_f32_e32 v134, v214, v46
	v_fmac_f32_e32 v135, v215, v47
	v_fmac_f32_e32 v136, v216, v48
	v_fmac_f32_e32 v137, v217, v49
	v_fmac_f32_e32 v138, v218, v50
	v_fmac_f32_e32 v139, v219, v51
	v_fmac_f32_e32 v140, v220, v52
	v_fmac_f32_e32 v141, v221, v53
	v_fmac_f32_e32 v142, v222, v54
	v_fmac_f32_e32 v143, v223, v55
	v_mul_f32_e32 v224, v128, v128
	v_fmac_f32_e32 v224, v129, v129
	v_fmac_f32_e32 v224, v130, v130
	v_fmac_f32_e32 v224, v131, v131
	v_fmac_f32_e32 v224, v132, v132
	v_fmac_f32_e32 v224, v133, v133
	v_fmac_f32_e32 v224, v134, v134
	v_fmac_f32_e32 v224, v135, v135
	v_fmac_f32_e32 v224, v136, v136
	v_fmac_f32_e32 v224, v137, v137
	v_fmac_f32_e32 v224, v138, v138
	v_fmac_f32_e32 v224, v139, v139
	v_fmac_f32_e32 v224, v140, v140
	v_fmac_f32_e32 v224, v141, v141
	v_fmac_f32_e32 v224, v142, v142
	v_fmac_f32_e32 v224, v143, v143
	s_nop 1
	v_add_f32_dpp v224, v224, v224 quad_perm:[1,0,3,2] row_mask:0xf bank_mask:0xf
	s_nop 1
	v_add_f32_dpp v224, v224, v224 quad_perm:[2,3,0,1] row_mask:0xf bank_mask:0xf
	s_nop 1
	v_add_f32_dpp v224, v224, v224 row_ror:4 row_mask:0xf bank_mask:0xf
	s_nop 1
	v_add_f32_dpp v224, v224, v224 row_ror:8 row_mask:0xf bank_mask:0xf
	s_nop 1
	v_readlane_b32 s20, v224, 0
	v_readlane_b32 s21, v224, 16
	v_readlane_b32 s22, v224, 32
	v_readlane_b32 s23, v224, 48
	s_nop 1
	v_mov_b32_e32 v225, s20
	v_add_f32_e32 v225, s21, v225
	v_add_f32_e32 v225, s22, v225
	v_add_f32_e32 v225, s23, v225
	v_mov_b32_e32 v226, 0x358637bd
	v_fmac_f32_e32 v226, 0x3a800000, v225
	v_rsq_f32_e32 v226, v226
	s_nop 0
	v_mul_f32_e32 v208, v128, v226
	v_mul_f32_e32 v209, v129, v226
	v_mul_f32_e32 v210, v130, v226
	v_mul_f32_e32 v211, v131, v226
	v_mul_f32_e32 v212, v132, v226
	v_mul_f32_e32 v213, v133, v226
	v_mul_f32_e32 v214, v134, v226
	v_mul_f32_e32 v215, v135, v226
	v_mul_f32_e32 v216, v136, v226
	v_mul_f32_e32 v217, v137, v226
	v_mul_f32_e32 v218, v138, v226
	v_mul_f32_e32 v219, v139, v226
	v_mul_f32_e32 v220, v140, v226
	v_mul_f32_e32 v221, v141, v226
	v_mul_f32_e32 v222, v142, v226
	v_mul_f32_e32 v223, v143, v226
	v_mul_f32_e32 v208, v208, v56
	v_mul_f32_e32 v209, v209, v57
	v_mul_f32_e32 v210, v210, v58
	v_mul_f32_e32 v211, v211, v59
	v_mul_f32_e32 v212, v212, v60
	v_mul_f32_e32 v213, v213, v61
	v_mul_f32_e32 v214, v214, v62
	v_mul_f32_e32 v215, v215, v63
	v_mul_f32_e32 v216, v216, v64
	v_mul_f32_e32 v217, v217, v65
	v_mul_f32_e32 v218, v218, v66
	v_mul_f32_e32 v219, v219, v67
	v_mul_f32_e32 v220, v220, v68
	v_mul_f32_e32 v221, v221, v69
	v_mul_f32_e32 v222, v222, v70
	v_mul_f32_e32 v223, v223, v71
	v_cvt_pk_bf16_f32 v144, v208, v209
	v_cvt_pk_bf16_f32 v145, v210, v211
	v_cvt_pk_bf16_f32 v146, v212, v213
	v_cvt_pk_bf16_f32 v147, v214, v215
	v_cvt_pk_bf16_f32 v148, v216, v217
	v_cvt_pk_bf16_f32 v149, v218, v219
	v_cvt_pk_bf16_f32 v150, v220, v221
	v_cvt_pk_bf16_f32 v151, v222, v223
	global_store_dwordx4 v2, v[144:147], s[14:15]
	global_store_dwordx4 v2, v[148:151], s[14:15] offset:1024
	s_add_u32 s14, s14, 0x800
	s_addc_u32 s15, s15, 0
	global_load_dwordx4 v[128:131], v1, s[6:7] offset:0
	global_load_dwordx4 v[132:135], v1, s[6:7] offset:16
	global_load_dwordx4 v[136:139], v1, s[6:7] offset:2048
	global_load_dwordx4 v[140:143], v1, s[6:7] offset:2064
	global_load_dwordx4 v[144:147], v2, s[10:11]
	global_load_dwordx4 v[148:151], v2, s[10:11] offset:1024
	s_add_u32 s6, s6, 0x1000
	s_addc_u32 s7, s7, 0
	s_add_u32 s10, s10, 0x800
	s_addc_u32 s11, s11, 0
	s_waitcnt vmcnt(16)
	v_lshlrev_b32_e32 v208, 16, v176
	v_and_b32_e32 v209, 0xffff0000, v176
	v_lshlrev_b32_e32 v210, 16, v177
	v_and_b32_e32 v211, 0xffff0000, v177
	v_lshlrev_b32_e32 v212, 16, v178
	v_and_b32_e32 v213, 0xffff0000, v178
	v_lshlrev_b32_e32 v214, 16, v179
	v_and_b32_e32 v215, 0xffff0000, v179
	v_lshlrev_b32_e32 v216, 16, v180
	v_and_b32_e32 v217, 0xffff0000, v180
	v_lshlrev_b32_e32 v218, 16, v181
	v_and_b32_e32 v219, 0xffff0000, v181
	v_lshlrev_b32_e32 v220, 16, v182
	v_and_b32_e32 v221, 0xffff0000, v182
	v_lshlrev_b32_e32 v222, 16, v183
	v_and_b32_e32 v223, 0xffff0000, v183
	v_mul_f32_e32 v224, v208, v208
	v_fmac_f32_e32 v224, v209, v209
	v_fmac_f32_e32 v224, v210, v210
	v_fmac_f32_e32 v224, v211, v211
	v_fmac_f32_e32 v224, v212, v212
	v_fmac_f32_e32 v224, v213, v213
	v_fmac_f32_e32 v224, v214, v214
	v_fmac_f32_e32 v224, v215, v215
	v_fmac_f32_e32 v224, v216, v216
	v_fmac_f32_e32 v224, v217, v217
	v_fmac_f32_e32 v224, v218, v218
	v_fmac_f32_e32 v224, v219, v219
	v_fmac_f32_e32 v224, v220, v220
	v_fmac_f32_e32 v224, v221, v221
	v_fmac_f32_e32 v224, v222, v222
	v_fmac_f32_e32 v224, v223, v223
	s_nop 1
	v_add_f32_dpp v224, v224, v224 quad_perm:[1,0,3,2] row_mask:0xf bank_mask:0xf
	s_nop 1
	v_add_f32_dpp v224, v224, v224 quad_perm:[2,3,0,1] row_mask:0xf bank_mask:0xf
	s_nop 1
	v_add_f32_dpp v224, v224, v224 row_ror:4 row_mask:0xf bank_mask:0xf
	s_nop 1
	v_add_f32_dpp v224, v224, v224 row_ror:8 row_mask:0xf bank_mask:0xf
	s_nop 1
	v_readlane_b32 s20, v224, 0
	v_readlane_b32 s21, v224, 16
	v_readlane_b32 s22, v224, 32
	v_readlane_b32 s23, v224, 48
; DI unsigned pk_bf16(float a, float b) { f32x2_t v = {a, b}; bf16x2_t r = __builtin_convertvector(v, bf16x2_t); return __builtin_bit_cast(unsigned, r); }
; DI float shx(float v, int mask) { const int l = olane(); return __builtin_bit_cast(float, __builtin_amdgcn_ds_bpermute(((l ^ mask) & 63) << 2, __builtin_bit_cast(int, v))); }
; DI void row_phase(const bf16_t* msrc, const float* xsrc, float* xdst, const float* g_post, const float* g_next, bf16_t* hdst, const int gw) {
;     ...
;             for (int j = 0; j < 4; ++j) { const f32x4 g = *(const f32x4*)(g_post + lane * 4 + 256 * j);
; #pragma unroll
;                 for (int r = 0; r < RB; ++r) { const float r1 = rsqrtf(ss[r] * (1.f / DM) + EPS); xv[r][j] = xv[r][j] + mv[r][j] * r1 * g; *(f32x4*)(xdst + (size_t)(rowb + r) * DM + lane * 4 + 256 * j) = xv[r][j]; } }
;         }
;         if (hdst) {
;             float ss[RB];
; #pragma unroll
;             for (int r = 0; r < RB; ++r) { ss[r] = 0.f;
; #pragma unroll
;                 for (int j = 0; j < 4; ++j) ss[r] += xv[r][j][0] * xv[r][j][0] + xv[r][j][1] * xv[r][j][1] + xv[r][j][2] * xv[r][j][2] + xv[r][j][3] * xv[r][j][3]; }
; #pragma unroll
;             for (int o = 32; o >= 1; o >>= 1)
; #pragma unroll
;                 for (int r = 0; r < RB; ++r) ss[r] += shx(ss[r], o);
; #pragma unroll
;             for (int j = 0; j < 4; ++j) { const f32x4 g = *(const f32x4*)(g_next + lane * 4 + 256 * j);
; #pragma unroll
;                 for (int r = 0; r < RB; ++r) { const float r2 = rsqrtf(ss[r] * (1.f / DM) + EPS); const f32x4 hv = xv[r][j] * r2 * g;
;                     u32x2 o; o[0] = pk_bf16(hv[0], hv[1]); o[1] = pk_bf16(hv[2], hv[3]); *(u32x2*)(hdst + (size_t)(rowb + r) * DM + lane * 4 + 256 * j) = o; } }
	s_nop 1
	v_mov_b32_e32 v225, s20
	v_add_f32_e32 v225, s21, v225
	v_add_f32_e32 v225, s22, v225
	v_add_f32_e32 v225, s23, v225
	v_mov_b32_e32 v226, 0x358637bd
	v_fmac_f32_e32 v226, 0x3a800000, v225
	v_rsq_f32_e32 v226, v226
	s_nop 0
	v_mul_f32_e32 v208, v208, v226
	v_mul_f32_e32 v209, v209, v226
	v_mul_f32_e32 v210, v210, v226
	v_mul_f32_e32 v211, v211, v226
	v_mul_f32_e32 v212, v212, v226
	v_mul_f32_e32 v213, v213, v226
	v_mul_f32_e32 v214, v214, v226
	v_mul_f32_e32 v215, v215, v226
	v_mul_f32_e32 v216, v216, v226
	v_mul_f32_e32 v217, v217, v226
	v_mul_f32_e32 v218, v218, v226
	v_mul_f32_e32 v219, v219, v226
	v_mul_f32_e32 v220, v220, v226
	v_mul_f32_e32 v221, v221, v226
	v_mul_f32_e32 v222, v222, v226
	v_mul_f32_e32 v223, v223, v226
	v_fmac_f32_e32 v160, v208, v40
	v_fmac_f32_e32 v161, v209, v41
	v_fmac_f32_e32 v162, v210, v42
	v_fmac_f32_e32 v163, v211, v43
	v_fmac_f32_e32 v164, v212, v44
	v_fmac_f32_e32 v165, v213, v45
	v_fmac_f32_e32 v166, v214, v46
	v_fmac_f32_e32 v167, v215, v47
	v_fmac_f32_e32 v168, v216, v48
	v_fmac_f32_e32 v169, v217, v49
	v_fmac_f32_e32 v170, v218, v50
	v_fmac_f32_e32 v171, v219, v51
	v_fmac_f32_e32 v172, v220, v52
	v_fmac_f32_e32 v173, v221, v53
	v_fmac_f32_e32 v174, v222, v54
	v_fmac_f32_e32 v175, v223, v55
	v_mul_f32_e32 v224, v160, v160
	v_fmac_f32_e32 v224, v161, v161
	v_fmac_f32_e32 v224, v162, v162
	v_fmac_f32_e32 v224, v163, v163
	v_fmac_f32_e32 v224, v164, v164
	v_fmac_f32_e32 v224, v165, v165
	v_fmac_f32_e32 v224, v166, v166
	v_fmac_f32_e32 v224, v167, v167
	v_fmac_f32_e32 v224, v168, v168
	v_fmac_f32_e32 v224, v169, v169
	v_fmac_f32_e32 v224, v170, v170
	v_fmac_f32_e32 v224, v171, v171
	v_fmac_f32_e32 v224, v172, v172
	v_fmac_f32_e32 v224, v173, v173
	v_fmac_f32_e32 v224, v174, v174
	v_fmac_f32_e32 v224, v175, v175
	s_nop 1
	v_add_f32_dpp v224, v224, v224 quad_perm:[1,0,3,2] row_mask:0xf bank_mask:0xf
	s_nop 1
	v_add_f32_dpp v224, v224, v224 quad_perm:[2,3,0,1] row_mask:0xf bank_mask:0xf
	s_nop 1
	v_add_f32_dpp v224, v224, v224 row_ror:4 row_mask:0xf bank_mask:0xf
	s_nop 1
	v_add_f32_dpp v224, v224, v224 row_ror:8 row_mask:0xf bank_mask:0xf
	s_nop 1
	v_readlane_b32 s20, v224, 0
	v_readlane_b32 s21, v224, 16
	v_readlane_b32 s22, v224, 32
	v_readlane_b32 s23, v224, 48
	s_nop 1
	v_mov_b32_e32 v225, s20
	v_add_f32_e32 v225, s21, v225
	v_add_f32_e32 v225, s22, v225
	v_add_f32_e32 v225, s23, v225
	v_mov_b32_e32 v226, 0x358637bd
	v_fmac_f32_e32 v226, 0x3a800000, v225
	v_rsq_f32_e32 v226, v226
	s_nop 0
	v_mul_f32_e32 v208, v160, v226
	v_mul_f32_e32 v209, v161, v226
	v_mul_f32_e32 v210, v162, v226
	v_mul_f32_e32 v211, v163, v226
	v_mul_f32_e32 v212, v164, v226
	v_mul_f32_e32 v213, v165, v226
	v_mul_f32_e32 v214, v166, v226
	v_mul_f32_e32 v215, v167, v226
	v_mul_f32_e32 v216, v168, v226
	v_mul_f32_e32 v217, v169, v226
	v_mul_f32_e32 v218, v170, v226
	v_mul_f32_e32 v219, v171, v226
	v_mul_f32_e32 v220, v172, v226
	v_mul_f32_e32 v221, v173, v226
	v_mul_f32_e32 v222, v174, v226
	v_mul_f32_e32 v223, v175, v226
	v_mul_f32_e32 v208, v208, v56
	v_mul_f32_e32 v209, v209, v57
	v_mul_f32_e32 v210, v210, v58
	v_mul_f32_e32 v211, v211, v59
	v_mul_f32_e32 v212, v212, v60
	v_mul_f32_e32 v213, v213, v61
	v_mul_f32_e32 v214, v214, v62
	v_mul_f32_e32 v215, v215, v63
	v_mul_f32_e32 v216, v216, v64
	v_mul_f32_e32 v217, v217, v65
	v_mul_f32_e32 v218, v218, v66
	v_mul_f32_e32 v219, v219, v67
	v_mul_f32_e32 v220, v220, v68
	v_mul_f32_e32 v221, v221, v69
	v_mul_f32_e32 v222, v222, v70
	v_mul_f32_e32 v223, v223, v71
	v_cvt_pk_bf16_f32 v176, v208, v209
	v_cvt_pk_bf16_f32 v177, v210, v211
	v_cvt_pk_bf16_f32 v178, v212, v213
	v_cvt_pk_bf16_f32 v179, v214, v215
	v_cvt_pk_bf16_f32 v180, v216, v217
	v_cvt_pk_bf16_f32 v181, v218, v219
	v_cvt_pk_bf16_f32 v182, v220, v221
	v_cvt_pk_bf16_f32 v183, v222, v223
	global_store_dwordx4 v2, v[176:179], s[14:15]
	global_store_dwordx4 v2, v[180:183], s[14:15] offset:1024
	s_add_u32 s14, s14, 0x800
	s_addc_u32 s15, s15, 0
	global_load_dwordx4 v[160:163], v1, s[6:7] offset:0
	global_load_dwordx4 v[164:167], v1, s[6:7] offset:16
	global_load_dwordx4 v[168:171], v1, s[6:7] offset:2048
	global_load_dwordx4 v[172:175], v1, s[6:7] offset:2064
	global_load_dwordx4 v[176:179], v2, s[10:11]
	global_load_dwordx4 v[180:183], v2, s[10:11] offset:1024
	s_add_u32 s6, s6, 0x1000
	s_addc_u32 s7, s7, 0
	s_add_u32 s10, s10, 0x800
	s_addc_u32 s11, s11, 0
	s_waitcnt vmcnt(16)
; DI unsigned pk_bf16(float a, float b) { f32x2_t v = {a, b}; bf16x2_t r = __builtin_convertvector(v, bf16x2_t); return __builtin_bit_cast(unsigned, r); }
; DI float shx(float v, int mask) { const int l = olane(); return __builtin_bit_cast(float, __builtin_amdgcn_ds_bpermute(((l ^ mask) & 63) << 2, __builtin_bit_cast(int, v))); }
; DI void row_phase(const bf16_t* msrc, const float* xsrc, float* xdst, const float* g_post, const float* g_next, bf16_t* hdst, const int gw) {
;     ...
;             for (int j = 0; j < 4; ++j) { const f32x4 g = *(const f32x4*)(g_post + lane * 4 + 256 * j);
; #pragma unroll
;                 for (int r = 0; r < RB; ++r) { const float r1 = rsqrtf(ss[r] * (1.f / DM) + EPS); xv[r][j] = xv[r][j] + mv[r][j] * r1 * g; *(f32x4*)(xdst + (size_t)(rowb + r) * DM + lane * 4 + 256 * j) = xv[r][j]; } }
;         }
;         if (hdst) {
;             float ss[RB];
; #pragma unroll
;             for (int r = 0; r < RB; ++r) { ss[r] = 0.f;
; #pragma unroll
;                 for (int j = 0; j < 4; ++j) ss[r] += xv[r][j][0] * xv[r][j][0] + xv[r][j][1] * xv[r][j][1] + xv[r][j][2] * xv[r][j][2] + xv[r][j][3] * xv[r][j][3]; }
; #pragma unroll
;             for (int o = 32; o >= 1; o >>= 1)
; #pragma unroll
;                 for (int r = 0; r < RB; ++r) ss[r] += shx(ss[r], o);
; #pragma unroll
;             for (int j = 0; j < 4; ++j) { const f32x4 g = *(const f32x4*)(g_next + lane * 4 + 256 * j);
; #pragma unroll
;                 for (int r = 0; r < RB; ++r) { const float r2 = rsqrtf(ss[r] * (1.f / DM) + EPS); const f32x4 hv = xv[r][j] * r2 * g;
;                     u32x2 o; o[0] = pk_bf16(hv[0], hv[1]); o[1] = pk_bf16(hv[2], hv[3]); *(u32x2*)(hdst + (size_t)(rowb + r) * DM + lane * 4 + 256 * j) = o; } }
	v_lshlrev_b32_e32 v208, 16, v112
	v_and_b32_e32 v209, 0xffff0000, v112
	v_lshlrev_b32_e32 v210, 16, v113
	v_and_b32_e32 v211, 0xffff0000, v113
	v_lshlrev_b32_e32 v212, 16, v114
	v_and_b32_e32 v213, 0xffff0000, v114
	v_lshlrev_b32_e32 v214, 16, v115
	v_and_b32_e32 v215, 0xffff0000, v115
	v_lshlrev_b32_e32 v216, 16, v116
	v_and_b32_e32 v217, 0xffff0000, v116
	v_lshlrev_b32_e32 v218, 16, v117
	v_and_b32_e32 v219, 0xffff0000, v117
	v_lshlrev_b32_e32 v220, 16, v118
	v_and_b32_e32 v221, 0xffff0000, v118
	v_lshlrev_b32_e32 v222, 16, v119
	v_and_b32_e32 v223, 0xffff0000, v119
	v_mul_f32_e32 v224, v208, v208
	v_fmac_f32_e32 v224, v209, v209
	v_fmac_f32_e32 v224, v210, v210
	v_fmac_f32_e32 v224, v211, v211
	v_fmac_f32_e32 v224, v212, v212
	v_fmac_f32_e32 v224, v213, v213
	v_fmac_f32_e32 v224, v214, v214
	v_fmac_f32_e32 v224, v215, v215
	v_fmac_f32_e32 v224, v216, v216
	v_fmac_f32_e32 v224, v217, v217
	v_fmac_f32_e32 v224, v218, v218
	v_fmac_f32_e32 v224, v219, v219
	v_fmac_f32_e32 v224, v220, v220
	v_fmac_f32_e32 v224, v221, v221
	v_fmac_f32_e32 v224, v222, v222
	v_fmac_f32_e32 v224, v223, v223
	s_nop 1
	v_add_f32_dpp v224, v224, v224 quad_perm:[1,0,3,2] row_mask:0xf bank_mask:0xf
	s_nop 1
	v_add_f32_dpp v224, v224, v224 quad_perm:[2,3,0,1] row_mask:0xf bank_mask:0xf
	s_nop 1
	v_add_f32_dpp v224, v224, v224 row_ror:4 row_mask:0xf bank_mask:0xf
	s_nop 1
	v_add_f32_dpp v224, v224, v224 row_ror:8 row_mask:0xf bank_mask:0xf
	s_nop 1
	v_readlane_b32 s20, v224, 0
	v_readlane_b32 s21, v224, 16
	v_readlane_b32 s22, v224, 32
	v_readlane_b32 s23, v224, 48
	s_nop 1
	v_mov_b32_e32 v225, s20
	v_add_f32_e32 v225, s21, v225
	v_add_f32_e32 v225, s22, v225
	v_add_f32_e32 v225, s23, v225
	v_mov_b32_e32 v226, 0x358637bd
	v_fmac_f32_e32 v226, 0x3a800000, v225
	v_rsq_f32_e32 v226, v226
	s_nop 0
	v_mul_f32_e32 v208, v208, v226
	v_mul_f32_e32 v209, v209, v226
	v_mul_f32_e32 v210, v210, v226
	v_mul_f32_e32 v211, v211, v226
	v_mul_f32_e32 v212, v212, v226
	v_mul_f32_e32 v213, v213, v226
	v_mul_f32_e32 v214, v214, v226
	v_mul_f32_e32 v215, v215, v226
	v_mul_f32_e32 v216, v216, v226
	v_mul_f32_e32 v217, v217, v226
	v_mul_f32_e32 v218, v218, v226
	v_mul_f32_e32 v219, v219, v226
	v_mul_f32_e32 v220, v220, v226
	v_mul_f32_e32 v221, v221, v226
	v_mul_f32_e32 v222, v222, v226
	v_mul_f32_e32 v223, v223, v226
	v_fmac_f32_e32 v96, v208, v40
	v_fmac_f32_e32 v97, v209, v41
	v_fmac_f32_e32 v98, v210, v42
	v_fmac_f32_e32 v99, v211, v43
	v_fmac_f32_e32 v100, v212, v44
	v_fmac_f32_e32 v101, v213, v45
	v_fmac_f32_e32 v102, v214, v46
	v_fmac_f32_e32 v103, v215, v47
	v_fmac_f32_e32 v104, v216, v48
	v_fmac_f32_e32 v105, v217, v49
	v_fmac_f32_e32 v106, v218, v50
	v_fmac_f32_e32 v107, v219, v51
	v_fmac_f32_e32 v108, v220, v52
	v_fmac_f32_e32 v109, v221, v53
	v_fmac_f32_e32 v110, v222, v54
	v_fmac_f32_e32 v111, v223, v55
	v_mul_f32_e32 v224, v96, v96
	v_fmac_f32_e32 v224, v97, v97
	v_fmac_f32_e32 v224, v98, v98
	v_fmac_f32_e32 v224, v99, v99
	v_fmac_f32_e32 v224, v100, v100
	v_fmac_f32_e32 v224, v101, v101
	v_fmac_f32_e32 v224, v102, v102
	v_fmac_f32_e32 v224, v103, v103
	v_fmac_f32_e32 v224, v104, v104
	v_fmac_f32_e32 v224, v105, v105
	v_fmac_f32_e32 v224, v106, v106
	v_fmac_f32_e32 v224, v107, v107
	v_fmac_f32_e32 v224, v108, v108
	v_fmac_f32_e32 v224, v109, v109
	v_fmac_f32_e32 v224, v110, v110
	v_fmac_f32_e32 v224, v111, v111
	s_nop 1
	v_add_f32_dpp v224, v224, v224 quad_perm:[1,0,3,2] row_mask:0xf bank_mask:0xf
	s_nop 1
	v_add_f32_dpp v224, v224, v224 quad_perm:[2,3,0,1] row_mask:0xf bank_mask:0xf
	s_nop 1
	v_add_f32_dpp v224, v224, v224 row_ror:4 row_mask:0xf bank_mask:0xf
	s_nop 1
	v_add_f32_dpp v224, v224, v224 row_ror:8 row_mask:0xf bank_mask:0xf
	s_nop 1
	v_readlane_b32 s20, v224, 0
	v_readlane_b32 s21, v224, 16
	v_readlane_b32 s22, v224, 32
	v_readlane_b32 s23, v224, 48
	s_nop 1
	v_mov_b32_e32 v225, s20
	v_add_f32_e32 v225, s21, v225
	v_add_f32_e32 v225, s22, v225
	v_add_f32_e32 v225, s23, v225
	v_mov_b32_e32 v226, 0x358637bd
	v_fmac_f32_e32 v226, 0x3a800000, v225
	v_rsq_f32_e32 v226, v226
	s_nop 0
	v_mul_f32_e32 v208, v96, v226
	v_mul_f32_e32 v209, v97, v226
	v_mul_f32_e32 v210, v98, v226
	v_mul_f32_e32 v211, v99, v226
	v_mul_f32_e32 v212, v100, v226
	v_mul_f32_e32 v213, v101, v226
	v_mul_f32_e32 v214, v102, v226
	v_mul_f32_e32 v215, v103, v226
	v_mul_f32_e32 v216, v104, v226
	v_mul_f32_e32 v217, v105, v226
	v_mul_f32_e32 v218, v106, v226
	v_mul_f32_e32 v219, v107, v226
	v_mul_f32_e32 v220, v108, v226
	v_mul_f32_e32 v221, v109, v226
	v_mul_f32_e32 v222, v110, v226
	v_mul_f32_e32 v223, v111, v226
	v_mul_f32_e32 v208, v208, v56
	v_mul_f32_e32 v209, v209, v57
	v_mul_f32_e32 v210, v210, v58
	v_mul_f32_e32 v211, v211, v59
	v_mul_f32_e32 v212, v212, v60
	v_mul_f32_e32 v213, v213, v61
	v_mul_f32_e32 v214, v214, v62
	v_mul_f32_e32 v215, v215, v63
	v_mul_f32_e32 v216, v216, v64
	v_mul_f32_e32 v217, v217, v65
	v_mul_f32_e32 v218, v218, v66
	v_mul_f32_e32 v219, v219, v67
	v_mul_f32_e32 v220, v220, v68
	v_mul_f32_e32 v221, v221, v69
	v_mul_f32_e32 v222, v222, v70
	v_mul_f32_e32 v223, v223, v71
	v_cvt_pk_bf16_f32 v112, v208, v209
	v_cvt_pk_bf16_f32 v113, v210, v211
	v_cvt_pk_bf16_f32 v114, v212, v213
	v_cvt_pk_bf16_f32 v115, v214, v215
	v_cvt_pk_bf16_f32 v116, v216, v217
	v_cvt_pk_bf16_f32 v117, v218, v219
	v_cvt_pk_bf16_f32 v118, v220, v221
	v_cvt_pk_bf16_f32 v119, v222, v223
	global_store_dwordx4 v2, v[112:115], s[14:15]
	global_store_dwordx4 v2, v[116:119], s[14:15] offset:1024
	s_add_u32 s14, s14, 0x800
	s_addc_u32 s15, s15, 0
	global_load_dwordx4 v[96:99], v1, s[6:7] offset:0
	global_load_dwordx4 v[100:103], v1, s[6:7] offset:16
	global_load_dwordx4 v[104:107], v1, s[6:7] offset:2048
	global_load_dwordx4 v[108:111], v1, s[6:7] offset:2064
	global_load_dwordx4 v[112:115], v2, s[10:11]
	global_load_dwordx4 v[116:119], v2, s[10:11] offset:1024
	s_add_u32 s6, s6, 0x1000
	s_addc_u32 s7, s7, 0
	s_add_u32 s10, s10, 0x800
	s_addc_u32 s11, s11, 0
	s_waitcnt vmcnt(16)
; DI unsigned pk_bf16(float a, float b) { f32x2_t v = {a, b}; bf16x2_t r = __builtin_convertvector(v, bf16x2_t); return __builtin_bit_cast(unsigned, r); }
; DI float shx(float v, int mask) { const int l = olane(); return __builtin_bit_cast(float, __builtin_amdgcn_ds_bpermute(((l ^ mask) & 63) << 2, __builtin_bit_cast(int, v))); }
; DI void row_phase(const bf16_t* msrc, const float* xsrc, float* xdst, const float* g_post, const float* g_next, bf16_t* hdst, const int gw) {
;     ...
;             for (int j = 0; j < 4; ++j) { const f32x4 g = *(const f32x4*)(g_post + lane * 4 + 256 * j);
; #pragma unroll
;                 for (int r = 0; r < RB; ++r) { const float r1 = rsqrtf(ss[r] * (1.f / DM) + EPS); xv[r][j] = xv[r][j] + mv[r][j] * r1 * g; *(f32x4*)(xdst + (size_t)(rowb + r) * DM + lane * 4 + 256 * j) = xv[r][j]; } }
;         }
;         if (hdst) {
;             float ss[RB];
; #pragma unroll
;             for (int r = 0; r < RB; ++r) { ss[r] = 0.f;
; #pragma unroll
;                 for (int j = 0; j < 4; ++j) ss[r] += xv[r][j][0] * xv[r][j][0] + xv[r][j][1] * xv[r][j][1] + xv[r][j][2] * xv[r][j][2] + xv[r][j][3] * xv[r][j][3]; }
; #pragma unroll
;             for (int o = 32; o >= 1; o >>= 1)
; #pragma unroll
;                 for (int r = 0; r < RB; ++r) ss[r] += shx(ss[r], o);
; #pragma unroll
;             for (int j = 0; j < 4; ++j) { const f32x4 g = *(const f32x4*)(g_next + lane * 4 + 256 * j);
; #pragma unroll
;                 for (int r = 0; r < RB; ++r) { const float r2 = rsqrtf(ss[r] * (1.f / DM) + EPS); const f32x4 hv = xv[r][j] * r2 * g;
;                     u32x2 o; o[0] = pk_bf16(hv[0], hv[1]); o[1] = pk_bf16(hv[2], hv[3]); *(u32x2*)(hdst + (size_t)(rowb + r) * DM + lane * 4 + 256 * j) = o; } }
	v_lshlrev_b32_e32 v208, 16, v144
	v_and_b32_e32 v209, 0xffff0000, v144
	v_lshlrev_b32_e32 v210, 16, v145
	v_and_b32_e32 v211, 0xffff0000, v145
	v_lshlrev_b32_e32 v212, 16, v146
	v_and_b32_e32 v213, 0xffff0000, v146
	v_lshlrev_b32_e32 v214, 16, v147
	v_and_b32_e32 v215, 0xffff0000, v147
	v_lshlrev_b32_e32 v216, 16, v148
	v_and_b32_e32 v217, 0xffff0000, v148
	v_lshlrev_b32_e32 v218, 16, v149
	v_and_b32_e32 v219, 0xffff0000, v149
	v_lshlrev_b32_e32 v220, 16, v150
	v_and_b32_e32 v221, 0xffff0000, v150
	v_lshlrev_b32_e32 v222, 16, v151
	v_and_b32_e32 v223, 0xffff0000, v151
	v_mul_f32_e32 v224, v208, v208
	v_fmac_f32_e32 v224, v209, v209
	v_fmac_f32_e32 v224, v210, v210
	v_fmac_f32_e32 v224, v211, v211
	v_fmac_f32_e32 v224, v212, v212
	v_fmac_f32_e32 v224, v213, v213
	v_fmac_f32_e32 v224, v214, v214
	v_fmac_f32_e32 v224, v215, v215
	v_fmac_f32_e32 v224, v216, v216
	v_fmac_f32_e32 v224, v217, v217
	v_fmac_f32_e32 v224, v218, v218
	v_fmac_f32_e32 v224, v219, v219
	v_fmac_f32_e32 v224, v220, v220
	v_fmac_f32_e32 v224, v221, v221
	v_fmac_f32_e32 v224, v222, v222
	v_fmac_f32_e32 v224, v223, v223
	s_nop 1
	v_add_f32_dpp v224, v224, v224 quad_perm:[1,0,3,2] row_mask:0xf bank_mask:0xf
	s_nop 1
	v_add_f32_dpp v224, v224, v224 quad_perm:[2,3,0,1] row_mask:0xf bank_mask:0xf
	s_nop 1
	v_add_f32_dpp v224, v224, v224 row_ror:4 row_mask:0xf bank_mask:0xf
	s_nop 1
	v_add_f32_dpp v224, v224, v224 row_ror:8 row_mask:0xf bank_mask:0xf
	s_nop 1
	v_readlane_b32 s20, v224, 0
	v_readlane_b32 s21, v224, 16
	v_readlane_b32 s22, v224, 32
	v_readlane_b32 s23, v224, 48
	s_nop 1
	v_mov_b32_e32 v225, s20
	v_add_f32_e32 v225, s21, v225
	v_add_f32_e32 v225, s22, v225
	v_add_f32_e32 v225, s23, v225
	v_mov_b32_e32 v226, 0x358637bd
	v_fmac_f32_e32 v226, 0x3a800000, v225
	v_rsq_f32_e32 v226, v226
	s_nop 0
	v_mul_f32_e32 v208, v208, v226
	v_mul_f32_e32 v209, v209, v226
	v_mul_f32_e32 v210, v210, v226
	v_mul_f32_e32 v211, v211, v226
	v_mul_f32_e32 v212, v212, v226
	v_mul_f32_e32 v213, v213, v226
	v_mul_f32_e32 v214, v214, v226
	v_mul_f32_e32 v215, v215, v226
	v_mul_f32_e32 v216, v216, v226
	v_mul_f32_e32 v217, v217, v226
	v_mul_f32_e32 v218, v218, v226
	v_mul_f32_e32 v219, v219, v226
	v_mul_f32_e32 v220, v220, v226
	v_mul_f32_e32 v221, v221, v226
	v_mul_f32_e32 v222, v222, v226
	v_mul_f32_e32 v223, v223, v226
	v_fmac_f32_e32 v128, v208, v40
	v_fmac_f32_e32 v129, v209, v41
	v_fmac_f32_e32 v130, v210, v42
	v_fmac_f32_e32 v131, v211, v43
	v_fmac_f32_e32 v132, v212, v44
	v_fmac_f32_e32 v133, v213, v45
	v_fmac_f32_e32 v134, v214, v46
	v_fmac_f32_e32 v135, v215, v47
	v_fmac_f32_e32 v136, v216, v48
	v_fmac_f32_e32 v137, v217, v49
	v_fmac_f32_e32 v138, v218, v50
	v_fmac_f32_e32 v139, v219, v51
	v_fmac_f32_e32 v140, v220, v52
	v_fmac_f32_e32 v141, v221, v53
	v_fmac_f32_e32 v142, v222, v54
	v_fmac_f32_e32 v143, v223, v55
	v_mul_f32_e32 v224, v128, v128
	v_fmac_f32_e32 v224, v129, v129
	v_fmac_f32_e32 v224, v130, v130
	v_fmac_f32_e32 v224, v131, v131
	v_fmac_f32_e32 v224, v132, v132
	v_fmac_f32_e32 v224, v133, v133
	v_fmac_f32_e32 v224, v134, v134
	v_fmac_f32_e32 v224, v135, v135
	v_fmac_f32_e32 v224, v136, v136
	v_fmac_f32_e32 v224, v137, v137
	v_fmac_f32_e32 v224, v138, v138
	v_fmac_f32_e32 v224, v139, v139
	v_fmac_f32_e32 v224, v140, v140
	v_fmac_f32_e32 v224, v141, v141
	v_fmac_f32_e32 v224, v142, v142
	v_fmac_f32_e32 v224, v143, v143
	s_nop 1
	v_add_f32_dpp v224, v224, v224 quad_perm:[1,0,3,2] row_mask:0xf bank_mask:0xf
	s_nop 1
	v_add_f32_dpp v224, v224, v224 quad_perm:[2,3,0,1] row_mask:0xf bank_mask:0xf
	s_nop 1
	v_add_f32_dpp v224, v224, v224 row_ror:4 row_mask:0xf bank_mask:0xf
	s_nop 1
	v_add_f32_dpp v224, v224, v224 row_ror:8 row_mask:0xf bank_mask:0xf
	s_nop 1
	v_readlane_b32 s20, v224, 0
	v_readlane_b32 s21, v224, 16
	v_readlane_b32 s22, v224, 32
	v_readlane_b32 s23, v224, 48
	s_nop 1
	v_mov_b32_e32 v225, s20
	v_add_f32_e32 v225, s21, v225
	v_add_f32_e32 v225, s22, v225
	v_add_f32_e32 v225, s23, v225
	v_mov_b32_e32 v226, 0x358637bd
	v_fmac_f32_e32 v226, 0x3a800000, v225
	v_rsq_f32_e32 v226, v226
	s_nop 0
	v_mul_f32_e32 v208, v128, v226
	v_mul_f32_e32 v209, v129, v226
	v_mul_f32_e32 v210, v130, v226
	v_mul_f32_e32 v211, v131, v226
	v_mul_f32_e32 v212, v132, v226
	v_mul_f32_e32 v213, v133, v226
	v_mul_f32_e32 v214, v134, v226
	v_mul_f32_e32 v215, v135, v226
	v_mul_f32_e32 v216, v136, v226
	v_mul_f32_e32 v217, v137, v226
	v_mul_f32_e32 v218, v138, v226
	v_mul_f32_e32 v219, v139, v226
	v_mul_f32_e32 v220, v140, v226
	v_mul_f32_e32 v221, v141, v226
	v_mul_f32_e32 v222, v142, v226
	v_mul_f32_e32 v223, v143, v226
	v_mul_f32_e32 v208, v208, v56
	v_mul_f32_e32 v209, v209, v57
	v_mul_f32_e32 v210, v210, v58
	v_mul_f32_e32 v211, v211, v59
	v_mul_f32_e32 v212, v212, v60
	v_mul_f32_e32 v213, v213, v61
	v_mul_f32_e32 v214, v214, v62
	v_mul_f32_e32 v215, v215, v63
	v_mul_f32_e32 v216, v216, v64
	v_mul_f32_e32 v217, v217, v65
	v_mul_f32_e32 v218, v218, v66
	v_mul_f32_e32 v219, v219, v67
	v_mul_f32_e32 v220, v220, v68
	v_mul_f32_e32 v221, v221, v69
	v_mul_f32_e32 v222, v222, v70
	v_mul_f32_e32 v223, v223, v71
	v_cvt_pk_bf16_f32 v144, v208, v209
	v_cvt_pk_bf16_f32 v145, v210, v211
	v_cvt_pk_bf16_f32 v146, v212, v213
	v_cvt_pk_bf16_f32 v147, v214, v215
	v_cvt_pk_bf16_f32 v148, v216, v217
	v_cvt_pk_bf16_f32 v149, v218, v219
	v_cvt_pk_bf16_f32 v150, v220, v221
	v_cvt_pk_bf16_f32 v151, v222, v223
	global_store_dwordx4 v2, v[144:147], s[14:15]
	global_store_dwordx4 v2, v[148:151], s[14:15] offset:1024
	s_add_u32 s14, s14, 0x800
	s_addc_u32 s15, s15, 0
	global_load_dwordx4 v[128:131], v1, s[6:7] offset:0
	global_load_dwordx4 v[132:135], v1, s[6:7] offset:16
	global_load_dwordx4 v[136:139], v1, s[6:7] offset:2048
	global_load_dwordx4 v[140:143], v1, s[6:7] offset:2064
	global_load_dwordx4 v[144:147], v2, s[10:11]
	global_load_dwordx4 v[148:151], v2, s[10:11] offset:1024
	s_add_u32 s6, s6, 0x1000
	s_addc_u32 s7, s7, 0
	s_add_u32 s10, s10, 0x800
	s_addc_u32 s11, s11, 0
	s_waitcnt vmcnt(16)
; DI unsigned pk_bf16(float a, float b) { f32x2_t v = {a, b}; bf16x2_t r = __builtin_convertvector(v, bf16x2_t); return __builtin_bit_cast(unsigned, r); }
; DI float shx(float v, int mask) { const int l = olane(); return __builtin_bit_cast(float, __builtin_amdgcn_ds_bpermute(((l ^ mask) & 63) << 2, __builtin_bit_cast(int, v))); }
; DI void row_phase(const bf16_t* msrc, const float* xsrc, float* xdst, const float* g_post, const float* g_next, bf16_t* hdst, const int gw) {
;     ...
;             for (int j = 0; j < 4; ++j) { const f32x4 g = *(const f32x4*)(g_post + lane * 4 + 256 * j);
; #pragma unroll
;                 for (int r = 0; r < RB; ++r) { const float r1 = rsqrtf(ss[r] * (1.f / DM) + EPS); xv[r][j] = xv[r][j] + mv[r][j] * r1 * g; *(f32x4*)(xdst + (size_t)(rowb + r) * DM + lane * 4 + 256 * j) = xv[r][j]; } }
;         }
;         if (hdst) {
;             float ss[RB];
; #pragma unroll
;             for (int r = 0; r < RB; ++r) { ss[r] = 0.f;
; #pragma unroll
;                 for (int j = 0; j < 4; ++j) ss[r] += xv[r][j][0] * xv[r][j][0] + xv[r][j][1] * xv[r][j][1] + xv[r][j][2] * xv[r][j][2] + xv[r][j][3] * xv[r][j][3]; }
; #pragma unroll
;             for (int o = 32; o >= 1; o >>= 1)
; #pragma unroll
;                 for (int r = 0; r < RB; ++r) ss[r] += shx(ss[r], o);
; #pragma unroll
;             for (int j = 0; j < 4; ++j) { const f32x4 g = *(const f32x4*)(g_next + lane * 4 + 256 * j);
; #pragma unroll
;                 for (int r = 0; r < RB; ++r) { const float r2 = rsqrtf(ss[r] * (1.f / DM) + EPS); const f32x4 hv = xv[r][j] * r2 * g;
;                     u32x2 o; o[0] = pk_bf16(hv[0], hv[1]); o[1] = pk_bf16(hv[2], hv[3]); *(u32x2*)(hdst + (size_t)(rowb + r) * DM + lane * 4 + 256 * j) = o; } }
	v_lshlrev_b32_e32 v208, 16, v176
	v_and_b32_e32 v209, 0xffff0000, v176
	v_lshlrev_b32_e32 v210, 16, v177
	v_and_b32_e32 v211, 0xffff0000, v177
	v_lshlrev_b32_e32 v212, 16, v178
	v_and_b32_e32 v213, 0xffff0000, v178
	v_lshlrev_b32_e32 v214, 16, v179
	v_and_b32_e32 v215, 0xffff0000, v179
	v_lshlrev_b32_e32 v216, 16, v180
	v_and_b32_e32 v217, 0xffff0000, v180
	v_lshlrev_b32_e32 v218, 16, v181
	v_and_b32_e32 v219, 0xffff0000, v181
	v_lshlrev_b32_e32 v220, 16, v182
	v_and_b32_e32 v221, 0xffff0000, v182
	v_lshlrev_b32_e32 v222, 16, v183
	v_and_b32_e32 v223, 0xffff0000, v183
	v_mul_f32_e32 v224, v208, v208
	v_fmac_f32_e32 v224, v209, v209
	v_fmac_f32_e32 v224, v210, v210
	v_fmac_f32_e32 v224, v211, v211
	v_fmac_f32_e32 v224, v212, v212
	v_fmac_f32_e32 v224, v213, v213
	v_fmac_f32_e32 v224, v214, v214
	v_fmac_f32_e32 v224, v215, v215
	v_fmac_f32_e32 v224, v216, v216
	v_fmac_f32_e32 v224, v217, v217
	v_fmac_f32_e32 v224, v218, v218
	v_fmac_f32_e32 v224, v219, v219
	v_fmac_f32_e32 v224, v220, v220
	v_fmac_f32_e32 v224, v221, v221
	v_fmac_f32_e32 v224, v222, v222
	v_fmac_f32_e32 v224, v223, v223
	s_nop 1
	v_add_f32_dpp v224, v224, v224 quad_perm:[1,0,3,2] row_mask:0xf bank_mask:0xf
	s_nop 1
	v_add_f32_dpp v224, v224, v224 quad_perm:[2,3,0,1] row_mask:0xf bank_mask:0xf
	s_nop 1
	v_add_f32_dpp v224, v224, v224 row_ror:4 row_mask:0xf bank_mask:0xf
	s_nop 1
	v_add_f32_dpp v224, v224, v224 row_ror:8 row_mask:0xf bank_mask:0xf
	s_nop 1
	v_readlane_b32 s20, v224, 0
	v_readlane_b32 s21, v224, 16
	v_readlane_b32 s22, v224, 32
	v_readlane_b32 s23, v224, 48
	s_nop 1
	v_mov_b32_e32 v225, s20
	v_add_f32_e32 v225, s21, v225
	v_add_f32_e32 v225, s22, v225
	v_add_f32_e32 v225, s23, v225
	v_mov_b32_e32 v226, 0x358637bd
	v_fmac_f32_e32 v226, 0x3a800000, v225
	v_rsq_f32_e32 v226, v226
	s_nop 0
	v_mul_f32_e32 v208, v208, v226
	v_mul_f32_e32 v209, v209, v226
	v_mul_f32_e32 v210, v210, v226
	v_mul_f32_e32 v211, v211, v226
	v_mul_f32_e32 v212, v212, v226
	v_mul_f32_e32 v213, v213, v226
	v_mul_f32_e32 v214, v214, v226
	v_mul_f32_e32 v215, v215, v226
	v_mul_f32_e32 v216, v216, v226
	v_mul_f32_e32 v217, v217, v226
	v_mul_f32_e32 v218, v218, v226
	v_mul_f32_e32 v219, v219, v226
	v_mul_f32_e32 v220, v220, v226
	v_mul_f32_e32 v221, v221, v226
	v_mul_f32_e32 v222, v222, v226
	v_mul_f32_e32 v223, v223, v226
	v_fmac_f32_e32 v160, v208, v40
	v_fmac_f32_e32 v161, v209, v41
	v_fmac_f32_e32 v162, v210, v42
	v_fmac_f32_e32 v163, v211, v43
	v_fmac_f32_e32 v164, v212, v44
	v_fmac_f32_e32 v165, v213, v45
	v_fmac_f32_e32 v166, v214, v46
	v_fmac_f32_e32 v167, v215, v47
	v_fmac_f32_e32 v168, v216, v48
	v_fmac_f32_e32 v169, v217, v49
	v_fmac_f32_e32 v170, v218, v50
	v_fmac_f32_e32 v171, v219, v51
	v_fmac_f32_e32 v172, v220, v52
	v_fmac_f32_e32 v173, v221, v53
	v_fmac_f32_e32 v174, v222, v54
	v_fmac_f32_e32 v175, v223, v55
	v_mul_f32_e32 v224, v160, v160
	v_fmac_f32_e32 v224, v161, v161
	v_fmac_f32_e32 v224, v162, v162
	v_fmac_f32_e32 v224, v163, v163
	v_fmac_f32_e32 v224, v164, v164
	v_fmac_f32_e32 v224, v165, v165
	v_fmac_f32_e32 v224, v166, v166
	v_fmac_f32_e32 v224, v167, v167
	v_fmac_f32_e32 v224, v168, v168
	v_fmac_f32_e32 v224, v169, v169
	v_fmac_f32_e32 v224, v170, v170
	v_fmac_f32_e32 v224, v171, v171
	v_fmac_f32_e32 v224, v172, v172
	v_fmac_f32_e32 v224, v173, v173
	v_fmac_f32_e32 v224, v174, v174
	v_fmac_f32_e32 v224, v175, v175
	s_nop 1
	v_add_f32_dpp v224, v224, v224 quad_perm:[1,0,3,2] row_mask:0xf bank_mask:0xf
	s_nop 1
	v_add_f32_dpp v224, v224, v224 quad_perm:[2,3,0,1] row_mask:0xf bank_mask:0xf
	s_nop 1
	v_add_f32_dpp v224, v224, v224 row_ror:4 row_mask:0xf bank_mask:0xf
	s_nop 1
	v_add_f32_dpp v224, v224, v224 row_ror:8 row_mask:0xf bank_mask:0xf
	s_nop 1
	v_readlane_b32 s20, v224, 0
	v_readlane_b32 s21, v224, 16
	v_readlane_b32 s22, v224, 32
	v_readlane_b32 s23, v224, 48
	s_nop 1
	v_mov_b32_e32 v225, s20
	v_add_f32_e32 v225, s21, v225
	v_add_f32_e32 v225, s22, v225
	v_add_f32_e32 v225, s23, v225
	v_mov_b32_e32 v226, 0x358637bd
	v_fmac_f32_e32 v226, 0x3a800000, v225
	v_rsq_f32_e32 v226, v226
	s_nop 0
	v_mul_f32_e32 v208, v160, v226
	v_mul_f32_e32 v209, v161, v226
	v_mul_f32_e32 v210, v162, v226
	v_mul_f32_e32 v211, v163, v226
	v_mul_f32_e32 v212, v164, v226
	v_mul_f32_e32 v213, v165, v226
	v_mul_f32_e32 v214, v166, v226
	v_mul_f32_e32 v215, v167, v226
	v_mul_f32_e32 v216, v168, v226
	v_mul_f32_e32 v217, v169, v226
	v_mul_f32_e32 v218, v170, v226
	v_mul_f32_e32 v219, v171, v226
	v_mul_f32_e32 v220, v172, v226
	v_mul_f32_e32 v221, v173, v226
	v_mul_f32_e32 v222, v174, v226
	v_mul_f32_e32 v223, v175, v226
	v_mul_f32_e32 v208, v208, v56
	v_mul_f32_e32 v209, v209, v57
	v_mul_f32_e32 v210, v210, v58
	v_mul_f32_e32 v211, v211, v59
	v_mul_f32_e32 v212, v212, v60
	v_mul_f32_e32 v213, v213, v61
	v_mul_f32_e32 v214, v214, v62
	v_mul_f32_e32 v215, v215, v63
	v_mul_f32_e32 v216, v216, v64
	v_mul_f32_e32 v217, v217, v65
	v_mul_f32_e32 v218, v218, v66
	v_mul_f32_e32 v219, v219, v67
	v_mul_f32_e32 v220, v220, v68
	v_mul_f32_e32 v221, v221, v69
	v_mul_f32_e32 v222, v222, v70
	v_mul_f32_e32 v223, v223, v71
	v_cvt_pk_bf16_f32 v176, v208, v209
	v_cvt_pk_bf16_f32 v177, v210, v211
	v_cvt_pk_bf16_f32 v178, v212, v213
	v_cvt_pk_bf16_f32 v179, v214, v215
	v_cvt_pk_bf16_f32 v180, v216, v217
	v_cvt_pk_bf16_f32 v181, v218, v219
	v_cvt_pk_bf16_f32 v182, v220, v221
	v_cvt_pk_bf16_f32 v183, v222, v223
	global_store_dwordx4 v2, v[176:179], s[14:15]
	global_store_dwordx4 v2, v[180:183], s[14:15] offset:1024
	s_add_u32 s14, s14, 0x800
	s_addc_u32 s15, s15, 0
	s_waitcnt vmcnt(10)
; DI unsigned pk_bf16(float a, float b) { f32x2_t v = {a, b}; bf16x2_t r = __builtin_convertvector(v, bf16x2_t); return __builtin_bit_cast(unsigned, r); }
; DI float shx(float v, int mask) { const int l = olane(); return __builtin_bit_cast(float, __builtin_amdgcn_ds_bpermute(((l ^ mask) & 63) << 2, __builtin_bit_cast(int, v))); }
; DI void row_phase(const bf16_t* msrc, const float* xsrc, float* xdst, const float* g_post, const float* g_next, bf16_t* hdst, const int gw) {
;     ...
;             for (int j = 0; j < 4; ++j) { const f32x4 g = *(const f32x4*)(g_post + lane * 4 + 256 * j);
; #pragma unroll
;                 for (int r = 0; r < RB; ++r) { const float r1 = rsqrtf(ss[r] * (1.f / DM) + EPS); xv[r][j] = xv[r][j] + mv[r][j] * r1 * g; *(f32x4*)(xdst + (size_t)(rowb + r) * DM + lane * 4 + 256 * j) = xv[r][j]; } }
;         }
;         if (hdst) {
;             float ss[RB];
; #pragma unroll
;             for (int r = 0; r < RB; ++r) { ss[r] = 0.f;
; #pragma unroll
;                 for (int j = 0; j < 4; ++j) ss[r] += xv[r][j][0] * xv[r][j][0] + xv[r][j][1] * xv[r][j][1] + xv[r][j][2] * xv[r][j][2] + xv[r][j][3] * xv[r][j][3]; }
; #pragma unroll
;             for (int o = 32; o >= 1; o >>= 1)
; #pragma unroll
;                 for (int r = 0; r < RB; ++r) ss[r] += shx(ss[r], o);
; #pragma unroll
;             for (int j = 0; j < 4; ++j) { const f32x4 g = *(const f32x4*)(g_next + lane * 4 + 256 * j);
; #pragma unroll
;                 for (int r = 0; r < RB; ++r) { const float r2 = rsqrtf(ss[r] * (1.f / DM) + EPS); const f32x4 hv = xv[r][j] * r2 * g;
;                     u32x2 o; o[0] = pk_bf16(hv[0], hv[1]); o[1] = pk_bf16(hv[2], hv[3]); *(u32x2*)(hdst + (size_t)(rowb + r) * DM + lane * 4 + 256 * j) = o; } }
	v_lshlrev_b32_e32 v208, 16, v112
	v_and_b32_e32 v209, 0xffff0000, v112
	v_lshlrev_b32_e32 v210, 16, v113
	v_and_b32_e32 v211, 0xffff0000, v113
	v_lshlrev_b32_e32 v212, 16, v114
	v_and_b32_e32 v213, 0xffff0000, v114
	v_lshlrev_b32_e32 v214, 16, v115
	v_and_b32_e32 v215, 0xffff0000, v115
	v_lshlrev_b32_e32 v216, 16, v116
	v_and_b32_e32 v217, 0xffff0000, v116
	v_lshlrev_b32_e32 v218, 16, v117
	v_and_b32_e32 v219, 0xffff0000, v117
	v_lshlrev_b32_e32 v220, 16, v118
	v_and_b32_e32 v221, 0xffff0000, v118
	v_lshlrev_b32_e32 v222, 16, v119
	v_and_b32_e32 v223, 0xffff0000, v119
	v_mul_f32_e32 v224, v208, v208
	v_fmac_f32_e32 v224, v209, v209
	v_fmac_f32_e32 v224, v210, v210
	v_fmac_f32_e32 v224, v211, v211
	v_fmac_f32_e32 v224, v212, v212
	v_fmac_f32_e32 v224, v213, v213
	v_fmac_f32_e32 v224, v214, v214
	v_fmac_f32_e32 v224, v215, v215
	v_fmac_f32_e32 v224, v216, v216
	v_fmac_f32_e32 v224, v217, v217
	v_fmac_f32_e32 v224, v218, v218
	v_fmac_f32_e32 v224, v219, v219
	v_fmac_f32_e32 v224, v220, v220
	v_fmac_f32_e32 v224, v221, v221
	v_fmac_f32_e32 v224, v222, v222
	v_fmac_f32_e32 v224, v223, v223
	s_nop 1
	v_add_f32_dpp v224, v224, v224 quad_perm:[1,0,3,2] row_mask:0xf bank_mask:0xf
	s_nop 1
	v_add_f32_dpp v224, v224, v224 quad_perm:[2,3,0,1] row_mask:0xf bank_mask:0xf
	s_nop 1
	v_add_f32_dpp v224, v224, v224 row_ror:4 row_mask:0xf bank_mask:0xf
	s_nop 1
	v_add_f32_dpp v224, v224, v224 row_ror:8 row_mask:0xf bank_mask:0xf
	s_nop 1
	v_readlane_b32 s20, v224, 0
	v_readlane_b32 s21, v224, 16
	v_readlane_b32 s22, v224, 32
	v_readlane_b32 s23, v224, 48
	s_nop 1
	v_mov_b32_e32 v225, s20
	v_add_f32_e32 v225, s21, v225
	v_add_f32_e32 v225, s22, v225
	v_add_f32_e32 v225, s23, v225
	v_mov_b32_e32 v226, 0x358637bd
	v_fmac_f32_e32 v226, 0x3a800000, v225
	v_rsq_f32_e32 v226, v226
	s_nop 0
	v_mul_f32_e32 v208, v208, v226
	v_mul_f32_e32 v209, v209, v226
	v_mul_f32_e32 v210, v210, v226
	v_mul_f32_e32 v211, v211, v226
	v_mul_f32_e32 v212, v212, v226
	v_mul_f32_e32 v213, v213, v226
	v_mul_f32_e32 v214, v214, v226
	v_mul_f32_e32 v215, v215, v226
	v_mul_f32_e32 v216, v216, v226
	v_mul_f32_e32 v217, v217, v226
	v_mul_f32_e32 v218, v218, v226
	v_mul_f32_e32 v219, v219, v226
	v_mul_f32_e32 v220, v220, v226
	v_mul_f32_e32 v221, v221, v226
	v_mul_f32_e32 v222, v222, v226
	v_mul_f32_e32 v223, v223, v226
	v_fmac_f32_e32 v96, v208, v40
	v_fmac_f32_e32 v97, v209, v41
	v_fmac_f32_e32 v98, v210, v42
	v_fmac_f32_e32 v99, v211, v43
	v_fmac_f32_e32 v100, v212, v44
	v_fmac_f32_e32 v101, v213, v45
	v_fmac_f32_e32 v102, v214, v46
	v_fmac_f32_e32 v103, v215, v47
	v_fmac_f32_e32 v104, v216, v48
	v_fmac_f32_e32 v105, v217, v49
	v_fmac_f32_e32 v106, v218, v50
	v_fmac_f32_e32 v107, v219, v51
	v_fmac_f32_e32 v108, v220, v52
	v_fmac_f32_e32 v109, v221, v53
	v_fmac_f32_e32 v110, v222, v54
	v_fmac_f32_e32 v111, v223, v55
	v_mul_f32_e32 v224, v96, v96
	v_fmac_f32_e32 v224, v97, v97
	v_fmac_f32_e32 v224, v98, v98
	v_fmac_f32_e32 v224, v99, v99
	v_fmac_f32_e32 v224, v100, v100
	v_fmac_f32_e32 v224, v101, v101
	v_fmac_f32_e32 v224, v102, v102
	v_fmac_f32_e32 v224, v103, v103
	v_fmac_f32_e32 v224, v104, v104
	v_fmac_f32_e32 v224, v105, v105
	v_fmac_f32_e32 v224, v106, v106
	v_fmac_f32_e32 v224, v107, v107
	v_fmac_f32_e32 v224, v108, v108
	v_fmac_f32_e32 v224, v109, v109
	v_fmac_f32_e32 v224, v110, v110
	v_fmac_f32_e32 v224, v111, v111
	s_nop 1
	v_add_f32_dpp v224, v224, v224 quad_perm:[1,0,3,2] row_mask:0xf bank_mask:0xf
	s_nop 1
	v_add_f32_dpp v224, v224, v224 quad_perm:[2,3,0,1] row_mask:0xf bank_mask:0xf
	s_nop 1
	v_add_f32_dpp v224, v224, v224 row_ror:4 row_mask:0xf bank_mask:0xf
	s_nop 1
	v_add_f32_dpp v224, v224, v224 row_ror:8 row_mask:0xf bank_mask:0xf
	s_nop 1
	v_readlane_b32 s20, v224, 0
	v_readlane_b32 s21, v224, 16
	v_readlane_b32 s22, v224, 32
	v_readlane_b32 s23, v224, 48
	s_nop 1
	v_mov_b32_e32 v225, s20
	v_add_f32_e32 v225, s21, v225
	v_add_f32_e32 v225, s22, v225
	v_add_f32_e32 v225, s23, v225
	v_mov_b32_e32 v226, 0x358637bd
	v_fmac_f32_e32 v226, 0x3a800000, v225
	v_rsq_f32_e32 v226, v226
	s_nop 0
	v_mul_f32_e32 v208, v96, v226
	v_mul_f32_e32 v209, v97, v226
	v_mul_f32_e32 v210, v98, v226
	v_mul_f32_e32 v211, v99, v226
	v_mul_f32_e32 v212, v100, v226
	v_mul_f32_e32 v213, v101, v226
	v_mul_f32_e32 v214, v102, v226
	v_mul_f32_e32 v215, v103, v226
	v_mul_f32_e32 v216, v104, v226
	v_mul_f32_e32 v217, v105, v226
	v_mul_f32_e32 v218, v106, v226
	v_mul_f32_e32 v219, v107, v226
	v_mul_f32_e32 v220, v108, v226
	v_mul_f32_e32 v221, v109, v226
	v_mul_f32_e32 v222, v110, v226
	v_mul_f32_e32 v223, v111, v226
	v_mul_f32_e32 v208, v208, v56
	v_mul_f32_e32 v209, v209, v57
	v_mul_f32_e32 v210, v210, v58
	v_mul_f32_e32 v211, v211, v59
	v_mul_f32_e32 v212, v212, v60
	v_mul_f32_e32 v213, v213, v61
	v_mul_f32_e32 v214, v214, v62
	v_mul_f32_e32 v215, v215, v63
	v_mul_f32_e32 v216, v216, v64
	v_mul_f32_e32 v217, v217, v65
	v_mul_f32_e32 v218, v218, v66
	v_mul_f32_e32 v219, v219, v67
	v_mul_f32_e32 v220, v220, v68
	v_mul_f32_e32 v221, v221, v69
	v_mul_f32_e32 v222, v222, v70
	v_mul_f32_e32 v223, v223, v71
	v_cvt_pk_bf16_f32 v112, v208, v209
	v_cvt_pk_bf16_f32 v113, v210, v211
	v_cvt_pk_bf16_f32 v114, v212, v213
	v_cvt_pk_bf16_f32 v115, v214, v215
	v_cvt_pk_bf16_f32 v116, v216, v217
	v_cvt_pk_bf16_f32 v117, v218, v219
	v_cvt_pk_bf16_f32 v118, v220, v221
	v_cvt_pk_bf16_f32 v119, v222, v223
	global_store_dwordx4 v2, v[112:115], s[14:15]
	global_store_dwordx4 v2, v[116:119], s[14:15] offset:1024
	s_add_u32 s14, s14, 0x800
	s_addc_u32 s15, s15, 0
	s_waitcnt vmcnt(4)
; DI unsigned pk_bf16(float a, float b) { f32x2_t v = {a, b}; bf16x2_t r = __builtin_convertvector(v, bf16x2_t); return __builtin_bit_cast(unsigned, r); }
; DI float shx(float v, int mask) { const int l = olane(); return __builtin_bit_cast(float, __builtin_amdgcn_ds_bpermute(((l ^ mask) & 63) << 2, __builtin_bit_cast(int, v))); }
; DI void row_phase(const bf16_t* msrc, const float* xsrc, float* xdst, const float* g_post, const float* g_next, bf16_t* hdst, const int gw) {
;     ...
;             for (int j = 0; j < 4; ++j) { const f32x4 g = *(const f32x4*)(g_post + lane * 4 + 256 * j);
; #pragma unroll
;                 for (int r = 0; r < RB; ++r) { const float r1 = rsqrtf(ss[r] * (1.f / DM) + EPS); xv[r][j] = xv[r][j] + mv[r][j] * r1 * g; *(f32x4*)(xdst + (size_t)(rowb + r) * DM + lane * 4 + 256 * j) = xv[r][j]; } }
;         }
;         if (hdst) {
;             float ss[RB];
; #pragma unroll
;             for (int r = 0; r < RB; ++r) { ss[r] = 0.f;
; #pragma unroll
;                 for (int j = 0; j < 4; ++j) ss[r] += xv[r][j][0] * xv[r][j][0] + xv[r][j][1] * xv[r][j][1] + xv[r][j][2] * xv[r][j][2] + xv[r][j][3] * xv[r][j][3]; }
; #pragma unroll
;             for (int o = 32; o >= 1; o >>= 1)
; #pragma unroll
;                 for (int r = 0; r < RB; ++r) ss[r] += shx(ss[r], o);
; #pragma unroll
;             for (int j = 0; j < 4; ++j) { const f32x4 g = *(const f32x4*)(g_next + lane * 4 + 256 * j);
; #pragma unroll
;                 for (int r = 0; r < RB; ++r) { const float r2 = rsqrtf(ss[r] * (1.f / DM) + EPS); const f32x4 hv = xv[r][j] * r2 * g;
;                     u32x2 o; o[0] = pk_bf16(hv[0], hv[1]); o[1] = pk_bf16(hv[2], hv[3]); *(u32x2*)(hdst + (size_t)(rowb + r) * DM + lane * 4 + 256 * j) = o; } }
;         }
;     }
	v_lshlrev_b32_e32 v208, 16, v144
	v_and_b32_e32 v209, 0xffff0000, v144
	v_lshlrev_b32_e32 v210, 16, v145
	v_and_b32_e32 v211, 0xffff0000, v145
	v_lshlrev_b32_e32 v212, 16, v146
	v_and_b32_e32 v213, 0xffff0000, v146
	v_lshlrev_b32_e32 v214, 16, v147
	v_and_b32_e32 v215, 0xffff0000, v147
	v_lshlrev_b32_e32 v216, 16, v148
	v_and_b32_e32 v217, 0xffff0000, v148
	v_lshlrev_b32_e32 v218, 16, v149
	v_and_b32_e32 v219, 0xffff0000, v149
	v_lshlrev_b32_e32 v220, 16, v150
	v_and_b32_e32 v221, 0xffff0000, v150
	v_lshlrev_b32_e32 v222, 16, v151
	v_and_b32_e32 v223, 0xffff0000, v151
	v_mul_f32_e32 v224, v208, v208
	v_fmac_f32_e32 v224, v209, v209
	v_fmac_f32_e32 v224, v210, v210
	v_fmac_f32_e32 v224, v211, v211
	v_fmac_f32_e32 v224, v212, v212
	v_fmac_f32_e32 v224, v213, v213
	v_fmac_f32_e32 v224, v214, v214
	v_fmac_f32_e32 v224, v215, v215
	v_fmac_f32_e32 v224, v216, v216
	v_fmac_f32_e32 v224, v217, v217
	v_fmac_f32_e32 v224, v218, v218
	v_fmac_f32_e32 v224, v219, v219
	v_fmac_f32_e32 v224, v220, v220
	v_fmac_f32_e32 v224, v221, v221
	v_fmac_f32_e32 v224, v222, v222
	v_fmac_f32_e32 v224, v223, v223
	s_nop 1
	v_add_f32_dpp v224, v224, v224 quad_perm:[1,0,3,2] row_mask:0xf bank_mask:0xf
	s_nop 1
	v_add_f32_dpp v224, v224, v224 quad_perm:[2,3,0,1] row_mask:0xf bank_mask:0xf
	s_nop 1
	v_add_f32_dpp v224, v224, v224 row_ror:4 row_mask:0xf bank_mask:0xf
	s_nop 1
	v_add_f32_dpp v224, v224, v224 row_ror:8 row_mask:0xf bank_mask:0xf
	s_nop 1
	v_readlane_b32 s20, v224, 0
	v_readlane_b32 s21, v224, 16
	v_readlane_b32 s22, v224, 32
	v_readlane_b32 s23, v224, 48
	s_nop 1
	v_mov_b32_e32 v225, s20
	v_add_f32_e32 v225, s21, v225
	v_add_f32_e32 v225, s22, v225
	v_add_f32_e32 v225, s23, v225
	v_mov_b32_e32 v226, 0x358637bd
	v_fmac_f32_e32 v226, 0x3a800000, v225
	v_rsq_f32_e32 v226, v226
	s_nop 0
	v_mul_f32_e32 v208, v208, v226
	v_mul_f32_e32 v209, v209, v226
	v_mul_f32_e32 v210, v210, v226
	v_mul_f32_e32 v211, v211, v226
	v_mul_f32_e32 v212, v212, v226
	v_mul_f32_e32 v213, v213, v226
	v_mul_f32_e32 v214, v214, v226
	v_mul_f32_e32 v215, v215, v226
	v_mul_f32_e32 v216, v216, v226
	v_mul_f32_e32 v217, v217, v226
	v_mul_f32_e32 v218, v218, v226
	v_mul_f32_e32 v219, v219, v226
	v_mul_f32_e32 v220, v220, v226
	v_mul_f32_e32 v221, v221, v226
	v_mul_f32_e32 v222, v222, v226
	v_mul_f32_e32 v223, v223, v226
	v_fmac_f32_e32 v128, v208, v40
	v_fmac_f32_e32 v129, v209, v41
	v_fmac_f32_e32 v130, v210, v42
	v_fmac_f32_e32 v131, v211, v43
	v_fmac_f32_e32 v132, v212, v44
	v_fmac_f32_e32 v133, v213, v45
	v_fmac_f32_e32 v134, v214, v46
	v_fmac_f32_e32 v135, v215, v47
	v_fmac_f32_e32 v136, v216, v48
	v_fmac_f32_e32 v137, v217, v49
	v_fmac_f32_e32 v138, v218, v50
	v_fmac_f32_e32 v139, v219, v51
	v_fmac_f32_e32 v140, v220, v52
	v_fmac_f32_e32 v141, v221, v53
	v_fmac_f32_e32 v142, v222, v54
	v_fmac_f32_e32 v143, v223, v55
	v_mul_f32_e32 v224, v128, v128
	v_fmac_f32_e32 v224, v129, v129
	v_fmac_f32_e32 v224, v130, v130
	v_fmac_f32_e32 v224, v131, v131
	v_fmac_f32_e32 v224, v132, v132
	v_fmac_f32_e32 v224, v133, v133
	v_fmac_f32_e32 v224, v134, v134
	v_fmac_f32_e32 v224, v135, v135
	v_fmac_f32_e32 v224, v136, v136
	v_fmac_f32_e32 v224, v137, v137
	v_fmac_f32_e32 v224, v138, v138
	v_fmac_f32_e32 v224, v139, v139
	v_fmac_f32_e32 v224, v140, v140
	v_fmac_f32_e32 v224, v141, v141
	v_fmac_f32_e32 v224, v142, v142
	v_fmac_f32_e32 v224, v143, v143
	s_nop 1
	v_add_f32_dpp v224, v224, v224 quad_perm:[1,0,3,2] row_mask:0xf bank_mask:0xf
	s_nop 1
	v_add_f32_dpp v224, v224, v224 quad_perm:[2,3,0,1] row_mask:0xf bank_mask:0xf
	s_nop 1
	v_add_f32_dpp v224, v224, v224 row_ror:4 row_mask:0xf bank_mask:0xf
	s_nop 1
	v_add_f32_dpp v224, v224, v224 row_ror:8 row_mask:0xf bank_mask:0xf
	s_nop 1
	v_readlane_b32 s20, v224, 0
	v_readlane_b32 s21, v224, 16
	v_readlane_b32 s22, v224, 32
	v_readlane_b32 s23, v224, 48
	s_nop 1
	v_mov_b32_e32 v225, s20
	v_add_f32_e32 v225, s21, v225
	v_add_f32_e32 v225, s22, v225
	v_add_f32_e32 v225, s23, v225
	v_mov_b32_e32 v226, 0x358637bd
	v_fmac_f32_e32 v226, 0x3a800000, v225
	v_rsq_f32_e32 v226, v226
	s_nop 0
	v_mul_f32_e32 v208, v128, v226
	v_mul_f32_e32 v209, v129, v226
	v_mul_f32_e32 v210, v130, v226
	v_mul_f32_e32 v211, v131, v226
	v_mul_f32_e32 v212, v132, v226
	v_mul_f32_e32 v213, v133, v226
	v_mul_f32_e32 v214, v134, v226
	v_mul_f32_e32 v215, v135, v226
	v_mul_f32_e32 v216, v136, v226
	v_mul_f32_e32 v217, v137, v226
	v_mul_f32_e32 v218, v138, v226
	v_mul_f32_e32 v219, v139, v226
	v_mul_f32_e32 v220, v140, v226
	v_mul_f32_e32 v221, v141, v226
	v_mul_f32_e32 v222, v142, v226
	v_mul_f32_e32 v223, v143, v226
	v_mul_f32_e32 v208, v208, v56
	v_mul_f32_e32 v209, v209, v57
	v_mul_f32_e32 v210, v210, v58
	v_mul_f32_e32 v211, v211, v59
	v_mul_f32_e32 v212, v212, v60
	v_mul_f32_e32 v213, v213, v61
	v_mul_f32_e32 v214, v214, v62
	v_mul_f32_e32 v215, v215, v63
	v_mul_f32_e32 v216, v216, v64
	v_mul_f32_e32 v217, v217, v65
	v_mul_f32_e32 v218, v218, v66
	v_mul_f32_e32 v219, v219, v67
	v_mul_f32_e32 v220, v220, v68
	v_mul_f32_e32 v221, v221, v69
	v_mul_f32_e32 v222, v222, v70
	v_mul_f32_e32 v223, v223, v71
	v_cvt_pk_bf16_f32 v144, v208, v209
	v_cvt_pk_bf16_f32 v145, v210, v211
	v_cvt_pk_bf16_f32 v146, v212, v213
	v_cvt_pk_bf16_f32 v147, v214, v215
	v_cvt_pk_bf16_f32 v148, v216, v217
	v_cvt_pk_bf16_f32 v149, v218, v219
	v_cvt_pk_bf16_f32 v150, v220, v221
	v_cvt_pk_bf16_f32 v151, v222, v223
	global_store_dwordx4 v2, v[144:147], s[14:15]
	global_store_dwordx4 v2, v[148:151], s[14:15] offset:1024
	s_add_u32 s14, s14, 0x800
	s_addc_u32 s15, s15, 0
	v_readlane_b32 s4, v3, 0
	v_readlane_b32 s5, v3, 1
	v_readlane_b32 s6, v3, 2
	v_readlane_b32 s7, v3, 3
	v_readlane_b32 s8, v3, 4
	v_readlane_b32 s9, v3, 5
	v_readlane_b32 s10, v3, 6
	v_readlane_b32 s11, v3, 7
	v_readlane_b32 s12, v3, 8
	v_readlane_b32 s13, v3, 9
	v_readlane_b32 s14, v3, 10
	v_readlane_b32 s15, v3, 11
	v_readlane_b32 s16, v3, 12
	v_readlane_b32 s17, v3, 13
	v_readlane_b32 s18, v3, 14
	v_readlane_b32 s19, v3, 15
	v_readlane_b32 s20, v3, 16
	v_readlane_b32 s21, v3, 17
	v_readlane_b32 s22, v3, 18
	v_readlane_b32 s23, v3, 19
	v_readlane_b32 s24, v3, 20
	v_readlane_b32 s25, v3, 21
	s_mov_b32 s6, 0x358637bd
	s_branch .LBB0_79
; DI int obid() { int b = blockIdx.x; asm volatile("" : "+s"(b)); return b; }
; DI int ogrid() { int g = gridDim.x; asm volatile("" : "+s"(g)); return g; }
; DI int otid_w(int gw) { return (gw << 6) | olane(); }
; DI float shx(float v, int mask) { const int l = olane(); return __builtin_bit_cast(float, __builtin_amdgcn_ds_bpermute(((l ^ mask) & 63) << 2, __builtin_bit_cast(int, v))); }
; DI void row_phase(const bf16_t* msrc, const float* xsrc, float* xdst, const float* g_post, const float* g_next, bf16_t* hdst, const int gw) {
;     ...
;     const int tid = otid_w(gw); const int lane = tid & 63, w = tid >> 6;
;     const int wg = obid() * 8 + w, nw = ogrid() * 8;
;     for (int rowb = wg * RB; rowb < M_TOK; rowb += nw * RB) {
;         f32x4 xv[RB][4], mv[RB][4];
; #pragma unroll
;         for (int r = 0; r < RB; ++r)
; #pragma unroll
;             for (int j = 0; j < 4; ++j) xv[r][j] = *(const f32x4*)(xsrc + (size_t)(rowb + r) * DM + lane * 4 + 256 * j);
;         if (msrc) {
; #pragma unroll
;             for (int r = 0; r < RB; ++r)
; #pragma unroll
;                 for (int j = 0; j < 4; ++j) { const u32x2 mw = *(const u32x2*)(msrc + (size_t)(rowb + r) * DM + lane * 4 + 256 * j);
;                     mv[r][j] = (f32x4){__uint_as_float(mw[0] << 16), __uint_as_float(mw[0] & 0xffff0000u), __uint_as_float(mw[1] << 16), __uint_as_float(mw[1] & 0xffff0000u)}; }
;             float ss[RB];
; #pragma unroll
;             for (int r = 0; r < RB; ++r) { ss[r] = 0.f;
; #pragma unroll
;                 for (int j = 0; j < 4; ++j) ss[r] += mv[r][j][0] * mv[r][j][0] + mv[r][j][1] * mv[r][j][1] + mv[r][j][2] * mv[r][j][2] + mv[r][j][3] * mv[r][j][3]; }
; #pragma unroll
;             for (int o = 32; o >= 1; o >>= 1)
; #pragma unroll
;                 for (int r = 0; r < RB; ++r) ss[r] += shx(ss[r], o);
; #pragma unroll
;             for (int j = 0; j < 4; ++j) { const f32x4 g = *(const f32x4*)(g_post + lane * 4 + 256 * j);
; #pragma unroll
;                 for (int r = 0; r < RB; ++r) { const float r1 = rsqrtf(ss[r] * (1.f / DM) + EPS); xv[r][j] = xv[r][j] + mv[r][j] * r1 * g; *(f32x4*)(xdst + (size_t)(rowb + r) * DM + lane * 4 + 256 * j) = xv[r][j]; } }
.Lrow_r2h:
	v_writelane_b32 v3, s4, 0
	v_writelane_b32 v3, s5, 1
	v_writelane_b32 v3, s6, 2
	v_writelane_b32 v3, s7, 3
	v_writelane_b32 v3, s8, 4
	v_writelane_b32 v3, s9, 5
	v_writelane_b32 v3, s10, 6
	v_writelane_b32 v3, s11, 7
	v_writelane_b32 v3, s12, 8
	v_writelane_b32 v3, s13, 9
	v_writelane_b32 v3, s14, 10
	v_writelane_b32 v3, s15, 11
	v_writelane_b32 v3, s16, 12
	v_writelane_b32 v3, s17, 13
	v_writelane_b32 v3, s18, 14
	v_writelane_b32 v3, s19, 15
	v_writelane_b32 v3, s20, 16
	v_writelane_b32 v3, s21, 17
	v_writelane_b32 v3, s22, 18
	v_writelane_b32 v3, s23, 19
	v_writelane_b32 v3, s24, 20
	v_writelane_b32 v3, s25, 21
	s_waitcnt vmcnt(0) lgkmcnt(0)
	v_mbcnt_lo_u32_b32 v0, -1, 0
	v_mbcnt_hi_u32_b32 v0, -1, v0
	v_lshlrev_b32_e32 v1, 5, v0
	v_lshlrev_b32_e32 v2, 4, v0
	s_lshr_b32 s4, s71, 6
	s_and_b32 s5, s2, 7
	s_lshl_b32 s5, s5, 8
	s_lshr_b32 s24, s2, 3
	s_lshl_b32 s24, s24, 3
	s_add_i32 s5, s5, s24
	s_add_i32 s5, s5, s4
	s_lshl_b32 s24, s5, 15
	s_lshl_b32 s25, s5, 14
	v_readlane_b32 s8, v254, 62
	v_readlane_b32 s9, v254, 63
	v_readlane_b32 s6, v255, 2
	v_readlane_b32 s7, v255, 3
	v_readlane_b32 s4, v255, 6
	v_readlane_b32 s16, v255, 10
	v_readlane_b32 s17, v255, 11
	s_nop 1
	s_cmp_eq_u32 s4, 0
	s_cselect_b32 s6, s6, s8
	s_cselect_b32 s7, s7, s9
	s_add_u32 s6, s6, s24
	s_addc_u32 s7, s7, 0
	s_add_u32 s8, s8, s24
	s_addc_u32 s9, s9, 0
	s_add_u32 s10, s68, 0x10681000
	s_addc_u32 s11, s69, 0
	s_add_u32 s10, s10, s25
	s_addc_u32 s11, s11, 0
	s_and_b32 s12, s2, 7
	s_lshl_b32 s12, s12, 22
	s_add_u32 s10, s10, s12
	s_addc_u32 s11, s11, 0
	s_add_u32 s12, s10, 0x400000
	s_addc_u32 s13, s11, 0
	s_add_u32 s14, s82, s25
	s_addc_u32 s15, s83, 0
	s_add_u32 s18, s16, 0x1000
	s_addc_u32 s19, s17, 0
	global_load_dwordx4 v[40:43], v1, s[18:19] offset:0
	global_load_dwordx4 v[44:47], v1, s[18:19] offset:16
	global_load_dwordx4 v[48:51], v1, s[18:19] offset:2048
	global_load_dwordx4 v[52:55], v1, s[18:19] offset:2064
	s_add_u32 s18, s16, 0x3000
	s_addc_u32 s19, s17, 0
	global_load_dwordx4 v[56:59], v1, s[18:19] offset:0
	global_load_dwordx4 v[60:63], v1, s[18:19] offset:16
	global_load_dwordx4 v[64:67], v1, s[18:19] offset:2048
	global_load_dwordx4 v[68:71], v1, s[18:19] offset:2064
	s_add_u32 s18, s16, 0x4000
	s_addc_u32 s19, s17, 0
	global_load_dwordx4 v[72:75], v1, s[18:19] offset:0
	global_load_dwordx4 v[76:79], v1, s[18:19] offset:16
	global_load_dwordx4 v[80:83], v1, s[18:19] offset:2048
	global_load_dwordx4 v[84:87], v1, s[18:19] offset:2064
	global_load_dwordx4 v[96:99], v1, s[6:7] offset:0
	global_load_dwordx4 v[100:103], v1, s[6:7] offset:16
	global_load_dwordx4 v[104:107], v1, s[6:7] offset:2048
	global_load_dwordx4 v[108:111], v1, s[6:7] offset:2064
	global_load_dwordx4 v[112:115], v2, s[10:11]
	global_load_dwordx4 v[116:119], v2, s[10:11] offset:1024
	global_load_dwordx4 v[120:123], v2, s[12:13]
	global_load_dwordx4 v[124:127], v2, s[12:13] offset:1024
	s_add_u32 s6, s6, 0x1000
	s_addc_u32 s7, s7, 0
	s_add_u32 s10, s10, 0x800
	s_addc_u32 s11, s11, 0
	s_add_u32 s12, s12, 0x800
	s_addc_u32 s13, s13, 0
	global_load_dwordx4 v[128:131], v1, s[6:7] offset:0
	global_load_dwordx4 v[132:135], v1, s[6:7] offset:16
	global_load_dwordx4 v[136:139], v1, s[6:7] offset:2048
	global_load_dwordx4 v[140:143], v1, s[6:7] offset:2064
	global_load_dwordx4 v[144:147], v2, s[10:11]
	global_load_dwordx4 v[148:151], v2, s[10:11] offset:1024
	global_load_dwordx4 v[152:155], v2, s[12:13]
	global_load_dwordx4 v[156:159], v2, s[12:13] offset:1024
	s_add_u32 s6, s6, 0x1000
	s_addc_u32 s7, s7, 0
	s_add_u32 s10, s10, 0x800
	s_addc_u32 s11, s11, 0
	s_add_u32 s12, s12, 0x800
	s_addc_u32 s13, s13, 0
	global_load_dwordx4 v[160:163], v1, s[6:7] offset:0
	global_load_dwordx4 v[164:167], v1, s[6:7] offset:16
	global_load_dwordx4 v[168:171], v1, s[6:7] offset:2048
	global_load_dwordx4 v[172:175], v1, s[6:7] offset:2064
	global_load_dwordx4 v[176:179], v2, s[10:11]
	global_load_dwordx4 v[180:183], v2, s[10:11] offset:1024
	global_load_dwordx4 v[184:187], v2, s[12:13]
	global_load_dwordx4 v[188:191], v2, s[12:13] offset:1024
	s_add_u32 s6, s6, 0x1000
	s_addc_u32 s7, s7, 0
	s_add_u32 s10, s10, 0x800
	s_addc_u32 s11, s11, 0
	s_add_u32 s12, s12, 0x800
	s_addc_u32 s13, s13, 0
	s_waitcnt vmcnt(16)
	v_lshlrev_b32_e32 v208, 16, v112
	v_and_b32_e32 v209, 0xffff0000, v112
	v_lshlrev_b32_e32 v210, 16, v113
	v_and_b32_e32 v211, 0xffff0000, v113
	v_lshlrev_b32_e32 v212, 16, v114
	v_and_b32_e32 v213, 0xffff0000, v114
	v_lshlrev_b32_e32 v214, 16, v115
	v_and_b32_e32 v215, 0xffff0000, v115
	v_lshlrev_b32_e32 v216, 16, v116
	v_and_b32_e32 v217, 0xffff0000, v116
	v_lshlrev_b32_e32 v218, 16, v117
	v_and_b32_e32 v219, 0xffff0000, v117
	v_lshlrev_b32_e32 v220, 16, v118
	v_and_b32_e32 v221, 0xffff0000, v118
	v_lshlrev_b32_e32 v222, 16, v119
	v_and_b32_e32 v223, 0xffff0000, v119
	v_mul_f32_e32 v224, v208, v208
	v_fmac_f32_e32 v224, v209, v209
	v_fmac_f32_e32 v224, v210, v210
	v_fmac_f32_e32 v224, v211, v211
	v_fmac_f32_e32 v224, v212, v212
	v_fmac_f32_e32 v224, v213, v213
	v_fmac_f32_e32 v224, v214, v214
	v_fmac_f32_e32 v224, v215, v215
	v_fmac_f32_e32 v224, v216, v216
	v_fmac_f32_e32 v224, v217, v217
	v_fmac_f32_e32 v224, v218, v218
	v_fmac_f32_e32 v224, v219, v219
	v_fmac_f32_e32 v224, v220, v220
	v_fmac_f32_e32 v224, v221, v221
	v_fmac_f32_e32 v224, v222, v222
	v_fmac_f32_e32 v224, v223, v223
	s_nop 1
	v_add_f32_dpp v224, v224, v224 quad_perm:[1,0,3,2] row_mask:0xf bank_mask:0xf
	s_nop 1
	v_add_f32_dpp v224, v224, v224 quad_perm:[2,3,0,1] row_mask:0xf bank_mask:0xf
	s_nop 1
	v_add_f32_dpp v224, v224, v224 row_ror:4 row_mask:0xf bank_mask:0xf
	s_nop 1
	v_add_f32_dpp v224, v224, v224 row_ror:8 row_mask:0xf bank_mask:0xf
; DI unsigned pk_bf16(float a, float b) { f32x2_t v = {a, b}; bf16x2_t r = __builtin_convertvector(v, bf16x2_t); return __builtin_bit_cast(unsigned, r); }
; DI void row_phase(const bf16_t* msrc, const float* xsrc, float* xdst, const float* g_post, const float* g_next, bf16_t* hdst, const int gw) {
;     ...
;                 for (int j = 0; j < 4; ++j) { const u32x2 mw = *(const u32x2*)(msrc + (size_t)(rowb + r) * DM + lane * 4 + 256 * j);
;                     mv[r][j] = (f32x4){__uint_as_float(mw[0] << 16), __uint_as_float(mw[0] & 0xffff0000u), __uint_as_float(mw[1] << 16), __uint_as_float(mw[1] & 0xffff0000u)}; }
;             float ss[RB];
; #pragma unroll
;             for (int r = 0; r < RB; ++r) { ss[r] = 0.f;
; #pragma unroll
;                 for (int j = 0; j < 4; ++j) ss[r] += mv[r][j][0] * mv[r][j][0] + mv[r][j][1] * mv[r][j][1] + mv[r][j][2] * mv[r][j][2] + mv[r][j][3] * mv[r][j][3]; }
; #pragma unroll
;             for (int o = 32; o >= 1; o >>= 1)
; #pragma unroll
;                 for (int r = 0; r < RB; ++r) ss[r] += shx(ss[r], o);
; #pragma unroll
;             for (int j = 0; j < 4; ++j) { const f32x4 g = *(const f32x4*)(g_post + lane * 4 + 256 * j);
; #pragma unroll
;                 for (int r = 0; r < RB; ++r) { const float r1 = rsqrtf(ss[r] * (1.f / DM) + EPS); xv[r][j] = xv[r][j] + mv[r][j] * r1 * g; *(f32x4*)(xdst + (size_t)(rowb + r) * DM + lane * 4 + 256 * j) = xv[r][j]; } }
;         }
;         if (hdst) {
;             float ss[RB];
; #pragma unroll
;             for (int r = 0; r < RB; ++r) { ss[r] = 0.f;
; #pragma unroll
;                 for (int j = 0; j < 4; ++j) ss[r] += xv[r][j][0] * xv[r][j][0] + xv[r][j][1] * xv[r][j][1] + xv[r][j][2] * xv[r][j][2] + xv[r][j][3] * xv[r][j][3]; }
; #pragma unroll
;             for (int o = 32; o >= 1; o >>= 1)
; #pragma unroll
;                 for (int r = 0; r < RB; ++r) ss[r] += shx(ss[r], o);
; #pragma unroll
;             for (int j = 0; j < 4; ++j) { const f32x4 g = *(const f32x4*)(g_next + lane * 4 + 256 * j);
; #pragma unroll
;                 for (int r = 0; r < RB; ++r) { const float r2 = rsqrtf(ss[r] * (1.f / DM) + EPS); const f32x4 hv = xv[r][j] * r2 * g;
;                     u32x2 o; o[0] = pk_bf16(hv[0], hv[1]); o[1] = pk_bf16(hv[2], hv[3]); *(u32x2*)(hdst + (size_t)(rowb + r) * DM + lane * 4 + 256 * j) = o; } }
	s_nop 1
	v_readlane_b32 s20, v224, 0
	v_readlane_b32 s21, v224, 16
	v_readlane_b32 s22, v224, 32
	v_readlane_b32 s23, v224, 48
	s_nop 1
	v_mov_b32_e32 v225, s20
	v_add_f32_e32 v225, s21, v225
	v_add_f32_e32 v225, s22, v225
	v_add_f32_e32 v225, s23, v225
	v_mov_b32_e32 v226, 0x358637bd
	v_fmac_f32_e32 v226, 0x3a800000, v225
	v_rsq_f32_e32 v226, v226
	s_nop 0
	v_mul_f32_e32 v208, v208, v226
	v_mul_f32_e32 v209, v209, v226
	v_mul_f32_e32 v210, v210, v226
	v_mul_f32_e32 v211, v211, v226
	v_mul_f32_e32 v212, v212, v226
	v_mul_f32_e32 v213, v213, v226
	v_mul_f32_e32 v214, v214, v226
	v_mul_f32_e32 v215, v215, v226
	v_mul_f32_e32 v216, v216, v226
	v_mul_f32_e32 v217, v217, v226
	v_mul_f32_e32 v218, v218, v226
	v_mul_f32_e32 v219, v219, v226
	v_mul_f32_e32 v220, v220, v226
	v_mul_f32_e32 v221, v221, v226
	v_mul_f32_e32 v222, v222, v226
	v_mul_f32_e32 v223, v223, v226
	v_fmac_f32_e32 v96, v208, v40
	v_fmac_f32_e32 v97, v209, v41
	v_fmac_f32_e32 v98, v210, v42
	v_fmac_f32_e32 v99, v211, v43
	v_fmac_f32_e32 v100, v212, v44
	v_fmac_f32_e32 v101, v213, v45
	v_fmac_f32_e32 v102, v214, v46
	v_fmac_f32_e32 v103, v215, v47
	v_fmac_f32_e32 v104, v216, v48
	v_fmac_f32_e32 v105, v217, v49
	v_fmac_f32_e32 v106, v218, v50
	v_fmac_f32_e32 v107, v219, v51
	v_fmac_f32_e32 v108, v220, v52
	v_fmac_f32_e32 v109, v221, v53
	v_fmac_f32_e32 v110, v222, v54
	v_fmac_f32_e32 v111, v223, v55
	v_lshlrev_b32_e32 v208, 16, v120
	v_and_b32_e32 v209, 0xffff0000, v120
	v_lshlrev_b32_e32 v210, 16, v121
	v_and_b32_e32 v211, 0xffff0000, v121
	v_lshlrev_b32_e32 v212, 16, v122
	v_and_b32_e32 v213, 0xffff0000, v122
	v_lshlrev_b32_e32 v214, 16, v123
	v_and_b32_e32 v215, 0xffff0000, v123
	v_lshlrev_b32_e32 v216, 16, v124
	v_and_b32_e32 v217, 0xffff0000, v124
	v_lshlrev_b32_e32 v218, 16, v125
	v_and_b32_e32 v219, 0xffff0000, v125
	v_lshlrev_b32_e32 v220, 16, v126
	v_and_b32_e32 v221, 0xffff0000, v126
	v_lshlrev_b32_e32 v222, 16, v127
	v_and_b32_e32 v223, 0xffff0000, v127
	v_mul_f32_e32 v224, v208, v208
	v_fmac_f32_e32 v224, v209, v209
	v_fmac_f32_e32 v224, v210, v210
	v_fmac_f32_e32 v224, v211, v211
	v_fmac_f32_e32 v224, v212, v212
	v_fmac_f32_e32 v224, v213, v213
	v_fmac_f32_e32 v224, v214, v214
	v_fmac_f32_e32 v224, v215, v215
	v_fmac_f32_e32 v224, v216, v216
	v_fmac_f32_e32 v224, v217, v217
	v_fmac_f32_e32 v224, v218, v218
	v_fmac_f32_e32 v224, v219, v219
	v_fmac_f32_e32 v224, v220, v220
	v_fmac_f32_e32 v224, v221, v221
	v_fmac_f32_e32 v224, v222, v222
	v_fmac_f32_e32 v224, v223, v223
	s_nop 1
	v_add_f32_dpp v224, v224, v224 quad_perm:[1,0,3,2] row_mask:0xf bank_mask:0xf
	s_nop 1
	v_add_f32_dpp v224, v224, v224 quad_perm:[2,3,0,1] row_mask:0xf bank_mask:0xf
	s_nop 1
	v_add_f32_dpp v224, v224, v224 row_ror:4 row_mask:0xf bank_mask:0xf
	s_nop 1
	v_add_f32_dpp v224, v224, v224 row_ror:8 row_mask:0xf bank_mask:0xf
	s_nop 1
	v_readlane_b32 s20, v224, 0
	v_readlane_b32 s21, v224, 16
	v_readlane_b32 s22, v224, 32
	v_readlane_b32 s23, v224, 48
	s_nop 1
	v_mov_b32_e32 v225, s20
	v_add_f32_e32 v225, s21, v225
	v_add_f32_e32 v225, s22, v225
	v_add_f32_e32 v225, s23, v225
	v_mov_b32_e32 v226, 0x358637bd
	v_fmac_f32_e32 v226, 0x3a800000, v225
	v_rsq_f32_e32 v226, v226
	s_nop 0
	v_mul_f32_e32 v208, v208, v226
	v_mul_f32_e32 v209, v209, v226
	v_mul_f32_e32 v210, v210, v226
	v_mul_f32_e32 v211, v211, v226
	v_mul_f32_e32 v212, v212, v226
	v_mul_f32_e32 v213, v213, v226
	v_mul_f32_e32 v214, v214, v226
	v_mul_f32_e32 v215, v215, v226
	v_mul_f32_e32 v216, v216, v226
	v_mul_f32_e32 v217, v217, v226
	v_mul_f32_e32 v218, v218, v226
	v_mul_f32_e32 v219, v219, v226
	v_mul_f32_e32 v220, v220, v226
	v_mul_f32_e32 v221, v221, v226
	v_mul_f32_e32 v222, v222, v226
	v_mul_f32_e32 v223, v223, v226
	v_fmac_f32_e32 v96, v208, v56
	v_fmac_f32_e32 v97, v209, v57
	v_fmac_f32_e32 v98, v210, v58
	v_fmac_f32_e32 v99, v211, v59
	v_fmac_f32_e32 v100, v212, v60
	v_fmac_f32_e32 v101, v213, v61
	v_fmac_f32_e32 v102, v214, v62
	v_fmac_f32_e32 v103, v215, v63
	v_fmac_f32_e32 v104, v216, v64
	v_fmac_f32_e32 v105, v217, v65
	v_fmac_f32_e32 v106, v218, v66
	v_fmac_f32_e32 v107, v219, v67
	v_fmac_f32_e32 v108, v220, v68
	v_fmac_f32_e32 v109, v221, v69
	v_fmac_f32_e32 v110, v222, v70
	v_fmac_f32_e32 v111, v223, v71
	global_store_dwordx4 v1, v[96:99], s[8:9] offset:0
	global_store_dwordx4 v1, v[100:103], s[8:9] offset:16
	global_store_dwordx4 v1, v[104:107], s[8:9] offset:2048
	global_store_dwordx4 v1, v[108:111], s[8:9] offset:2064
	s_add_u32 s8, s8, 0x1000
	s_addc_u32 s9, s9, 0
	v_mul_f32_e32 v224, v96, v96
	v_fmac_f32_e32 v224, v97, v97
	v_fmac_f32_e32 v224, v98, v98
	v_fmac_f32_e32 v224, v99, v99
	v_fmac_f32_e32 v224, v100, v100
	v_fmac_f32_e32 v224, v101, v101
	v_fmac_f32_e32 v224, v102, v102
	v_fmac_f32_e32 v224, v103, v103
	v_fmac_f32_e32 v224, v104, v104
	v_fmac_f32_e32 v224, v105, v105
	v_fmac_f32_e32 v224, v106, v106
	v_fmac_f32_e32 v224, v107, v107
	v_fmac_f32_e32 v224, v108, v108
	v_fmac_f32_e32 v224, v109, v109
	v_fmac_f32_e32 v224, v110, v110
	v_fmac_f32_e32 v224, v111, v111
	s_nop 1
	v_add_f32_dpp v224, v224, v224 quad_perm:[1,0,3,2] row_mask:0xf bank_mask:0xf
	s_nop 1
	v_add_f32_dpp v224, v224, v224 quad_perm:[2,3,0,1] row_mask:0xf bank_mask:0xf
	s_nop 1
	v_add_f32_dpp v224, v224, v224 row_ror:4 row_mask:0xf bank_mask:0xf
	s_nop 1
	v_add_f32_dpp v224, v224, v224 row_ror:8 row_mask:0xf bank_mask:0xf
	s_nop 1
	v_readlane_b32 s20, v224, 0
	v_readlane_b32 s21, v224, 16
	v_readlane_b32 s22, v224, 32
	v_readlane_b32 s23, v224, 48
	s_nop 1
	v_mov_b32_e32 v225, s20
	v_add_f32_e32 v225, s21, v225
	v_add_f32_e32 v225, s22, v225
	v_add_f32_e32 v225, s23, v225
	v_mov_b32_e32 v226, 0x358637bd
	v_fmac_f32_e32 v226, 0x3a800000, v225
; DI unsigned pk_bf16(float a, float b) { f32x2_t v = {a, b}; bf16x2_t r = __builtin_convertvector(v, bf16x2_t); return __builtin_bit_cast(unsigned, r); }
; DI float shx(float v, int mask) { const int l = olane(); return __builtin_bit_cast(float, __builtin_amdgcn_ds_bpermute(((l ^ mask) & 63) << 2, __builtin_bit_cast(int, v))); }
; DI void row_phase(const bf16_t* msrc, const float* xsrc, float* xdst, const float* g_post, const float* g_next, bf16_t* hdst, const int gw) {
;     ...
;             for (int j = 0; j < 4; ++j) { const f32x4 g = *(const f32x4*)(g_post + lane * 4 + 256 * j);
; #pragma unroll
;                 for (int r = 0; r < RB; ++r) { const float r1 = rsqrtf(ss[r] * (1.f / DM) + EPS); xv[r][j] = xv[r][j] + mv[r][j] * r1 * g; *(f32x4*)(xdst + (size_t)(rowb + r) * DM + lane * 4 + 256 * j) = xv[r][j]; } }
;         }
;         if (hdst) {
;             float ss[RB];
; #pragma unroll
;             for (int r = 0; r < RB; ++r) { ss[r] = 0.f;
; #pragma unroll
;                 for (int j = 0; j < 4; ++j) ss[r] += xv[r][j][0] * xv[r][j][0] + xv[r][j][1] * xv[r][j][1] + xv[r][j][2] * xv[r][j][2] + xv[r][j][3] * xv[r][j][3]; }
; #pragma unroll
;             for (int o = 32; o >= 1; o >>= 1)
; #pragma unroll
;                 for (int r = 0; r < RB; ++r) ss[r] += shx(ss[r], o);
; #pragma unroll
;             for (int j = 0; j < 4; ++j) { const f32x4 g = *(const f32x4*)(g_next + lane * 4 + 256 * j);
; #pragma unroll
;                 for (int r = 0; r < RB; ++r) { const float r2 = rsqrtf(ss[r] * (1.f / DM) + EPS); const f32x4 hv = xv[r][j] * r2 * g;
;                     u32x2 o; o[0] = pk_bf16(hv[0], hv[1]); o[1] = pk_bf16(hv[2], hv[3]); *(u32x2*)(hdst + (size_t)(rowb + r) * DM + lane * 4 + 256 * j) = o; } }
	v_rsq_f32_e32 v226, v226
	s_nop 0
	v_mul_f32_e32 v208, v96, v226
	v_mul_f32_e32 v209, v97, v226
	v_mul_f32_e32 v210, v98, v226
	v_mul_f32_e32 v211, v99, v226
	v_mul_f32_e32 v212, v100, v226
	v_mul_f32_e32 v213, v101, v226
	v_mul_f32_e32 v214, v102, v226
	v_mul_f32_e32 v215, v103, v226
	v_mul_f32_e32 v216, v104, v226
	v_mul_f32_e32 v217, v105, v226
	v_mul_f32_e32 v218, v106, v226
	v_mul_f32_e32 v219, v107, v226
	v_mul_f32_e32 v220, v108, v226
	v_mul_f32_e32 v221, v109, v226
	v_mul_f32_e32 v222, v110, v226
	v_mul_f32_e32 v223, v111, v226
	v_mul_f32_e32 v208, v208, v72
	v_mul_f32_e32 v209, v209, v73
	v_mul_f32_e32 v210, v210, v74
	v_mul_f32_e32 v211, v211, v75
	v_mul_f32_e32 v212, v212, v76
	v_mul_f32_e32 v213, v213, v77
	v_mul_f32_e32 v214, v214, v78
	v_mul_f32_e32 v215, v215, v79
	v_mul_f32_e32 v216, v216, v80
	v_mul_f32_e32 v217, v217, v81
	v_mul_f32_e32 v218, v218, v82
	v_mul_f32_e32 v219, v219, v83
	v_mul_f32_e32 v220, v220, v84
	v_mul_f32_e32 v221, v221, v85
	v_mul_f32_e32 v222, v222, v86
	v_mul_f32_e32 v223, v223, v87
	v_cvt_pk_bf16_f32 v112, v208, v209
	v_cvt_pk_bf16_f32 v113, v210, v211
	v_cvt_pk_bf16_f32 v114, v212, v213
	v_cvt_pk_bf16_f32 v115, v214, v215
	v_cvt_pk_bf16_f32 v116, v216, v217
	v_cvt_pk_bf16_f32 v117, v218, v219
	v_cvt_pk_bf16_f32 v118, v220, v221
	v_cvt_pk_bf16_f32 v119, v222, v223
	global_store_dwordx4 v2, v[112:115], s[14:15]
	global_store_dwordx4 v2, v[116:119], s[14:15] offset:1024
	s_add_u32 s14, s14, 0x800
	s_addc_u32 s15, s15, 0
	global_load_dwordx4 v[96:99], v1, s[6:7] offset:0
	global_load_dwordx4 v[100:103], v1, s[6:7] offset:16
	global_load_dwordx4 v[104:107], v1, s[6:7] offset:2048
	global_load_dwordx4 v[108:111], v1, s[6:7] offset:2064
	global_load_dwordx4 v[112:115], v2, s[10:11]
	global_load_dwordx4 v[116:119], v2, s[10:11] offset:1024
	global_load_dwordx4 v[120:123], v2, s[12:13]
	global_load_dwordx4 v[124:127], v2, s[12:13] offset:1024
	s_add_u32 s6, s6, 0x1000
	s_addc_u32 s7, s7, 0
	s_add_u32 s10, s10, 0x800
	s_addc_u32 s11, s11, 0
	s_add_u32 s12, s12, 0x800
	s_addc_u32 s13, s13, 0
	s_waitcnt vmcnt(22)
	v_lshlrev_b32_e32 v208, 16, v144
	v_and_b32_e32 v209, 0xffff0000, v144
	v_lshlrev_b32_e32 v210, 16, v145
	v_and_b32_e32 v211, 0xffff0000, v145
	v_lshlrev_b32_e32 v212, 16, v146
	v_and_b32_e32 v213, 0xffff0000, v146
	v_lshlrev_b32_e32 v214, 16, v147
	v_and_b32_e32 v215, 0xffff0000, v147
	v_lshlrev_b32_e32 v216, 16, v148
	v_and_b32_e32 v217, 0xffff0000, v148
	v_lshlrev_b32_e32 v218, 16, v149
	v_and_b32_e32 v219, 0xffff0000, v149
	v_lshlrev_b32_e32 v220, 16, v150
	v_and_b32_e32 v221, 0xffff0000, v150
	v_lshlrev_b32_e32 v222, 16, v151
	v_and_b32_e32 v223, 0xffff0000, v151
	v_mul_f32_e32 v224, v208, v208
	v_fmac_f32_e32 v224, v209, v209
	v_fmac_f32_e32 v224, v210, v210
	v_fmac_f32_e32 v224, v211, v211
	v_fmac_f32_e32 v224, v212, v212
	v_fmac_f32_e32 v224, v213, v213
	v_fmac_f32_e32 v224, v214, v214
	v_fmac_f32_e32 v224, v215, v215
	v_fmac_f32_e32 v224, v216, v216
	v_fmac_f32_e32 v224, v217, v217
	v_fmac_f32_e32 v224, v218, v218
	v_fmac_f32_e32 v224, v219, v219
	v_fmac_f32_e32 v224, v220, v220
	v_fmac_f32_e32 v224, v221, v221
	v_fmac_f32_e32 v224, v222, v222
	v_fmac_f32_e32 v224, v223, v223
	s_nop 1
	v_add_f32_dpp v224, v224, v224 quad_perm:[1,0,3,2] row_mask:0xf bank_mask:0xf
	s_nop 1
	v_add_f32_dpp v224, v224, v224 quad_perm:[2,3,0,1] row_mask:0xf bank_mask:0xf
	s_nop 1
	v_add_f32_dpp v224, v224, v224 row_ror:4 row_mask:0xf bank_mask:0xf
	s_nop 1
	v_add_f32_dpp v224, v224, v224 row_ror:8 row_mask:0xf bank_mask:0xf
	s_nop 1
	v_readlane_b32 s20, v224, 0
	v_readlane_b32 s21, v224, 16
	v_readlane_b32 s22, v224, 32
	v_readlane_b32 s23, v224, 48
	s_nop 1
	v_mov_b32_e32 v225, s20
	v_add_f32_e32 v225, s21, v225
	v_add_f32_e32 v225, s22, v225
	v_add_f32_e32 v225, s23, v225
	v_mov_b32_e32 v226, 0x358637bd
	v_fmac_f32_e32 v226, 0x3a800000, v225
	v_rsq_f32_e32 v226, v226
	s_nop 0
	v_mul_f32_e32 v208, v208, v226
	v_mul_f32_e32 v209, v209, v226
	v_mul_f32_e32 v210, v210, v226
	v_mul_f32_e32 v211, v211, v226
	v_mul_f32_e32 v212, v212, v226
	v_mul_f32_e32 v213, v213, v226
	v_mul_f32_e32 v214, v214, v226
	v_mul_f32_e32 v215, v215, v226
	v_mul_f32_e32 v216, v216, v226
	v_mul_f32_e32 v217, v217, v226
	v_mul_f32_e32 v218, v218, v226
	v_mul_f32_e32 v219, v219, v226
	v_mul_f32_e32 v220, v220, v226
	v_mul_f32_e32 v221, v221, v226
	v_mul_f32_e32 v222, v222, v226
	v_mul_f32_e32 v223, v223, v226
	v_fmac_f32_e32 v128, v208, v40
	v_fmac_f32_e32 v129, v209, v41
	v_fmac_f32_e32 v130, v210, v42
	v_fmac_f32_e32 v131, v211, v43
	v_fmac_f32_e32 v132, v212, v44
	v_fmac_f32_e32 v133, v213, v45
	v_fmac_f32_e32 v134, v214, v46
	v_fmac_f32_e32 v135, v215, v47
	v_fmac_f32_e32 v136, v216, v48
	v_fmac_f32_e32 v137, v217, v49
	v_fmac_f32_e32 v138, v218, v50
	v_fmac_f32_e32 v139, v219, v51
	v_fmac_f32_e32 v140, v220, v52
	v_fmac_f32_e32 v141, v221, v53
	v_fmac_f32_e32 v142, v222, v54
	v_fmac_f32_e32 v143, v223, v55
	v_lshlrev_b32_e32 v208, 16, v152
	v_and_b32_e32 v209, 0xffff0000, v152
	v_lshlrev_b32_e32 v210, 16, v153
	v_and_b32_e32 v211, 0xffff0000, v153
	v_lshlrev_b32_e32 v212, 16, v154
	v_and_b32_e32 v213, 0xffff0000, v154
	v_lshlrev_b32_e32 v214, 16, v155
	v_and_b32_e32 v215, 0xffff0000, v155
	v_lshlrev_b32_e32 v216, 16, v156
	v_and_b32_e32 v217, 0xffff0000, v156
	v_lshlrev_b32_e32 v218, 16, v157
	v_and_b32_e32 v219, 0xffff0000, v157
	v_lshlrev_b32_e32 v220, 16, v158
	v_and_b32_e32 v221, 0xffff0000, v158
	v_lshlrev_b32_e32 v222, 16, v159
	v_and_b32_e32 v223, 0xffff0000, v159
	v_mul_f32_e32 v224, v208, v208
	v_fmac_f32_e32 v224, v209, v209
	v_fmac_f32_e32 v224, v210, v210
	v_fmac_f32_e32 v224, v211, v211
	v_fmac_f32_e32 v224, v212, v212
; DI unsigned pk_bf16(float a, float b) { f32x2_t v = {a, b}; bf16x2_t r = __builtin_convertvector(v, bf16x2_t); return __builtin_bit_cast(unsigned, r); }
; DI void row_phase(const bf16_t* msrc, const float* xsrc, float* xdst, const float* g_post, const float* g_next, bf16_t* hdst, const int gw) {
;     ...
;                 for (int j = 0; j < 4; ++j) { const u32x2 mw = *(const u32x2*)(msrc + (size_t)(rowb + r) * DM + lane * 4 + 256 * j);
;                     mv[r][j] = (f32x4){__uint_as_float(mw[0] << 16), __uint_as_float(mw[0] & 0xffff0000u), __uint_as_float(mw[1] << 16), __uint_as_float(mw[1] & 0xffff0000u)}; }
;             float ss[RB];
; #pragma unroll
;             for (int r = 0; r < RB; ++r) { ss[r] = 0.f;
; #pragma unroll
;                 for (int j = 0; j < 4; ++j) ss[r] += mv[r][j][0] * mv[r][j][0] + mv[r][j][1] * mv[r][j][1] + mv[r][j][2] * mv[r][j][2] + mv[r][j][3] * mv[r][j][3]; }
; #pragma unroll
;             for (int o = 32; o >= 1; o >>= 1)
; #pragma unroll
;                 for (int r = 0; r < RB; ++r) ss[r] += shx(ss[r], o);
; #pragma unroll
;             for (int j = 0; j < 4; ++j) { const f32x4 g = *(const f32x4*)(g_post + lane * 4 + 256 * j);
; #pragma unroll
;                 for (int r = 0; r < RB; ++r) { const float r1 = rsqrtf(ss[r] * (1.f / DM) + EPS); xv[r][j] = xv[r][j] + mv[r][j] * r1 * g; *(f32x4*)(xdst + (size_t)(rowb + r) * DM + lane * 4 + 256 * j) = xv[r][j]; } }
;         }
;         if (hdst) {
;             float ss[RB];
; #pragma unroll
;             for (int r = 0; r < RB; ++r) { ss[r] = 0.f;
; #pragma unroll
;                 for (int j = 0; j < 4; ++j) ss[r] += xv[r][j][0] * xv[r][j][0] + xv[r][j][1] * xv[r][j][1] + xv[r][j][2] * xv[r][j][2] + xv[r][j][3] * xv[r][j][3]; }
; #pragma unroll
;             for (int o = 32; o >= 1; o >>= 1)
; #pragma unroll
;                 for (int r = 0; r < RB; ++r) ss[r] += shx(ss[r], o);
; #pragma unroll
;             for (int j = 0; j < 4; ++j) { const f32x4 g = *(const f32x4*)(g_next + lane * 4 + 256 * j);
; #pragma unroll
;                 for (int r = 0; r < RB; ++r) { const float r2 = rsqrtf(ss[r] * (1.f / DM) + EPS); const f32x4 hv = xv[r][j] * r2 * g;
;                     u32x2 o; o[0] = pk_bf16(hv[0], hv[1]); o[1] = pk_bf16(hv[2], hv[3]); *(u32x2*)(hdst + (size_t)(rowb + r) * DM + lane * 4 + 256 * j) = o; } }
	v_fmac_f32_e32 v224, v213, v213
	v_fmac_f32_e32 v224, v214, v214
	v_fmac_f32_e32 v224, v215, v215
	v_fmac_f32_e32 v224, v216, v216
	v_fmac_f32_e32 v224, v217, v217
	v_fmac_f32_e32 v224, v218, v218
	v_fmac_f32_e32 v224, v219, v219
	v_fmac_f32_e32 v224, v220, v220
	v_fmac_f32_e32 v224, v221, v221
	v_fmac_f32_e32 v224, v222, v222
	v_fmac_f32_e32 v224, v223, v223
	s_nop 1
	v_add_f32_dpp v224, v224, v224 quad_perm:[1,0,3,2] row_mask:0xf bank_mask:0xf
	s_nop 1
	v_add_f32_dpp v224, v224, v224 quad_perm:[2,3,0,1] row_mask:0xf bank_mask:0xf
	s_nop 1
	v_add_f32_dpp v224, v224, v224 row_ror:4 row_mask:0xf bank_mask:0xf
	s_nop 1
	v_add_f32_dpp v224, v224, v224 row_ror:8 row_mask:0xf bank_mask:0xf
	s_nop 1
	v_readlane_b32 s20, v224, 0
	v_readlane_b32 s21, v224, 16
	v_readlane_b32 s22, v224, 32
	v_readlane_b32 s23, v224, 48
	s_nop 1
	v_mov_b32_e32 v225, s20
	v_add_f32_e32 v225, s21, v225
	v_add_f32_e32 v225, s22, v225
	v_add_f32_e32 v225, s23, v225
	v_mov_b32_e32 v226, 0x358637bd
	v_fmac_f32_e32 v226, 0x3a800000, v225
	v_rsq_f32_e32 v226, v226
	s_nop 0
	v_mul_f32_e32 v208, v208, v226
	v_mul_f32_e32 v209, v209, v226
	v_mul_f32_e32 v210, v210, v226
	v_mul_f32_e32 v211, v211, v226
	v_mul_f32_e32 v212, v212, v226
	v_mul_f32_e32 v213, v213, v226
	v_mul_f32_e32 v214, v214, v226
	v_mul_f32_e32 v215, v215, v226
	v_mul_f32_e32 v216, v216, v226
	v_mul_f32_e32 v217, v217, v226
	v_mul_f32_e32 v218, v218, v226
	v_mul_f32_e32 v219, v219, v226
	v_mul_f32_e32 v220, v220, v226
	v_mul_f32_e32 v221, v221, v226
	v_mul_f32_e32 v222, v222, v226
	v_mul_f32_e32 v223, v223, v226
	v_fmac_f32_e32 v128, v208, v56
	v_fmac_f32_e32 v129, v209, v57
	v_fmac_f32_e32 v130, v210, v58
	v_fmac_f32_e32 v131, v211, v59
	v_fmac_f32_e32 v132, v212, v60
	v_fmac_f32_e32 v133, v213, v61
	v_fmac_f32_e32 v134, v214, v62
	v_fmac_f32_e32 v135, v215, v63
	v_fmac_f32_e32 v136, v216, v64
	v_fmac_f32_e32 v137, v217, v65
	v_fmac_f32_e32 v138, v218, v66
	v_fmac_f32_e32 v139, v219, v67
	v_fmac_f32_e32 v140, v220, v68
	v_fmac_f32_e32 v141, v221, v69
	v_fmac_f32_e32 v142, v222, v70
	v_fmac_f32_e32 v143, v223, v71
	global_store_dwordx4 v1, v[128:131], s[8:9] offset:0
	global_store_dwordx4 v1, v[132:135], s[8:9] offset:16
	global_store_dwordx4 v1, v[136:139], s[8:9] offset:2048
	global_store_dwordx4 v1, v[140:143], s[8:9] offset:2064
	s_add_u32 s8, s8, 0x1000
	s_addc_u32 s9, s9, 0
	v_mul_f32_e32 v224, v128, v128
	v_fmac_f32_e32 v224, v129, v129
	v_fmac_f32_e32 v224, v130, v130
	v_fmac_f32_e32 v224, v131, v131
	v_fmac_f32_e32 v224, v132, v132
	v_fmac_f32_e32 v224, v133, v133
	v_fmac_f32_e32 v224, v134, v134
	v_fmac_f32_e32 v224, v135, v135
	v_fmac_f32_e32 v224, v136, v136
	v_fmac_f32_e32 v224, v137, v137
	v_fmac_f32_e32 v224, v138, v138
	v_fmac_f32_e32 v224, v139, v139
	v_fmac_f32_e32 v224, v140, v140
	v_fmac_f32_e32 v224, v141, v141
	v_fmac_f32_e32 v224, v142, v142
	v_fmac_f32_e32 v224, v143, v143
	s_nop 1
	v_add_f32_dpp v224, v224, v224 quad_perm:[1,0,3,2] row_mask:0xf bank_mask:0xf
	s_nop 1
	v_add_f32_dpp v224, v224, v224 quad_perm:[2,3,0,1] row_mask:0xf bank_mask:0xf
	s_nop 1
	v_add_f32_dpp v224, v224, v224 row_ror:4 row_mask:0xf bank_mask:0xf
	s_nop 1
	v_add_f32_dpp v224, v224, v224 row_ror:8 row_mask:0xf bank_mask:0xf
	s_nop 1
	v_readlane_b32 s20, v224, 0
	v_readlane_b32 s21, v224, 16
	v_readlane_b32 s22, v224, 32
	v_readlane_b32 s23, v224, 48
	s_nop 1
	v_mov_b32_e32 v225, s20
	v_add_f32_e32 v225, s21, v225
	v_add_f32_e32 v225, s22, v225
	v_add_f32_e32 v225, s23, v225
	v_mov_b32_e32 v226, 0x358637bd
	v_fmac_f32_e32 v226, 0x3a800000, v225
	v_rsq_f32_e32 v226, v226
	s_nop 0
	v_mul_f32_e32 v208, v128, v226
	v_mul_f32_e32 v209, v129, v226
	v_mul_f32_e32 v210, v130, v226
	v_mul_f32_e32 v211, v131, v226
	v_mul_f32_e32 v212, v132, v226
	v_mul_f32_e32 v213, v133, v226
	v_mul_f32_e32 v214, v134, v226
	v_mul_f32_e32 v215, v135, v226
	v_mul_f32_e32 v216, v136, v226
	v_mul_f32_e32 v217, v137, v226
	v_mul_f32_e32 v218, v138, v226
	v_mul_f32_e32 v219, v139, v226
	v_mul_f32_e32 v220, v140, v226
	v_mul_f32_e32 v221, v141, v226
	v_mul_f32_e32 v222, v142, v226
	v_mul_f32_e32 v223, v143, v226
	v_mul_f32_e32 v208, v208, v72
	v_mul_f32_e32 v209, v209, v73
	v_mul_f32_e32 v210, v210, v74
	v_mul_f32_e32 v211, v211, v75
	v_mul_f32_e32 v212, v212, v76
	v_mul_f32_e32 v213, v213, v77
	v_mul_f32_e32 v214, v214, v78
	v_mul_f32_e32 v215, v215, v79
	v_mul_f32_e32 v216, v216, v80
	v_mul_f32_e32 v217, v217, v81
	v_mul_f32_e32 v218, v218, v82
	v_mul_f32_e32 v219, v219, v83
	v_mul_f32_e32 v220, v220, v84
	v_mul_f32_e32 v221, v221, v85
	v_mul_f32_e32 v222, v222, v86
	v_mul_f32_e32 v223, v223, v87
	v_cvt_pk_bf16_f32 v144, v208, v209
	v_cvt_pk_bf16_f32 v145, v210, v211
	v_cvt_pk_bf16_f32 v146, v212, v213
	v_cvt_pk_bf16_f32 v147, v214, v215
	v_cvt_pk_bf16_f32 v148, v216, v217
	v_cvt_pk_bf16_f32 v149, v218, v219
	v_cvt_pk_bf16_f32 v150, v220, v221
	v_cvt_pk_bf16_f32 v151, v222, v223
	global_store_dwordx4 v2, v[144:147], s[14:15]
	global_store_dwordx4 v2, v[148:151], s[14:15] offset:1024
	s_add_u32 s14, s14, 0x800
	s_addc_u32 s15, s15, 0
	global_load_dwordx4 v[128:131], v1, s[6:7] offset:0
	global_load_dwordx4 v[132:135], v1, s[6:7] offset:16
	global_load_dwordx4 v[136:139], v1, s[6:7] offset:2048
	global_load_dwordx4 v[140:143], v1, s[6:7] offset:2064
	global_load_dwordx4 v[144:147], v2, s[10:11]
	global_load_dwordx4 v[148:151], v2, s[10:11] offset:1024
	global_load_dwordx4 v[152:155], v2, s[12:13]
	global_load_dwordx4 v[156:159], v2, s[12:13] offset:1024
	s_add_u32 s6, s6, 0x1000
	s_addc_u32 s7, s7, 0
	s_add_u32 s10, s10, 0x800
	s_addc_u32 s11, s11, 0
	s_add_u32 s12, s12, 0x800
	s_addc_u32 s13, s13, 0
	s_waitcnt vmcnt(28)
; DI float shx(float v, int mask) { const int l = olane(); return __builtin_bit_cast(float, __builtin_amdgcn_ds_bpermute(((l ^ mask) & 63) << 2, __builtin_bit_cast(int, v))); }
; DI void row_phase(const bf16_t* msrc, const float* xsrc, float* xdst, const float* g_post, const float* g_next, bf16_t* hdst, const int gw) {
;     ...
;                 for (int j = 0; j < 4; ++j) { const u32x2 mw = *(const u32x2*)(msrc + (size_t)(rowb + r) * DM + lane * 4 + 256 * j);
;                     mv[r][j] = (f32x4){__uint_as_float(mw[0] << 16), __uint_as_float(mw[0] & 0xffff0000u), __uint_as_float(mw[1] << 16), __uint_as_float(mw[1] & 0xffff0000u)}; }
;             float ss[RB];
; #pragma unroll
;             for (int r = 0; r < RB; ++r) { ss[r] = 0.f;
; #pragma unroll
;                 for (int j = 0; j < 4; ++j) ss[r] += mv[r][j][0] * mv[r][j][0] + mv[r][j][1] * mv[r][j][1] + mv[r][j][2] * mv[r][j][2] + mv[r][j][3] * mv[r][j][3]; }
; #pragma unroll
;             for (int o = 32; o >= 1; o >>= 1)
; #pragma unroll
;                 for (int r = 0; r < RB; ++r) ss[r] += shx(ss[r], o);
; #pragma unroll
;             for (int j = 0; j < 4; ++j) { const f32x4 g = *(const f32x4*)(g_post + lane * 4 + 256 * j);
; #pragma unroll
;                 for (int r = 0; r < RB; ++r) { const float r1 = rsqrtf(ss[r] * (1.f / DM) + EPS); xv[r][j] = xv[r][j] + mv[r][j] * r1 * g; *(f32x4*)(xdst + (size_t)(rowb + r) * DM + lane * 4 + 256 * j) = xv[r][j]; } }
	v_lshlrev_b32_e32 v208, 16, v176
	v_and_b32_e32 v209, 0xffff0000, v176
	v_lshlrev_b32_e32 v210, 16, v177
	v_and_b32_e32 v211, 0xffff0000, v177
	v_lshlrev_b32_e32 v212, 16, v178
	v_and_b32_e32 v213, 0xffff0000, v178
	v_lshlrev_b32_e32 v214, 16, v179
	v_and_b32_e32 v215, 0xffff0000, v179
	v_lshlrev_b32_e32 v216, 16, v180
	v_and_b32_e32 v217, 0xffff0000, v180
	v_lshlrev_b32_e32 v218, 16, v181
	v_and_b32_e32 v219, 0xffff0000, v181
	v_lshlrev_b32_e32 v220, 16, v182
	v_and_b32_e32 v221, 0xffff0000, v182
	v_lshlrev_b32_e32 v222, 16, v183
	v_and_b32_e32 v223, 0xffff0000, v183
	v_mul_f32_e32 v224, v208, v208
	v_fmac_f32_e32 v224, v209, v209
	v_fmac_f32_e32 v224, v210, v210
	v_fmac_f32_e32 v224, v211, v211
	v_fmac_f32_e32 v224, v212, v212
	v_fmac_f32_e32 v224, v213, v213
	v_fmac_f32_e32 v224, v214, v214
	v_fmac_f32_e32 v224, v215, v215
	v_fmac_f32_e32 v224, v216, v216
	v_fmac_f32_e32 v224, v217, v217
	v_fmac_f32_e32 v224, v218, v218
	v_fmac_f32_e32 v224, v219, v219
	v_fmac_f32_e32 v224, v220, v220
	v_fmac_f32_e32 v224, v221, v221
	v_fmac_f32_e32 v224, v222, v222
	v_fmac_f32_e32 v224, v223, v223
	s_nop 1
	v_add_f32_dpp v224, v224, v224 quad_perm:[1,0,3,2] row_mask:0xf bank_mask:0xf
	s_nop 1
	v_add_f32_dpp v224, v224, v224 quad_perm:[2,3,0,1] row_mask:0xf bank_mask:0xf
	s_nop 1
	v_add_f32_dpp v224, v224, v224 row_ror:4 row_mask:0xf bank_mask:0xf
	s_nop 1
	v_add_f32_dpp v224, v224, v224 row_ror:8 row_mask:0xf bank_mask:0xf
	s_nop 1
	v_readlane_b32 s20, v224, 0
	v_readlane_b32 s21, v224, 16
	v_readlane_b32 s22, v224, 32
	v_readlane_b32 s23, v224, 48
	s_nop 1
	v_mov_b32_e32 v225, s20
	v_add_f32_e32 v225, s21, v225
	v_add_f32_e32 v225, s22, v225
	v_add_f32_e32 v225, s23, v225
	v_mov_b32_e32 v226, 0x358637bd
	v_fmac_f32_e32 v226, 0x3a800000, v225
	v_rsq_f32_e32 v226, v226
	s_nop 0
	v_mul_f32_e32 v208, v208, v226
	v_mul_f32_e32 v209, v209, v226
	v_mul_f32_e32 v210, v210, v226
	v_mul_f32_e32 v211, v211, v226
	v_mul_f32_e32 v212, v212, v226
	v_mul_f32_e32 v213, v213, v226
	v_mul_f32_e32 v214, v214, v226
	v_mul_f32_e32 v215, v215, v226
	v_mul_f32_e32 v216, v216, v226
	v_mul_f32_e32 v217, v217, v226
	v_mul_f32_e32 v218, v218, v226
	v_mul_f32_e32 v219, v219, v226
	v_mul_f32_e32 v220, v220, v226
	v_mul_f32_e32 v221, v221, v226
	v_mul_f32_e32 v222, v222, v226
	v_mul_f32_e32 v223, v223, v226
	v_fmac_f32_e32 v160, v208, v40
	v_fmac_f32_e32 v161, v209, v41
	v_fmac_f32_e32 v162, v210, v42
	v_fmac_f32_e32 v163, v211, v43
	v_fmac_f32_e32 v164, v212, v44
	v_fmac_f32_e32 v165, v213, v45
	v_fmac_f32_e32 v166, v214, v46
	v_fmac_f32_e32 v167, v215, v47
	v_fmac_f32_e32 v168, v216, v48
	v_fmac_f32_e32 v169, v217, v49
	v_fmac_f32_e32 v170, v218, v50
	v_fmac_f32_e32 v171, v219, v51
	v_fmac_f32_e32 v172, v220, v52
	v_fmac_f32_e32 v173, v221, v53
	v_fmac_f32_e32 v174, v222, v54
	v_fmac_f32_e32 v175, v223, v55
	v_lshlrev_b32_e32 v208, 16, v184
	v_and_b32_e32 v209, 0xffff0000, v184
	v_lshlrev_b32_e32 v210, 16, v185
	v_and_b32_e32 v211, 0xffff0000, v185
	v_lshlrev_b32_e32 v212, 16, v186
	v_and_b32_e32 v213, 0xffff0000, v186
	v_lshlrev_b32_e32 v214, 16, v187
	v_and_b32_e32 v215, 0xffff0000, v187
	v_lshlrev_b32_e32 v216, 16, v188
	v_and_b32_e32 v217, 0xffff0000, v188
	v_lshlrev_b32_e32 v218, 16, v189
	v_and_b32_e32 v219, 0xffff0000, v189
	v_lshlrev_b32_e32 v220, 16, v190
	v_and_b32_e32 v221, 0xffff0000, v190
	v_lshlrev_b32_e32 v222, 16, v191
	v_and_b32_e32 v223, 0xffff0000, v191
	v_mul_f32_e32 v224, v208, v208
	v_fmac_f32_e32 v224, v209, v209
	v_fmac_f32_e32 v224, v210, v210
	v_fmac_f32_e32 v224, v211, v211
	v_fmac_f32_e32 v224, v212, v212
	v_fmac_f32_e32 v224, v213, v213
	v_fmac_f32_e32 v224, v214, v214
	v_fmac_f32_e32 v224, v215, v215
	v_fmac_f32_e32 v224, v216, v216
	v_fmac_f32_e32 v224, v217, v217
	v_fmac_f32_e32 v224, v218, v218
	v_fmac_f32_e32 v224, v219, v219
	v_fmac_f32_e32 v224, v220, v220
	v_fmac_f32_e32 v224, v221, v221
	v_fmac_f32_e32 v224, v222, v222
	v_fmac_f32_e32 v224, v223, v223
	s_nop 1
	v_add_f32_dpp v224, v224, v224 quad_perm:[1,0,3,2] row_mask:0xf bank_mask:0xf
	s_nop 1
	v_add_f32_dpp v224, v224, v224 quad_perm:[2,3,0,1] row_mask:0xf bank_mask:0xf
	s_nop 1
	v_add_f32_dpp v224, v224, v224 row_ror:4 row_mask:0xf bank_mask:0xf
	s_nop 1
	v_add_f32_dpp v224, v224, v224 row_ror:8 row_mask:0xf bank_mask:0xf
	s_nop 1
	v_readlane_b32 s20, v224, 0
	v_readlane_b32 s21, v224, 16
	v_readlane_b32 s22, v224, 32
	v_readlane_b32 s23, v224, 48
	s_nop 1
	v_mov_b32_e32 v225, s20
	v_add_f32_e32 v225, s21, v225
	v_add_f32_e32 v225, s22, v225
	v_add_f32_e32 v225, s23, v225
	v_mov_b32_e32 v226, 0x358637bd
	v_fmac_f32_e32 v226, 0x3a800000, v225
	v_rsq_f32_e32 v226, v226
	s_nop 0
	v_mul_f32_e32 v208, v208, v226
	v_mul_f32_e32 v209, v209, v226
	v_mul_f32_e32 v210, v210, v226
	v_mul_f32_e32 v211, v211, v226
	v_mul_f32_e32 v212, v212, v226
	v_mul_f32_e32 v213, v213, v226
	v_mul_f32_e32 v214, v214, v226
	v_mul_f32_e32 v215, v215, v226
	v_mul_f32_e32 v216, v216, v226
	v_mul_f32_e32 v217, v217, v226
	v_mul_f32_e32 v218, v218, v226
	v_mul_f32_e32 v219, v219, v226
	v_mul_f32_e32 v220, v220, v226
	v_mul_f32_e32 v221, v221, v226
	v_mul_f32_e32 v222, v222, v226
	v_mul_f32_e32 v223, v223, v226
	v_fmac_f32_e32 v160, v208, v56
	v_fmac_f32_e32 v161, v209, v57
	v_fmac_f32_e32 v162, v210, v58
	v_fmac_f32_e32 v163, v211, v59
	v_fmac_f32_e32 v164, v212, v60
	v_fmac_f32_e32 v165, v213, v61
	v_fmac_f32_e32 v166, v214, v62
	v_fmac_f32_e32 v167, v215, v63
	v_fmac_f32_e32 v168, v216, v64
	v_fmac_f32_e32 v169, v217, v65
	v_fmac_f32_e32 v170, v218, v66
	v_fmac_f32_e32 v171, v219, v67
	v_fmac_f32_e32 v172, v220, v68
	v_fmac_f32_e32 v173, v221, v69
	v_fmac_f32_e32 v174, v222, v70
	v_fmac_f32_e32 v175, v223, v71
; DI unsigned pk_bf16(float a, float b) { f32x2_t v = {a, b}; bf16x2_t r = __builtin_convertvector(v, bf16x2_t); return __builtin_bit_cast(unsigned, r); }
; DI float shx(float v, int mask) { const int l = olane(); return __builtin_bit_cast(float, __builtin_amdgcn_ds_bpermute(((l ^ mask) & 63) << 2, __builtin_bit_cast(int, v))); }
; DI void row_phase(const bf16_t* msrc, const float* xsrc, float* xdst, const float* g_post, const float* g_next, bf16_t* hdst, const int gw) {
;     ...
;             for (int j = 0; j < 4; ++j) { const f32x4 g = *(const f32x4*)(g_post + lane * 4 + 256 * j);
; #pragma unroll
;                 for (int r = 0; r < RB; ++r) { const float r1 = rsqrtf(ss[r] * (1.f / DM) + EPS); xv[r][j] = xv[r][j] + mv[r][j] * r1 * g; *(f32x4*)(xdst + (size_t)(rowb + r) * DM + lane * 4 + 256 * j) = xv[r][j]; } }
;         }
;         if (hdst) {
;             float ss[RB];
; #pragma unroll
;             for (int r = 0; r < RB; ++r) { ss[r] = 0.f;
; #pragma unroll
;                 for (int j = 0; j < 4; ++j) ss[r] += xv[r][j][0] * xv[r][j][0] + xv[r][j][1] * xv[r][j][1] + xv[r][j][2] * xv[r][j][2] + xv[r][j][3] * xv[r][j][3]; }
; #pragma unroll
;             for (int o = 32; o >= 1; o >>= 1)
; #pragma unroll
;                 for (int r = 0; r < RB; ++r) ss[r] += shx(ss[r], o);
; #pragma unroll
;             for (int j = 0; j < 4; ++j) { const f32x4 g = *(const f32x4*)(g_next + lane * 4 + 256 * j);
; #pragma unroll
;                 for (int r = 0; r < RB; ++r) { const float r2 = rsqrtf(ss[r] * (1.f / DM) + EPS); const f32x4 hv = xv[r][j] * r2 * g;
;                     u32x2 o; o[0] = pk_bf16(hv[0], hv[1]); o[1] = pk_bf16(hv[2], hv[3]); *(u32x2*)(hdst + (size_t)(rowb + r) * DM + lane * 4 + 256 * j) = o; } }
	global_store_dwordx4 v1, v[160:163], s[8:9] offset:0
	global_store_dwordx4 v1, v[164:167], s[8:9] offset:16
	global_store_dwordx4 v1, v[168:171], s[8:9] offset:2048
	global_store_dwordx4 v1, v[172:175], s[8:9] offset:2064
	s_add_u32 s8, s8, 0x1000
	s_addc_u32 s9, s9, 0
	v_mul_f32_e32 v224, v160, v160
	v_fmac_f32_e32 v224, v161, v161
	v_fmac_f32_e32 v224, v162, v162
	v_fmac_f32_e32 v224, v163, v163
	v_fmac_f32_e32 v224, v164, v164
	v_fmac_f32_e32 v224, v165, v165
	v_fmac_f32_e32 v224, v166, v166
	v_fmac_f32_e32 v224, v167, v167
	v_fmac_f32_e32 v224, v168, v168
	v_fmac_f32_e32 v224, v169, v169
	v_fmac_f32_e32 v224, v170, v170
	v_fmac_f32_e32 v224, v171, v171
	v_fmac_f32_e32 v224, v172, v172
	v_fmac_f32_e32 v224, v173, v173
	v_fmac_f32_e32 v224, v174, v174
	v_fmac_f32_e32 v224, v175, v175
	s_nop 1
	v_add_f32_dpp v224, v224, v224 quad_perm:[1,0,3,2] row_mask:0xf bank_mask:0xf
	s_nop 1
	v_add_f32_dpp v224, v224, v224 quad_perm:[2,3,0,1] row_mask:0xf bank_mask:0xf
	s_nop 1
	v_add_f32_dpp v224, v224, v224 row_ror:4 row_mask:0xf bank_mask:0xf
	s_nop 1
	v_add_f32_dpp v224, v224, v224 row_ror:8 row_mask:0xf bank_mask:0xf
	s_nop 1
	v_readlane_b32 s20, v224, 0
	v_readlane_b32 s21, v224, 16
	v_readlane_b32 s22, v224, 32
	v_readlane_b32 s23, v224, 48
	s_nop 1
	v_mov_b32_e32 v225, s20
	v_add_f32_e32 v225, s21, v225
	v_add_f32_e32 v225, s22, v225
	v_add_f32_e32 v225, s23, v225
	v_mov_b32_e32 v226, 0x358637bd
	v_fmac_f32_e32 v226, 0x3a800000, v225
	v_rsq_f32_e32 v226, v226
	s_nop 0
	v_mul_f32_e32 v208, v160, v226
	v_mul_f32_e32 v209, v161, v226
	v_mul_f32_e32 v210, v162, v226
	v_mul_f32_e32 v211, v163, v226
	v_mul_f32_e32 v212, v164, v226
	v_mul_f32_e32 v213, v165, v226
	v_mul_f32_e32 v214, v166, v226
	v_mul_f32_e32 v215, v167, v226
	v_mul_f32_e32 v216, v168, v226
	v_mul_f32_e32 v217, v169, v226
	v_mul_f32_e32 v218, v170, v226
	v_mul_f32_e32 v219, v171, v226
	v_mul_f32_e32 v220, v172, v226
	v_mul_f32_e32 v221, v173, v226
	v_mul_f32_e32 v222, v174, v226
	v_mul_f32_e32 v223, v175, v226
	v_mul_f32_e32 v208, v208, v72
	v_mul_f32_e32 v209, v209, v73
	v_mul_f32_e32 v210, v210, v74
	v_mul_f32_e32 v211, v211, v75
	v_mul_f32_e32 v212, v212, v76
	v_mul_f32_e32 v213, v213, v77
	v_mul_f32_e32 v214, v214, v78
	v_mul_f32_e32 v215, v215, v79
	v_mul_f32_e32 v216, v216, v80
	v_mul_f32_e32 v217, v217, v81
	v_mul_f32_e32 v218, v218, v82
	v_mul_f32_e32 v219, v219, v83
	v_mul_f32_e32 v220, v220, v84
	v_mul_f32_e32 v221, v221, v85
	v_mul_f32_e32 v222, v222, v86
	v_mul_f32_e32 v223, v223, v87
	v_cvt_pk_bf16_f32 v176, v208, v209
	v_cvt_pk_bf16_f32 v177, v210, v211
	v_cvt_pk_bf16_f32 v178, v212, v213
	v_cvt_pk_bf16_f32 v179, v214, v215
	v_cvt_pk_bf16_f32 v180, v216, v217
	v_cvt_pk_bf16_f32 v181, v218, v219
	v_cvt_pk_bf16_f32 v182, v220, v221
	v_cvt_pk_bf16_f32 v183, v222, v223
	global_store_dwordx4 v2, v[176:179], s[14:15]
	global_store_dwordx4 v2, v[180:183], s[14:15] offset:1024
	s_add_u32 s14, s14, 0x800
	s_addc_u32 s15, s15, 0
	global_load_dwordx4 v[160:163], v1, s[6:7] offset:0
	global_load_dwordx4 v[164:167], v1, s[6:7] offset:16
	global_load_dwordx4 v[168:171], v1, s[6:7] offset:2048
	global_load_dwordx4 v[172:175], v1, s[6:7] offset:2064
	global_load_dwordx4 v[176:179], v2, s[10:11]
	global_load_dwordx4 v[180:183], v2, s[10:11] offset:1024
	global_load_dwordx4 v[184:187], v2, s[12:13]
	global_load_dwordx4 v[188:191], v2, s[12:13] offset:1024
	s_add_u32 s6, s6, 0x1000
	s_addc_u32 s7, s7, 0
	s_add_u32 s10, s10, 0x800
	s_addc_u32 s11, s11, 0
	s_add_u32 s12, s12, 0x800
	s_addc_u32 s13, s13, 0
	s_waitcnt vmcnt(28)
	v_lshlrev_b32_e32 v208, 16, v112
	v_and_b32_e32 v209, 0xffff0000, v112
	v_lshlrev_b32_e32 v210, 16, v113
	v_and_b32_e32 v211, 0xffff0000, v113
	v_lshlrev_b32_e32 v212, 16, v114
	v_and_b32_e32 v213, 0xffff0000, v114
	v_lshlrev_b32_e32 v214, 16, v115
	v_and_b32_e32 v215, 0xffff0000, v115
	v_lshlrev_b32_e32 v216, 16, v116
	v_and_b32_e32 v217, 0xffff0000, v116
	v_lshlrev_b32_e32 v218, 16, v117
	v_and_b32_e32 v219, 0xffff0000, v117
	v_lshlrev_b32_e32 v220, 16, v118
	v_and_b32_e32 v221, 0xffff0000, v118
	v_lshlrev_b32_e32 v222, 16, v119
	v_and_b32_e32 v223, 0xffff0000, v119
	v_mul_f32_e32 v224, v208, v208
	v_fmac_f32_e32 v224, v209, v209
	v_fmac_f32_e32 v224, v210, v210
	v_fmac_f32_e32 v224, v211, v211
	v_fmac_f32_e32 v224, v212, v212
	v_fmac_f32_e32 v224, v213, v213
	v_fmac_f32_e32 v224, v214, v214
	v_fmac_f32_e32 v224, v215, v215
	v_fmac_f32_e32 v224, v216, v216
	v_fmac_f32_e32 v224, v217, v217
	v_fmac_f32_e32 v224, v218, v218
	v_fmac_f32_e32 v224, v219, v219
	v_fmac_f32_e32 v224, v220, v220
	v_fmac_f32_e32 v224, v221, v221
	v_fmac_f32_e32 v224, v222, v222
	v_fmac_f32_e32 v224, v223, v223
	s_nop 1
	v_add_f32_dpp v224, v224, v224 quad_perm:[1,0,3,2] row_mask:0xf bank_mask:0xf
	s_nop 1
	v_add_f32_dpp v224, v224, v224 quad_perm:[2,3,0,1] row_mask:0xf bank_mask:0xf
	s_nop 1
	v_add_f32_dpp v224, v224, v224 row_ror:4 row_mask:0xf bank_mask:0xf
	s_nop 1
	v_add_f32_dpp v224, v224, v224 row_ror:8 row_mask:0xf bank_mask:0xf
	s_nop 1
	v_readlane_b32 s20, v224, 0
	v_readlane_b32 s21, v224, 16
	v_readlane_b32 s22, v224, 32
	v_readlane_b32 s23, v224, 48
	s_nop 1
	v_mov_b32_e32 v225, s20
	v_add_f32_e32 v225, s21, v225
	v_add_f32_e32 v225, s22, v225
	v_add_f32_e32 v225, s23, v225
	v_mov_b32_e32 v226, 0x358637bd
	v_fmac_f32_e32 v226, 0x3a800000, v225
	v_rsq_f32_e32 v226, v226
	s_nop 0
	v_mul_f32_e32 v208, v208, v226
	v_mul_f32_e32 v209, v209, v226
	v_mul_f32_e32 v210, v210, v226
	v_mul_f32_e32 v211, v211, v226
	v_mul_f32_e32 v212, v212, v226
	v_mul_f32_e32 v213, v213, v226
	v_mul_f32_e32 v214, v214, v226
	v_mul_f32_e32 v215, v215, v226
	v_mul_f32_e32 v216, v216, v226
; DI unsigned pk_bf16(float a, float b) { f32x2_t v = {a, b}; bf16x2_t r = __builtin_convertvector(v, bf16x2_t); return __builtin_bit_cast(unsigned, r); }
; DI void row_phase(const bf16_t* msrc, const float* xsrc, float* xdst, const float* g_post, const float* g_next, bf16_t* hdst, const int gw) {
;     ...
;                 for (int j = 0; j < 4; ++j) { const u32x2 mw = *(const u32x2*)(msrc + (size_t)(rowb + r) * DM + lane * 4 + 256 * j);
;                     mv[r][j] = (f32x4){__uint_as_float(mw[0] << 16), __uint_as_float(mw[0] & 0xffff0000u), __uint_as_float(mw[1] << 16), __uint_as_float(mw[1] & 0xffff0000u)}; }
;             float ss[RB];
; #pragma unroll
;             for (int r = 0; r < RB; ++r) { ss[r] = 0.f;
; #pragma unroll
;                 for (int j = 0; j < 4; ++j) ss[r] += mv[r][j][0] * mv[r][j][0] + mv[r][j][1] * mv[r][j][1] + mv[r][j][2] * mv[r][j][2] + mv[r][j][3] * mv[r][j][3]; }
; #pragma unroll
;             for (int o = 32; o >= 1; o >>= 1)
; #pragma unroll
;                 for (int r = 0; r < RB; ++r) ss[r] += shx(ss[r], o);
; #pragma unroll
;             for (int j = 0; j < 4; ++j) { const f32x4 g = *(const f32x4*)(g_post + lane * 4 + 256 * j);
; #pragma unroll
;                 for (int r = 0; r < RB; ++r) { const float r1 = rsqrtf(ss[r] * (1.f / DM) + EPS); xv[r][j] = xv[r][j] + mv[r][j] * r1 * g; *(f32x4*)(xdst + (size_t)(rowb + r) * DM + lane * 4 + 256 * j) = xv[r][j]; } }
;         }
;         if (hdst) {
;             float ss[RB];
; #pragma unroll
;             for (int r = 0; r < RB; ++r) { ss[r] = 0.f;
; #pragma unroll
;                 for (int j = 0; j < 4; ++j) ss[r] += xv[r][j][0] * xv[r][j][0] + xv[r][j][1] * xv[r][j][1] + xv[r][j][2] * xv[r][j][2] + xv[r][j][3] * xv[r][j][3]; }
; #pragma unroll
;             for (int o = 32; o >= 1; o >>= 1)
; #pragma unroll
;                 for (int r = 0; r < RB; ++r) ss[r] += shx(ss[r], o);
; #pragma unroll
;             for (int j = 0; j < 4; ++j) { const f32x4 g = *(const f32x4*)(g_next + lane * 4 + 256 * j);
; #pragma unroll
;                 for (int r = 0; r < RB; ++r) { const float r2 = rsqrtf(ss[r] * (1.f / DM) + EPS); const f32x4 hv = xv[r][j] * r2 * g;
;                     u32x2 o; o[0] = pk_bf16(hv[0], hv[1]); o[1] = pk_bf16(hv[2], hv[3]); *(u32x2*)(hdst + (size_t)(rowb + r) * DM + lane * 4 + 256 * j) = o; } }
	v_mul_f32_e32 v217, v217, v226
	v_mul_f32_e32 v218, v218, v226
	v_mul_f32_e32 v219, v219, v226
	v_mul_f32_e32 v220, v220, v226
	v_mul_f32_e32 v221, v221, v226
	v_mul_f32_e32 v222, v222, v226
	v_mul_f32_e32 v223, v223, v226
	v_fmac_f32_e32 v96, v208, v40
	v_fmac_f32_e32 v97, v209, v41
	v_fmac_f32_e32 v98, v210, v42
	v_fmac_f32_e32 v99, v211, v43
	v_fmac_f32_e32 v100, v212, v44
	v_fmac_f32_e32 v101, v213, v45
	v_fmac_f32_e32 v102, v214, v46
	v_fmac_f32_e32 v103, v215, v47
	v_fmac_f32_e32 v104, v216, v48
	v_fmac_f32_e32 v105, v217, v49
	v_fmac_f32_e32 v106, v218, v50
	v_fmac_f32_e32 v107, v219, v51
	v_fmac_f32_e32 v108, v220, v52
	v_fmac_f32_e32 v109, v221, v53
	v_fmac_f32_e32 v110, v222, v54
	v_fmac_f32_e32 v111, v223, v55
	v_lshlrev_b32_e32 v208, 16, v120
	v_and_b32_e32 v209, 0xffff0000, v120
	v_lshlrev_b32_e32 v210, 16, v121
	v_and_b32_e32 v211, 0xffff0000, v121
	v_lshlrev_b32_e32 v212, 16, v122
	v_and_b32_e32 v213, 0xffff0000, v122
	v_lshlrev_b32_e32 v214, 16, v123
	v_and_b32_e32 v215, 0xffff0000, v123
	v_lshlrev_b32_e32 v216, 16, v124
	v_and_b32_e32 v217, 0xffff0000, v124
	v_lshlrev_b32_e32 v218, 16, v125
	v_and_b32_e32 v219, 0xffff0000, v125
	v_lshlrev_b32_e32 v220, 16, v126
	v_and_b32_e32 v221, 0xffff0000, v126
	v_lshlrev_b32_e32 v222, 16, v127
	v_and_b32_e32 v223, 0xffff0000, v127
	v_mul_f32_e32 v224, v208, v208
	v_fmac_f32_e32 v224, v209, v209
	v_fmac_f32_e32 v224, v210, v210
	v_fmac_f32_e32 v224, v211, v211
	v_fmac_f32_e32 v224, v212, v212
	v_fmac_f32_e32 v224, v213, v213
	v_fmac_f32_e32 v224, v214, v214
	v_fmac_f32_e32 v224, v215, v215
	v_fmac_f32_e32 v224, v216, v216
	v_fmac_f32_e32 v224, v217, v217
	v_fmac_f32_e32 v224, v218, v218
	v_fmac_f32_e32 v224, v219, v219
	v_fmac_f32_e32 v224, v220, v220
	v_fmac_f32_e32 v224, v221, v221
	v_fmac_f32_e32 v224, v222, v222
	v_fmac_f32_e32 v224, v223, v223
	s_nop 1
	v_add_f32_dpp v224, v224, v224 quad_perm:[1,0,3,2] row_mask:0xf bank_mask:0xf
	s_nop 1
	v_add_f32_dpp v224, v224, v224 quad_perm:[2,3,0,1] row_mask:0xf bank_mask:0xf
	s_nop 1
	v_add_f32_dpp v224, v224, v224 row_ror:4 row_mask:0xf bank_mask:0xf
	s_nop 1
	v_add_f32_dpp v224, v224, v224 row_ror:8 row_mask:0xf bank_mask:0xf
	s_nop 1
	v_readlane_b32 s20, v224, 0
	v_readlane_b32 s21, v224, 16
	v_readlane_b32 s22, v224, 32
	v_readlane_b32 s23, v224, 48
	s_nop 1
	v_mov_b32_e32 v225, s20
	v_add_f32_e32 v225, s21, v225
	v_add_f32_e32 v225, s22, v225
	v_add_f32_e32 v225, s23, v225
	v_mov_b32_e32 v226, 0x358637bd
	v_fmac_f32_e32 v226, 0x3a800000, v225
	v_rsq_f32_e32 v226, v226
	s_nop 0
	v_mul_f32_e32 v208, v208, v226
	v_mul_f32_e32 v209, v209, v226
	v_mul_f32_e32 v210, v210, v226
	v_mul_f32_e32 v211, v211, v226
	v_mul_f32_e32 v212, v212, v226
	v_mul_f32_e32 v213, v213, v226
	v_mul_f32_e32 v214, v214, v226
	v_mul_f32_e32 v215, v215, v226
	v_mul_f32_e32 v216, v216, v226
	v_mul_f32_e32 v217, v217, v226
	v_mul_f32_e32 v218, v218, v226
	v_mul_f32_e32 v219, v219, v226
	v_mul_f32_e32 v220, v220, v226
	v_mul_f32_e32 v221, v221, v226
	v_mul_f32_e32 v222, v222, v226
	v_mul_f32_e32 v223, v223, v226
	v_fmac_f32_e32 v96, v208, v56
	v_fmac_f32_e32 v97, v209, v57
	v_fmac_f32_e32 v98, v210, v58
	v_fmac_f32_e32 v99, v211, v59
	v_fmac_f32_e32 v100, v212, v60
	v_fmac_f32_e32 v101, v213, v61
	v_fmac_f32_e32 v102, v214, v62
	v_fmac_f32_e32 v103, v215, v63
	v_fmac_f32_e32 v104, v216, v64
	v_fmac_f32_e32 v105, v217, v65
	v_fmac_f32_e32 v106, v218, v66
	v_fmac_f32_e32 v107, v219, v67
	v_fmac_f32_e32 v108, v220, v68
	v_fmac_f32_e32 v109, v221, v69
	v_fmac_f32_e32 v110, v222, v70
	v_fmac_f32_e32 v111, v223, v71
	global_store_dwordx4 v1, v[96:99], s[8:9] offset:0
	global_store_dwordx4 v1, v[100:103], s[8:9] offset:16
	global_store_dwordx4 v1, v[104:107], s[8:9] offset:2048
	global_store_dwordx4 v1, v[108:111], s[8:9] offset:2064
	s_add_u32 s8, s8, 0x1000
	s_addc_u32 s9, s9, 0
	v_mul_f32_e32 v224, v96, v96
	v_fmac_f32_e32 v224, v97, v97
	v_fmac_f32_e32 v224, v98, v98
	v_fmac_f32_e32 v224, v99, v99
	v_fmac_f32_e32 v224, v100, v100
	v_fmac_f32_e32 v224, v101, v101
	v_fmac_f32_e32 v224, v102, v102
	v_fmac_f32_e32 v224, v103, v103
	v_fmac_f32_e32 v224, v104, v104
	v_fmac_f32_e32 v224, v105, v105
	v_fmac_f32_e32 v224, v106, v106
	v_fmac_f32_e32 v224, v107, v107
	v_fmac_f32_e32 v224, v108, v108
	v_fmac_f32_e32 v224, v109, v109
	v_fmac_f32_e32 v224, v110, v110
	v_fmac_f32_e32 v224, v111, v111
	s_nop 1
	v_add_f32_dpp v224, v224, v224 quad_perm:[1,0,3,2] row_mask:0xf bank_mask:0xf
	s_nop 1
	v_add_f32_dpp v224, v224, v224 quad_perm:[2,3,0,1] row_mask:0xf bank_mask:0xf
	s_nop 1
	v_add_f32_dpp v224, v224, v224 row_ror:4 row_mask:0xf bank_mask:0xf
	s_nop 1
	v_add_f32_dpp v224, v224, v224 row_ror:8 row_mask:0xf bank_mask:0xf
	s_nop 1
	v_readlane_b32 s20, v224, 0
	v_readlane_b32 s21, v224, 16
	v_readlane_b32 s22, v224, 32
	v_readlane_b32 s23, v224, 48
	s_nop 1
	v_mov_b32_e32 v225, s20
	v_add_f32_e32 v225, s21, v225
	v_add_f32_e32 v225, s22, v225
	v_add_f32_e32 v225, s23, v225
	v_mov_b32_e32 v226, 0x358637bd
	v_fmac_f32_e32 v226, 0x3a800000, v225
	v_rsq_f32_e32 v226, v226
	s_nop 0
	v_mul_f32_e32 v208, v96, v226
	v_mul_f32_e32 v209, v97, v226
	v_mul_f32_e32 v210, v98, v226
	v_mul_f32_e32 v211, v99, v226
	v_mul_f32_e32 v212, v100, v226
	v_mul_f32_e32 v213, v101, v226
	v_mul_f32_e32 v214, v102, v226
	v_mul_f32_e32 v215, v103, v226
	v_mul_f32_e32 v216, v104, v226
	v_mul_f32_e32 v217, v105, v226
	v_mul_f32_e32 v218, v106, v226
	v_mul_f32_e32 v219, v107, v226
	v_mul_f32_e32 v220, v108, v226
	v_mul_f32_e32 v221, v109, v226
	v_mul_f32_e32 v222, v110, v226
	v_mul_f32_e32 v223, v111, v226
	v_mul_f32_e32 v208, v208, v72
	v_mul_f32_e32 v209, v209, v73
	v_mul_f32_e32 v210, v210, v74
; DI unsigned pk_bf16(float a, float b) { f32x2_t v = {a, b}; bf16x2_t r = __builtin_convertvector(v, bf16x2_t); return __builtin_bit_cast(unsigned, r); }
; DI float shx(float v, int mask) { const int l = olane(); return __builtin_bit_cast(float, __builtin_amdgcn_ds_bpermute(((l ^ mask) & 63) << 2, __builtin_bit_cast(int, v))); }
; DI void row_phase(const bf16_t* msrc, const float* xsrc, float* xdst, const float* g_post, const float* g_next, bf16_t* hdst, const int gw) {
;     ...
;             for (int j = 0; j < 4; ++j) { const f32x4 g = *(const f32x4*)(g_post + lane * 4 + 256 * j);
; #pragma unroll
;                 for (int r = 0; r < RB; ++r) { const float r1 = rsqrtf(ss[r] * (1.f / DM) + EPS); xv[r][j] = xv[r][j] + mv[r][j] * r1 * g; *(f32x4*)(xdst + (size_t)(rowb + r) * DM + lane * 4 + 256 * j) = xv[r][j]; } }
;         }
;         if (hdst) {
;             float ss[RB];
; #pragma unroll
;             for (int r = 0; r < RB; ++r) { ss[r] = 0.f;
; #pragma unroll
;                 for (int j = 0; j < 4; ++j) ss[r] += xv[r][j][0] * xv[r][j][0] + xv[r][j][1] * xv[r][j][1] + xv[r][j][2] * xv[r][j][2] + xv[r][j][3] * xv[r][j][3]; }
; #pragma unroll
;             for (int o = 32; o >= 1; o >>= 1)
; #pragma unroll
;                 for (int r = 0; r < RB; ++r) ss[r] += shx(ss[r], o);
; #pragma unroll
;             for (int j = 0; j < 4; ++j) { const f32x4 g = *(const f32x4*)(g_next + lane * 4 + 256 * j);
; #pragma unroll
;                 for (int r = 0; r < RB; ++r) { const float r2 = rsqrtf(ss[r] * (1.f / DM) + EPS); const f32x4 hv = xv[r][j] * r2 * g;
;                     u32x2 o; o[0] = pk_bf16(hv[0], hv[1]); o[1] = pk_bf16(hv[2], hv[3]); *(u32x2*)(hdst + (size_t)(rowb + r) * DM + lane * 4 + 256 * j) = o; } }
	v_mul_f32_e32 v211, v211, v75
	v_mul_f32_e32 v212, v212, v76
	v_mul_f32_e32 v213, v213, v77
	v_mul_f32_e32 v214, v214, v78
	v_mul_f32_e32 v215, v215, v79
	v_mul_f32_e32 v216, v216, v80
	v_mul_f32_e32 v217, v217, v81
	v_mul_f32_e32 v218, v218, v82
	v_mul_f32_e32 v219, v219, v83
	v_mul_f32_e32 v220, v220, v84
	v_mul_f32_e32 v221, v221, v85
	v_mul_f32_e32 v222, v222, v86
	v_mul_f32_e32 v223, v223, v87
	v_cvt_pk_bf16_f32 v112, v208, v209
	v_cvt_pk_bf16_f32 v113, v210, v211
	v_cvt_pk_bf16_f32 v114, v212, v213
	v_cvt_pk_bf16_f32 v115, v214, v215
	v_cvt_pk_bf16_f32 v116, v216, v217
	v_cvt_pk_bf16_f32 v117, v218, v219
	v_cvt_pk_bf16_f32 v118, v220, v221
	v_cvt_pk_bf16_f32 v119, v222, v223
	global_store_dwordx4 v2, v[112:115], s[14:15]
	global_store_dwordx4 v2, v[116:119], s[14:15] offset:1024
	s_add_u32 s14, s14, 0x800
	s_addc_u32 s15, s15, 0
	global_load_dwordx4 v[96:99], v1, s[6:7] offset:0
	global_load_dwordx4 v[100:103], v1, s[6:7] offset:16
	global_load_dwordx4 v[104:107], v1, s[6:7] offset:2048
	global_load_dwordx4 v[108:111], v1, s[6:7] offset:2064
	global_load_dwordx4 v[112:115], v2, s[10:11]
	global_load_dwordx4 v[116:119], v2, s[10:11] offset:1024
	global_load_dwordx4 v[120:123], v2, s[12:13]
	global_load_dwordx4 v[124:127], v2, s[12:13] offset:1024
	s_add_u32 s6, s6, 0x1000
	s_addc_u32 s7, s7, 0
	s_add_u32 s10, s10, 0x800
	s_addc_u32 s11, s11, 0
	s_add_u32 s12, s12, 0x800
	s_addc_u32 s13, s13, 0
	s_waitcnt vmcnt(28)
	v_lshlrev_b32_e32 v208, 16, v144
	v_and_b32_e32 v209, 0xffff0000, v144
	v_lshlrev_b32_e32 v210, 16, v145
	v_and_b32_e32 v211, 0xffff0000, v145
	v_lshlrev_b32_e32 v212, 16, v146
	v_and_b32_e32 v213, 0xffff0000, v146
	v_lshlrev_b32_e32 v214, 16, v147
	v_and_b32_e32 v215, 0xffff0000, v147
	v_lshlrev_b32_e32 v216, 16, v148
	v_and_b32_e32 v217, 0xffff0000, v148
	v_lshlrev_b32_e32 v218, 16, v149
	v_and_b32_e32 v219, 0xffff0000, v149
	v_lshlrev_b32_e32 v220, 16, v150
	v_and_b32_e32 v221, 0xffff0000, v150
	v_lshlrev_b32_e32 v222, 16, v151
	v_and_b32_e32 v223, 0xffff0000, v151
	v_mul_f32_e32 v224, v208, v208
	v_fmac_f32_e32 v224, v209, v209
	v_fmac_f32_e32 v224, v210, v210
	v_fmac_f32_e32 v224, v211, v211
	v_fmac_f32_e32 v224, v212, v212
	v_fmac_f32_e32 v224, v213, v213
	v_fmac_f32_e32 v224, v214, v214
	v_fmac_f32_e32 v224, v215, v215
	v_fmac_f32_e32 v224, v216, v216
	v_fmac_f32_e32 v224, v217, v217
	v_fmac_f32_e32 v224, v218, v218
	v_fmac_f32_e32 v224, v219, v219
	v_fmac_f32_e32 v224, v220, v220
	v_fmac_f32_e32 v224, v221, v221
	v_fmac_f32_e32 v224, v222, v222
	v_fmac_f32_e32 v224, v223, v223
	s_nop 1
	v_add_f32_dpp v224, v224, v224 quad_perm:[1,0,3,2] row_mask:0xf bank_mask:0xf
	s_nop 1
	v_add_f32_dpp v224, v224, v224 quad_perm:[2,3,0,1] row_mask:0xf bank_mask:0xf
	s_nop 1
	v_add_f32_dpp v224, v224, v224 row_ror:4 row_mask:0xf bank_mask:0xf
	s_nop 1
	v_add_f32_dpp v224, v224, v224 row_ror:8 row_mask:0xf bank_mask:0xf
	s_nop 1
	v_readlane_b32 s20, v224, 0
	v_readlane_b32 s21, v224, 16
	v_readlane_b32 s22, v224, 32
	v_readlane_b32 s23, v224, 48
	s_nop 1
	v_mov_b32_e32 v225, s20
	v_add_f32_e32 v225, s21, v225
	v_add_f32_e32 v225, s22, v225
	v_add_f32_e32 v225, s23, v225
	v_mov_b32_e32 v226, 0x358637bd
	v_fmac_f32_e32 v226, 0x3a800000, v225
	v_rsq_f32_e32 v226, v226
	s_nop 0
	v_mul_f32_e32 v208, v208, v226
	v_mul_f32_e32 v209, v209, v226
	v_mul_f32_e32 v210, v210, v226
	v_mul_f32_e32 v211, v211, v226
	v_mul_f32_e32 v212, v212, v226
	v_mul_f32_e32 v213, v213, v226
	v_mul_f32_e32 v214, v214, v226
	v_mul_f32_e32 v215, v215, v226
	v_mul_f32_e32 v216, v216, v226
	v_mul_f32_e32 v217, v217, v226
	v_mul_f32_e32 v218, v218, v226
	v_mul_f32_e32 v219, v219, v226
	v_mul_f32_e32 v220, v220, v226
	v_mul_f32_e32 v221, v221, v226
	v_mul_f32_e32 v222, v222, v226
	v_mul_f32_e32 v223, v223, v226
	v_fmac_f32_e32 v128, v208, v40
	v_fmac_f32_e32 v129, v209, v41
	v_fmac_f32_e32 v130, v210, v42
	v_fmac_f32_e32 v131, v211, v43
	v_fmac_f32_e32 v132, v212, v44
	v_fmac_f32_e32 v133, v213, v45
	v_fmac_f32_e32 v134, v214, v46
	v_fmac_f32_e32 v135, v215, v47
	v_fmac_f32_e32 v136, v216, v48
	v_fmac_f32_e32 v137, v217, v49
	v_fmac_f32_e32 v138, v218, v50
	v_fmac_f32_e32 v139, v219, v51
	v_fmac_f32_e32 v140, v220, v52
	v_fmac_f32_e32 v141, v221, v53
	v_fmac_f32_e32 v142, v222, v54
	v_fmac_f32_e32 v143, v223, v55
	v_lshlrev_b32_e32 v208, 16, v152
	v_and_b32_e32 v209, 0xffff0000, v152
	v_lshlrev_b32_e32 v210, 16, v153
	v_and_b32_e32 v211, 0xffff0000, v153
	v_lshlrev_b32_e32 v212, 16, v154
	v_and_b32_e32 v213, 0xffff0000, v154
	v_lshlrev_b32_e32 v214, 16, v155
	v_and_b32_e32 v215, 0xffff0000, v155
	v_lshlrev_b32_e32 v216, 16, v156
	v_and_b32_e32 v217, 0xffff0000, v156
	v_lshlrev_b32_e32 v218, 16, v157
	v_and_b32_e32 v219, 0xffff0000, v157
	v_lshlrev_b32_e32 v220, 16, v158
	v_and_b32_e32 v221, 0xffff0000, v158
	v_lshlrev_b32_e32 v222, 16, v159
	v_and_b32_e32 v223, 0xffff0000, v159
	v_mul_f32_e32 v224, v208, v208
	v_fmac_f32_e32 v224, v209, v209
	v_fmac_f32_e32 v224, v210, v210
	v_fmac_f32_e32 v224, v211, v211
	v_fmac_f32_e32 v224, v212, v212
	v_fmac_f32_e32 v224, v213, v213
	v_fmac_f32_e32 v224, v214, v214
	v_fmac_f32_e32 v224, v215, v215
	v_fmac_f32_e32 v224, v216, v216
	v_fmac_f32_e32 v224, v217, v217
	v_fmac_f32_e32 v224, v218, v218
	v_fmac_f32_e32 v224, v219, v219
	v_fmac_f32_e32 v224, v220, v220
	v_fmac_f32_e32 v224, v221, v221
	v_fmac_f32_e32 v224, v222, v222
	v_fmac_f32_e32 v224, v223, v223
	s_nop 1
	v_add_f32_dpp v224, v224, v224 quad_perm:[1,0,3,2] row_mask:0xf bank_mask:0xf
	s_nop 1
	v_add_f32_dpp v224, v224, v224 quad_perm:[2,3,0,1] row_mask:0xf bank_mask:0xf
	s_nop 1
	v_add_f32_dpp v224, v224, v224 row_ror:4 row_mask:0xf bank_mask:0xf
	s_nop 1
; DI unsigned pk_bf16(float a, float b) { f32x2_t v = {a, b}; bf16x2_t r = __builtin_convertvector(v, bf16x2_t); return __builtin_bit_cast(unsigned, r); }
; DI float shx(float v, int mask) { const int l = olane(); return __builtin_bit_cast(float, __builtin_amdgcn_ds_bpermute(((l ^ mask) & 63) << 2, __builtin_bit_cast(int, v))); }
; DI void row_phase(const bf16_t* msrc, const float* xsrc, float* xdst, const float* g_post, const float* g_next, bf16_t* hdst, const int gw) {
;     ...
;             for (int j = 0; j < 4; ++j) { const f32x4 g = *(const f32x4*)(g_post + lane * 4 + 256 * j);
; #pragma unroll
;                 for (int r = 0; r < RB; ++r) { const float r1 = rsqrtf(ss[r] * (1.f / DM) + EPS); xv[r][j] = xv[r][j] + mv[r][j] * r1 * g; *(f32x4*)(xdst + (size_t)(rowb + r) * DM + lane * 4 + 256 * j) = xv[r][j]; } }
;         }
;         if (hdst) {
;             float ss[RB];
; #pragma unroll
;             for (int r = 0; r < RB; ++r) { ss[r] = 0.f;
; #pragma unroll
;                 for (int j = 0; j < 4; ++j) ss[r] += xv[r][j][0] * xv[r][j][0] + xv[r][j][1] * xv[r][j][1] + xv[r][j][2] * xv[r][j][2] + xv[r][j][3] * xv[r][j][3]; }
; #pragma unroll
;             for (int o = 32; o >= 1; o >>= 1)
; #pragma unroll
;                 for (int r = 0; r < RB; ++r) ss[r] += shx(ss[r], o);
; #pragma unroll
;             for (int j = 0; j < 4; ++j) { const f32x4 g = *(const f32x4*)(g_next + lane * 4 + 256 * j);
; #pragma unroll
;                 for (int r = 0; r < RB; ++r) { const float r2 = rsqrtf(ss[r] * (1.f / DM) + EPS); const f32x4 hv = xv[r][j] * r2 * g;
;                     u32x2 o; o[0] = pk_bf16(hv[0], hv[1]); o[1] = pk_bf16(hv[2], hv[3]); *(u32x2*)(hdst + (size_t)(rowb + r) * DM + lane * 4 + 256 * j) = o; } }
	v_add_f32_dpp v224, v224, v224 row_ror:8 row_mask:0xf bank_mask:0xf
	s_nop 1
	v_readlane_b32 s20, v224, 0
	v_readlane_b32 s21, v224, 16
	v_readlane_b32 s22, v224, 32
	v_readlane_b32 s23, v224, 48
	s_nop 1
	v_mov_b32_e32 v225, s20
	v_add_f32_e32 v225, s21, v225
	v_add_f32_e32 v225, s22, v225
	v_add_f32_e32 v225, s23, v225
	v_mov_b32_e32 v226, 0x358637bd
	v_fmac_f32_e32 v226, 0x3a800000, v225
	v_rsq_f32_e32 v226, v226
	s_nop 0
	v_mul_f32_e32 v208, v208, v226
	v_mul_f32_e32 v209, v209, v226
	v_mul_f32_e32 v210, v210, v226
	v_mul_f32_e32 v211, v211, v226
	v_mul_f32_e32 v212, v212, v226
	v_mul_f32_e32 v213, v213, v226
	v_mul_f32_e32 v214, v214, v226
	v_mul_f32_e32 v215, v215, v226
	v_mul_f32_e32 v216, v216, v226
	v_mul_f32_e32 v217, v217, v226
	v_mul_f32_e32 v218, v218, v226
	v_mul_f32_e32 v219, v219, v226
	v_mul_f32_e32 v220, v220, v226
	v_mul_f32_e32 v221, v221, v226
	v_mul_f32_e32 v222, v222, v226
	v_mul_f32_e32 v223, v223, v226
	v_fmac_f32_e32 v128, v208, v56
	v_fmac_f32_e32 v129, v209, v57
	v_fmac_f32_e32 v130, v210, v58
	v_fmac_f32_e32 v131, v211, v59
	v_fmac_f32_e32 v132, v212, v60
	v_fmac_f32_e32 v133, v213, v61
	v_fmac_f32_e32 v134, v214, v62
	v_fmac_f32_e32 v135, v215, v63
	v_fmac_f32_e32 v136, v216, v64
	v_fmac_f32_e32 v137, v217, v65
	v_fmac_f32_e32 v138, v218, v66
	v_fmac_f32_e32 v139, v219, v67
	v_fmac_f32_e32 v140, v220, v68
	v_fmac_f32_e32 v141, v221, v69
	v_fmac_f32_e32 v142, v222, v70
	v_fmac_f32_e32 v143, v223, v71
	global_store_dwordx4 v1, v[128:131], s[8:9] offset:0
	global_store_dwordx4 v1, v[132:135], s[8:9] offset:16
	global_store_dwordx4 v1, v[136:139], s[8:9] offset:2048
	global_store_dwordx4 v1, v[140:143], s[8:9] offset:2064
	s_add_u32 s8, s8, 0x1000
	s_addc_u32 s9, s9, 0
	v_mul_f32_e32 v224, v128, v128
	v_fmac_f32_e32 v224, v129, v129
	v_fmac_f32_e32 v224, v130, v130
	v_fmac_f32_e32 v224, v131, v131
	v_fmac_f32_e32 v224, v132, v132
	v_fmac_f32_e32 v224, v133, v133
	v_fmac_f32_e32 v224, v134, v134
	v_fmac_f32_e32 v224, v135, v135
	v_fmac_f32_e32 v224, v136, v136
	v_fmac_f32_e32 v224, v137, v137
	v_fmac_f32_e32 v224, v138, v138
	v_fmac_f32_e32 v224, v139, v139
	v_fmac_f32_e32 v224, v140, v140
	v_fmac_f32_e32 v224, v141, v141
	v_fmac_f32_e32 v224, v142, v142
	v_fmac_f32_e32 v224, v143, v143
	s_nop 1
	v_add_f32_dpp v224, v224, v224 quad_perm:[1,0,3,2] row_mask:0xf bank_mask:0xf
	s_nop 1
	v_add_f32_dpp v224, v224, v224 quad_perm:[2,3,0,1] row_mask:0xf bank_mask:0xf
	s_nop 1
	v_add_f32_dpp v224, v224, v224 row_ror:4 row_mask:0xf bank_mask:0xf
	s_nop 1
	v_add_f32_dpp v224, v224, v224 row_ror:8 row_mask:0xf bank_mask:0xf
	s_nop 1
	v_readlane_b32 s20, v224, 0
	v_readlane_b32 s21, v224, 16
	v_readlane_b32 s22, v224, 32
	v_readlane_b32 s23, v224, 48
	s_nop 1
	v_mov_b32_e32 v225, s20
	v_add_f32_e32 v225, s21, v225
	v_add_f32_e32 v225, s22, v225
	v_add_f32_e32 v225, s23, v225
	v_mov_b32_e32 v226, 0x358637bd
	v_fmac_f32_e32 v226, 0x3a800000, v225
	v_rsq_f32_e32 v226, v226
	s_nop 0
	v_mul_f32_e32 v208, v128, v226
	v_mul_f32_e32 v209, v129, v226
	v_mul_f32_e32 v210, v130, v226
	v_mul_f32_e32 v211, v131, v226
	v_mul_f32_e32 v212, v132, v226
	v_mul_f32_e32 v213, v133, v226
	v_mul_f32_e32 v214, v134, v226
	v_mul_f32_e32 v215, v135, v226
	v_mul_f32_e32 v216, v136, v226
	v_mul_f32_e32 v217, v137, v226
	v_mul_f32_e32 v218, v138, v226
	v_mul_f32_e32 v219, v139, v226
	v_mul_f32_e32 v220, v140, v226
	v_mul_f32_e32 v221, v141, v226
	v_mul_f32_e32 v222, v142, v226
	v_mul_f32_e32 v223, v143, v226
	v_mul_f32_e32 v208, v208, v72
	v_mul_f32_e32 v209, v209, v73
	v_mul_f32_e32 v210, v210, v74
	v_mul_f32_e32 v211, v211, v75
	v_mul_f32_e32 v212, v212, v76
	v_mul_f32_e32 v213, v213, v77
	v_mul_f32_e32 v214, v214, v78
	v_mul_f32_e32 v215, v215, v79
	v_mul_f32_e32 v216, v216, v80
	v_mul_f32_e32 v217, v217, v81
	v_mul_f32_e32 v218, v218, v82
	v_mul_f32_e32 v219, v219, v83
	v_mul_f32_e32 v220, v220, v84
	v_mul_f32_e32 v221, v221, v85
	v_mul_f32_e32 v222, v222, v86
	v_mul_f32_e32 v223, v223, v87
	v_cvt_pk_bf16_f32 v144, v208, v209
	v_cvt_pk_bf16_f32 v145, v210, v211
	v_cvt_pk_bf16_f32 v146, v212, v213
	v_cvt_pk_bf16_f32 v147, v214, v215
	v_cvt_pk_bf16_f32 v148, v216, v217
	v_cvt_pk_bf16_f32 v149, v218, v219
	v_cvt_pk_bf16_f32 v150, v220, v221
	v_cvt_pk_bf16_f32 v151, v222, v223
	global_store_dwordx4 v2, v[144:147], s[14:15]
	global_store_dwordx4 v2, v[148:151], s[14:15] offset:1024
	s_add_u32 s14, s14, 0x800
	s_addc_u32 s15, s15, 0
	global_load_dwordx4 v[128:131], v1, s[6:7] offset:0
	global_load_dwordx4 v[132:135], v1, s[6:7] offset:16
	global_load_dwordx4 v[136:139], v1, s[6:7] offset:2048
	global_load_dwordx4 v[140:143], v1, s[6:7] offset:2064
	global_load_dwordx4 v[144:147], v2, s[10:11]
	global_load_dwordx4 v[148:151], v2, s[10:11] offset:1024
	global_load_dwordx4 v[152:155], v2, s[12:13]
	global_load_dwordx4 v[156:159], v2, s[12:13] offset:1024
	s_add_u32 s6, s6, 0x1000
	s_addc_u32 s7, s7, 0
	s_add_u32 s10, s10, 0x800
	s_addc_u32 s11, s11, 0
	s_add_u32 s12, s12, 0x800
	s_addc_u32 s13, s13, 0
	s_waitcnt vmcnt(28)
; DI float shx(float v, int mask) { const int l = olane(); return __builtin_bit_cast(float, __builtin_amdgcn_ds_bpermute(((l ^ mask) & 63) << 2, __builtin_bit_cast(int, v))); }
; DI void row_phase(const bf16_t* msrc, const float* xsrc, float* xdst, const float* g_post, const float* g_next, bf16_t* hdst, const int gw) {
;     ...
;                 for (int j = 0; j < 4; ++j) { const u32x2 mw = *(const u32x2*)(msrc + (size_t)(rowb + r) * DM + lane * 4 + 256 * j);
;                     mv[r][j] = (f32x4){__uint_as_float(mw[0] << 16), __uint_as_float(mw[0] & 0xffff0000u), __uint_as_float(mw[1] << 16), __uint_as_float(mw[1] & 0xffff0000u)}; }
;             float ss[RB];
; #pragma unroll
;             for (int r = 0; r < RB; ++r) { ss[r] = 0.f;
; #pragma unroll
;                 for (int j = 0; j < 4; ++j) ss[r] += mv[r][j][0] * mv[r][j][0] + mv[r][j][1] * mv[r][j][1] + mv[r][j][2] * mv[r][j][2] + mv[r][j][3] * mv[r][j][3]; }
; #pragma unroll
;             for (int o = 32; o >= 1; o >>= 1)
; #pragma unroll
;                 for (int r = 0; r < RB; ++r) ss[r] += shx(ss[r], o);
; #pragma unroll
;             for (int j = 0; j < 4; ++j) { const f32x4 g = *(const f32x4*)(g_post + lane * 4 + 256 * j);
; #pragma unroll
;                 for (int r = 0; r < RB; ++r) { const float r1 = rsqrtf(ss[r] * (1.f / DM) + EPS); xv[r][j] = xv[r][j] + mv[r][j] * r1 * g; *(f32x4*)(xdst + (size_t)(rowb + r) * DM + lane * 4 + 256 * j) = xv[r][j]; } }
	v_lshlrev_b32_e32 v208, 16, v176
	v_and_b32_e32 v209, 0xffff0000, v176
	v_lshlrev_b32_e32 v210, 16, v177
	v_and_b32_e32 v211, 0xffff0000, v177
	v_lshlrev_b32_e32 v212, 16, v178
	v_and_b32_e32 v213, 0xffff0000, v178
	v_lshlrev_b32_e32 v214, 16, v179
	v_and_b32_e32 v215, 0xffff0000, v179
	v_lshlrev_b32_e32 v216, 16, v180
	v_and_b32_e32 v217, 0xffff0000, v180
	v_lshlrev_b32_e32 v218, 16, v181
	v_and_b32_e32 v219, 0xffff0000, v181
	v_lshlrev_b32_e32 v220, 16, v182
	v_and_b32_e32 v221, 0xffff0000, v182
	v_lshlrev_b32_e32 v222, 16, v183
	v_and_b32_e32 v223, 0xffff0000, v183
	v_mul_f32_e32 v224, v208, v208
	v_fmac_f32_e32 v224, v209, v209
	v_fmac_f32_e32 v224, v210, v210
	v_fmac_f32_e32 v224, v211, v211
	v_fmac_f32_e32 v224, v212, v212
	v_fmac_f32_e32 v224, v213, v213
	v_fmac_f32_e32 v224, v214, v214
	v_fmac_f32_e32 v224, v215, v215
	v_fmac_f32_e32 v224, v216, v216
	v_fmac_f32_e32 v224, v217, v217
	v_fmac_f32_e32 v224, v218, v218
	v_fmac_f32_e32 v224, v219, v219
	v_fmac_f32_e32 v224, v220, v220
	v_fmac_f32_e32 v224, v221, v221
	v_fmac_f32_e32 v224, v222, v222
	v_fmac_f32_e32 v224, v223, v223
	s_nop 1
	v_add_f32_dpp v224, v224, v224 quad_perm:[1,0,3,2] row_mask:0xf bank_mask:0xf
	s_nop 1
	v_add_f32_dpp v224, v224, v224 quad_perm:[2,3,0,1] row_mask:0xf bank_mask:0xf
	s_nop 1
	v_add_f32_dpp v224, v224, v224 row_ror:4 row_mask:0xf bank_mask:0xf
	s_nop 1
	v_add_f32_dpp v224, v224, v224 row_ror:8 row_mask:0xf bank_mask:0xf
	s_nop 1
	v_readlane_b32 s20, v224, 0
	v_readlane_b32 s21, v224, 16
	v_readlane_b32 s22, v224, 32
	v_readlane_b32 s23, v224, 48
	s_nop 1
	v_mov_b32_e32 v225, s20
	v_add_f32_e32 v225, s21, v225
	v_add_f32_e32 v225, s22, v225
	v_add_f32_e32 v225, s23, v225
	v_mov_b32_e32 v226, 0x358637bd
	v_fmac_f32_e32 v226, 0x3a800000, v225
	v_rsq_f32_e32 v226, v226
	s_nop 0
	v_mul_f32_e32 v208, v208, v226
	v_mul_f32_e32 v209, v209, v226
	v_mul_f32_e32 v210, v210, v226
	v_mul_f32_e32 v211, v211, v226
	v_mul_f32_e32 v212, v212, v226
	v_mul_f32_e32 v213, v213, v226
	v_mul_f32_e32 v214, v214, v226
	v_mul_f32_e32 v215, v215, v226
	v_mul_f32_e32 v216, v216, v226
	v_mul_f32_e32 v217, v217, v226
	v_mul_f32_e32 v218, v218, v226
	v_mul_f32_e32 v219, v219, v226
	v_mul_f32_e32 v220, v220, v226
	v_mul_f32_e32 v221, v221, v226
	v_mul_f32_e32 v222, v222, v226
	v_mul_f32_e32 v223, v223, v226
	v_fmac_f32_e32 v160, v208, v40
	v_fmac_f32_e32 v161, v209, v41
	v_fmac_f32_e32 v162, v210, v42
	v_fmac_f32_e32 v163, v211, v43
	v_fmac_f32_e32 v164, v212, v44
	v_fmac_f32_e32 v165, v213, v45
	v_fmac_f32_e32 v166, v214, v46
	v_fmac_f32_e32 v167, v215, v47
	v_fmac_f32_e32 v168, v216, v48
	v_fmac_f32_e32 v169, v217, v49
	v_fmac_f32_e32 v170, v218, v50
	v_fmac_f32_e32 v171, v219, v51
	v_fmac_f32_e32 v172, v220, v52
	v_fmac_f32_e32 v173, v221, v53
	v_fmac_f32_e32 v174, v222, v54
	v_fmac_f32_e32 v175, v223, v55
	v_lshlrev_b32_e32 v208, 16, v184
	v_and_b32_e32 v209, 0xffff0000, v184
	v_lshlrev_b32_e32 v210, 16, v185
	v_and_b32_e32 v211, 0xffff0000, v185
	v_lshlrev_b32_e32 v212, 16, v186
	v_and_b32_e32 v213, 0xffff0000, v186
	v_lshlrev_b32_e32 v214, 16, v187
	v_and_b32_e32 v215, 0xffff0000, v187
	v_lshlrev_b32_e32 v216, 16, v188
	v_and_b32_e32 v217, 0xffff0000, v188
	v_lshlrev_b32_e32 v218, 16, v189
	v_and_b32_e32 v219, 0xffff0000, v189
	v_lshlrev_b32_e32 v220, 16, v190
	v_and_b32_e32 v221, 0xffff0000, v190
	v_lshlrev_b32_e32 v222, 16, v191
	v_and_b32_e32 v223, 0xffff0000, v191
	v_mul_f32_e32 v224, v208, v208
	v_fmac_f32_e32 v224, v209, v209
	v_fmac_f32_e32 v224, v210, v210
	v_fmac_f32_e32 v224, v211, v211
	v_fmac_f32_e32 v224, v212, v212
	v_fmac_f32_e32 v224, v213, v213
	v_fmac_f32_e32 v224, v214, v214
	v_fmac_f32_e32 v224, v215, v215
	v_fmac_f32_e32 v224, v216, v216
	v_fmac_f32_e32 v224, v217, v217
	v_fmac_f32_e32 v224, v218, v218
	v_fmac_f32_e32 v224, v219, v219
	v_fmac_f32_e32 v224, v220, v220
	v_fmac_f32_e32 v224, v221, v221
	v_fmac_f32_e32 v224, v222, v222
	v_fmac_f32_e32 v224, v223, v223
	s_nop 1
	v_add_f32_dpp v224, v224, v224 quad_perm:[1,0,3,2] row_mask:0xf bank_mask:0xf
	s_nop 1
	v_add_f32_dpp v224, v224, v224 quad_perm:[2,3,0,1] row_mask:0xf bank_mask:0xf
	s_nop 1
	v_add_f32_dpp v224, v224, v224 row_ror:4 row_mask:0xf bank_mask:0xf
	s_nop 1
	v_add_f32_dpp v224, v224, v224 row_ror:8 row_mask:0xf bank_mask:0xf
	s_nop 1
	v_readlane_b32 s20, v224, 0
	v_readlane_b32 s21, v224, 16
	v_readlane_b32 s22, v224, 32
	v_readlane_b32 s23, v224, 48
	s_nop 1
	v_mov_b32_e32 v225, s20
	v_add_f32_e32 v225, s21, v225
	v_add_f32_e32 v225, s22, v225
	v_add_f32_e32 v225, s23, v225
	v_mov_b32_e32 v226, 0x358637bd
	v_fmac_f32_e32 v226, 0x3a800000, v225
	v_rsq_f32_e32 v226, v226
	s_nop 0
	v_mul_f32_e32 v208, v208, v226
	v_mul_f32_e32 v209, v209, v226
	v_mul_f32_e32 v210, v210, v226
	v_mul_f32_e32 v211, v211, v226
	v_mul_f32_e32 v212, v212, v226
	v_mul_f32_e32 v213, v213, v226
	v_mul_f32_e32 v214, v214, v226
	v_mul_f32_e32 v215, v215, v226
	v_mul_f32_e32 v216, v216, v226
	v_mul_f32_e32 v217, v217, v226
	v_mul_f32_e32 v218, v218, v226
	v_mul_f32_e32 v219, v219, v226
	v_mul_f32_e32 v220, v220, v226
	v_mul_f32_e32 v221, v221, v226
	v_mul_f32_e32 v222, v222, v226
	v_mul_f32_e32 v223, v223, v226
	v_fmac_f32_e32 v160, v208, v56
	v_fmac_f32_e32 v161, v209, v57
	v_fmac_f32_e32 v162, v210, v58
	v_fmac_f32_e32 v163, v211, v59
	v_fmac_f32_e32 v164, v212, v60
	v_fmac_f32_e32 v165, v213, v61
	v_fmac_f32_e32 v166, v214, v62
	v_fmac_f32_e32 v167, v215, v63
	v_fmac_f32_e32 v168, v216, v64
	v_fmac_f32_e32 v169, v217, v65
	v_fmac_f32_e32 v170, v218, v66
	v_fmac_f32_e32 v171, v219, v67
	v_fmac_f32_e32 v172, v220, v68
	v_fmac_f32_e32 v173, v221, v69
	v_fmac_f32_e32 v174, v222, v70
	v_fmac_f32_e32 v175, v223, v71
; DI unsigned pk_bf16(float a, float b) { f32x2_t v = {a, b}; bf16x2_t r = __builtin_convertvector(v, bf16x2_t); return __builtin_bit_cast(unsigned, r); }
; DI float shx(float v, int mask) { const int l = olane(); return __builtin_bit_cast(float, __builtin_amdgcn_ds_bpermute(((l ^ mask) & 63) << 2, __builtin_bit_cast(int, v))); }
; DI void row_phase(const bf16_t* msrc, const float* xsrc, float* xdst, const float* g_post, const float* g_next, bf16_t* hdst, const int gw) {
;     ...
;             for (int j = 0; j < 4; ++j) { const f32x4 g = *(const f32x4*)(g_post + lane * 4 + 256 * j);
; #pragma unroll
;                 for (int r = 0; r < RB; ++r) { const float r1 = rsqrtf(ss[r] * (1.f / DM) + EPS); xv[r][j] = xv[r][j] + mv[r][j] * r1 * g; *(f32x4*)(xdst + (size_t)(rowb + r) * DM + lane * 4 + 256 * j) = xv[r][j]; } }
;         }
;         if (hdst) {
;             float ss[RB];
; #pragma unroll
;             for (int r = 0; r < RB; ++r) { ss[r] = 0.f;
; #pragma unroll
;                 for (int j = 0; j < 4; ++j) ss[r] += xv[r][j][0] * xv[r][j][0] + xv[r][j][1] * xv[r][j][1] + xv[r][j][2] * xv[r][j][2] + xv[r][j][3] * xv[r][j][3]; }
; #pragma unroll
;             for (int o = 32; o >= 1; o >>= 1)
; #pragma unroll
;                 for (int r = 0; r < RB; ++r) ss[r] += shx(ss[r], o);
; #pragma unroll
;             for (int j = 0; j < 4; ++j) { const f32x4 g = *(const f32x4*)(g_next + lane * 4 + 256 * j);
; #pragma unroll
;                 for (int r = 0; r < RB; ++r) { const float r2 = rsqrtf(ss[r] * (1.f / DM) + EPS); const f32x4 hv = xv[r][j] * r2 * g;
;                     u32x2 o; o[0] = pk_bf16(hv[0], hv[1]); o[1] = pk_bf16(hv[2], hv[3]); *(u32x2*)(hdst + (size_t)(rowb + r) * DM + lane * 4 + 256 * j) = o; } }
	global_store_dwordx4 v1, v[160:163], s[8:9] offset:0
	global_store_dwordx4 v1, v[164:167], s[8:9] offset:16
	global_store_dwordx4 v1, v[168:171], s[8:9] offset:2048
	global_store_dwordx4 v1, v[172:175], s[8:9] offset:2064
	s_add_u32 s8, s8, 0x1000
	s_addc_u32 s9, s9, 0
	v_mul_f32_e32 v224, v160, v160
	v_fmac_f32_e32 v224, v161, v161
	v_fmac_f32_e32 v224, v162, v162
	v_fmac_f32_e32 v224, v163, v163
	v_fmac_f32_e32 v224, v164, v164
	v_fmac_f32_e32 v224, v165, v165
	v_fmac_f32_e32 v224, v166, v166
	v_fmac_f32_e32 v224, v167, v167
	v_fmac_f32_e32 v224, v168, v168
	v_fmac_f32_e32 v224, v169, v169
	v_fmac_f32_e32 v224, v170, v170
	v_fmac_f32_e32 v224, v171, v171
	v_fmac_f32_e32 v224, v172, v172
	v_fmac_f32_e32 v224, v173, v173
	v_fmac_f32_e32 v224, v174, v174
	v_fmac_f32_e32 v224, v175, v175
	s_nop 1
	v_add_f32_dpp v224, v224, v224 quad_perm:[1,0,3,2] row_mask:0xf bank_mask:0xf
	s_nop 1
	v_add_f32_dpp v224, v224, v224 quad_perm:[2,3,0,1] row_mask:0xf bank_mask:0xf
	s_nop 1
	v_add_f32_dpp v224, v224, v224 row_ror:4 row_mask:0xf bank_mask:0xf
	s_nop 1
	v_add_f32_dpp v224, v224, v224 row_ror:8 row_mask:0xf bank_mask:0xf
	s_nop 1
	v_readlane_b32 s20, v224, 0
	v_readlane_b32 s21, v224, 16
	v_readlane_b32 s22, v224, 32
	v_readlane_b32 s23, v224, 48
	s_nop 1
	v_mov_b32_e32 v225, s20
	v_add_f32_e32 v225, s21, v225
	v_add_f32_e32 v225, s22, v225
	v_add_f32_e32 v225, s23, v225
	v_mov_b32_e32 v226, 0x358637bd
	v_fmac_f32_e32 v226, 0x3a800000, v225
	v_rsq_f32_e32 v226, v226
	s_nop 0
	v_mul_f32_e32 v208, v160, v226
	v_mul_f32_e32 v209, v161, v226
	v_mul_f32_e32 v210, v162, v226
	v_mul_f32_e32 v211, v163, v226
	v_mul_f32_e32 v212, v164, v226
	v_mul_f32_e32 v213, v165, v226
	v_mul_f32_e32 v214, v166, v226
	v_mul_f32_e32 v215, v167, v226
	v_mul_f32_e32 v216, v168, v226
	v_mul_f32_e32 v217, v169, v226
	v_mul_f32_e32 v218, v170, v226
	v_mul_f32_e32 v219, v171, v226
	v_mul_f32_e32 v220, v172, v226
	v_mul_f32_e32 v221, v173, v226
	v_mul_f32_e32 v222, v174, v226
	v_mul_f32_e32 v223, v175, v226
	v_mul_f32_e32 v208, v208, v72
	v_mul_f32_e32 v209, v209, v73
	v_mul_f32_e32 v210, v210, v74
	v_mul_f32_e32 v211, v211, v75
	v_mul_f32_e32 v212, v212, v76
	v_mul_f32_e32 v213, v213, v77
	v_mul_f32_e32 v214, v214, v78
	v_mul_f32_e32 v215, v215, v79
	v_mul_f32_e32 v216, v216, v80
	v_mul_f32_e32 v217, v217, v81
	v_mul_f32_e32 v218, v218, v82
	v_mul_f32_e32 v219, v219, v83
	v_mul_f32_e32 v220, v220, v84
	v_mul_f32_e32 v221, v221, v85
	v_mul_f32_e32 v222, v222, v86
	v_mul_f32_e32 v223, v223, v87
	v_cvt_pk_bf16_f32 v176, v208, v209
	v_cvt_pk_bf16_f32 v177, v210, v211
	v_cvt_pk_bf16_f32 v178, v212, v213
	v_cvt_pk_bf16_f32 v179, v214, v215
	v_cvt_pk_bf16_f32 v180, v216, v217
	v_cvt_pk_bf16_f32 v181, v218, v219
	v_cvt_pk_bf16_f32 v182, v220, v221
	v_cvt_pk_bf16_f32 v183, v222, v223
	global_store_dwordx4 v2, v[176:179], s[14:15]
	global_store_dwordx4 v2, v[180:183], s[14:15] offset:1024
	s_add_u32 s14, s14, 0x800
	s_addc_u32 s15, s15, 0
	s_waitcnt vmcnt(20)
	v_lshlrev_b32_e32 v208, 16, v112
	v_and_b32_e32 v209, 0xffff0000, v112
	v_lshlrev_b32_e32 v210, 16, v113
	v_and_b32_e32 v211, 0xffff0000, v113
	v_lshlrev_b32_e32 v212, 16, v114
	v_and_b32_e32 v213, 0xffff0000, v114
	v_lshlrev_b32_e32 v214, 16, v115
	v_and_b32_e32 v215, 0xffff0000, v115
	v_lshlrev_b32_e32 v216, 16, v116
	v_and_b32_e32 v217, 0xffff0000, v116
	v_lshlrev_b32_e32 v218, 16, v117
	v_and_b32_e32 v219, 0xffff0000, v117
	v_lshlrev_b32_e32 v220, 16, v118
	v_and_b32_e32 v221, 0xffff0000, v118
	v_lshlrev_b32_e32 v222, 16, v119
	v_and_b32_e32 v223, 0xffff0000, v119
	v_mul_f32_e32 v224, v208, v208
	v_fmac_f32_e32 v224, v209, v209
	v_fmac_f32_e32 v224, v210, v210
	v_fmac_f32_e32 v224, v211, v211
	v_fmac_f32_e32 v224, v212, v212
	v_fmac_f32_e32 v224, v213, v213
	v_fmac_f32_e32 v224, v214, v214
	v_fmac_f32_e32 v224, v215, v215
	v_fmac_f32_e32 v224, v216, v216
	v_fmac_f32_e32 v224, v217, v217
	v_fmac_f32_e32 v224, v218, v218
	v_fmac_f32_e32 v224, v219, v219
	v_fmac_f32_e32 v224, v220, v220
	v_fmac_f32_e32 v224, v221, v221
	v_fmac_f32_e32 v224, v222, v222
	v_fmac_f32_e32 v224, v223, v223
	s_nop 1
	v_add_f32_dpp v224, v224, v224 quad_perm:[1,0,3,2] row_mask:0xf bank_mask:0xf
	s_nop 1
	v_add_f32_dpp v224, v224, v224 quad_perm:[2,3,0,1] row_mask:0xf bank_mask:0xf
	s_nop 1
	v_add_f32_dpp v224, v224, v224 row_ror:4 row_mask:0xf bank_mask:0xf
	s_nop 1
	v_add_f32_dpp v224, v224, v224 row_ror:8 row_mask:0xf bank_mask:0xf
	s_nop 1
	v_readlane_b32 s20, v224, 0
	v_readlane_b32 s21, v224, 16
	v_readlane_b32 s22, v224, 32
	v_readlane_b32 s23, v224, 48
	s_nop 1
	v_mov_b32_e32 v225, s20
	v_add_f32_e32 v225, s21, v225
	v_add_f32_e32 v225, s22, v225
	v_add_f32_e32 v225, s23, v225
	v_mov_b32_e32 v226, 0x358637bd
	v_fmac_f32_e32 v226, 0x3a800000, v225
	v_rsq_f32_e32 v226, v226
	s_nop 0
	v_mul_f32_e32 v208, v208, v226
	v_mul_f32_e32 v209, v209, v226
	v_mul_f32_e32 v210, v210, v226
	v_mul_f32_e32 v211, v211, v226
	v_mul_f32_e32 v212, v212, v226
	v_mul_f32_e32 v213, v213, v226
	v_mul_f32_e32 v214, v214, v226
	v_mul_f32_e32 v215, v215, v226
	v_mul_f32_e32 v216, v216, v226
	v_mul_f32_e32 v217, v217, v226
	v_mul_f32_e32 v218, v218, v226
	v_mul_f32_e32 v219, v219, v226
	v_mul_f32_e32 v220, v220, v226
	v_mul_f32_e32 v221, v221, v226
	v_mul_f32_e32 v222, v222, v226
	v_mul_f32_e32 v223, v223, v226
	v_fmac_f32_e32 v96, v208, v40
	v_fmac_f32_e32 v97, v209, v41
	v_fmac_f32_e32 v98, v210, v42
	v_fmac_f32_e32 v99, v211, v43
	v_fmac_f32_e32 v100, v212, v44
	v_fmac_f32_e32 v101, v213, v45
	v_fmac_f32_e32 v102, v214, v46
	v_fmac_f32_e32 v103, v215, v47
	v_fmac_f32_e32 v104, v216, v48
	v_fmac_f32_e32 v105, v217, v49
	v_fmac_f32_e32 v106, v218, v50
	v_fmac_f32_e32 v107, v219, v51
; DI unsigned pk_bf16(float a, float b) { f32x2_t v = {a, b}; bf16x2_t r = __builtin_convertvector(v, bf16x2_t); return __builtin_bit_cast(unsigned, r); }
; DI void row_phase(const bf16_t* msrc, const float* xsrc, float* xdst, const float* g_post, const float* g_next, bf16_t* hdst, const int gw) {
;     ...
;                 for (int j = 0; j < 4; ++j) { const u32x2 mw = *(const u32x2*)(msrc + (size_t)(rowb + r) * DM + lane * 4 + 256 * j);
;                     mv[r][j] = (f32x4){__uint_as_float(mw[0] << 16), __uint_as_float(mw[0] & 0xffff0000u), __uint_as_float(mw[1] << 16), __uint_as_float(mw[1] & 0xffff0000u)}; }
;             float ss[RB];
; #pragma unroll
;             for (int r = 0; r < RB; ++r) { ss[r] = 0.f;
; #pragma unroll
;                 for (int j = 0; j < 4; ++j) ss[r] += mv[r][j][0] * mv[r][j][0] + mv[r][j][1] * mv[r][j][1] + mv[r][j][2] * mv[r][j][2] + mv[r][j][3] * mv[r][j][3]; }
; #pragma unroll
;             for (int o = 32; o >= 1; o >>= 1)
; #pragma unroll
;                 for (int r = 0; r < RB; ++r) ss[r] += shx(ss[r], o);
; #pragma unroll
;             for (int j = 0; j < 4; ++j) { const f32x4 g = *(const f32x4*)(g_post + lane * 4 + 256 * j);
; #pragma unroll
;                 for (int r = 0; r < RB; ++r) { const float r1 = rsqrtf(ss[r] * (1.f / DM) + EPS); xv[r][j] = xv[r][j] + mv[r][j] * r1 * g; *(f32x4*)(xdst + (size_t)(rowb + r) * DM + lane * 4 + 256 * j) = xv[r][j]; } }
;         }
;         if (hdst) {
;             float ss[RB];
; #pragma unroll
;             for (int r = 0; r < RB; ++r) { ss[r] = 0.f;
; #pragma unroll
;                 for (int j = 0; j < 4; ++j) ss[r] += xv[r][j][0] * xv[r][j][0] + xv[r][j][1] * xv[r][j][1] + xv[r][j][2] * xv[r][j][2] + xv[r][j][3] * xv[r][j][3]; }
; #pragma unroll
;             for (int o = 32; o >= 1; o >>= 1)
; #pragma unroll
;                 for (int r = 0; r < RB; ++r) ss[r] += shx(ss[r], o);
; #pragma unroll
;             for (int j = 0; j < 4; ++j) { const f32x4 g = *(const f32x4*)(g_next + lane * 4 + 256 * j);
; #pragma unroll
;                 for (int r = 0; r < RB; ++r) { const float r2 = rsqrtf(ss[r] * (1.f / DM) + EPS); const f32x4 hv = xv[r][j] * r2 * g;
;                     u32x2 o; o[0] = pk_bf16(hv[0], hv[1]); o[1] = pk_bf16(hv[2], hv[3]); *(u32x2*)(hdst + (size_t)(rowb + r) * DM + lane * 4 + 256 * j) = o; } }
	v_fmac_f32_e32 v108, v220, v52
	v_fmac_f32_e32 v109, v221, v53
	v_fmac_f32_e32 v110, v222, v54
	v_fmac_f32_e32 v111, v223, v55
	v_lshlrev_b32_e32 v208, 16, v120
	v_and_b32_e32 v209, 0xffff0000, v120
	v_lshlrev_b32_e32 v210, 16, v121
	v_and_b32_e32 v211, 0xffff0000, v121
	v_lshlrev_b32_e32 v212, 16, v122
	v_and_b32_e32 v213, 0xffff0000, v122
	v_lshlrev_b32_e32 v214, 16, v123
	v_and_b32_e32 v215, 0xffff0000, v123
	v_lshlrev_b32_e32 v216, 16, v124
	v_and_b32_e32 v217, 0xffff0000, v124
	v_lshlrev_b32_e32 v218, 16, v125
	v_and_b32_e32 v219, 0xffff0000, v125
	v_lshlrev_b32_e32 v220, 16, v126
	v_and_b32_e32 v221, 0xffff0000, v126
	v_lshlrev_b32_e32 v222, 16, v127
	v_and_b32_e32 v223, 0xffff0000, v127
	v_mul_f32_e32 v224, v208, v208
	v_fmac_f32_e32 v224, v209, v209
	v_fmac_f32_e32 v224, v210, v210
	v_fmac_f32_e32 v224, v211, v211
	v_fmac_f32_e32 v224, v212, v212
	v_fmac_f32_e32 v224, v213, v213
	v_fmac_f32_e32 v224, v214, v214
	v_fmac_f32_e32 v224, v215, v215
	v_fmac_f32_e32 v224, v216, v216
	v_fmac_f32_e32 v224, v217, v217
	v_fmac_f32_e32 v224, v218, v218
	v_fmac_f32_e32 v224, v219, v219
	v_fmac_f32_e32 v224, v220, v220
	v_fmac_f32_e32 v224, v221, v221
	v_fmac_f32_e32 v224, v222, v222
	v_fmac_f32_e32 v224, v223, v223
	s_nop 1
	v_add_f32_dpp v224, v224, v224 quad_perm:[1,0,3,2] row_mask:0xf bank_mask:0xf
	s_nop 1
	v_add_f32_dpp v224, v224, v224 quad_perm:[2,3,0,1] row_mask:0xf bank_mask:0xf
	s_nop 1
	v_add_f32_dpp v224, v224, v224 row_ror:4 row_mask:0xf bank_mask:0xf
	s_nop 1
	v_add_f32_dpp v224, v224, v224 row_ror:8 row_mask:0xf bank_mask:0xf
	s_nop 1
	v_readlane_b32 s20, v224, 0
	v_readlane_b32 s21, v224, 16
	v_readlane_b32 s22, v224, 32
	v_readlane_b32 s23, v224, 48
	s_nop 1
	v_mov_b32_e32 v225, s20
	v_add_f32_e32 v225, s21, v225
	v_add_f32_e32 v225, s22, v225
	v_add_f32_e32 v225, s23, v225
	v_mov_b32_e32 v226, 0x358637bd
	v_fmac_f32_e32 v226, 0x3a800000, v225
	v_rsq_f32_e32 v226, v226
	s_nop 0
	v_mul_f32_e32 v208, v208, v226
	v_mul_f32_e32 v209, v209, v226
	v_mul_f32_e32 v210, v210, v226
	v_mul_f32_e32 v211, v211, v226
	v_mul_f32_e32 v212, v212, v226
	v_mul_f32_e32 v213, v213, v226
	v_mul_f32_e32 v214, v214, v226
	v_mul_f32_e32 v215, v215, v226
	v_mul_f32_e32 v216, v216, v226
	v_mul_f32_e32 v217, v217, v226
	v_mul_f32_e32 v218, v218, v226
	v_mul_f32_e32 v219, v219, v226
	v_mul_f32_e32 v220, v220, v226
	v_mul_f32_e32 v221, v221, v226
	v_mul_f32_e32 v222, v222, v226
	v_mul_f32_e32 v223, v223, v226
	v_fmac_f32_e32 v96, v208, v56
	v_fmac_f32_e32 v97, v209, v57
	v_fmac_f32_e32 v98, v210, v58
	v_fmac_f32_e32 v99, v211, v59
	v_fmac_f32_e32 v100, v212, v60
	v_fmac_f32_e32 v101, v213, v61
	v_fmac_f32_e32 v102, v214, v62
	v_fmac_f32_e32 v103, v215, v63
	v_fmac_f32_e32 v104, v216, v64
	v_fmac_f32_e32 v105, v217, v65
	v_fmac_f32_e32 v106, v218, v66
	v_fmac_f32_e32 v107, v219, v67
	v_fmac_f32_e32 v108, v220, v68
	v_fmac_f32_e32 v109, v221, v69
	v_fmac_f32_e32 v110, v222, v70
	v_fmac_f32_e32 v111, v223, v71
	global_store_dwordx4 v1, v[96:99], s[8:9] offset:0
	global_store_dwordx4 v1, v[100:103], s[8:9] offset:16
	global_store_dwordx4 v1, v[104:107], s[8:9] offset:2048
	global_store_dwordx4 v1, v[108:111], s[8:9] offset:2064
	s_add_u32 s8, s8, 0x1000
	s_addc_u32 s9, s9, 0
	v_mul_f32_e32 v224, v96, v96
	v_fmac_f32_e32 v224, v97, v97
	v_fmac_f32_e32 v224, v98, v98
	v_fmac_f32_e32 v224, v99, v99
	v_fmac_f32_e32 v224, v100, v100
	v_fmac_f32_e32 v224, v101, v101
	v_fmac_f32_e32 v224, v102, v102
	v_fmac_f32_e32 v224, v103, v103
	v_fmac_f32_e32 v224, v104, v104
	v_fmac_f32_e32 v224, v105, v105
	v_fmac_f32_e32 v224, v106, v106
	v_fmac_f32_e32 v224, v107, v107
	v_fmac_f32_e32 v224, v108, v108
	v_fmac_f32_e32 v224, v109, v109
	v_fmac_f32_e32 v224, v110, v110
	v_fmac_f32_e32 v224, v111, v111
	s_nop 1
	v_add_f32_dpp v224, v224, v224 quad_perm:[1,0,3,2] row_mask:0xf bank_mask:0xf
	s_nop 1
	v_add_f32_dpp v224, v224, v224 quad_perm:[2,3,0,1] row_mask:0xf bank_mask:0xf
	s_nop 1
	v_add_f32_dpp v224, v224, v224 row_ror:4 row_mask:0xf bank_mask:0xf
	s_nop 1
	v_add_f32_dpp v224, v224, v224 row_ror:8 row_mask:0xf bank_mask:0xf
	s_nop 1
	v_readlane_b32 s20, v224, 0
	v_readlane_b32 s21, v224, 16
	v_readlane_b32 s22, v224, 32
	v_readlane_b32 s23, v224, 48
	s_nop 1
	v_mov_b32_e32 v225, s20
	v_add_f32_e32 v225, s21, v225
	v_add_f32_e32 v225, s22, v225
	v_add_f32_e32 v225, s23, v225
	v_mov_b32_e32 v226, 0x358637bd
	v_fmac_f32_e32 v226, 0x3a800000, v225
	v_rsq_f32_e32 v226, v226
	s_nop 0
	v_mul_f32_e32 v208, v96, v226
	v_mul_f32_e32 v209, v97, v226
	v_mul_f32_e32 v210, v98, v226
	v_mul_f32_e32 v211, v99, v226
	v_mul_f32_e32 v212, v100, v226
	v_mul_f32_e32 v213, v101, v226
	v_mul_f32_e32 v214, v102, v226
	v_mul_f32_e32 v215, v103, v226
	v_mul_f32_e32 v216, v104, v226
	v_mul_f32_e32 v217, v105, v226
	v_mul_f32_e32 v218, v106, v226
	v_mul_f32_e32 v219, v107, v226
	v_mul_f32_e32 v220, v108, v226
	v_mul_f32_e32 v221, v109, v226
	v_mul_f32_e32 v222, v110, v226
	v_mul_f32_e32 v223, v111, v226
	v_mul_f32_e32 v208, v208, v72
	v_mul_f32_e32 v209, v209, v73
	v_mul_f32_e32 v210, v210, v74
	v_mul_f32_e32 v211, v211, v75
	v_mul_f32_e32 v212, v212, v76
	v_mul_f32_e32 v213, v213, v77
	v_mul_f32_e32 v214, v214, v78
	v_mul_f32_e32 v215, v215, v79
	v_mul_f32_e32 v216, v216, v80
	v_mul_f32_e32 v217, v217, v81
	v_mul_f32_e32 v218, v218, v82
	v_mul_f32_e32 v219, v219, v83
	v_mul_f32_e32 v220, v220, v84
	v_mul_f32_e32 v221, v221, v85
	v_mul_f32_e32 v222, v222, v86
	v_mul_f32_e32 v223, v223, v87
	v_cvt_pk_bf16_f32 v112, v208, v209
	v_cvt_pk_bf16_f32 v113, v210, v211
	v_cvt_pk_bf16_f32 v114, v212, v213
	v_cvt_pk_bf16_f32 v115, v214, v215
	v_cvt_pk_bf16_f32 v116, v216, v217
	v_cvt_pk_bf16_f32 v117, v218, v219
	v_cvt_pk_bf16_f32 v118, v220, v221
	v_cvt_pk_bf16_f32 v119, v222, v223
	global_store_dwordx4 v2, v[112:115], s[14:15]
	global_store_dwordx4 v2, v[116:119], s[14:15] offset:1024
	s_add_u32 s14, s14, 0x800
	s_addc_u32 s15, s15, 0
	s_waitcnt vmcnt(12)
; DI float shx(float v, int mask) { const int l = olane(); return __builtin_bit_cast(float, __builtin_amdgcn_ds_bpermute(((l ^ mask) & 63) << 2, __builtin_bit_cast(int, v))); }
; DI void row_phase(const bf16_t* msrc, const float* xsrc, float* xdst, const float* g_post, const float* g_next, bf16_t* hdst, const int gw) {
;     ...
;                 for (int j = 0; j < 4; ++j) { const u32x2 mw = *(const u32x2*)(msrc + (size_t)(rowb + r) * DM + lane * 4 + 256 * j);
;                     mv[r][j] = (f32x4){__uint_as_float(mw[0] << 16), __uint_as_float(mw[0] & 0xffff0000u), __uint_as_float(mw[1] << 16), __uint_as_float(mw[1] & 0xffff0000u)}; }
;             float ss[RB];
; #pragma unroll
;             for (int r = 0; r < RB; ++r) { ss[r] = 0.f;
; #pragma unroll
;                 for (int j = 0; j < 4; ++j) ss[r] += mv[r][j][0] * mv[r][j][0] + mv[r][j][1] * mv[r][j][1] + mv[r][j][2] * mv[r][j][2] + mv[r][j][3] * mv[r][j][3]; }
; #pragma unroll
;             for (int o = 32; o >= 1; o >>= 1)
; #pragma unroll
;                 for (int r = 0; r < RB; ++r) ss[r] += shx(ss[r], o);
; #pragma unroll
;             for (int j = 0; j < 4; ++j) { const f32x4 g = *(const f32x4*)(g_post + lane * 4 + 256 * j);
; #pragma unroll
;                 for (int r = 0; r < RB; ++r) { const float r1 = rsqrtf(ss[r] * (1.f / DM) + EPS); xv[r][j] = xv[r][j] + mv[r][j] * r1 * g; *(f32x4*)(xdst + (size_t)(rowb + r) * DM + lane * 4 + 256 * j) = xv[r][j]; } }
	v_lshlrev_b32_e32 v208, 16, v144
	v_and_b32_e32 v209, 0xffff0000, v144
	v_lshlrev_b32_e32 v210, 16, v145
	v_and_b32_e32 v211, 0xffff0000, v145
	v_lshlrev_b32_e32 v212, 16, v146
	v_and_b32_e32 v213, 0xffff0000, v146
	v_lshlrev_b32_e32 v214, 16, v147
	v_and_b32_e32 v215, 0xffff0000, v147
	v_lshlrev_b32_e32 v216, 16, v148
	v_and_b32_e32 v217, 0xffff0000, v148
	v_lshlrev_b32_e32 v218, 16, v149
	v_and_b32_e32 v219, 0xffff0000, v149
	v_lshlrev_b32_e32 v220, 16, v150
	v_and_b32_e32 v221, 0xffff0000, v150
	v_lshlrev_b32_e32 v222, 16, v151
	v_and_b32_e32 v223, 0xffff0000, v151
	v_mul_f32_e32 v224, v208, v208
	v_fmac_f32_e32 v224, v209, v209
	v_fmac_f32_e32 v224, v210, v210
	v_fmac_f32_e32 v224, v211, v211
	v_fmac_f32_e32 v224, v212, v212
	v_fmac_f32_e32 v224, v213, v213
	v_fmac_f32_e32 v224, v214, v214
	v_fmac_f32_e32 v224, v215, v215
	v_fmac_f32_e32 v224, v216, v216
	v_fmac_f32_e32 v224, v217, v217
	v_fmac_f32_e32 v224, v218, v218
	v_fmac_f32_e32 v224, v219, v219
	v_fmac_f32_e32 v224, v220, v220
	v_fmac_f32_e32 v224, v221, v221
	v_fmac_f32_e32 v224, v222, v222
	v_fmac_f32_e32 v224, v223, v223
	s_nop 1
	v_add_f32_dpp v224, v224, v224 quad_perm:[1,0,3,2] row_mask:0xf bank_mask:0xf
	s_nop 1
	v_add_f32_dpp v224, v224, v224 quad_perm:[2,3,0,1] row_mask:0xf bank_mask:0xf
	s_nop 1
	v_add_f32_dpp v224, v224, v224 row_ror:4 row_mask:0xf bank_mask:0xf
	s_nop 1
	v_add_f32_dpp v224, v224, v224 row_ror:8 row_mask:0xf bank_mask:0xf
	s_nop 1
	v_readlane_b32 s20, v224, 0
	v_readlane_b32 s21, v224, 16
	v_readlane_b32 s22, v224, 32
	v_readlane_b32 s23, v224, 48
	s_nop 1
	v_mov_b32_e32 v225, s20
	v_add_f32_e32 v225, s21, v225
	v_add_f32_e32 v225, s22, v225
	v_add_f32_e32 v225, s23, v225
	v_mov_b32_e32 v226, 0x358637bd
	v_fmac_f32_e32 v226, 0x3a800000, v225
	v_rsq_f32_e32 v226, v226
	s_nop 0
	v_mul_f32_e32 v208, v208, v226
	v_mul_f32_e32 v209, v209, v226
	v_mul_f32_e32 v210, v210, v226
	v_mul_f32_e32 v211, v211, v226
	v_mul_f32_e32 v212, v212, v226
	v_mul_f32_e32 v213, v213, v226
	v_mul_f32_e32 v214, v214, v226
	v_mul_f32_e32 v215, v215, v226
	v_mul_f32_e32 v216, v216, v226
	v_mul_f32_e32 v217, v217, v226
	v_mul_f32_e32 v218, v218, v226
	v_mul_f32_e32 v219, v219, v226
	v_mul_f32_e32 v220, v220, v226
	v_mul_f32_e32 v221, v221, v226
	v_mul_f32_e32 v222, v222, v226
	v_mul_f32_e32 v223, v223, v226
	v_fmac_f32_e32 v128, v208, v40
	v_fmac_f32_e32 v129, v209, v41
	v_fmac_f32_e32 v130, v210, v42
	v_fmac_f32_e32 v131, v211, v43
	v_fmac_f32_e32 v132, v212, v44
	v_fmac_f32_e32 v133, v213, v45
	v_fmac_f32_e32 v134, v214, v46
	v_fmac_f32_e32 v135, v215, v47
	v_fmac_f32_e32 v136, v216, v48
	v_fmac_f32_e32 v137, v217, v49
	v_fmac_f32_e32 v138, v218, v50
	v_fmac_f32_e32 v139, v219, v51
	v_fmac_f32_e32 v140, v220, v52
	v_fmac_f32_e32 v141, v221, v53
	v_fmac_f32_e32 v142, v222, v54
	v_fmac_f32_e32 v143, v223, v55
	v_lshlrev_b32_e32 v208, 16, v152
	v_and_b32_e32 v209, 0xffff0000, v152
	v_lshlrev_b32_e32 v210, 16, v153
	v_and_b32_e32 v211, 0xffff0000, v153
	v_lshlrev_b32_e32 v212, 16, v154
	v_and_b32_e32 v213, 0xffff0000, v154
	v_lshlrev_b32_e32 v214, 16, v155
	v_and_b32_e32 v215, 0xffff0000, v155
	v_lshlrev_b32_e32 v216, 16, v156
	v_and_b32_e32 v217, 0xffff0000, v156
	v_lshlrev_b32_e32 v218, 16, v157
	v_and_b32_e32 v219, 0xffff0000, v157
	v_lshlrev_b32_e32 v220, 16, v158
	v_and_b32_e32 v221, 0xffff0000, v158
	v_lshlrev_b32_e32 v222, 16, v159
	v_and_b32_e32 v223, 0xffff0000, v159
	v_mul_f32_e32 v224, v208, v208
	v_fmac_f32_e32 v224, v209, v209
	v_fmac_f32_e32 v224, v210, v210
	v_fmac_f32_e32 v224, v211, v211
	v_fmac_f32_e32 v224, v212, v212
	v_fmac_f32_e32 v224, v213, v213
	v_fmac_f32_e32 v224, v214, v214
	v_fmac_f32_e32 v224, v215, v215
	v_fmac_f32_e32 v224, v216, v216
	v_fmac_f32_e32 v224, v217, v217
	v_fmac_f32_e32 v224, v218, v218
	v_fmac_f32_e32 v224, v219, v219
	v_fmac_f32_e32 v224, v220, v220
	v_fmac_f32_e32 v224, v221, v221
	v_fmac_f32_e32 v224, v222, v222
	v_fmac_f32_e32 v224, v223, v223
	s_nop 1
	v_add_f32_dpp v224, v224, v224 quad_perm:[1,0,3,2] row_mask:0xf bank_mask:0xf
	s_nop 1
	v_add_f32_dpp v224, v224, v224 quad_perm:[2,3,0,1] row_mask:0xf bank_mask:0xf
	s_nop 1
	v_add_f32_dpp v224, v224, v224 row_ror:4 row_mask:0xf bank_mask:0xf
	s_nop 1
	v_add_f32_dpp v224, v224, v224 row_ror:8 row_mask:0xf bank_mask:0xf
	s_nop 1
	v_readlane_b32 s20, v224, 0
	v_readlane_b32 s21, v224, 16
	v_readlane_b32 s22, v224, 32
	v_readlane_b32 s23, v224, 48
	s_nop 1
	v_mov_b32_e32 v225, s20
	v_add_f32_e32 v225, s21, v225
	v_add_f32_e32 v225, s22, v225
	v_add_f32_e32 v225, s23, v225
	v_mov_b32_e32 v226, 0x358637bd
	v_fmac_f32_e32 v226, 0x3a800000, v225
	v_rsq_f32_e32 v226, v226
	s_nop 0
	v_mul_f32_e32 v208, v208, v226
	v_mul_f32_e32 v209, v209, v226
	v_mul_f32_e32 v210, v210, v226
	v_mul_f32_e32 v211, v211, v226
	v_mul_f32_e32 v212, v212, v226
	v_mul_f32_e32 v213, v213, v226
	v_mul_f32_e32 v214, v214, v226
	v_mul_f32_e32 v215, v215, v226
	v_mul_f32_e32 v216, v216, v226
	v_mul_f32_e32 v217, v217, v226
	v_mul_f32_e32 v218, v218, v226
	v_mul_f32_e32 v219, v219, v226
	v_mul_f32_e32 v220, v220, v226
	v_mul_f32_e32 v221, v221, v226
	v_mul_f32_e32 v222, v222, v226
	v_mul_f32_e32 v223, v223, v226
	v_fmac_f32_e32 v128, v208, v56
	v_fmac_f32_e32 v129, v209, v57
	v_fmac_f32_e32 v130, v210, v58
	v_fmac_f32_e32 v131, v211, v59
	v_fmac_f32_e32 v132, v212, v60
	v_fmac_f32_e32 v133, v213, v61
	v_fmac_f32_e32 v134, v214, v62
	v_fmac_f32_e32 v135, v215, v63
	v_fmac_f32_e32 v136, v216, v64
	v_fmac_f32_e32 v137, v217, v65
	v_fmac_f32_e32 v138, v218, v66
	v_fmac_f32_e32 v139, v219, v67
	v_fmac_f32_e32 v140, v220, v68
	v_fmac_f32_e32 v141, v221, v69
	v_fmac_f32_e32 v142, v222, v70
	v_fmac_f32_e32 v143, v223, v71
; DI unsigned pk_bf16(float a, float b) { f32x2_t v = {a, b}; bf16x2_t r = __builtin_convertvector(v, bf16x2_t); return __builtin_bit_cast(unsigned, r); }
; DI float shx(float v, int mask) { const int l = olane(); return __builtin_bit_cast(float, __builtin_amdgcn_ds_bpermute(((l ^ mask) & 63) << 2, __builtin_bit_cast(int, v))); }
; DI void row_phase(const bf16_t* msrc, const float* xsrc, float* xdst, const float* g_post, const float* g_next, bf16_t* hdst, const int gw) {
;     ...
;             for (int j = 0; j < 4; ++j) { const f32x4 g = *(const f32x4*)(g_post + lane * 4 + 256 * j);
; #pragma unroll
;                 for (int r = 0; r < RB; ++r) { const float r1 = rsqrtf(ss[r] * (1.f / DM) + EPS); xv[r][j] = xv[r][j] + mv[r][j] * r1 * g; *(f32x4*)(xdst + (size_t)(rowb + r) * DM + lane * 4 + 256 * j) = xv[r][j]; } }
;         }
;         if (hdst) {
;             float ss[RB];
; #pragma unroll
;             for (int r = 0; r < RB; ++r) { ss[r] = 0.f;
; #pragma unroll
;                 for (int j = 0; j < 4; ++j) ss[r] += xv[r][j][0] * xv[r][j][0] + xv[r][j][1] * xv[r][j][1] + xv[r][j][2] * xv[r][j][2] + xv[r][j][3] * xv[r][j][3]; }
; #pragma unroll
;             for (int o = 32; o >= 1; o >>= 1)
; #pragma unroll
;                 for (int r = 0; r < RB; ++r) ss[r] += shx(ss[r], o);
; #pragma unroll
;             for (int j = 0; j < 4; ++j) { const f32x4 g = *(const f32x4*)(g_next + lane * 4 + 256 * j);
; #pragma unroll
;                 for (int r = 0; r < RB; ++r) { const float r2 = rsqrtf(ss[r] * (1.f / DM) + EPS); const f32x4 hv = xv[r][j] * r2 * g;
;                     u32x2 o; o[0] = pk_bf16(hv[0], hv[1]); o[1] = pk_bf16(hv[2], hv[3]); *(u32x2*)(hdst + (size_t)(rowb + r) * DM + lane * 4 + 256 * j) = o; } }
	global_store_dwordx4 v1, v[128:131], s[8:9] offset:0
	global_store_dwordx4 v1, v[132:135], s[8:9] offset:16
	global_store_dwordx4 v1, v[136:139], s[8:9] offset:2048
	global_store_dwordx4 v1, v[140:143], s[8:9] offset:2064
	s_add_u32 s8, s8, 0x1000
	s_addc_u32 s9, s9, 0
	v_mul_f32_e32 v224, v128, v128
	v_fmac_f32_e32 v224, v129, v129
	v_fmac_f32_e32 v224, v130, v130
	v_fmac_f32_e32 v224, v131, v131
	v_fmac_f32_e32 v224, v132, v132
	v_fmac_f32_e32 v224, v133, v133
	v_fmac_f32_e32 v224, v134, v134
	v_fmac_f32_e32 v224, v135, v135
	v_fmac_f32_e32 v224, v136, v136
	v_fmac_f32_e32 v224, v137, v137
	v_fmac_f32_e32 v224, v138, v138
	v_fmac_f32_e32 v224, v139, v139
	v_fmac_f32_e32 v224, v140, v140
	v_fmac_f32_e32 v224, v141, v141
	v_fmac_f32_e32 v224, v142, v142
	v_fmac_f32_e32 v224, v143, v143
	s_nop 1
	v_add_f32_dpp v224, v224, v224 quad_perm:[1,0,3,2] row_mask:0xf bank_mask:0xf
	s_nop 1
	v_add_f32_dpp v224, v224, v224 quad_perm:[2,3,0,1] row_mask:0xf bank_mask:0xf
	s_nop 1
	v_add_f32_dpp v224, v224, v224 row_ror:4 row_mask:0xf bank_mask:0xf
	s_nop 1
	v_add_f32_dpp v224, v224, v224 row_ror:8 row_mask:0xf bank_mask:0xf
	s_nop 1
	v_readlane_b32 s20, v224, 0
	v_readlane_b32 s21, v224, 16
	v_readlane_b32 s22, v224, 32
	v_readlane_b32 s23, v224, 48
	s_nop 1
	v_mov_b32_e32 v225, s20
	v_add_f32_e32 v225, s21, v225
	v_add_f32_e32 v225, s22, v225
	v_add_f32_e32 v225, s23, v225
	v_mov_b32_e32 v226, 0x358637bd
	v_fmac_f32_e32 v226, 0x3a800000, v225
	v_rsq_f32_e32 v226, v226
	s_nop 0
	v_mul_f32_e32 v208, v128, v226
	v_mul_f32_e32 v209, v129, v226
	v_mul_f32_e32 v210, v130, v226
	v_mul_f32_e32 v211, v131, v226
	v_mul_f32_e32 v212, v132, v226
	v_mul_f32_e32 v213, v133, v226
	v_mul_f32_e32 v214, v134, v226
	v_mul_f32_e32 v215, v135, v226
	v_mul_f32_e32 v216, v136, v226
	v_mul_f32_e32 v217, v137, v226
	v_mul_f32_e32 v218, v138, v226
	v_mul_f32_e32 v219, v139, v226
	v_mul_f32_e32 v220, v140, v226
	v_mul_f32_e32 v221, v141, v226
	v_mul_f32_e32 v222, v142, v226
	v_mul_f32_e32 v223, v143, v226
	v_mul_f32_e32 v208, v208, v72
	v_mul_f32_e32 v209, v209, v73
	v_mul_f32_e32 v210, v210, v74
	v_mul_f32_e32 v211, v211, v75
	v_mul_f32_e32 v212, v212, v76
	v_mul_f32_e32 v213, v213, v77
	v_mul_f32_e32 v214, v214, v78
	v_mul_f32_e32 v215, v215, v79
	v_mul_f32_e32 v216, v216, v80
	v_mul_f32_e32 v217, v217, v81
	v_mul_f32_e32 v218, v218, v82
	v_mul_f32_e32 v219, v219, v83
	v_mul_f32_e32 v220, v220, v84
	v_mul_f32_e32 v221, v221, v85
	v_mul_f32_e32 v222, v222, v86
	v_mul_f32_e32 v223, v223, v87
	v_cvt_pk_bf16_f32 v144, v208, v209
	v_cvt_pk_bf16_f32 v145, v210, v211
	v_cvt_pk_bf16_f32 v146, v212, v213
	v_cvt_pk_bf16_f32 v147, v214, v215
	v_cvt_pk_bf16_f32 v148, v216, v217
	v_cvt_pk_bf16_f32 v149, v218, v219
	v_cvt_pk_bf16_f32 v150, v220, v221
	v_cvt_pk_bf16_f32 v151, v222, v223
	global_store_dwordx4 v2, v[144:147], s[14:15]
	global_store_dwordx4 v2, v[148:151], s[14:15] offset:1024
	s_add_u32 s14, s14, 0x800
	s_addc_u32 s15, s15, 0
	v_readlane_b32 s4, v3, 0
	v_readlane_b32 s5, v3, 1
	v_readlane_b32 s6, v3, 2
	v_readlane_b32 s7, v3, 3
	v_readlane_b32 s8, v3, 4
	v_readlane_b32 s9, v3, 5
	v_readlane_b32 s10, v3, 6
	v_readlane_b32 s11, v3, 7
	v_readlane_b32 s12, v3, 8
	v_readlane_b32 s13, v3, 9
	v_readlane_b32 s14, v3, 10
	v_readlane_b32 s15, v3, 11
	v_readlane_b32 s16, v3, 12
	v_readlane_b32 s17, v3, 13
	v_readlane_b32 s18, v3, 14
	v_readlane_b32 s19, v3, 15
	v_readlane_b32 s20, v3, 16
	v_readlane_b32 s21, v3, 17
	v_readlane_b32 s22, v3, 18
	v_readlane_b32 s23, v3, 19
	v_readlane_b32 s24, v3, 20
	v_readlane_b32 s25, v3, 21
	s_mov_b32 s6, 0x358637bd
	s_mov_b64 s[34:35], 0
	s_branch .LBB0_74
.Lrow_r2:
	v_writelane_b32 v3, s4, 0
	v_writelane_b32 v3, s5, 1
	v_writelane_b32 v3, s6, 2
	v_writelane_b32 v3, s7, 3
	v_writelane_b32 v3, s8, 4
	v_writelane_b32 v3, s9, 5
	v_writelane_b32 v3, s10, 6
	v_writelane_b32 v3, s11, 7
	v_writelane_b32 v3, s12, 8
	v_writelane_b32 v3, s13, 9
	v_writelane_b32 v3, s14, 10
	v_writelane_b32 v3, s15, 11
	v_writelane_b32 v3, s16, 12
	v_writelane_b32 v3, s17, 13
	v_writelane_b32 v3, s18, 14
	v_writelane_b32 v3, s19, 15
	v_writelane_b32 v3, s20, 16
	v_writelane_b32 v3, s21, 17
	v_writelane_b32 v3, s22, 18
	v_writelane_b32 v3, s23, 19
	v_writelane_b32 v3, s24, 20
	v_writelane_b32 v3, s25, 21
	s_waitcnt vmcnt(0) lgkmcnt(0)
; DI int obid() { int b = blockIdx.x; asm volatile("" : "+s"(b)); return b; }
; DI int ogrid() { int g = gridDim.x; asm volatile("" : "+s"(g)); return g; }
; DI int otid_w(int gw) { return (gw << 6) | olane(); }
; DI void row_phase(const bf16_t* msrc, const float* xsrc, float* xdst, const float* g_post, const float* g_next, bf16_t* hdst, const int gw) {
;     ...
;     const int tid = otid_w(gw); const int lane = tid & 63, w = tid >> 6;
;     const int wg = obid() * 8 + w, nw = ogrid() * 8;
;     for (int rowb = wg * RB; rowb < M_TOK; rowb += nw * RB) {
;         f32x4 xv[RB][4], mv[RB][4];
; #pragma unroll
;         for (int r = 0; r < RB; ++r)
; #pragma unroll
;             for (int j = 0; j < 4; ++j) xv[r][j] = *(const f32x4*)(xsrc + (size_t)(rowb + r) * DM + lane * 4 + 256 * j);
;         if (msrc) {
; #pragma unroll
;             for (int r = 0; r < RB; ++r)
; #pragma unroll
;                 for (int j = 0; j < 4; ++j) { const u32x2 mw = *(const u32x2*)(msrc + (size_t)(rowb + r) * DM + lane * 4 + 256 * j);
;                     mv[r][j] = (f32x4){__uint_as_float(mw[0] << 16), __uint_as_float(mw[0] & 0xffff0000u), __uint_as_float(mw[1] << 16), __uint_as_float(mw[1] & 0xffff0000u)}; }
;             float ss[RB];
; #pragma unroll
;             for (int r = 0; r < RB; ++r) { ss[r] = 0.f;
; #pragma unroll
;                 for (int j = 0; j < 4; ++j) ss[r] += mv[r][j][0] * mv[r][j][0] + mv[r][j][1] * mv[r][j][1] + mv[r][j][2] * mv[r][j][2] + mv[r][j][3] * mv[r][j][3]; }
	v_mbcnt_lo_u32_b32 v0, -1, 0
	v_mbcnt_hi_u32_b32 v0, -1, v0
	v_lshlrev_b32_e32 v1, 5, v0
	v_lshlrev_b32_e32 v2, 4, v0
	s_lshr_b32 s4, s71, 6
	s_and_b32 s5, s2, 7
	s_lshl_b32 s5, s5, 8
	s_lshr_b32 s24, s2, 3
	s_lshl_b32 s24, s24, 3
	s_add_i32 s5, s5, s24
	s_add_i32 s5, s5, s4
	s_lshl_b32 s24, s5, 15
	s_lshl_b32 s25, s5, 14
	v_readlane_b32 s8, v254, 62
	v_readlane_b32 s9, v254, 63
	v_readlane_b32 s6, v255, 2
	v_readlane_b32 s7, v255, 3
	v_readlane_b32 s4, v255, 6
	v_readlane_b32 s16, v255, 10
	v_readlane_b32 s17, v255, 11
	s_nop 1
	s_cmp_eq_u32 s4, 0
	s_cselect_b32 s6, s6, s8
	s_cselect_b32 s7, s7, s9
	s_add_u32 s6, s6, s24
	s_addc_u32 s7, s7, 0
	s_add_u32 s8, s8, s24
	s_addc_u32 s9, s9, 0
	s_add_u32 s10, s68, 0x10681000
	s_addc_u32 s11, s69, 0
	s_add_u32 s10, s10, s25
	s_addc_u32 s11, s11, 0
	s_and_b32 s12, s2, 7
	s_lshl_b32 s12, s12, 22
	s_add_u32 s10, s10, s12
	s_addc_u32 s11, s11, 0
	s_add_u32 s12, s10, 0x400000
	s_addc_u32 s13, s11, 0
	s_add_u32 s14, s82, s25
	s_addc_u32 s15, s83, 0
	s_add_u32 s18, s16, 0x1000
	s_addc_u32 s19, s17, 0
	global_load_dwordx4 v[40:43], v1, s[18:19] offset:0
	global_load_dwordx4 v[44:47], v1, s[18:19] offset:16
	global_load_dwordx4 v[48:51], v1, s[18:19] offset:2048
	global_load_dwordx4 v[52:55], v1, s[18:19] offset:2064
	s_add_u32 s18, s16, 0x3000
	s_addc_u32 s19, s17, 0
	global_load_dwordx4 v[56:59], v1, s[18:19] offset:0
	global_load_dwordx4 v[60:63], v1, s[18:19] offset:16
	global_load_dwordx4 v[64:67], v1, s[18:19] offset:2048
	global_load_dwordx4 v[68:71], v1, s[18:19] offset:2064
	global_load_dwordx4 v[96:99], v1, s[6:7] offset:0
	global_load_dwordx4 v[100:103], v1, s[6:7] offset:16
	global_load_dwordx4 v[104:107], v1, s[6:7] offset:2048
	global_load_dwordx4 v[108:111], v1, s[6:7] offset:2064
	global_load_dwordx4 v[112:115], v2, s[10:11]
	global_load_dwordx4 v[116:119], v2, s[10:11] offset:1024
	global_load_dwordx4 v[120:123], v2, s[12:13]
	global_load_dwordx4 v[124:127], v2, s[12:13] offset:1024
	s_add_u32 s6, s6, 0x1000
	s_addc_u32 s7, s7, 0
	s_add_u32 s10, s10, 0x800
	s_addc_u32 s11, s11, 0
	s_add_u32 s12, s12, 0x800
	s_addc_u32 s13, s13, 0
	global_load_dwordx4 v[128:131], v1, s[6:7] offset:0
	global_load_dwordx4 v[132:135], v1, s[6:7] offset:16
	global_load_dwordx4 v[136:139], v1, s[6:7] offset:2048
	global_load_dwordx4 v[140:143], v1, s[6:7] offset:2064
	global_load_dwordx4 v[144:147], v2, s[10:11]
	global_load_dwordx4 v[148:151], v2, s[10:11] offset:1024
	global_load_dwordx4 v[152:155], v2, s[12:13]
	global_load_dwordx4 v[156:159], v2, s[12:13] offset:1024
	s_add_u32 s6, s6, 0x1000
	s_addc_u32 s7, s7, 0
	s_add_u32 s10, s10, 0x800
	s_addc_u32 s11, s11, 0
	s_add_u32 s12, s12, 0x800
	s_addc_u32 s13, s13, 0
	global_load_dwordx4 v[160:163], v1, s[6:7] offset:0
	global_load_dwordx4 v[164:167], v1, s[6:7] offset:16
	global_load_dwordx4 v[168:171], v1, s[6:7] offset:2048
	global_load_dwordx4 v[172:175], v1, s[6:7] offset:2064
	global_load_dwordx4 v[176:179], v2, s[10:11]
	global_load_dwordx4 v[180:183], v2, s[10:11] offset:1024
	global_load_dwordx4 v[184:187], v2, s[12:13]
	global_load_dwordx4 v[188:191], v2, s[12:13] offset:1024
	s_add_u32 s6, s6, 0x1000
	s_addc_u32 s7, s7, 0
	s_add_u32 s10, s10, 0x800
	s_addc_u32 s11, s11, 0
	s_add_u32 s12, s12, 0x800
	s_addc_u32 s13, s13, 0
	s_waitcnt vmcnt(16)
	v_lshlrev_b32_e32 v208, 16, v112
	v_and_b32_e32 v209, 0xffff0000, v112
	v_lshlrev_b32_e32 v210, 16, v113
	v_and_b32_e32 v211, 0xffff0000, v113
	v_lshlrev_b32_e32 v212, 16, v114
	v_and_b32_e32 v213, 0xffff0000, v114
	v_lshlrev_b32_e32 v214, 16, v115
	v_and_b32_e32 v215, 0xffff0000, v115
	v_lshlrev_b32_e32 v216, 16, v116
	v_and_b32_e32 v217, 0xffff0000, v116
	v_lshlrev_b32_e32 v218, 16, v117
	v_and_b32_e32 v219, 0xffff0000, v117
	v_lshlrev_b32_e32 v220, 16, v118
	v_and_b32_e32 v221, 0xffff0000, v118
	v_lshlrev_b32_e32 v222, 16, v119
	v_and_b32_e32 v223, 0xffff0000, v119
	v_mul_f32_e32 v224, v208, v208
	v_fmac_f32_e32 v224, v209, v209
	v_fmac_f32_e32 v224, v210, v210
	v_fmac_f32_e32 v224, v211, v211
	v_fmac_f32_e32 v224, v212, v212
	v_fmac_f32_e32 v224, v213, v213
	v_fmac_f32_e32 v224, v214, v214
	v_fmac_f32_e32 v224, v215, v215
	v_fmac_f32_e32 v224, v216, v216
	v_fmac_f32_e32 v224, v217, v217
	v_fmac_f32_e32 v224, v218, v218
	v_fmac_f32_e32 v224, v219, v219
	v_fmac_f32_e32 v224, v220, v220
	v_fmac_f32_e32 v224, v221, v221
	v_fmac_f32_e32 v224, v222, v222
	v_fmac_f32_e32 v224, v223, v223
	s_nop 1
	v_add_f32_dpp v224, v224, v224 quad_perm:[1,0,3,2] row_mask:0xf bank_mask:0xf
	s_nop 1
	v_add_f32_dpp v224, v224, v224 quad_perm:[2,3,0,1] row_mask:0xf bank_mask:0xf
	s_nop 1
	v_add_f32_dpp v224, v224, v224 row_ror:4 row_mask:0xf bank_mask:0xf
	s_nop 1
	v_add_f32_dpp v224, v224, v224 row_ror:8 row_mask:0xf bank_mask:0xf
	s_nop 1
	v_readlane_b32 s20, v224, 0
	v_readlane_b32 s21, v224, 16
	v_readlane_b32 s22, v224, 32
	v_readlane_b32 s23, v224, 48
	s_nop 1
	v_mov_b32_e32 v225, s20
	v_add_f32_e32 v225, s21, v225
	v_add_f32_e32 v225, s22, v225
	v_add_f32_e32 v225, s23, v225
	v_mov_b32_e32 v226, 0x358637bd
	v_fmac_f32_e32 v226, 0x3a800000, v225
	v_rsq_f32_e32 v226, v226
	s_nop 0
	v_mul_f32_e32 v208, v208, v226
	v_mul_f32_e32 v209, v209, v226
	v_mul_f32_e32 v210, v210, v226
	v_mul_f32_e32 v211, v211, v226
	v_mul_f32_e32 v212, v212, v226
	v_mul_f32_e32 v213, v213, v226
	v_mul_f32_e32 v214, v214, v226
	v_mul_f32_e32 v215, v215, v226
	v_mul_f32_e32 v216, v216, v226
	v_mul_f32_e32 v217, v217, v226
	v_mul_f32_e32 v218, v218, v226
	v_mul_f32_e32 v219, v219, v226
	v_mul_f32_e32 v220, v220, v226
	v_mul_f32_e32 v221, v221, v226
	v_mul_f32_e32 v222, v222, v226
	v_mul_f32_e32 v223, v223, v226
	v_fmac_f32_e32 v96, v208, v40
; DI float shx(float v, int mask) { const int l = olane(); return __builtin_bit_cast(float, __builtin_amdgcn_ds_bpermute(((l ^ mask) & 63) << 2, __builtin_bit_cast(int, v))); }
; DI void row_phase(const bf16_t* msrc, const float* xsrc, float* xdst, const float* g_post, const float* g_next, bf16_t* hdst, const int gw) {
;     ...
;                 for (int j = 0; j < 4; ++j) { const u32x2 mw = *(const u32x2*)(msrc + (size_t)(rowb + r) * DM + lane * 4 + 256 * j);
;                     mv[r][j] = (f32x4){__uint_as_float(mw[0] << 16), __uint_as_float(mw[0] & 0xffff0000u), __uint_as_float(mw[1] << 16), __uint_as_float(mw[1] & 0xffff0000u)}; }
;             float ss[RB];
; #pragma unroll
;             for (int r = 0; r < RB; ++r) { ss[r] = 0.f;
; #pragma unroll
;                 for (int j = 0; j < 4; ++j) ss[r] += mv[r][j][0] * mv[r][j][0] + mv[r][j][1] * mv[r][j][1] + mv[r][j][2] * mv[r][j][2] + mv[r][j][3] * mv[r][j][3]; }
; #pragma unroll
;             for (int o = 32; o >= 1; o >>= 1)
; #pragma unroll
;                 for (int r = 0; r < RB; ++r) ss[r] += shx(ss[r], o);
; #pragma unroll
;             for (int j = 0; j < 4; ++j) { const f32x4 g = *(const f32x4*)(g_post + lane * 4 + 256 * j);
; #pragma unroll
;                 for (int r = 0; r < RB; ++r) { const float r1 = rsqrtf(ss[r] * (1.f / DM) + EPS); xv[r][j] = xv[r][j] + mv[r][j] * r1 * g; *(f32x4*)(xdst + (size_t)(rowb + r) * DM + lane * 4 + 256 * j) = xv[r][j]; } }
	v_fmac_f32_e32 v97, v209, v41
	v_fmac_f32_e32 v98, v210, v42
	v_fmac_f32_e32 v99, v211, v43
	v_fmac_f32_e32 v100, v212, v44
	v_fmac_f32_e32 v101, v213, v45
	v_fmac_f32_e32 v102, v214, v46
	v_fmac_f32_e32 v103, v215, v47
	v_fmac_f32_e32 v104, v216, v48
	v_fmac_f32_e32 v105, v217, v49
	v_fmac_f32_e32 v106, v218, v50
	v_fmac_f32_e32 v107, v219, v51
	v_fmac_f32_e32 v108, v220, v52
	v_fmac_f32_e32 v109, v221, v53
	v_fmac_f32_e32 v110, v222, v54
	v_fmac_f32_e32 v111, v223, v55
	v_lshlrev_b32_e32 v208, 16, v120
	v_and_b32_e32 v209, 0xffff0000, v120
	v_lshlrev_b32_e32 v210, 16, v121
	v_and_b32_e32 v211, 0xffff0000, v121
	v_lshlrev_b32_e32 v212, 16, v122
	v_and_b32_e32 v213, 0xffff0000, v122
	v_lshlrev_b32_e32 v214, 16, v123
	v_and_b32_e32 v215, 0xffff0000, v123
	v_lshlrev_b32_e32 v216, 16, v124
	v_and_b32_e32 v217, 0xffff0000, v124
	v_lshlrev_b32_e32 v218, 16, v125
	v_and_b32_e32 v219, 0xffff0000, v125
	v_lshlrev_b32_e32 v220, 16, v126
	v_and_b32_e32 v221, 0xffff0000, v126
	v_lshlrev_b32_e32 v222, 16, v127
	v_and_b32_e32 v223, 0xffff0000, v127
	v_mul_f32_e32 v224, v208, v208
	v_fmac_f32_e32 v224, v209, v209
	v_fmac_f32_e32 v224, v210, v210
	v_fmac_f32_e32 v224, v211, v211
	v_fmac_f32_e32 v224, v212, v212
	v_fmac_f32_e32 v224, v213, v213
	v_fmac_f32_e32 v224, v214, v214
	v_fmac_f32_e32 v224, v215, v215
	v_fmac_f32_e32 v224, v216, v216
	v_fmac_f32_e32 v224, v217, v217
	v_fmac_f32_e32 v224, v218, v218
	v_fmac_f32_e32 v224, v219, v219
	v_fmac_f32_e32 v224, v220, v220
	v_fmac_f32_e32 v224, v221, v221
	v_fmac_f32_e32 v224, v222, v222
	v_fmac_f32_e32 v224, v223, v223
	s_nop 1
	v_add_f32_dpp v224, v224, v224 quad_perm:[1,0,3,2] row_mask:0xf bank_mask:0xf
	s_nop 1
	v_add_f32_dpp v224, v224, v224 quad_perm:[2,3,0,1] row_mask:0xf bank_mask:0xf
	s_nop 1
	v_add_f32_dpp v224, v224, v224 row_ror:4 row_mask:0xf bank_mask:0xf
	s_nop 1
	v_add_f32_dpp v224, v224, v224 row_ror:8 row_mask:0xf bank_mask:0xf
	s_nop 1
	v_readlane_b32 s20, v224, 0
	v_readlane_b32 s21, v224, 16
	v_readlane_b32 s22, v224, 32
	v_readlane_b32 s23, v224, 48
	s_nop 1
	v_mov_b32_e32 v225, s20
	v_add_f32_e32 v225, s21, v225
	v_add_f32_e32 v225, s22, v225
	v_add_f32_e32 v225, s23, v225
	v_mov_b32_e32 v226, 0x358637bd
	v_fmac_f32_e32 v226, 0x3a800000, v225
	v_rsq_f32_e32 v226, v226
	s_nop 0
	v_mul_f32_e32 v208, v208, v226
	v_mul_f32_e32 v209, v209, v226
	v_mul_f32_e32 v210, v210, v226
	v_mul_f32_e32 v211, v211, v226
	v_mul_f32_e32 v212, v212, v226
	v_mul_f32_e32 v213, v213, v226
	v_mul_f32_e32 v214, v214, v226
	v_mul_f32_e32 v215, v215, v226
	v_mul_f32_e32 v216, v216, v226
	v_mul_f32_e32 v217, v217, v226
	v_mul_f32_e32 v218, v218, v226
	v_mul_f32_e32 v219, v219, v226
	v_mul_f32_e32 v220, v220, v226
	v_mul_f32_e32 v221, v221, v226
	v_mul_f32_e32 v222, v222, v226
	v_mul_f32_e32 v223, v223, v226
	v_fmac_f32_e32 v96, v208, v56
	v_fmac_f32_e32 v97, v209, v57
	v_fmac_f32_e32 v98, v210, v58
	v_fmac_f32_e32 v99, v211, v59
	v_fmac_f32_e32 v100, v212, v60
	v_fmac_f32_e32 v101, v213, v61
	v_fmac_f32_e32 v102, v214, v62
	v_fmac_f32_e32 v103, v215, v63
	v_fmac_f32_e32 v104, v216, v64
	v_fmac_f32_e32 v105, v217, v65
	v_fmac_f32_e32 v106, v218, v66
	v_fmac_f32_e32 v107, v219, v67
	v_fmac_f32_e32 v108, v220, v68
	v_fmac_f32_e32 v109, v221, v69
	v_fmac_f32_e32 v110, v222, v70
	v_fmac_f32_e32 v111, v223, v71
	global_store_dwordx4 v1, v[96:99], s[8:9] offset:0
	global_store_dwordx4 v1, v[100:103], s[8:9] offset:16
	global_store_dwordx4 v1, v[104:107], s[8:9] offset:2048
	global_store_dwordx4 v1, v[108:111], s[8:9] offset:2064
	s_add_u32 s8, s8, 0x1000
	s_addc_u32 s9, s9, 0
	global_load_dwordx4 v[96:99], v1, s[6:7] offset:0
	global_load_dwordx4 v[100:103], v1, s[6:7] offset:16
	global_load_dwordx4 v[104:107], v1, s[6:7] offset:2048
	global_load_dwordx4 v[108:111], v1, s[6:7] offset:2064
	global_load_dwordx4 v[112:115], v2, s[10:11]
	global_load_dwordx4 v[116:119], v2, s[10:11] offset:1024
	global_load_dwordx4 v[120:123], v2, s[12:13]
	global_load_dwordx4 v[124:127], v2, s[12:13] offset:1024
	s_add_u32 s6, s6, 0x1000
	s_addc_u32 s7, s7, 0
	s_add_u32 s10, s10, 0x800
	s_addc_u32 s11, s11, 0
	s_add_u32 s12, s12, 0x800
	s_addc_u32 s13, s13, 0
	s_waitcnt vmcnt(20)
	v_lshlrev_b32_e32 v208, 16, v144
	v_and_b32_e32 v209, 0xffff0000, v144
	v_lshlrev_b32_e32 v210, 16, v145
	v_and_b32_e32 v211, 0xffff0000, v145
	v_lshlrev_b32_e32 v212, 16, v146
	v_and_b32_e32 v213, 0xffff0000, v146
	v_lshlrev_b32_e32 v214, 16, v147
	v_and_b32_e32 v215, 0xffff0000, v147
	v_lshlrev_b32_e32 v216, 16, v148
	v_and_b32_e32 v217, 0xffff0000, v148
	v_lshlrev_b32_e32 v218, 16, v149
	v_and_b32_e32 v219, 0xffff0000, v149
	v_lshlrev_b32_e32 v220, 16, v150
	v_and_b32_e32 v221, 0xffff0000, v150
	v_lshlrev_b32_e32 v222, 16, v151
	v_and_b32_e32 v223, 0xffff0000, v151
	v_mul_f32_e32 v224, v208, v208
	v_fmac_f32_e32 v224, v209, v209
	v_fmac_f32_e32 v224, v210, v210
	v_fmac_f32_e32 v224, v211, v211
	v_fmac_f32_e32 v224, v212, v212
	v_fmac_f32_e32 v224, v213, v213
	v_fmac_f32_e32 v224, v214, v214
	v_fmac_f32_e32 v224, v215, v215
	v_fmac_f32_e32 v224, v216, v216
	v_fmac_f32_e32 v224, v217, v217
	v_fmac_f32_e32 v224, v218, v218
	v_fmac_f32_e32 v224, v219, v219
	v_fmac_f32_e32 v224, v220, v220
	v_fmac_f32_e32 v224, v221, v221
	v_fmac_f32_e32 v224, v222, v222
	v_fmac_f32_e32 v224, v223, v223
	s_nop 1
	v_add_f32_dpp v224, v224, v224 quad_perm:[1,0,3,2] row_mask:0xf bank_mask:0xf
	s_nop 1
	v_add_f32_dpp v224, v224, v224 quad_perm:[2,3,0,1] row_mask:0xf bank_mask:0xf
	s_nop 1
	v_add_f32_dpp v224, v224, v224 row_ror:4 row_mask:0xf bank_mask:0xf
	s_nop 1
	v_add_f32_dpp v224, v224, v224 row_ror:8 row_mask:0xf bank_mask:0xf
	s_nop 1
	v_readlane_b32 s20, v224, 0
; DI float shx(float v, int mask) { const int l = olane(); return __builtin_bit_cast(float, __builtin_amdgcn_ds_bpermute(((l ^ mask) & 63) << 2, __builtin_bit_cast(int, v))); }
; DI void row_phase(const bf16_t* msrc, const float* xsrc, float* xdst, const float* g_post, const float* g_next, bf16_t* hdst, const int gw) {
;     ...
;                 for (int j = 0; j < 4; ++j) { const u32x2 mw = *(const u32x2*)(msrc + (size_t)(rowb + r) * DM + lane * 4 + 256 * j);
;                     mv[r][j] = (f32x4){__uint_as_float(mw[0] << 16), __uint_as_float(mw[0] & 0xffff0000u), __uint_as_float(mw[1] << 16), __uint_as_float(mw[1] & 0xffff0000u)}; }
;             float ss[RB];
; #pragma unroll
;             for (int r = 0; r < RB; ++r) { ss[r] = 0.f;
; #pragma unroll
;                 for (int j = 0; j < 4; ++j) ss[r] += mv[r][j][0] * mv[r][j][0] + mv[r][j][1] * mv[r][j][1] + mv[r][j][2] * mv[r][j][2] + mv[r][j][3] * mv[r][j][3]; }
; #pragma unroll
;             for (int o = 32; o >= 1; o >>= 1)
; #pragma unroll
;                 for (int r = 0; r < RB; ++r) ss[r] += shx(ss[r], o);
; #pragma unroll
;             for (int j = 0; j < 4; ++j) { const f32x4 g = *(const f32x4*)(g_post + lane * 4 + 256 * j);
; #pragma unroll
;                 for (int r = 0; r < RB; ++r) { const float r1 = rsqrtf(ss[r] * (1.f / DM) + EPS); xv[r][j] = xv[r][j] + mv[r][j] * r1 * g; *(f32x4*)(xdst + (size_t)(rowb + r) * DM + lane * 4 + 256 * j) = xv[r][j]; } }
	v_readlane_b32 s21, v224, 16
	v_readlane_b32 s22, v224, 32
	v_readlane_b32 s23, v224, 48
	s_nop 1
	v_mov_b32_e32 v225, s20
	v_add_f32_e32 v225, s21, v225
	v_add_f32_e32 v225, s22, v225
	v_add_f32_e32 v225, s23, v225
	v_mov_b32_e32 v226, 0x358637bd
	v_fmac_f32_e32 v226, 0x3a800000, v225
	v_rsq_f32_e32 v226, v226
	s_nop 0
	v_mul_f32_e32 v208, v208, v226
	v_mul_f32_e32 v209, v209, v226
	v_mul_f32_e32 v210, v210, v226
	v_mul_f32_e32 v211, v211, v226
	v_mul_f32_e32 v212, v212, v226
	v_mul_f32_e32 v213, v213, v226
	v_mul_f32_e32 v214, v214, v226
	v_mul_f32_e32 v215, v215, v226
	v_mul_f32_e32 v216, v216, v226
	v_mul_f32_e32 v217, v217, v226
	v_mul_f32_e32 v218, v218, v226
	v_mul_f32_e32 v219, v219, v226
	v_mul_f32_e32 v220, v220, v226
	v_mul_f32_e32 v221, v221, v226
	v_mul_f32_e32 v222, v222, v226
	v_mul_f32_e32 v223, v223, v226
	v_fmac_f32_e32 v128, v208, v40
	v_fmac_f32_e32 v129, v209, v41
	v_fmac_f32_e32 v130, v210, v42
	v_fmac_f32_e32 v131, v211, v43
	v_fmac_f32_e32 v132, v212, v44
	v_fmac_f32_e32 v133, v213, v45
	v_fmac_f32_e32 v134, v214, v46
	v_fmac_f32_e32 v135, v215, v47
	v_fmac_f32_e32 v136, v216, v48
	v_fmac_f32_e32 v137, v217, v49
	v_fmac_f32_e32 v138, v218, v50
	v_fmac_f32_e32 v139, v219, v51
	v_fmac_f32_e32 v140, v220, v52
	v_fmac_f32_e32 v141, v221, v53
	v_fmac_f32_e32 v142, v222, v54
	v_fmac_f32_e32 v143, v223, v55
	v_lshlrev_b32_e32 v208, 16, v152
	v_and_b32_e32 v209, 0xffff0000, v152
	v_lshlrev_b32_e32 v210, 16, v153
	v_and_b32_e32 v211, 0xffff0000, v153
	v_lshlrev_b32_e32 v212, 16, v154
	v_and_b32_e32 v213, 0xffff0000, v154
	v_lshlrev_b32_e32 v214, 16, v155
	v_and_b32_e32 v215, 0xffff0000, v155
	v_lshlrev_b32_e32 v216, 16, v156
	v_and_b32_e32 v217, 0xffff0000, v156
	v_lshlrev_b32_e32 v218, 16, v157
	v_and_b32_e32 v219, 0xffff0000, v157
	v_lshlrev_b32_e32 v220, 16, v158
	v_and_b32_e32 v221, 0xffff0000, v158
	v_lshlrev_b32_e32 v222, 16, v159
	v_and_b32_e32 v223, 0xffff0000, v159
	v_mul_f32_e32 v224, v208, v208
	v_fmac_f32_e32 v224, v209, v209
	v_fmac_f32_e32 v224, v210, v210
	v_fmac_f32_e32 v224, v211, v211
	v_fmac_f32_e32 v224, v212, v212
	v_fmac_f32_e32 v224, v213, v213
	v_fmac_f32_e32 v224, v214, v214
	v_fmac_f32_e32 v224, v215, v215
	v_fmac_f32_e32 v224, v216, v216
	v_fmac_f32_e32 v224, v217, v217
	v_fmac_f32_e32 v224, v218, v218
	v_fmac_f32_e32 v224, v219, v219
	v_fmac_f32_e32 v224, v220, v220
	v_fmac_f32_e32 v224, v221, v221
	v_fmac_f32_e32 v224, v222, v222
	v_fmac_f32_e32 v224, v223, v223
	s_nop 1
	v_add_f32_dpp v224, v224, v224 quad_perm:[1,0,3,2] row_mask:0xf bank_mask:0xf
	s_nop 1
	v_add_f32_dpp v224, v224, v224 quad_perm:[2,3,0,1] row_mask:0xf bank_mask:0xf
	s_nop 1
	v_add_f32_dpp v224, v224, v224 row_ror:4 row_mask:0xf bank_mask:0xf
	s_nop 1
	v_add_f32_dpp v224, v224, v224 row_ror:8 row_mask:0xf bank_mask:0xf
	s_nop 1
	v_readlane_b32 s20, v224, 0
	v_readlane_b32 s21, v224, 16
	v_readlane_b32 s22, v224, 32
	v_readlane_b32 s23, v224, 48
	s_nop 1
	v_mov_b32_e32 v225, s20
	v_add_f32_e32 v225, s21, v225
	v_add_f32_e32 v225, s22, v225
	v_add_f32_e32 v225, s23, v225
	v_mov_b32_e32 v226, 0x358637bd
	v_fmac_f32_e32 v226, 0x3a800000, v225
	v_rsq_f32_e32 v226, v226
	s_nop 0
	v_mul_f32_e32 v208, v208, v226
	v_mul_f32_e32 v209, v209, v226
	v_mul_f32_e32 v210, v210, v226
	v_mul_f32_e32 v211, v211, v226
	v_mul_f32_e32 v212, v212, v226
	v_mul_f32_e32 v213, v213, v226
	v_mul_f32_e32 v214, v214, v226
	v_mul_f32_e32 v215, v215, v226
	v_mul_f32_e32 v216, v216, v226
	v_mul_f32_e32 v217, v217, v226
	v_mul_f32_e32 v218, v218, v226
	v_mul_f32_e32 v219, v219, v226
	v_mul_f32_e32 v220, v220, v226
	v_mul_f32_e32 v221, v221, v226
	v_mul_f32_e32 v222, v222, v226
	v_mul_f32_e32 v223, v223, v226
	v_fmac_f32_e32 v128, v208, v56
	v_fmac_f32_e32 v129, v209, v57
	v_fmac_f32_e32 v130, v210, v58
	v_fmac_f32_e32 v131, v211, v59
	v_fmac_f32_e32 v132, v212, v60
	v_fmac_f32_e32 v133, v213, v61
	v_fmac_f32_e32 v134, v214, v62
	v_fmac_f32_e32 v135, v215, v63
	v_fmac_f32_e32 v136, v216, v64
	v_fmac_f32_e32 v137, v217, v65
	v_fmac_f32_e32 v138, v218, v66
	v_fmac_f32_e32 v139, v219, v67
	v_fmac_f32_e32 v140, v220, v68
	v_fmac_f32_e32 v141, v221, v69
	v_fmac_f32_e32 v142, v222, v70
	v_fmac_f32_e32 v143, v223, v71
	global_store_dwordx4 v1, v[128:131], s[8:9] offset:0
	global_store_dwordx4 v1, v[132:135], s[8:9] offset:16
	global_store_dwordx4 v1, v[136:139], s[8:9] offset:2048
	global_store_dwordx4 v1, v[140:143], s[8:9] offset:2064
	s_add_u32 s8, s8, 0x1000
	s_addc_u32 s9, s9, 0
	global_load_dwordx4 v[128:131], v1, s[6:7] offset:0
	global_load_dwordx4 v[132:135], v1, s[6:7] offset:16
	global_load_dwordx4 v[136:139], v1, s[6:7] offset:2048
	global_load_dwordx4 v[140:143], v1, s[6:7] offset:2064
	global_load_dwordx4 v[144:147], v2, s[10:11]
	global_load_dwordx4 v[148:151], v2, s[10:11] offset:1024
	global_load_dwordx4 v[152:155], v2, s[12:13]
	global_load_dwordx4 v[156:159], v2, s[12:13] offset:1024
	s_add_u32 s6, s6, 0x1000
	s_addc_u32 s7, s7, 0
	s_add_u32 s10, s10, 0x800
	s_addc_u32 s11, s11, 0
	s_add_u32 s12, s12, 0x800
	s_addc_u32 s13, s13, 0
	s_waitcnt vmcnt(24)
; DI float shx(float v, int mask) { const int l = olane(); return __builtin_bit_cast(float, __builtin_amdgcn_ds_bpermute(((l ^ mask) & 63) << 2, __builtin_bit_cast(int, v))); }
; DI void row_phase(const bf16_t* msrc, const float* xsrc, float* xdst, const float* g_post, const float* g_next, bf16_t* hdst, const int gw) {
;     ...
;                 for (int j = 0; j < 4; ++j) { const u32x2 mw = *(const u32x2*)(msrc + (size_t)(rowb + r) * DM + lane * 4 + 256 * j);
;                     mv[r][j] = (f32x4){__uint_as_float(mw[0] << 16), __uint_as_float(mw[0] & 0xffff0000u), __uint_as_float(mw[1] << 16), __uint_as_float(mw[1] & 0xffff0000u)}; }
;             float ss[RB];
; #pragma unroll
;             for (int r = 0; r < RB; ++r) { ss[r] = 0.f;
; #pragma unroll
;                 for (int j = 0; j < 4; ++j) ss[r] += mv[r][j][0] * mv[r][j][0] + mv[r][j][1] * mv[r][j][1] + mv[r][j][2] * mv[r][j][2] + mv[r][j][3] * mv[r][j][3]; }
; #pragma unroll
;             for (int o = 32; o >= 1; o >>= 1)
; #pragma unroll
;                 for (int r = 0; r < RB; ++r) ss[r] += shx(ss[r], o);
; #pragma unroll
;             for (int j = 0; j < 4; ++j) { const f32x4 g = *(const f32x4*)(g_post + lane * 4 + 256 * j);
; #pragma unroll
;                 for (int r = 0; r < RB; ++r) { const float r1 = rsqrtf(ss[r] * (1.f / DM) + EPS); xv[r][j] = xv[r][j] + mv[r][j] * r1 * g; *(f32x4*)(xdst + (size_t)(rowb + r) * DM + lane * 4 + 256 * j) = xv[r][j]; } }
	v_lshlrev_b32_e32 v208, 16, v176
	v_and_b32_e32 v209, 0xffff0000, v176
	v_lshlrev_b32_e32 v210, 16, v177
	v_and_b32_e32 v211, 0xffff0000, v177
	v_lshlrev_b32_e32 v212, 16, v178
	v_and_b32_e32 v213, 0xffff0000, v178
	v_lshlrev_b32_e32 v214, 16, v179
	v_and_b32_e32 v215, 0xffff0000, v179
	v_lshlrev_b32_e32 v216, 16, v180
	v_and_b32_e32 v217, 0xffff0000, v180
	v_lshlrev_b32_e32 v218, 16, v181
	v_and_b32_e32 v219, 0xffff0000, v181
	v_lshlrev_b32_e32 v220, 16, v182
	v_and_b32_e32 v221, 0xffff0000, v182
	v_lshlrev_b32_e32 v222, 16, v183
	v_and_b32_e32 v223, 0xffff0000, v183
	v_mul_f32_e32 v224, v208, v208
	v_fmac_f32_e32 v224, v209, v209
	v_fmac_f32_e32 v224, v210, v210
	v_fmac_f32_e32 v224, v211, v211
	v_fmac_f32_e32 v224, v212, v212
	v_fmac_f32_e32 v224, v213, v213
	v_fmac_f32_e32 v224, v214, v214
	v_fmac_f32_e32 v224, v215, v215
	v_fmac_f32_e32 v224, v216, v216
	v_fmac_f32_e32 v224, v217, v217
	v_fmac_f32_e32 v224, v218, v218
	v_fmac_f32_e32 v224, v219, v219
	v_fmac_f32_e32 v224, v220, v220
	v_fmac_f32_e32 v224, v221, v221
	v_fmac_f32_e32 v224, v222, v222
	v_fmac_f32_e32 v224, v223, v223
	s_nop 1
	v_add_f32_dpp v224, v224, v224 quad_perm:[1,0,3,2] row_mask:0xf bank_mask:0xf
	s_nop 1
	v_add_f32_dpp v224, v224, v224 quad_perm:[2,3,0,1] row_mask:0xf bank_mask:0xf
	s_nop 1
	v_add_f32_dpp v224, v224, v224 row_ror:4 row_mask:0xf bank_mask:0xf
	s_nop 1
	v_add_f32_dpp v224, v224, v224 row_ror:8 row_mask:0xf bank_mask:0xf
	s_nop 1
	v_readlane_b32 s20, v224, 0
	v_readlane_b32 s21, v224, 16
	v_readlane_b32 s22, v224, 32
	v_readlane_b32 s23, v224, 48
	s_nop 1
	v_mov_b32_e32 v225, s20
	v_add_f32_e32 v225, s21, v225
	v_add_f32_e32 v225, s22, v225
	v_add_f32_e32 v225, s23, v225
	v_mov_b32_e32 v226, 0x358637bd
	v_fmac_f32_e32 v226, 0x3a800000, v225
	v_rsq_f32_e32 v226, v226
	s_nop 0
	v_mul_f32_e32 v208, v208, v226
	v_mul_f32_e32 v209, v209, v226
	v_mul_f32_e32 v210, v210, v226
	v_mul_f32_e32 v211, v211, v226
	v_mul_f32_e32 v212, v212, v226
	v_mul_f32_e32 v213, v213, v226
	v_mul_f32_e32 v214, v214, v226
	v_mul_f32_e32 v215, v215, v226
	v_mul_f32_e32 v216, v216, v226
	v_mul_f32_e32 v217, v217, v226
	v_mul_f32_e32 v218, v218, v226
	v_mul_f32_e32 v219, v219, v226
	v_mul_f32_e32 v220, v220, v226
	v_mul_f32_e32 v221, v221, v226
	v_mul_f32_e32 v222, v222, v226
	v_mul_f32_e32 v223, v223, v226
	v_fmac_f32_e32 v160, v208, v40
	v_fmac_f32_e32 v161, v209, v41
	v_fmac_f32_e32 v162, v210, v42
	v_fmac_f32_e32 v163, v211, v43
	v_fmac_f32_e32 v164, v212, v44
	v_fmac_f32_e32 v165, v213, v45
	v_fmac_f32_e32 v166, v214, v46
	v_fmac_f32_e32 v167, v215, v47
	v_fmac_f32_e32 v168, v216, v48
	v_fmac_f32_e32 v169, v217, v49
	v_fmac_f32_e32 v170, v218, v50
	v_fmac_f32_e32 v171, v219, v51
	v_fmac_f32_e32 v172, v220, v52
	v_fmac_f32_e32 v173, v221, v53
	v_fmac_f32_e32 v174, v222, v54
	v_fmac_f32_e32 v175, v223, v55
	v_lshlrev_b32_e32 v208, 16, v184
	v_and_b32_e32 v209, 0xffff0000, v184
	v_lshlrev_b32_e32 v210, 16, v185
	v_and_b32_e32 v211, 0xffff0000, v185
	v_lshlrev_b32_e32 v212, 16, v186
	v_and_b32_e32 v213, 0xffff0000, v186
	v_lshlrev_b32_e32 v214, 16, v187
	v_and_b32_e32 v215, 0xffff0000, v187
	v_lshlrev_b32_e32 v216, 16, v188
	v_and_b32_e32 v217, 0xffff0000, v188
	v_lshlrev_b32_e32 v218, 16, v189
	v_and_b32_e32 v219, 0xffff0000, v189
	v_lshlrev_b32_e32 v220, 16, v190
	v_and_b32_e32 v221, 0xffff0000, v190
	v_lshlrev_b32_e32 v222, 16, v191
	v_and_b32_e32 v223, 0xffff0000, v191
	v_mul_f32_e32 v224, v208, v208
	v_fmac_f32_e32 v224, v209, v209
	v_fmac_f32_e32 v224, v210, v210
	v_fmac_f32_e32 v224, v211, v211
	v_fmac_f32_e32 v224, v212, v212
	v_fmac_f32_e32 v224, v213, v213
	v_fmac_f32_e32 v224, v214, v214
	v_fmac_f32_e32 v224, v215, v215
	v_fmac_f32_e32 v224, v216, v216
	v_fmac_f32_e32 v224, v217, v217
	v_fmac_f32_e32 v224, v218, v218
	v_fmac_f32_e32 v224, v219, v219
	v_fmac_f32_e32 v224, v220, v220
	v_fmac_f32_e32 v224, v221, v221
	v_fmac_f32_e32 v224, v222, v222
	v_fmac_f32_e32 v224, v223, v223
	s_nop 1
	v_add_f32_dpp v224, v224, v224 quad_perm:[1,0,3,2] row_mask:0xf bank_mask:0xf
	s_nop 1
	v_add_f32_dpp v224, v224, v224 quad_perm:[2,3,0,1] row_mask:0xf bank_mask:0xf
	s_nop 1
	v_add_f32_dpp v224, v224, v224 row_ror:4 row_mask:0xf bank_mask:0xf
	s_nop 1
	v_add_f32_dpp v224, v224, v224 row_ror:8 row_mask:0xf bank_mask:0xf
	s_nop 1
	v_readlane_b32 s20, v224, 0
	v_readlane_b32 s21, v224, 16
	v_readlane_b32 s22, v224, 32
	v_readlane_b32 s23, v224, 48
	s_nop 1
	v_mov_b32_e32 v225, s20
	v_add_f32_e32 v225, s21, v225
	v_add_f32_e32 v225, s22, v225
	v_add_f32_e32 v225, s23, v225
	v_mov_b32_e32 v226, 0x358637bd
	v_fmac_f32_e32 v226, 0x3a800000, v225
	v_rsq_f32_e32 v226, v226
	s_nop 0
	v_mul_f32_e32 v208, v208, v226
	v_mul_f32_e32 v209, v209, v226
	v_mul_f32_e32 v210, v210, v226
	v_mul_f32_e32 v211, v211, v226
	v_mul_f32_e32 v212, v212, v226
	v_mul_f32_e32 v213, v213, v226
	v_mul_f32_e32 v214, v214, v226
	v_mul_f32_e32 v215, v215, v226
	v_mul_f32_e32 v216, v216, v226
	v_mul_f32_e32 v217, v217, v226
	v_mul_f32_e32 v218, v218, v226
	v_mul_f32_e32 v219, v219, v226
	v_mul_f32_e32 v220, v220, v226
	v_mul_f32_e32 v221, v221, v226
	v_mul_f32_e32 v222, v222, v226
	v_mul_f32_e32 v223, v223, v226
	v_fmac_f32_e32 v160, v208, v56
	v_fmac_f32_e32 v161, v209, v57
	v_fmac_f32_e32 v162, v210, v58
	v_fmac_f32_e32 v163, v211, v59
	v_fmac_f32_e32 v164, v212, v60
	v_fmac_f32_e32 v165, v213, v61
	v_fmac_f32_e32 v166, v214, v62
	v_fmac_f32_e32 v167, v215, v63
	v_fmac_f32_e32 v168, v216, v64
	v_fmac_f32_e32 v169, v217, v65
	v_fmac_f32_e32 v170, v218, v66
	v_fmac_f32_e32 v171, v219, v67
	v_fmac_f32_e32 v172, v220, v68
	v_fmac_f32_e32 v173, v221, v69
	v_fmac_f32_e32 v174, v222, v70
	v_fmac_f32_e32 v175, v223, v71
	global_store_dwordx4 v1, v[160:163], s[8:9] offset:0
	global_store_dwordx4 v1, v[164:167], s[8:9] offset:16
	global_store_dwordx4 v1, v[168:171], s[8:9] offset:2048
	global_store_dwordx4 v1, v[172:175], s[8:9] offset:2064
	s_add_u32 s8, s8, 0x1000
	s_addc_u32 s9, s9, 0
	global_load_dwordx4 v[160:163], v1, s[6:7] offset:0
	global_load_dwordx4 v[164:167], v1, s[6:7] offset:16
	global_load_dwordx4 v[168:171], v1, s[6:7] offset:2048
	global_load_dwordx4 v[172:175], v1, s[6:7] offset:2064
	global_load_dwordx4 v[176:179], v2, s[10:11]
	global_load_dwordx4 v[180:183], v2, s[10:11] offset:1024
	global_load_dwordx4 v[184:187], v2, s[12:13]
	global_load_dwordx4 v[188:191], v2, s[12:13] offset:1024
	s_add_u32 s6, s6, 0x1000
	s_addc_u32 s7, s7, 0
	s_add_u32 s10, s10, 0x800
	s_addc_u32 s11, s11, 0
	s_add_u32 s12, s12, 0x800
	s_addc_u32 s13, s13, 0
	s_waitcnt vmcnt(24)
; DI float shx(float v, int mask) { const int l = olane(); return __builtin_bit_cast(float, __builtin_amdgcn_ds_bpermute(((l ^ mask) & 63) << 2, __builtin_bit_cast(int, v))); }
; DI void row_phase(const bf16_t* msrc, const float* xsrc, float* xdst, const float* g_post, const float* g_next, bf16_t* hdst, const int gw) {
;     ...
;                 for (int j = 0; j < 4; ++j) { const u32x2 mw = *(const u32x2*)(msrc + (size_t)(rowb + r) * DM + lane * 4 + 256 * j);
;                     mv[r][j] = (f32x4){__uint_as_float(mw[0] << 16), __uint_as_float(mw[0] & 0xffff0000u), __uint_as_float(mw[1] << 16), __uint_as_float(mw[1] & 0xffff0000u)}; }
;             float ss[RB];
; #pragma unroll
;             for (int r = 0; r < RB; ++r) { ss[r] = 0.f;
; #pragma unroll
;                 for (int j = 0; j < 4; ++j) ss[r] += mv[r][j][0] * mv[r][j][0] + mv[r][j][1] * mv[r][j][1] + mv[r][j][2] * mv[r][j][2] + mv[r][j][3] * mv[r][j][3]; }
; #pragma unroll
;             for (int o = 32; o >= 1; o >>= 1)
; #pragma unroll
;                 for (int r = 0; r < RB; ++r) ss[r] += shx(ss[r], o);
; #pragma unroll
;             for (int j = 0; j < 4; ++j) { const f32x4 g = *(const f32x4*)(g_post + lane * 4 + 256 * j);
; #pragma unroll
;                 for (int r = 0; r < RB; ++r) { const float r1 = rsqrtf(ss[r] * (1.f / DM) + EPS); xv[r][j] = xv[r][j] + mv[r][j] * r1 * g; *(f32x4*)(xdst + (size_t)(rowb + r) * DM + lane * 4 + 256 * j) = xv[r][j]; } }
	v_lshlrev_b32_e32 v208, 16, v112
	v_and_b32_e32 v209, 0xffff0000, v112
	v_lshlrev_b32_e32 v210, 16, v113
	v_and_b32_e32 v211, 0xffff0000, v113
	v_lshlrev_b32_e32 v212, 16, v114
	v_and_b32_e32 v213, 0xffff0000, v114
	v_lshlrev_b32_e32 v214, 16, v115
	v_and_b32_e32 v215, 0xffff0000, v115
	v_lshlrev_b32_e32 v216, 16, v116
	v_and_b32_e32 v217, 0xffff0000, v116
	v_lshlrev_b32_e32 v218, 16, v117
	v_and_b32_e32 v219, 0xffff0000, v117
	v_lshlrev_b32_e32 v220, 16, v118
	v_and_b32_e32 v221, 0xffff0000, v118
	v_lshlrev_b32_e32 v222, 16, v119
	v_and_b32_e32 v223, 0xffff0000, v119
	v_mul_f32_e32 v224, v208, v208
	v_fmac_f32_e32 v224, v209, v209
	v_fmac_f32_e32 v224, v210, v210
	v_fmac_f32_e32 v224, v211, v211
	v_fmac_f32_e32 v224, v212, v212
	v_fmac_f32_e32 v224, v213, v213
	v_fmac_f32_e32 v224, v214, v214
	v_fmac_f32_e32 v224, v215, v215
	v_fmac_f32_e32 v224, v216, v216
	v_fmac_f32_e32 v224, v217, v217
	v_fmac_f32_e32 v224, v218, v218
	v_fmac_f32_e32 v224, v219, v219
	v_fmac_f32_e32 v224, v220, v220
	v_fmac_f32_e32 v224, v221, v221
	v_fmac_f32_e32 v224, v222, v222
	v_fmac_f32_e32 v224, v223, v223
	s_nop 1
	v_add_f32_dpp v224, v224, v224 quad_perm:[1,0,3,2] row_mask:0xf bank_mask:0xf
	s_nop 1
	v_add_f32_dpp v224, v224, v224 quad_perm:[2,3,0,1] row_mask:0xf bank_mask:0xf
	s_nop 1
	v_add_f32_dpp v224, v224, v224 row_ror:4 row_mask:0xf bank_mask:0xf
	s_nop 1
	v_add_f32_dpp v224, v224, v224 row_ror:8 row_mask:0xf bank_mask:0xf
	s_nop 1
	v_readlane_b32 s20, v224, 0
	v_readlane_b32 s21, v224, 16
	v_readlane_b32 s22, v224, 32
	v_readlane_b32 s23, v224, 48
	s_nop 1
	v_mov_b32_e32 v225, s20
	v_add_f32_e32 v225, s21, v225
	v_add_f32_e32 v225, s22, v225
	v_add_f32_e32 v225, s23, v225
	v_mov_b32_e32 v226, 0x358637bd
	v_fmac_f32_e32 v226, 0x3a800000, v225
	v_rsq_f32_e32 v226, v226
	s_nop 0
	v_mul_f32_e32 v208, v208, v226
	v_mul_f32_e32 v209, v209, v226
	v_mul_f32_e32 v210, v210, v226
	v_mul_f32_e32 v211, v211, v226
	v_mul_f32_e32 v212, v212, v226
	v_mul_f32_e32 v213, v213, v226
	v_mul_f32_e32 v214, v214, v226
	v_mul_f32_e32 v215, v215, v226
	v_mul_f32_e32 v216, v216, v226
	v_mul_f32_e32 v217, v217, v226
	v_mul_f32_e32 v218, v218, v226
	v_mul_f32_e32 v219, v219, v226
	v_mul_f32_e32 v220, v220, v226
	v_mul_f32_e32 v221, v221, v226
	v_mul_f32_e32 v222, v222, v226
	v_mul_f32_e32 v223, v223, v226
	v_fmac_f32_e32 v96, v208, v40
	v_fmac_f32_e32 v97, v209, v41
	v_fmac_f32_e32 v98, v210, v42
	v_fmac_f32_e32 v99, v211, v43
	v_fmac_f32_e32 v100, v212, v44
	v_fmac_f32_e32 v101, v213, v45
	v_fmac_f32_e32 v102, v214, v46
	v_fmac_f32_e32 v103, v215, v47
	v_fmac_f32_e32 v104, v216, v48
	v_fmac_f32_e32 v105, v217, v49
	v_fmac_f32_e32 v106, v218, v50
	v_fmac_f32_e32 v107, v219, v51
	v_fmac_f32_e32 v108, v220, v52
	v_fmac_f32_e32 v109, v221, v53
	v_fmac_f32_e32 v110, v222, v54
	v_fmac_f32_e32 v111, v223, v55
	v_lshlrev_b32_e32 v208, 16, v120
	v_and_b32_e32 v209, 0xffff0000, v120
	v_lshlrev_b32_e32 v210, 16, v121
	v_and_b32_e32 v211, 0xffff0000, v121
	v_lshlrev_b32_e32 v212, 16, v122
	v_and_b32_e32 v213, 0xffff0000, v122
	v_lshlrev_b32_e32 v214, 16, v123
	v_and_b32_e32 v215, 0xffff0000, v123
	v_lshlrev_b32_e32 v216, 16, v124
	v_and_b32_e32 v217, 0xffff0000, v124
	v_lshlrev_b32_e32 v218, 16, v125
	v_and_b32_e32 v219, 0xffff0000, v125
	v_lshlrev_b32_e32 v220, 16, v126
	v_and_b32_e32 v221, 0xffff0000, v126
	v_lshlrev_b32_e32 v222, 16, v127
	v_and_b32_e32 v223, 0xffff0000, v127
	v_mul_f32_e32 v224, v208, v208
	v_fmac_f32_e32 v224, v209, v209
	v_fmac_f32_e32 v224, v210, v210
	v_fmac_f32_e32 v224, v211, v211
	v_fmac_f32_e32 v224, v212, v212
	v_fmac_f32_e32 v224, v213, v213
	v_fmac_f32_e32 v224, v214, v214
	v_fmac_f32_e32 v224, v215, v215
	v_fmac_f32_e32 v224, v216, v216
	v_fmac_f32_e32 v224, v217, v217
	v_fmac_f32_e32 v224, v218, v218
	v_fmac_f32_e32 v224, v219, v219
	v_fmac_f32_e32 v224, v220, v220
	v_fmac_f32_e32 v224, v221, v221
	v_fmac_f32_e32 v224, v222, v222
	v_fmac_f32_e32 v224, v223, v223
	s_nop 1
	v_add_f32_dpp v224, v224, v224 quad_perm:[1,0,3,2] row_mask:0xf bank_mask:0xf
	s_nop 1
	v_add_f32_dpp v224, v224, v224 quad_perm:[2,3,0,1] row_mask:0xf bank_mask:0xf
	s_nop 1
	v_add_f32_dpp v224, v224, v224 row_ror:4 row_mask:0xf bank_mask:0xf
	s_nop 1
	v_add_f32_dpp v224, v224, v224 row_ror:8 row_mask:0xf bank_mask:0xf
	s_nop 1
	v_readlane_b32 s20, v224, 0
	v_readlane_b32 s21, v224, 16
	v_readlane_b32 s22, v224, 32
	v_readlane_b32 s23, v224, 48
	s_nop 1
	v_mov_b32_e32 v225, s20
	v_add_f32_e32 v225, s21, v225
	v_add_f32_e32 v225, s22, v225
	v_add_f32_e32 v225, s23, v225
	v_mov_b32_e32 v226, 0x358637bd
	v_fmac_f32_e32 v226, 0x3a800000, v225
	v_rsq_f32_e32 v226, v226
	s_nop 0
	v_mul_f32_e32 v208, v208, v226
	v_mul_f32_e32 v209, v209, v226
	v_mul_f32_e32 v210, v210, v226
	v_mul_f32_e32 v211, v211, v226
	v_mul_f32_e32 v212, v212, v226
	v_mul_f32_e32 v213, v213, v226
	v_mul_f32_e32 v214, v214, v226
	v_mul_f32_e32 v215, v215, v226
	v_mul_f32_e32 v216, v216, v226
	v_mul_f32_e32 v217, v217, v226
	v_mul_f32_e32 v218, v218, v226
	v_mul_f32_e32 v219, v219, v226
	v_mul_f32_e32 v220, v220, v226
	v_mul_f32_e32 v221, v221, v226
	v_mul_f32_e32 v222, v222, v226
	v_mul_f32_e32 v223, v223, v226
	v_fmac_f32_e32 v96, v208, v56
	v_fmac_f32_e32 v97, v209, v57
	v_fmac_f32_e32 v98, v210, v58
	v_fmac_f32_e32 v99, v211, v59
	v_fmac_f32_e32 v100, v212, v60
	v_fmac_f32_e32 v101, v213, v61
	v_fmac_f32_e32 v102, v214, v62
	v_fmac_f32_e32 v103, v215, v63
	v_fmac_f32_e32 v104, v216, v64
	v_fmac_f32_e32 v105, v217, v65
	v_fmac_f32_e32 v106, v218, v66
	v_fmac_f32_e32 v107, v219, v67
	v_fmac_f32_e32 v108, v220, v68
	v_fmac_f32_e32 v109, v221, v69
	v_fmac_f32_e32 v110, v222, v70
	v_fmac_f32_e32 v111, v223, v71
	global_store_dwordx4 v1, v[96:99], s[8:9] offset:0
	global_store_dwordx4 v1, v[100:103], s[8:9] offset:16
	global_store_dwordx4 v1, v[104:107], s[8:9] offset:2048
	global_store_dwordx4 v1, v[108:111], s[8:9] offset:2064
	s_add_u32 s8, s8, 0x1000
	s_addc_u32 s9, s9, 0
	global_load_dwordx4 v[96:99], v1, s[6:7] offset:0
	global_load_dwordx4 v[100:103], v1, s[6:7] offset:16
	global_load_dwordx4 v[104:107], v1, s[6:7] offset:2048
	global_load_dwordx4 v[108:111], v1, s[6:7] offset:2064
	global_load_dwordx4 v[112:115], v2, s[10:11]
	global_load_dwordx4 v[116:119], v2, s[10:11] offset:1024
	global_load_dwordx4 v[120:123], v2, s[12:13]
	global_load_dwordx4 v[124:127], v2, s[12:13] offset:1024
	s_add_u32 s6, s6, 0x1000
	s_addc_u32 s7, s7, 0
	s_add_u32 s10, s10, 0x800
	s_addc_u32 s11, s11, 0
	s_add_u32 s12, s12, 0x800
	s_addc_u32 s13, s13, 0
	s_waitcnt vmcnt(24)
; DI float shx(float v, int mask) { const int l = olane(); return __builtin_bit_cast(float, __builtin_amdgcn_ds_bpermute(((l ^ mask) & 63) << 2, __builtin_bit_cast(int, v))); }
; DI void row_phase(const bf16_t* msrc, const float* xsrc, float* xdst, const float* g_post, const float* g_next, bf16_t* hdst, const int gw) {
;     ...
;                 for (int j = 0; j < 4; ++j) { const u32x2 mw = *(const u32x2*)(msrc + (size_t)(rowb + r) * DM + lane * 4 + 256 * j);
;                     mv[r][j] = (f32x4){__uint_as_float(mw[0] << 16), __uint_as_float(mw[0] & 0xffff0000u), __uint_as_float(mw[1] << 16), __uint_as_float(mw[1] & 0xffff0000u)}; }
;             float ss[RB];
; #pragma unroll
;             for (int r = 0; r < RB; ++r) { ss[r] = 0.f;
; #pragma unroll
;                 for (int j = 0; j < 4; ++j) ss[r] += mv[r][j][0] * mv[r][j][0] + mv[r][j][1] * mv[r][j][1] + mv[r][j][2] * mv[r][j][2] + mv[r][j][3] * mv[r][j][3]; }
; #pragma unroll
;             for (int o = 32; o >= 1; o >>= 1)
; #pragma unroll
;                 for (int r = 0; r < RB; ++r) ss[r] += shx(ss[r], o);
; #pragma unroll
;             for (int j = 0; j < 4; ++j) { const f32x4 g = *(const f32x4*)(g_post + lane * 4 + 256 * j);
; #pragma unroll
;                 for (int r = 0; r < RB; ++r) { const float r1 = rsqrtf(ss[r] * (1.f / DM) + EPS); xv[r][j] = xv[r][j] + mv[r][j] * r1 * g; *(f32x4*)(xdst + (size_t)(rowb + r) * DM + lane * 4 + 256 * j) = xv[r][j]; } }
	v_lshlrev_b32_e32 v208, 16, v144
	v_and_b32_e32 v209, 0xffff0000, v144
	v_lshlrev_b32_e32 v210, 16, v145
	v_and_b32_e32 v211, 0xffff0000, v145
	v_lshlrev_b32_e32 v212, 16, v146
	v_and_b32_e32 v213, 0xffff0000, v146
	v_lshlrev_b32_e32 v214, 16, v147
	v_and_b32_e32 v215, 0xffff0000, v147
	v_lshlrev_b32_e32 v216, 16, v148
	v_and_b32_e32 v217, 0xffff0000, v148
	v_lshlrev_b32_e32 v218, 16, v149
	v_and_b32_e32 v219, 0xffff0000, v149
	v_lshlrev_b32_e32 v220, 16, v150
	v_and_b32_e32 v221, 0xffff0000, v150
	v_lshlrev_b32_e32 v222, 16, v151
	v_and_b32_e32 v223, 0xffff0000, v151
	v_mul_f32_e32 v224, v208, v208
	v_fmac_f32_e32 v224, v209, v209
	v_fmac_f32_e32 v224, v210, v210
	v_fmac_f32_e32 v224, v211, v211
	v_fmac_f32_e32 v224, v212, v212
	v_fmac_f32_e32 v224, v213, v213
	v_fmac_f32_e32 v224, v214, v214
	v_fmac_f32_e32 v224, v215, v215
	v_fmac_f32_e32 v224, v216, v216
	v_fmac_f32_e32 v224, v217, v217
	v_fmac_f32_e32 v224, v218, v218
	v_fmac_f32_e32 v224, v219, v219
	v_fmac_f32_e32 v224, v220, v220
	v_fmac_f32_e32 v224, v221, v221
	v_fmac_f32_e32 v224, v222, v222
	v_fmac_f32_e32 v224, v223, v223
	s_nop 1
	v_add_f32_dpp v224, v224, v224 quad_perm:[1,0,3,2] row_mask:0xf bank_mask:0xf
	s_nop 1
	v_add_f32_dpp v224, v224, v224 quad_perm:[2,3,0,1] row_mask:0xf bank_mask:0xf
	s_nop 1
	v_add_f32_dpp v224, v224, v224 row_ror:4 row_mask:0xf bank_mask:0xf
	s_nop 1
	v_add_f32_dpp v224, v224, v224 row_ror:8 row_mask:0xf bank_mask:0xf
	s_nop 1
	v_readlane_b32 s20, v224, 0
	v_readlane_b32 s21, v224, 16
	v_readlane_b32 s22, v224, 32
	v_readlane_b32 s23, v224, 48
	s_nop 1
	v_mov_b32_e32 v225, s20
	v_add_f32_e32 v225, s21, v225
	v_add_f32_e32 v225, s22, v225
	v_add_f32_e32 v225, s23, v225
	v_mov_b32_e32 v226, 0x358637bd
	v_fmac_f32_e32 v226, 0x3a800000, v225
	v_rsq_f32_e32 v226, v226
	s_nop 0
	v_mul_f32_e32 v208, v208, v226
	v_mul_f32_e32 v209, v209, v226
	v_mul_f32_e32 v210, v210, v226
	v_mul_f32_e32 v211, v211, v226
	v_mul_f32_e32 v212, v212, v226
	v_mul_f32_e32 v213, v213, v226
	v_mul_f32_e32 v214, v214, v226
	v_mul_f32_e32 v215, v215, v226
	v_mul_f32_e32 v216, v216, v226
	v_mul_f32_e32 v217, v217, v226
	v_mul_f32_e32 v218, v218, v226
	v_mul_f32_e32 v219, v219, v226
	v_mul_f32_e32 v220, v220, v226
	v_mul_f32_e32 v221, v221, v226
	v_mul_f32_e32 v222, v222, v226
	v_mul_f32_e32 v223, v223, v226
	v_fmac_f32_e32 v128, v208, v40
	v_fmac_f32_e32 v129, v209, v41
	v_fmac_f32_e32 v130, v210, v42
	v_fmac_f32_e32 v131, v211, v43
	v_fmac_f32_e32 v132, v212, v44
	v_fmac_f32_e32 v133, v213, v45
	v_fmac_f32_e32 v134, v214, v46
	v_fmac_f32_e32 v135, v215, v47
	v_fmac_f32_e32 v136, v216, v48
	v_fmac_f32_e32 v137, v217, v49
	v_fmac_f32_e32 v138, v218, v50
	v_fmac_f32_e32 v139, v219, v51
	v_fmac_f32_e32 v140, v220, v52
	v_fmac_f32_e32 v141, v221, v53
	v_fmac_f32_e32 v142, v222, v54
	v_fmac_f32_e32 v143, v223, v55
	v_lshlrev_b32_e32 v208, 16, v152
	v_and_b32_e32 v209, 0xffff0000, v152
	v_lshlrev_b32_e32 v210, 16, v153
	v_and_b32_e32 v211, 0xffff0000, v153
	v_lshlrev_b32_e32 v212, 16, v154
	v_and_b32_e32 v213, 0xffff0000, v154
	v_lshlrev_b32_e32 v214, 16, v155
	v_and_b32_e32 v215, 0xffff0000, v155
	v_lshlrev_b32_e32 v216, 16, v156
	v_and_b32_e32 v217, 0xffff0000, v156
	v_lshlrev_b32_e32 v218, 16, v157
	v_and_b32_e32 v219, 0xffff0000, v157
	v_lshlrev_b32_e32 v220, 16, v158
	v_and_b32_e32 v221, 0xffff0000, v158
	v_lshlrev_b32_e32 v222, 16, v159
	v_and_b32_e32 v223, 0xffff0000, v159
	v_mul_f32_e32 v224, v208, v208
	v_fmac_f32_e32 v224, v209, v209
	v_fmac_f32_e32 v224, v210, v210
	v_fmac_f32_e32 v224, v211, v211
	v_fmac_f32_e32 v224, v212, v212
	v_fmac_f32_e32 v224, v213, v213
	v_fmac_f32_e32 v224, v214, v214
	v_fmac_f32_e32 v224, v215, v215
	v_fmac_f32_e32 v224, v216, v216
	v_fmac_f32_e32 v224, v217, v217
	v_fmac_f32_e32 v224, v218, v218
	v_fmac_f32_e32 v224, v219, v219
	v_fmac_f32_e32 v224, v220, v220
	v_fmac_f32_e32 v224, v221, v221
	v_fmac_f32_e32 v224, v222, v222
	v_fmac_f32_e32 v224, v223, v223
	s_nop 1
	v_add_f32_dpp v224, v224, v224 quad_perm:[1,0,3,2] row_mask:0xf bank_mask:0xf
	s_nop 1
	v_add_f32_dpp v224, v224, v224 quad_perm:[2,3,0,1] row_mask:0xf bank_mask:0xf
	s_nop 1
	v_add_f32_dpp v224, v224, v224 row_ror:4 row_mask:0xf bank_mask:0xf
	s_nop 1
	v_add_f32_dpp v224, v224, v224 row_ror:8 row_mask:0xf bank_mask:0xf
	s_nop 1
	v_readlane_b32 s20, v224, 0
	v_readlane_b32 s21, v224, 16
	v_readlane_b32 s22, v224, 32
	v_readlane_b32 s23, v224, 48
	s_nop 1
	v_mov_b32_e32 v225, s20
	v_add_f32_e32 v225, s21, v225
	v_add_f32_e32 v225, s22, v225
	v_add_f32_e32 v225, s23, v225
	v_mov_b32_e32 v226, 0x358637bd
	v_fmac_f32_e32 v226, 0x3a800000, v225
	v_rsq_f32_e32 v226, v226
	s_nop 0
	v_mul_f32_e32 v208, v208, v226
	v_mul_f32_e32 v209, v209, v226
	v_mul_f32_e32 v210, v210, v226
	v_mul_f32_e32 v211, v211, v226
	v_mul_f32_e32 v212, v212, v226
	v_mul_f32_e32 v213, v213, v226
	v_mul_f32_e32 v214, v214, v226
	v_mul_f32_e32 v215, v215, v226
	v_mul_f32_e32 v216, v216, v226
	v_mul_f32_e32 v217, v217, v226
	v_mul_f32_e32 v218, v218, v226
	v_mul_f32_e32 v219, v219, v226
	v_mul_f32_e32 v220, v220, v226
	v_mul_f32_e32 v221, v221, v226
	v_mul_f32_e32 v222, v222, v226
	v_mul_f32_e32 v223, v223, v226
	v_fmac_f32_e32 v128, v208, v56
	v_fmac_f32_e32 v129, v209, v57
	v_fmac_f32_e32 v130, v210, v58
	v_fmac_f32_e32 v131, v211, v59
	v_fmac_f32_e32 v132, v212, v60
	v_fmac_f32_e32 v133, v213, v61
	v_fmac_f32_e32 v134, v214, v62
	v_fmac_f32_e32 v135, v215, v63
	v_fmac_f32_e32 v136, v216, v64
	v_fmac_f32_e32 v137, v217, v65
	v_fmac_f32_e32 v138, v218, v66
	v_fmac_f32_e32 v139, v219, v67
	v_fmac_f32_e32 v140, v220, v68
	v_fmac_f32_e32 v141, v221, v69
	v_fmac_f32_e32 v142, v222, v70
	v_fmac_f32_e32 v143, v223, v71
	global_store_dwordx4 v1, v[128:131], s[8:9] offset:0
	global_store_dwordx4 v1, v[132:135], s[8:9] offset:16
	global_store_dwordx4 v1, v[136:139], s[8:9] offset:2048
	global_store_dwordx4 v1, v[140:143], s[8:9] offset:2064
	s_add_u32 s8, s8, 0x1000
	s_addc_u32 s9, s9, 0
	global_load_dwordx4 v[128:131], v1, s[6:7] offset:0
	global_load_dwordx4 v[132:135], v1, s[6:7] offset:16
	global_load_dwordx4 v[136:139], v1, s[6:7] offset:2048
	global_load_dwordx4 v[140:143], v1, s[6:7] offset:2064
	global_load_dwordx4 v[144:147], v2, s[10:11]
	global_load_dwordx4 v[148:151], v2, s[10:11] offset:1024
	global_load_dwordx4 v[152:155], v2, s[12:13]
	global_load_dwordx4 v[156:159], v2, s[12:13] offset:1024
	s_add_u32 s6, s6, 0x1000
	s_addc_u32 s7, s7, 0
	s_add_u32 s10, s10, 0x800
	s_addc_u32 s11, s11, 0
	s_add_u32 s12, s12, 0x800
	s_addc_u32 s13, s13, 0
	s_waitcnt vmcnt(24)
; DI float shx(float v, int mask) { const int l = olane(); return __builtin_bit_cast(float, __builtin_amdgcn_ds_bpermute(((l ^ mask) & 63) << 2, __builtin_bit_cast(int, v))); }
; DI void row_phase(const bf16_t* msrc, const float* xsrc, float* xdst, const float* g_post, const float* g_next, bf16_t* hdst, const int gw) {
;     ...
;                 for (int j = 0; j < 4; ++j) { const u32x2 mw = *(const u32x2*)(msrc + (size_t)(rowb + r) * DM + lane * 4 + 256 * j);
;                     mv[r][j] = (f32x4){__uint_as_float(mw[0] << 16), __uint_as_float(mw[0] & 0xffff0000u), __uint_as_float(mw[1] << 16), __uint_as_float(mw[1] & 0xffff0000u)}; }
;             float ss[RB];
; #pragma unroll
;             for (int r = 0; r < RB; ++r) { ss[r] = 0.f;
; #pragma unroll
;                 for (int j = 0; j < 4; ++j) ss[r] += mv[r][j][0] * mv[r][j][0] + mv[r][j][1] * mv[r][j][1] + mv[r][j][2] * mv[r][j][2] + mv[r][j][3] * mv[r][j][3]; }
; #pragma unroll
;             for (int o = 32; o >= 1; o >>= 1)
; #pragma unroll
;                 for (int r = 0; r < RB; ++r) ss[r] += shx(ss[r], o);
; #pragma unroll
;             for (int j = 0; j < 4; ++j) { const f32x4 g = *(const f32x4*)(g_post + lane * 4 + 256 * j);
; #pragma unroll
;                 for (int r = 0; r < RB; ++r) { const float r1 = rsqrtf(ss[r] * (1.f / DM) + EPS); xv[r][j] = xv[r][j] + mv[r][j] * r1 * g; *(f32x4*)(xdst + (size_t)(rowb + r) * DM + lane * 4 + 256 * j) = xv[r][j]; } }
	v_lshlrev_b32_e32 v208, 16, v176
	v_and_b32_e32 v209, 0xffff0000, v176
	v_lshlrev_b32_e32 v210, 16, v177
	v_and_b32_e32 v211, 0xffff0000, v177
	v_lshlrev_b32_e32 v212, 16, v178
	v_and_b32_e32 v213, 0xffff0000, v178
	v_lshlrev_b32_e32 v214, 16, v179
	v_and_b32_e32 v215, 0xffff0000, v179
	v_lshlrev_b32_e32 v216, 16, v180
	v_and_b32_e32 v217, 0xffff0000, v180
	v_lshlrev_b32_e32 v218, 16, v181
	v_and_b32_e32 v219, 0xffff0000, v181
	v_lshlrev_b32_e32 v220, 16, v182
	v_and_b32_e32 v221, 0xffff0000, v182
	v_lshlrev_b32_e32 v222, 16, v183
	v_and_b32_e32 v223, 0xffff0000, v183
	v_mul_f32_e32 v224, v208, v208
	v_fmac_f32_e32 v224, v209, v209
	v_fmac_f32_e32 v224, v210, v210
	v_fmac_f32_e32 v224, v211, v211
	v_fmac_f32_e32 v224, v212, v212
	v_fmac_f32_e32 v224, v213, v213
	v_fmac_f32_e32 v224, v214, v214
	v_fmac_f32_e32 v224, v215, v215
	v_fmac_f32_e32 v224, v216, v216
	v_fmac_f32_e32 v224, v217, v217
	v_fmac_f32_e32 v224, v218, v218
	v_fmac_f32_e32 v224, v219, v219
	v_fmac_f32_e32 v224, v220, v220
	v_fmac_f32_e32 v224, v221, v221
	v_fmac_f32_e32 v224, v222, v222
	v_fmac_f32_e32 v224, v223, v223
	s_nop 1
	v_add_f32_dpp v224, v224, v224 quad_perm:[1,0,3,2] row_mask:0xf bank_mask:0xf
	s_nop 1
	v_add_f32_dpp v224, v224, v224 quad_perm:[2,3,0,1] row_mask:0xf bank_mask:0xf
	s_nop 1
	v_add_f32_dpp v224, v224, v224 row_ror:4 row_mask:0xf bank_mask:0xf
	s_nop 1
	v_add_f32_dpp v224, v224, v224 row_ror:8 row_mask:0xf bank_mask:0xf
	s_nop 1
	v_readlane_b32 s20, v224, 0
	v_readlane_b32 s21, v224, 16
	v_readlane_b32 s22, v224, 32
	v_readlane_b32 s23, v224, 48
	s_nop 1
	v_mov_b32_e32 v225, s20
	v_add_f32_e32 v225, s21, v225
	v_add_f32_e32 v225, s22, v225
	v_add_f32_e32 v225, s23, v225
	v_mov_b32_e32 v226, 0x358637bd
	v_fmac_f32_e32 v226, 0x3a800000, v225
	v_rsq_f32_e32 v226, v226
	s_nop 0
	v_mul_f32_e32 v208, v208, v226
	v_mul_f32_e32 v209, v209, v226
	v_mul_f32_e32 v210, v210, v226
	v_mul_f32_e32 v211, v211, v226
	v_mul_f32_e32 v212, v212, v226
	v_mul_f32_e32 v213, v213, v226
	v_mul_f32_e32 v214, v214, v226
	v_mul_f32_e32 v215, v215, v226
	v_mul_f32_e32 v216, v216, v226
	v_mul_f32_e32 v217, v217, v226
	v_mul_f32_e32 v218, v218, v226
	v_mul_f32_e32 v219, v219, v226
	v_mul_f32_e32 v220, v220, v226
	v_mul_f32_e32 v221, v221, v226
	v_mul_f32_e32 v222, v222, v226
	v_mul_f32_e32 v223, v223, v226
	v_fmac_f32_e32 v160, v208, v40
	v_fmac_f32_e32 v161, v209, v41
	v_fmac_f32_e32 v162, v210, v42
	v_fmac_f32_e32 v163, v211, v43
	v_fmac_f32_e32 v164, v212, v44
	v_fmac_f32_e32 v165, v213, v45
	v_fmac_f32_e32 v166, v214, v46
	v_fmac_f32_e32 v167, v215, v47
	v_fmac_f32_e32 v168, v216, v48
	v_fmac_f32_e32 v169, v217, v49
	v_fmac_f32_e32 v170, v218, v50
	v_fmac_f32_e32 v171, v219, v51
	v_fmac_f32_e32 v172, v220, v52
	v_fmac_f32_e32 v173, v221, v53
	v_fmac_f32_e32 v174, v222, v54
	v_fmac_f32_e32 v175, v223, v55
	v_lshlrev_b32_e32 v208, 16, v184
	v_and_b32_e32 v209, 0xffff0000, v184
	v_lshlrev_b32_e32 v210, 16, v185
	v_and_b32_e32 v211, 0xffff0000, v185
	v_lshlrev_b32_e32 v212, 16, v186
	v_and_b32_e32 v213, 0xffff0000, v186
	v_lshlrev_b32_e32 v214, 16, v187
	v_and_b32_e32 v215, 0xffff0000, v187
	v_lshlrev_b32_e32 v216, 16, v188
	v_and_b32_e32 v217, 0xffff0000, v188
	v_lshlrev_b32_e32 v218, 16, v189
	v_and_b32_e32 v219, 0xffff0000, v189
	v_lshlrev_b32_e32 v220, 16, v190
	v_and_b32_e32 v221, 0xffff0000, v190
	v_lshlrev_b32_e32 v222, 16, v191
	v_and_b32_e32 v223, 0xffff0000, v191
	v_mul_f32_e32 v224, v208, v208
	v_fmac_f32_e32 v224, v209, v209
	v_fmac_f32_e32 v224, v210, v210
	v_fmac_f32_e32 v224, v211, v211
	v_fmac_f32_e32 v224, v212, v212
	v_fmac_f32_e32 v224, v213, v213
	v_fmac_f32_e32 v224, v214, v214
	v_fmac_f32_e32 v224, v215, v215
	v_fmac_f32_e32 v224, v216, v216
	v_fmac_f32_e32 v224, v217, v217
	v_fmac_f32_e32 v224, v218, v218
	v_fmac_f32_e32 v224, v219, v219
	v_fmac_f32_e32 v224, v220, v220
	v_fmac_f32_e32 v224, v221, v221
	v_fmac_f32_e32 v224, v222, v222
	v_fmac_f32_e32 v224, v223, v223
	s_nop 1
	v_add_f32_dpp v224, v224, v224 quad_perm:[1,0,3,2] row_mask:0xf bank_mask:0xf
	s_nop 1
	v_add_f32_dpp v224, v224, v224 quad_perm:[2,3,0,1] row_mask:0xf bank_mask:0xf
	s_nop 1
	v_add_f32_dpp v224, v224, v224 row_ror:4 row_mask:0xf bank_mask:0xf
	s_nop 1
	v_add_f32_dpp v224, v224, v224 row_ror:8 row_mask:0xf bank_mask:0xf
	s_nop 1
	v_readlane_b32 s20, v224, 0
	v_readlane_b32 s21, v224, 16
	v_readlane_b32 s22, v224, 32
	v_readlane_b32 s23, v224, 48
	s_nop 1
	v_mov_b32_e32 v225, s20
	v_add_f32_e32 v225, s21, v225
	v_add_f32_e32 v225, s22, v225
	v_add_f32_e32 v225, s23, v225
	v_mov_b32_e32 v226, 0x358637bd
	v_fmac_f32_e32 v226, 0x3a800000, v225
	v_rsq_f32_e32 v226, v226
	s_nop 0
	v_mul_f32_e32 v208, v208, v226
	v_mul_f32_e32 v209, v209, v226
	v_mul_f32_e32 v210, v210, v226
	v_mul_f32_e32 v211, v211, v226
	v_mul_f32_e32 v212, v212, v226
	v_mul_f32_e32 v213, v213, v226
	v_mul_f32_e32 v214, v214, v226
	v_mul_f32_e32 v215, v215, v226
	v_mul_f32_e32 v216, v216, v226
	v_mul_f32_e32 v217, v217, v226
	v_mul_f32_e32 v218, v218, v226
	v_mul_f32_e32 v219, v219, v226
	v_mul_f32_e32 v220, v220, v226
	v_mul_f32_e32 v221, v221, v226
	v_mul_f32_e32 v222, v222, v226
	v_mul_f32_e32 v223, v223, v226
	v_fmac_f32_e32 v160, v208, v56
	v_fmac_f32_e32 v161, v209, v57
	v_fmac_f32_e32 v162, v210, v58
	v_fmac_f32_e32 v163, v211, v59
	v_fmac_f32_e32 v164, v212, v60
	v_fmac_f32_e32 v165, v213, v61
	v_fmac_f32_e32 v166, v214, v62
	v_fmac_f32_e32 v167, v215, v63
	v_fmac_f32_e32 v168, v216, v64
	v_fmac_f32_e32 v169, v217, v65
	v_fmac_f32_e32 v170, v218, v66
	v_fmac_f32_e32 v171, v219, v67
	v_fmac_f32_e32 v172, v220, v68
	v_fmac_f32_e32 v173, v221, v69
	v_fmac_f32_e32 v174, v222, v70
	v_fmac_f32_e32 v175, v223, v71
	global_store_dwordx4 v1, v[160:163], s[8:9] offset:0
	global_store_dwordx4 v1, v[164:167], s[8:9] offset:16
	global_store_dwordx4 v1, v[168:171], s[8:9] offset:2048
	global_store_dwordx4 v1, v[172:175], s[8:9] offset:2064
	s_add_u32 s8, s8, 0x1000
	s_addc_u32 s9, s9, 0
	s_waitcnt vmcnt(16)
; DI float shx(float v, int mask) { const int l = olane(); return __builtin_bit_cast(float, __builtin_amdgcn_ds_bpermute(((l ^ mask) & 63) << 2, __builtin_bit_cast(int, v))); }
; DI void row_phase(const bf16_t* msrc, const float* xsrc, float* xdst, const float* g_post, const float* g_next, bf16_t* hdst, const int gw) {
;     ...
;                 for (int j = 0; j < 4; ++j) { const u32x2 mw = *(const u32x2*)(msrc + (size_t)(rowb + r) * DM + lane * 4 + 256 * j);
;                     mv[r][j] = (f32x4){__uint_as_float(mw[0] << 16), __uint_as_float(mw[0] & 0xffff0000u), __uint_as_float(mw[1] << 16), __uint_as_float(mw[1] & 0xffff0000u)}; }
;             float ss[RB];
; #pragma unroll
;             for (int r = 0; r < RB; ++r) { ss[r] = 0.f;
; #pragma unroll
;                 for (int j = 0; j < 4; ++j) ss[r] += mv[r][j][0] * mv[r][j][0] + mv[r][j][1] * mv[r][j][1] + mv[r][j][2] * mv[r][j][2] + mv[r][j][3] * mv[r][j][3]; }
; #pragma unroll
;             for (int o = 32; o >= 1; o >>= 1)
; #pragma unroll
;                 for (int r = 0; r < RB; ++r) ss[r] += shx(ss[r], o);
; #pragma unroll
;             for (int j = 0; j < 4; ++j) { const f32x4 g = *(const f32x4*)(g_post + lane * 4 + 256 * j);
; #pragma unroll
;                 for (int r = 0; r < RB; ++r) { const float r1 = rsqrtf(ss[r] * (1.f / DM) + EPS); xv[r][j] = xv[r][j] + mv[r][j] * r1 * g; *(f32x4*)(xdst + (size_t)(rowb + r) * DM + lane * 4 + 256 * j) = xv[r][j]; } }
	v_lshlrev_b32_e32 v208, 16, v112
	v_and_b32_e32 v209, 0xffff0000, v112
	v_lshlrev_b32_e32 v210, 16, v113
	v_and_b32_e32 v211, 0xffff0000, v113
	v_lshlrev_b32_e32 v212, 16, v114
	v_and_b32_e32 v213, 0xffff0000, v114
	v_lshlrev_b32_e32 v214, 16, v115
	v_and_b32_e32 v215, 0xffff0000, v115
	v_lshlrev_b32_e32 v216, 16, v116
	v_and_b32_e32 v217, 0xffff0000, v116
	v_lshlrev_b32_e32 v218, 16, v117
	v_and_b32_e32 v219, 0xffff0000, v117
	v_lshlrev_b32_e32 v220, 16, v118
	v_and_b32_e32 v221, 0xffff0000, v118
	v_lshlrev_b32_e32 v222, 16, v119
	v_and_b32_e32 v223, 0xffff0000, v119
	v_mul_f32_e32 v224, v208, v208
	v_fmac_f32_e32 v224, v209, v209
	v_fmac_f32_e32 v224, v210, v210
	v_fmac_f32_e32 v224, v211, v211
	v_fmac_f32_e32 v224, v212, v212
	v_fmac_f32_e32 v224, v213, v213
	v_fmac_f32_e32 v224, v214, v214
	v_fmac_f32_e32 v224, v215, v215
	v_fmac_f32_e32 v224, v216, v216
	v_fmac_f32_e32 v224, v217, v217
	v_fmac_f32_e32 v224, v218, v218
	v_fmac_f32_e32 v224, v219, v219
	v_fmac_f32_e32 v224, v220, v220
	v_fmac_f32_e32 v224, v221, v221
	v_fmac_f32_e32 v224, v222, v222
	v_fmac_f32_e32 v224, v223, v223
	s_nop 1
	v_add_f32_dpp v224, v224, v224 quad_perm:[1,0,3,2] row_mask:0xf bank_mask:0xf
	s_nop 1
	v_add_f32_dpp v224, v224, v224 quad_perm:[2,3,0,1] row_mask:0xf bank_mask:0xf
	s_nop 1
	v_add_f32_dpp v224, v224, v224 row_ror:4 row_mask:0xf bank_mask:0xf
	s_nop 1
	v_add_f32_dpp v224, v224, v224 row_ror:8 row_mask:0xf bank_mask:0xf
	s_nop 1
	v_readlane_b32 s20, v224, 0
	v_readlane_b32 s21, v224, 16
	v_readlane_b32 s22, v224, 32
	v_readlane_b32 s23, v224, 48
	s_nop 1
	v_mov_b32_e32 v225, s20
	v_add_f32_e32 v225, s21, v225
	v_add_f32_e32 v225, s22, v225
	v_add_f32_e32 v225, s23, v225
	v_mov_b32_e32 v226, 0x358637bd
	v_fmac_f32_e32 v226, 0x3a800000, v225
	v_rsq_f32_e32 v226, v226
	s_nop 0
	v_mul_f32_e32 v208, v208, v226
	v_mul_f32_e32 v209, v209, v226
	v_mul_f32_e32 v210, v210, v226
	v_mul_f32_e32 v211, v211, v226
	v_mul_f32_e32 v212, v212, v226
	v_mul_f32_e32 v213, v213, v226
	v_mul_f32_e32 v214, v214, v226
	v_mul_f32_e32 v215, v215, v226
	v_mul_f32_e32 v216, v216, v226
	v_mul_f32_e32 v217, v217, v226
	v_mul_f32_e32 v218, v218, v226
	v_mul_f32_e32 v219, v219, v226
	v_mul_f32_e32 v220, v220, v226
	v_mul_f32_e32 v221, v221, v226
	v_mul_f32_e32 v222, v222, v226
	v_mul_f32_e32 v223, v223, v226
	v_fmac_f32_e32 v96, v208, v40
	v_fmac_f32_e32 v97, v209, v41
	v_fmac_f32_e32 v98, v210, v42
	v_fmac_f32_e32 v99, v211, v43
	v_fmac_f32_e32 v100, v212, v44
	v_fmac_f32_e32 v101, v213, v45
	v_fmac_f32_e32 v102, v214, v46
	v_fmac_f32_e32 v103, v215, v47
	v_fmac_f32_e32 v104, v216, v48
	v_fmac_f32_e32 v105, v217, v49
	v_fmac_f32_e32 v106, v218, v50
	v_fmac_f32_e32 v107, v219, v51
	v_fmac_f32_e32 v108, v220, v52
	v_fmac_f32_e32 v109, v221, v53
	v_fmac_f32_e32 v110, v222, v54
	v_fmac_f32_e32 v111, v223, v55
	v_lshlrev_b32_e32 v208, 16, v120
	v_and_b32_e32 v209, 0xffff0000, v120
	v_lshlrev_b32_e32 v210, 16, v121
	v_and_b32_e32 v211, 0xffff0000, v121
	v_lshlrev_b32_e32 v212, 16, v122
	v_and_b32_e32 v213, 0xffff0000, v122
	v_lshlrev_b32_e32 v214, 16, v123
	v_and_b32_e32 v215, 0xffff0000, v123
	v_lshlrev_b32_e32 v216, 16, v124
	v_and_b32_e32 v217, 0xffff0000, v124
	v_lshlrev_b32_e32 v218, 16, v125
	v_and_b32_e32 v219, 0xffff0000, v125
	v_lshlrev_b32_e32 v220, 16, v126
	v_and_b32_e32 v221, 0xffff0000, v126
	v_lshlrev_b32_e32 v222, 16, v127
	v_and_b32_e32 v223, 0xffff0000, v127
	v_mul_f32_e32 v224, v208, v208
	v_fmac_f32_e32 v224, v209, v209
	v_fmac_f32_e32 v224, v210, v210
	v_fmac_f32_e32 v224, v211, v211
	v_fmac_f32_e32 v224, v212, v212
	v_fmac_f32_e32 v224, v213, v213
	v_fmac_f32_e32 v224, v214, v214
	v_fmac_f32_e32 v224, v215, v215
	v_fmac_f32_e32 v224, v216, v216
	v_fmac_f32_e32 v224, v217, v217
	v_fmac_f32_e32 v224, v218, v218
	v_fmac_f32_e32 v224, v219, v219
	v_fmac_f32_e32 v224, v220, v220
	v_fmac_f32_e32 v224, v221, v221
	v_fmac_f32_e32 v224, v222, v222
	v_fmac_f32_e32 v224, v223, v223
	s_nop 1
	v_add_f32_dpp v224, v224, v224 quad_perm:[1,0,3,2] row_mask:0xf bank_mask:0xf
	s_nop 1
	v_add_f32_dpp v224, v224, v224 quad_perm:[2,3,0,1] row_mask:0xf bank_mask:0xf
	s_nop 1
	v_add_f32_dpp v224, v224, v224 row_ror:4 row_mask:0xf bank_mask:0xf
	s_nop 1
	v_add_f32_dpp v224, v224, v224 row_ror:8 row_mask:0xf bank_mask:0xf
	s_nop 1
	v_readlane_b32 s20, v224, 0
	v_readlane_b32 s21, v224, 16
	v_readlane_b32 s22, v224, 32
	v_readlane_b32 s23, v224, 48
	s_nop 1
	v_mov_b32_e32 v225, s20
	v_add_f32_e32 v225, s21, v225
	v_add_f32_e32 v225, s22, v225
	v_add_f32_e32 v225, s23, v225
	v_mov_b32_e32 v226, 0x358637bd
	v_fmac_f32_e32 v226, 0x3a800000, v225
	v_rsq_f32_e32 v226, v226
	s_nop 0
	v_mul_f32_e32 v208, v208, v226
	v_mul_f32_e32 v209, v209, v226
	v_mul_f32_e32 v210, v210, v226
	v_mul_f32_e32 v211, v211, v226
	v_mul_f32_e32 v212, v212, v226
	v_mul_f32_e32 v213, v213, v226
	v_mul_f32_e32 v214, v214, v226
	v_mul_f32_e32 v215, v215, v226
	v_mul_f32_e32 v216, v216, v226
	v_mul_f32_e32 v217, v217, v226
	v_mul_f32_e32 v218, v218, v226
	v_mul_f32_e32 v219, v219, v226
	v_mul_f32_e32 v220, v220, v226
	v_mul_f32_e32 v221, v221, v226
	v_mul_f32_e32 v222, v222, v226
	v_mul_f32_e32 v223, v223, v226
	v_fmac_f32_e32 v96, v208, v56
	v_fmac_f32_e32 v97, v209, v57
	v_fmac_f32_e32 v98, v210, v58
	v_fmac_f32_e32 v99, v211, v59
	v_fmac_f32_e32 v100, v212, v60
	v_fmac_f32_e32 v101, v213, v61
	v_fmac_f32_e32 v102, v214, v62
	v_fmac_f32_e32 v103, v215, v63
	v_fmac_f32_e32 v104, v216, v64
	v_fmac_f32_e32 v105, v217, v65
	v_fmac_f32_e32 v106, v218, v66
	v_fmac_f32_e32 v107, v219, v67
	v_fmac_f32_e32 v108, v220, v68
	v_fmac_f32_e32 v109, v221, v69
	v_fmac_f32_e32 v110, v222, v70
	v_fmac_f32_e32 v111, v223, v71
	global_store_dwordx4 v1, v[96:99], s[8:9] offset:0
	global_store_dwordx4 v1, v[100:103], s[8:9] offset:16
	global_store_dwordx4 v1, v[104:107], s[8:9] offset:2048
	global_store_dwordx4 v1, v[108:111], s[8:9] offset:2064
	s_add_u32 s8, s8, 0x1000
	s_addc_u32 s9, s9, 0
	s_waitcnt vmcnt(8)
; DI float shx(float v, int mask) { const int l = olane(); return __builtin_bit_cast(float, __builtin_amdgcn_ds_bpermute(((l ^ mask) & 63) << 2, __builtin_bit_cast(int, v))); }
; DI void row_phase(const bf16_t* msrc, const float* xsrc, float* xdst, const float* g_post, const float* g_next, bf16_t* hdst, const int gw) {
;     ...
;         if (msrc) {
; #pragma unroll
;             for (int r = 0; r < RB; ++r)
; #pragma unroll
;                 for (int j = 0; j < 4; ++j) { const u32x2 mw = *(const u32x2*)(msrc + (size_t)(rowb + r) * DM + lane * 4 + 256 * j);
;                     mv[r][j] = (f32x4){__uint_as_float(mw[0] << 16), __uint_as_float(mw[0] & 0xffff0000u), __uint_as_float(mw[1] << 16), __uint_as_float(mw[1] & 0xffff0000u)}; }
;             float ss[RB];
; #pragma unroll
;             for (int r = 0; r < RB; ++r) { ss[r] = 0.f;
; #pragma unroll
;                 for (int j = 0; j < 4; ++j) ss[r] += mv[r][j][0] * mv[r][j][0] + mv[r][j][1] * mv[r][j][1] + mv[r][j][2] * mv[r][j][2] + mv[r][j][3] * mv[r][j][3]; }
; #pragma unroll
;             for (int o = 32; o >= 1; o >>= 1)
; #pragma unroll
;                 for (int r = 0; r < RB; ++r) ss[r] += shx(ss[r], o);
; #pragma unroll
;             for (int j = 0; j < 4; ++j) { const f32x4 g = *(const f32x4*)(g_post + lane * 4 + 256 * j);
; #pragma unroll
;                 for (int r = 0; r < RB; ++r) { const float r1 = rsqrtf(ss[r] * (1.f / DM) + EPS); xv[r][j] = xv[r][j] + mv[r][j] * r1 * g; *(f32x4*)(xdst + (size_t)(rowb + r) * DM + lane * 4 + 256 * j) = xv[r][j]; } }
;         }
	v_lshlrev_b32_e32 v208, 16, v144
	v_and_b32_e32 v209, 0xffff0000, v144
	v_lshlrev_b32_e32 v210, 16, v145
	v_and_b32_e32 v211, 0xffff0000, v145
	v_lshlrev_b32_e32 v212, 16, v146
	v_and_b32_e32 v213, 0xffff0000, v146
	v_lshlrev_b32_e32 v214, 16, v147
	v_and_b32_e32 v215, 0xffff0000, v147
	v_lshlrev_b32_e32 v216, 16, v148
	v_and_b32_e32 v217, 0xffff0000, v148
	v_lshlrev_b32_e32 v218, 16, v149
	v_and_b32_e32 v219, 0xffff0000, v149
	v_lshlrev_b32_e32 v220, 16, v150
	v_and_b32_e32 v221, 0xffff0000, v150
	v_lshlrev_b32_e32 v222, 16, v151
	v_and_b32_e32 v223, 0xffff0000, v151
	v_mul_f32_e32 v224, v208, v208
	v_fmac_f32_e32 v224, v209, v209
	v_fmac_f32_e32 v224, v210, v210
	v_fmac_f32_e32 v224, v211, v211
	v_fmac_f32_e32 v224, v212, v212
	v_fmac_f32_e32 v224, v213, v213
	v_fmac_f32_e32 v224, v214, v214
	v_fmac_f32_e32 v224, v215, v215
	v_fmac_f32_e32 v224, v216, v216
	v_fmac_f32_e32 v224, v217, v217
	v_fmac_f32_e32 v224, v218, v218
	v_fmac_f32_e32 v224, v219, v219
	v_fmac_f32_e32 v224, v220, v220
	v_fmac_f32_e32 v224, v221, v221
	v_fmac_f32_e32 v224, v222, v222
	v_fmac_f32_e32 v224, v223, v223
	s_nop 1
	v_add_f32_dpp v224, v224, v224 quad_perm:[1,0,3,2] row_mask:0xf bank_mask:0xf
	s_nop 1
	v_add_f32_dpp v224, v224, v224 quad_perm:[2,3,0,1] row_mask:0xf bank_mask:0xf
	s_nop 1
	v_add_f32_dpp v224, v224, v224 row_ror:4 row_mask:0xf bank_mask:0xf
	s_nop 1
	v_add_f32_dpp v224, v224, v224 row_ror:8 row_mask:0xf bank_mask:0xf
	s_nop 1
	v_readlane_b32 s20, v224, 0
	v_readlane_b32 s21, v224, 16
	v_readlane_b32 s22, v224, 32
	v_readlane_b32 s23, v224, 48
	s_nop 1
	v_mov_b32_e32 v225, s20
	v_add_f32_e32 v225, s21, v225
	v_add_f32_e32 v225, s22, v225
	v_add_f32_e32 v225, s23, v225
	v_mov_b32_e32 v226, 0x358637bd
	v_fmac_f32_e32 v226, 0x3a800000, v225
	v_rsq_f32_e32 v226, v226
	s_nop 0
	v_mul_f32_e32 v208, v208, v226
	v_mul_f32_e32 v209, v209, v226
	v_mul_f32_e32 v210, v210, v226
	v_mul_f32_e32 v211, v211, v226
	v_mul_f32_e32 v212, v212, v226
	v_mul_f32_e32 v213, v213, v226
	v_mul_f32_e32 v214, v214, v226
	v_mul_f32_e32 v215, v215, v226
	v_mul_f32_e32 v216, v216, v226
	v_mul_f32_e32 v217, v217, v226
	v_mul_f32_e32 v218, v218, v226
	v_mul_f32_e32 v219, v219, v226
	v_mul_f32_e32 v220, v220, v226
	v_mul_f32_e32 v221, v221, v226
	v_mul_f32_e32 v222, v222, v226
	v_mul_f32_e32 v223, v223, v226
	v_fmac_f32_e32 v128, v208, v40
	v_fmac_f32_e32 v129, v209, v41
	v_fmac_f32_e32 v130, v210, v42
	v_fmac_f32_e32 v131, v211, v43
	v_fmac_f32_e32 v132, v212, v44
	v_fmac_f32_e32 v133, v213, v45
	v_fmac_f32_e32 v134, v214, v46
	v_fmac_f32_e32 v135, v215, v47
	v_fmac_f32_e32 v136, v216, v48
	v_fmac_f32_e32 v137, v217, v49
	v_fmac_f32_e32 v138, v218, v50
	v_fmac_f32_e32 v139, v219, v51
	v_fmac_f32_e32 v140, v220, v52
	v_fmac_f32_e32 v141, v221, v53
	v_fmac_f32_e32 v142, v222, v54
	v_fmac_f32_e32 v143, v223, v55
	v_lshlrev_b32_e32 v208, 16, v152
	v_and_b32_e32 v209, 0xffff0000, v152
	v_lshlrev_b32_e32 v210, 16, v153
	v_and_b32_e32 v211, 0xffff0000, v153
	v_lshlrev_b32_e32 v212, 16, v154
	v_and_b32_e32 v213, 0xffff0000, v154
	v_lshlrev_b32_e32 v214, 16, v155
	v_and_b32_e32 v215, 0xffff0000, v155
	v_lshlrev_b32_e32 v216, 16, v156
	v_and_b32_e32 v217, 0xffff0000, v156
	v_lshlrev_b32_e32 v218, 16, v157
	v_and_b32_e32 v219, 0xffff0000, v157
	v_lshlrev_b32_e32 v220, 16, v158
	v_and_b32_e32 v221, 0xffff0000, v158
	v_lshlrev_b32_e32 v222, 16, v159
	v_and_b32_e32 v223, 0xffff0000, v159
	v_mul_f32_e32 v224, v208, v208
	v_fmac_f32_e32 v224, v209, v209
	v_fmac_f32_e32 v224, v210, v210
	v_fmac_f32_e32 v224, v211, v211
	v_fmac_f32_e32 v224, v212, v212
	v_fmac_f32_e32 v224, v213, v213
	v_fmac_f32_e32 v224, v214, v214
	v_fmac_f32_e32 v224, v215, v215
	v_fmac_f32_e32 v224, v216, v216
	v_fmac_f32_e32 v224, v217, v217
	v_fmac_f32_e32 v224, v218, v218
	v_fmac_f32_e32 v224, v219, v219
	v_fmac_f32_e32 v224, v220, v220
	v_fmac_f32_e32 v224, v221, v221
	v_fmac_f32_e32 v224, v222, v222
	v_fmac_f32_e32 v224, v223, v223
	s_nop 1
	v_add_f32_dpp v224, v224, v224 quad_perm:[1,0,3,2] row_mask:0xf bank_mask:0xf
	s_nop 1
	v_add_f32_dpp v224, v224, v224 quad_perm:[2,3,0,1] row_mask:0xf bank_mask:0xf
	s_nop 1
	v_add_f32_dpp v224, v224, v224 row_ror:4 row_mask:0xf bank_mask:0xf
	s_nop 1
	v_add_f32_dpp v224, v224, v224 row_ror:8 row_mask:0xf bank_mask:0xf
	s_nop 1
	v_readlane_b32 s20, v224, 0
	v_readlane_b32 s21, v224, 16
	v_readlane_b32 s22, v224, 32
	v_readlane_b32 s23, v224, 48
	s_nop 1
	v_mov_b32_e32 v225, s20
	v_add_f32_e32 v225, s21, v225
	v_add_f32_e32 v225, s22, v225
	v_add_f32_e32 v225, s23, v225
	v_mov_b32_e32 v226, 0x358637bd
	v_fmac_f32_e32 v226, 0x3a800000, v225
	v_rsq_f32_e32 v226, v226
	s_nop 0
	v_mul_f32_e32 v208, v208, v226
	v_mul_f32_e32 v209, v209, v226
	v_mul_f32_e32 v210, v210, v226
	v_mul_f32_e32 v211, v211, v226
	v_mul_f32_e32 v212, v212, v226
	v_mul_f32_e32 v213, v213, v226
	v_mul_f32_e32 v214, v214, v226
	v_mul_f32_e32 v215, v215, v226
	v_mul_f32_e32 v216, v216, v226
	v_mul_f32_e32 v217, v217, v226
	v_mul_f32_e32 v218, v218, v226
	v_mul_f32_e32 v219, v219, v226
	v_mul_f32_e32 v220, v220, v226
	v_mul_f32_e32 v221, v221, v226
	v_mul_f32_e32 v222, v222, v226
	v_mul_f32_e32 v223, v223, v226
	v_fmac_f32_e32 v128, v208, v56
	v_fmac_f32_e32 v129, v209, v57
	v_fmac_f32_e32 v130, v210, v58
	v_fmac_f32_e32 v131, v211, v59
	v_fmac_f32_e32 v132, v212, v60
	v_fmac_f32_e32 v133, v213, v61
	v_fmac_f32_e32 v134, v214, v62
	v_fmac_f32_e32 v135, v215, v63
	v_fmac_f32_e32 v136, v216, v64
	v_fmac_f32_e32 v137, v217, v65
	v_fmac_f32_e32 v138, v218, v66
	v_fmac_f32_e32 v139, v219, v67
	v_fmac_f32_e32 v140, v220, v68
	v_fmac_f32_e32 v141, v221, v69
	v_fmac_f32_e32 v142, v222, v70
	v_fmac_f32_e32 v143, v223, v71
	global_store_dwordx4 v1, v[128:131], s[8:9] offset:0
	global_store_dwordx4 v1, v[132:135], s[8:9] offset:16
	global_store_dwordx4 v1, v[136:139], s[8:9] offset:2048
	global_store_dwordx4 v1, v[140:143], s[8:9] offset:2064
	s_add_u32 s8, s8, 0x1000
	s_addc_u32 s9, s9, 0
	v_readlane_b32 s4, v3, 0
	v_readlane_b32 s5, v3, 1
	v_readlane_b32 s6, v3, 2
	v_readlane_b32 s7, v3, 3
	v_readlane_b32 s8, v3, 4
	v_readlane_b32 s9, v3, 5
	v_readlane_b32 s10, v3, 6
	v_readlane_b32 s11, v3, 7
	v_readlane_b32 s12, v3, 8
	v_readlane_b32 s13, v3, 9
	v_readlane_b32 s14, v3, 10
	v_readlane_b32 s15, v3, 11
	v_readlane_b32 s16, v3, 12
	v_readlane_b32 s17, v3, 13
	v_readlane_b32 s18, v3, 14
	v_readlane_b32 s19, v3, 15
	v_readlane_b32 s20, v3, 16
	v_readlane_b32 s21, v3, 17
	v_readlane_b32 s22, v3, 18
	v_readlane_b32 s23, v3, 19
	v_readlane_b32 s24, v3, 20
	v_readlane_b32 s25, v3, 21
	s_mov_b32 s6, 0x358637bd
	s_mov_b64 s[34:35], 0
	s_branch .LBB0_74

; DI int obid() { int b = blockIdx.x; asm volatile("" : "+s"(b)); return b; }
; #define STAGE(bufoff, GB) do { const char* g_ = (GB); \
;         _Pragma("unroll") for (int i_ = 0; i_ < 2; ++i_) __builtin_amdgcn_global_load_lds((const unsigned*)(g_ + voff[i_]), (LAS3 unsigned*)(L + (bufoff) + stoff + i_ * 8192), 16, 0, 0); } while (0)
; #define WAIT_V(n) asm volatile("s_waitcnt vmcnt(" #n ")" ::: "memory")
; #define BAR __builtin_amdgcn_s_barrier()
; #define VOFF_INIT() do { _Pragma("unroll") for (int i = 0; i < 2; ++i) { int R, C; stage_rc((wid * 64 + olane()) * 16 + i * 8192, R, C); voff[i] = (unsigned)(R * K + C) * 2u; } } while (0)
; template <int EPI>
; DI void gemm_phase(const bf16_t* __restrict__ A, const bf16_t* __restrict__ Bt, const int K, const int N, const Params& p, const int layer_j, char* lds) {
;     ...
;     if (obid() >= nwg) return;
;     int pm, pn;
;     TILE_COORDS(obid(), pm, pn);
;     const size_t kstep = 128, hstep = (size_t)HALF * K * 2, tstep = 2 * hstep;
;     const char* cA = (const char*)A + (size_t)pm * tstep; const char* cB = (const char*)Bt + (size_t)pn * tstep;
;     f32x4 acc[2][2][4][2];
; #pragma unroll
;     for (int a = 0; a < 2; ++a)
; #pragma unroll
;         for (int b = 0; b < 2; ++b)
; #pragma unroll
;             for (int m = 0; m < 4; ++m)
; #pragma unroll
;                 for (int n = 0; n < 2; ++n) acc[a][b][m][n] = (f32x4){0.f, 0.f, 0.f, 0.f};
;     bf16x8 At[4][2], B0[2][2], B1[2][2];
;     {
;         unsigned voff[2]; VOFF_INIT();
;         asm volatile("s_waitcnt vmcnt(0) lgkmcnt(0)" ::: "memory");
;         __syncthreads();
;         STAGE(SB(0, 0), cB); STAGE(SB(0, 1), cB + hstep); STAGE(SA(0, 0), cA); STAGE(SA(0, 1), cA + hstep);
;         if (wr == 1) BAR;
;         WAIT_V(2); BAR;
;         STAGE(SB(1, 0), cB + kstep); STAGE(SA(1, 0), cA + kstep); STAGE(SB(1, 1), cB + hstep + kstep);
;         WAIT_V(6); BAR;
.LBB0_94:
	s_ashr_i32 s8, s11, 3
	s_add_u32 s9, s68, 0x8681000
	s_addc_u32 s11, s69, 0
	s_and_b64 s[4:5], s[4:5], exec
	s_cselect_b32 s21, s83, s11
	s_cselect_b32 s22, s82, s9
	s_add_i32 s4, s10, s8
	s_ashr_i32 s5, s4, 31
	s_lshr_b32 s5, s5, 30
	s_add_i32 s5, s4, s5
	s_ashr_i32 s8, s5, 2
	s_sub_i32 s9, 64, s8
	s_min_i32 s9, s9, 1
	s_abs_i32 s10, s9
	v_cvt_f32_u32_e32 v0, s10
	s_sub_i32 s12, 0, s10
	s_and_b32 s5, s5, -4
	s_sub_i32 s4, s4, s5
	v_rcp_iflag_f32_e32 v0, v0
	s_abs_i32 s5, s4
	s_xor_b32 s11, s4, s9
	s_ashr_i32 s11, s11, 31
	v_mul_f32_e32 v0, 0x4f7ffffe, v0
	v_cvt_u32_f32_e32 v0, v0
	v_add_u32_e32 v139, 0x10000, v136
	v_add_u32_e32 v140, 0x12000, v136
	v_add_u32_e32 v141, 0x14000, v136
	v_readfirstlane_b32 s13, v0
	s_mul_i32 s12, s12, s13
	s_mul_hi_u32 s12, s13, s12
	s_add_i32 s13, s13, s12
	s_mul_hi_u32 s12, s5, s13
	s_mul_i32 s13, s12, s10
	s_sub_i32 s5, s5, s13
	s_add_i32 s14, s12, 1
	s_sub_i32 s13, s5, s10
	s_cmp_ge_u32 s5, s10
	s_cselect_b32 s12, s14, s12
	s_cselect_b32 s5, s13, s5
	s_add_i32 s13, s12, 1
	s_cmp_ge_u32 s5, s10
	s_cselect_b32 s5, s13, s12
	s_xor_b32 s5, s5, s11
	s_sub_i32 s31, s5, s11
	s_mul_i32 s5, s31, s9
	s_sub_i32 s4, s4, s5
	v_mbcnt_lo_u32_b32 v0, -1, 0
	v_mbcnt_hi_u32_b32 v0, -1, v0
	s_add_i32 s34, s8, s4
	v_add_u32_e32 v1, s71, v0
	s_lshl_b32 s23, s20, 9
	v_ashrrev_i32_e32 v3, 6, v1
	s_lshl_b32 s88, s20, 8
	s_mul_i32 s5, s23, s34
	v_lshrrev_b32_e32 v4, 31, v3
	s_mul_hi_i32 s4, s23, s34
	s_add_u32 s18, s22, s5
	v_lshlrev_b32_e32 v2, 4, v1
	v_and_b32_e32 v0, 32, v0
	v_add_u32_e32 v4, v3, v4
	s_addc_u32 s19, s21, s4
	s_lshr_b32 s99, s34, 3
	s_lshl_b32 s99, s99, 20
	s_cmp_eq_u32 s20, 0xb00
	s_cselect_b32 s99, s99, 0
	s_add_u32 s18, s18, s99
	s_addc_u32 s19, s19, 0
	v_lshlrev_b32_e32 v5, 3, v4
	v_bfe_u32 v1, v1, 2, 4
	s_mov_b32 s4, 0x7ffffff0
	v_and_b32_e32 v4, 0x3fffffe, v4
	v_bitop3_b32 v0, v2, v0, 48 bitop3:0x6c
	v_and_or_b32 v1, v5, s4, v1
	v_sub_u32_e32 v3, v3, v4
	v_lshrrev_b32_e32 v0, 1, v0
	v_lshl_or_b32 v0, v3, 5, v0
	v_mul_lo_u32 v1, v1, s20
	v_add_lshl_u32 v32, v0, v1, 1
	v_mbcnt_lo_u32_b32 v0, -1, 0
	v_mbcnt_hi_u32_b32 v0, -1, v0
	s_mul_i32 s16, s23, s31
	v_add_u32_e32 v1, s71, v0
	v_lshlrev_b32_e32 v2, 4, v1
	v_add_u32_e32 v3, 0x2000, v2
	v_ashrrev_i32_e32 v3, 10, v3
	v_lshrrev_b32_e32 v4, 31, v3
	v_and_b32_e32 v0, 32, v0
	v_add_u32_e32 v4, v3, v4
	v_lshlrev_b32_e32 v5, 3, v4
	v_bfe_u32 v1, v1, 2, 4
	v_and_b32_e32 v4, 0x3fffffe, v4
	v_bitop3_b32 v0, v2, v0, 48 bitop3:0x6c
	s_mul_hi_i32 s17, s23, s31
	v_and_or_b32 v1, v5, s4, v1
	v_sub_u32_e32 v3, v3, v4
	v_lshrrev_b32_e32 v0, 1, v0
	s_add_u32 s8, s6, s16
	v_readfirstlane_b32 s4, v139
	v_lshl_or_b32 v0, v3, 5, v0
	v_mul_lo_u32 v1, v1, s20
	s_addc_u32 s9, s7, s17
	s_mov_b32 m0, s4
	v_readfirstlane_b32 s4, v140
	v_add_lshl_u32 v0, v0, v1, 1
	s_waitcnt vmcnt(0) lgkmcnt(0)
	s_waitcnt lgkmcnt(0)
	s_barrier
	global_load_lds_dwordx4 v32, s[8:9]
	s_mov_b32 m0, s4
	s_add_u32 s10, s8, s88
	v_readfirstlane_b32 s4, v141
	v_add_u32_e32 v142, 0x16000, v136
	global_load_lds_dwordx4 v0, s[8:9]
	s_addc_u32 s11, s9, 0
	s_mov_b32 m0, s4
	v_readfirstlane_b32 s4, v142
	global_load_lds_dwordx4 v32, s[10:11]
	s_mov_b32 m0, s4
	v_readfirstlane_b32 s4, v136
	v_add_u32_e32 v143, 0x2000, v136
	global_load_lds_dwordx4 v0, s[10:11]
	s_mov_b32 m0, s4
	v_readfirstlane_b32 s4, v143
	v_add_u32_e32 v144, 0x4000, v136
	global_load_lds_dwordx4 v32, s[18:19]
	s_mov_b32 m0, s4
	s_add_u32 s4, s18, s88
	v_readfirstlane_b32 s12, v144
	v_add_u32_e32 v145, 0x6000, v136
	global_load_lds_dwordx4 v0, s[18:19]
	s_addc_u32 s5, s19, 0
	s_mov_b32 m0, s12
	v_readfirstlane_b32 s12, v145
	global_load_lds_dwordx4 v32, s[4:5]
	s_mov_b32 m0, s12
	v_readlane_b32 s12, v254, 10
	global_load_lds_dwordx4 v0, s[4:5]
	v_readlane_b32 s13, v254, 11
	s_andn2_b64 vcc, exec, s[12:13]
	s_nop 0
	v_cndmask_b32_e64 v1, 0, 1, s[12:13]
	v_cmp_ne_u32_e64 s[4:5], 1, v1
	s_cbranch_vccnz .LBB0_96
	s_barrier

; DI bf16_t f2bf(float a) { return (bf16_t)(pk_bf16(a, 0.f) & 0xffffu); }
; template <int EPI>
; DI void gemm_phase(const bf16_t* __restrict__ A, const bf16_t* __restrict__ Bt, const int K, const int N, const Params& p, const int layer_j, char* lds) {
;     ...
;         if (EPI == EPI_F32) {
;             bf16_t* T = (bf16_t*)(ws + OFF_T) + (size_t)row0 * DM + col0 + fr;
; #pragma unroll
;             for (int ai = 0; ai < 2; ++ai)
; #pragma unroll
;                 for (int m = 0; m < 4; ++m)
; #pragma unroll
;                     for (int j = 0; j < 4; ++j)
; #pragma unroll
;                         for (int bj = 0; bj < 2; ++bj)
; #pragma unroll
;                             for (int n = 0; n < 2; ++n) T[(size_t)(ai * 128 + m * 16 + j) * DM + bj * 32 + n * 16] = f2bf(acc[ai][bj][m][n][j]);
.LBB0_109:
	v_mbcnt_lo_u32_b32 v152, -1, 0
	v_mbcnt_hi_u32_b32 v152, -1, v152
	s_mul_i32 s16, s71, 34
	s_add_i32 s16, s16, 0x20100
	v_and_b32_e32 v153, 15, v152
	v_lshrrev_b32_e32 v154, 4, v152
	v_mul_u32_u24_e32 v153, 136, v153
	v_lshl_add_u32 v153, v154, 3, v153
	v_add_u32_e32 v153, s16, v153
	v_lshrrev_b32_e32 v155, 3, v152
	v_and_b32_e32 v156, 7, v152
	v_mul_u32_u24_e32 v154, 136, v155
	v_lshl_add_u32 v154, v156, 4, v154
	v_add_u32_e32 v154, s16, v154
	v_readlane_b32 s16, v254, 7
	v_readlane_b32 s17, v254, 14
	v_lshlrev_b32_e32 v156, 4, v156
	v_add_u32_e32 v155, s16, v155
	v_lshl_add_u32 v155, v155, 11, v156
	s_lshl_b32 s17, s17, 1
	v_add_u32_e32 v155, s17, v155
	v_add_u32_e32 v156, 0x4000, v155
	s_lshl_b32 s16, s34, 19
	s_lshl_b32 s17, s31, 9
	s_add_u32 s16, s16, s17
	s_add_u32 s16, s8, s16
	s_addc_u32 s17, s9, 0
	s_lshr_b32 vcc_lo, s34, 3
	s_lshl_b32 vcc_lo, vcc_lo, 22
	s_add_u32 s16, s16, vcc_lo
	s_addc_u32 s17, s17, 0
	s_cmp_eq_u32 s24, 44
	s_cselect_b32 vcc_lo, 0x400000, 0
	s_add_u32 s16, s16, vcc_lo
	s_addc_u32 s17, s17, 0
	v_cvt_pk_bf16_f32 v160, v126, v127
	v_cvt_pk_bf16_f32 v161, v128, v129
	v_cvt_pk_bf16_f32 v162, v122, v123
	v_cvt_pk_bf16_f32 v163, v124, v125
	v_cvt_pk_bf16_f32 v164, v118, v119
	v_cvt_pk_bf16_f32 v165, v120, v121
	v_cvt_pk_bf16_f32 v166, v114, v115
	v_cvt_pk_bf16_f32 v167, v116, v117
	ds_write_b64 v153, v[160:161]
	ds_write_b64 v153, v[162:163] offset:32
	ds_write_b64 v153, v[164:165] offset:64
	ds_write_b64 v153, v[166:167] offset:96
	ds_read2_b64 v[168:171], v154 offset1:1
	ds_read2_b64 v[172:175], v154 offset0:136 offset1:137
	s_waitcnt lgkmcnt(0)
	global_store_dwordx4 v155, v[168:171], s[16:17]
	global_store_dwordx4 v156, v[172:175], s[16:17]
	v_cvt_pk_bf16_f32 v160, v110, v111
	v_cvt_pk_bf16_f32 v161, v112, v113
	v_cvt_pk_bf16_f32 v162, v106, v107
	v_cvt_pk_bf16_f32 v163, v108, v109
	v_cvt_pk_bf16_f32 v164, v102, v103
	v_cvt_pk_bf16_f32 v165, v104, v105
	v_cvt_pk_bf16_f32 v166, v98, v99
	v_cvt_pk_bf16_f32 v167, v100, v101
	ds_write_b64 v153, v[160:161]
	ds_write_b64 v153, v[162:163] offset:32
	ds_write_b64 v153, v[164:165] offset:64
	ds_write_b64 v153, v[166:167] offset:96
	ds_read2_b64 v[168:171], v154 offset1:1
	ds_read2_b64 v[172:175], v154 offset0:136 offset1:137
	v_add_u32_e32 v157, 0x8000, v155
	v_add_u32_e32 v158, 0x8000, v156
	s_waitcnt lgkmcnt(0)
	global_store_dwordx4 v157, v[168:171], s[16:17]
	global_store_dwordx4 v158, v[172:175], s[16:17]
	v_cvt_pk_bf16_f32 v160, v94, v95
	v_cvt_pk_bf16_f32 v161, v96, v97
	v_cvt_pk_bf16_f32 v162, v90, v91
	v_cvt_pk_bf16_f32 v163, v92, v93
	v_cvt_pk_bf16_f32 v164, v86, v87
	v_cvt_pk_bf16_f32 v165, v88, v89
	v_cvt_pk_bf16_f32 v166, v82, v83
	v_cvt_pk_bf16_f32 v167, v84, v85
	ds_write_b64 v153, v[160:161]
	ds_write_b64 v153, v[162:163] offset:32
	ds_write_b64 v153, v[164:165] offset:64
	ds_write_b64 v153, v[166:167] offset:96
	ds_read2_b64 v[168:171], v154 offset1:1
	ds_read2_b64 v[172:175], v154 offset0:136 offset1:137
	v_add_u32_e32 v157, 0x10000, v155
	v_add_u32_e32 v158, 0x10000, v156
	s_waitcnt lgkmcnt(0)
	global_store_dwordx4 v157, v[168:171], s[16:17]
	global_store_dwordx4 v158, v[172:175], s[16:17]
	v_cvt_pk_bf16_f32 v160, v78, v79
	v_cvt_pk_bf16_f32 v161, v80, v81
	v_cvt_pk_bf16_f32 v162, v74, v75
	v_cvt_pk_bf16_f32 v163, v76, v77
	v_cvt_pk_bf16_f32 v164, v70, v71
	v_cvt_pk_bf16_f32 v165, v72, v73
	v_cvt_pk_bf16_f32 v166, v66, v67
	v_cvt_pk_bf16_f32 v167, v68, v69
	ds_write_b64 v153, v[160:161]
	ds_write_b64 v153, v[162:163] offset:32
	ds_write_b64 v153, v[164:165] offset:64
	ds_write_b64 v153, v[166:167] offset:96
	ds_read2_b64 v[168:171], v154 offset1:1
	ds_read2_b64 v[172:175], v154 offset0:136 offset1:137
	v_add_u32_e32 v157, 0x18000, v155
	v_add_u32_e32 v158, 0x18000, v156
	s_waitcnt lgkmcnt(0)
	global_store_dwordx4 v157, v[168:171], s[16:17]
	global_store_dwordx4 v158, v[172:175], s[16:17]
	v_cvt_pk_bf16_f32 v160, v62, v63
	v_cvt_pk_bf16_f32 v161, v64, v65
	v_cvt_pk_bf16_f32 v162, v58, v59
	v_cvt_pk_bf16_f32 v163, v60, v61
	v_cvt_pk_bf16_f32 v164, v46, v47
	v_cvt_pk_bf16_f32 v165, v48, v49
	v_cvt_pk_bf16_f32 v166, v42, v43
	v_cvt_pk_bf16_f32 v167, v44, v45
	ds_write_b64 v153, v[160:161]
	ds_write_b64 v153, v[162:163] offset:32
	ds_write_b64 v153, v[164:165] offset:64
	ds_write_b64 v153, v[166:167] offset:96
	ds_read2_b64 v[168:171], v154 offset1:1
	ds_read2_b64 v[172:175], v154 offset0:136 offset1:137
	v_add_u32_e32 v157, 0x40000, v155
	v_add_u32_e32 v158, 0x40000, v156
	s_waitcnt lgkmcnt(0)
	global_store_dwordx4 v157, v[168:171], s[16:17]
	global_store_dwordx4 v158, v[172:175], s[16:17]
	v_cvt_pk_bf16_f32 v160, v38, v39
	v_cvt_pk_bf16_f32 v161, v40, v41
	v_cvt_pk_bf16_f32 v162, v24, v25
	v_cvt_pk_bf16_f32 v163, v26, v27
	v_cvt_pk_bf16_f32 v164, v20, v21
	v_cvt_pk_bf16_f32 v165, v22, v23
	v_cvt_pk_bf16_f32 v166, v16, v17
	v_cvt_pk_bf16_f32 v167, v18, v19
	ds_write_b64 v153, v[160:161]
	ds_write_b64 v153, v[162:163] offset:32
	ds_write_b64 v153, v[164:165] offset:64
	ds_write_b64 v153, v[166:167] offset:96
	ds_read2_b64 v[168:171], v154 offset1:1
	ds_read2_b64 v[172:175], v154 offset0:136 offset1:137
	v_add_u32_e32 v157, 0x48000, v155
	v_add_u32_e32 v158, 0x48000, v156
	s_waitcnt lgkmcnt(0)
	global_store_dwordx4 v157, v[168:171], s[16:17]
	global_store_dwordx4 v158, v[172:175], s[16:17]
	v_cvt_pk_bf16_f32 v160, v12, v13
	v_cvt_pk_bf16_f32 v161, v14, v15
	v_cvt_pk_bf16_f32 v162, v8, v9
	v_cvt_pk_bf16_f32 v163, v10, v11
	v_cvt_pk_bf16_f32 v164, v50, v51
	v_cvt_pk_bf16_f32 v165, v52, v53
	v_cvt_pk_bf16_f32 v166, v54, v55
	v_cvt_pk_bf16_f32 v167, v56, v57
	ds_write_b64 v153, v[160:161]
	ds_write_b64 v153, v[162:163] offset:32
	ds_write_b64 v153, v[164:165] offset:64
	ds_write_b64 v153, v[166:167] offset:96
	ds_read2_b64 v[168:171], v154 offset1:1
	ds_read2_b64 v[172:175], v154 offset0:136 offset1:137
	v_add_u32_e32 v157, 0x50000, v155
	v_add_u32_e32 v158, 0x50000, v156
	s_waitcnt lgkmcnt(0)
	global_store_dwordx4 v157, v[168:171], s[16:17]
	global_store_dwordx4 v158, v[172:175], s[16:17]
	v_cvt_pk_bf16_f32 v160, v4, v5
	v_cvt_pk_bf16_f32 v161, v6, v7
	v_cvt_pk_bf16_f32 v162, v0, v1
	v_cvt_pk_bf16_f32 v163, v2, v3
	v_cvt_pk_bf16_f32 v164, v28, v29
	v_cvt_pk_bf16_f32 v165, v30, v31
	v_cvt_pk_bf16_f32 v166, v34, v35
	v_cvt_pk_bf16_f32 v167, v36, v37
	ds_write_b64 v153, v[160:161]
	ds_write_b64 v153, v[162:163] offset:32
	ds_write_b64 v153, v[164:165] offset:64
	ds_write_b64 v153, v[166:167] offset:96
	ds_read2_b64 v[168:171], v154 offset1:1
	ds_read2_b64 v[172:175], v154 offset0:136 offset1:137
	v_add_u32_e32 v157, 0x58000, v155
	v_add_u32_e32 v158, 0x58000, v156
	s_waitcnt lgkmcnt(0)
	global_store_dwordx4 v157, v[168:171], s[16:17]
	global_store_dwordx4 v158, v[172:175], s[16:17]
	s_andn2_b64 vcc, exec, s[10:11]
	s_mov_b64 s[10:11], -1
	s_mov_b32 s39, 0x2e8ba2e9
	s_cbranch_vccnz .LBB0_98
	s_and_b64 vcc, exec, s[4:5]
	s_cbranch_vccnz .LBB0_97
	s_barrier
	s_branch .LBB0_97

; DI int olane() { int l; asm volatile("v_mbcnt_lo_u32_b32 %0, -1, 0\n\tv_mbcnt_hi_u32_b32 %0, -1, %0" : "=v"(l)); return l; }
; DI unsigned xb_ld(unsigned* p)              { return __hip_atomic_load(p, __ATOMIC_RELAXED, __HIP_MEMORY_SCOPE_AGENT); }
; DI unsigned xb_add(unsigned* p, unsigned v) { return __hip_atomic_fetch_add(p, v, __ATOMIC_RELAXED, __HIP_MEMORY_SCOPE_AGENT); }
; #define XB_SPIN(cond, bar) do { unsigned _sp = 0; while (cond) { __builtin_amdgcn_s_sleep(1); \
;     if ((++_sp & 255u) == 0u) { if (xb_ld(&(bar)[XB_TMO])) break; if (_sp > XB_SPIN_CAP) { atomicAdd(&(bar)[XB_TMO], 1u); break; } } } } while (0)
; DI void xcd_barrier(const XcdBarrier& b, const int gw) {
;     asm volatile("s_waitcnt vmcnt(0)" ::: "memory");
;     __syncthreads();
;     if (gw == 0 && olane() == 0) {
;         unsigned* bar = b.bar;
;         __builtin_amdgcn_s_waitcnt(0);
;         unsigned nloc = b.st[0], nx = b.st[1];
;         if (nloc == 0u) { xcd_barrier_complete(bar, b.x, nloc, nx); b.st[0] = nloc; b.st[1] = nx; }
;         const unsigned old = xb_add(&bar[XB_XSUB(b.x)], 1u);
;         const unsigned gen = old / nloc;
;         if (old + 1u == (gen + 1u) * nloc) {
;             __builtin_amdgcn_fence(__ATOMIC_RELEASE, "agent");
;             asm volatile("s_waitcnt vmcnt(0)" ::: "memory");
;             const unsigned og = xb_add(&bar[XB_TOP], 1u);
;             const unsigned tg = og / nx;
;             if (og + 1u == (tg + 1u) * nx) xb_add(&bar[XB_TOPGEN], 1u);
;             else XB_SPIN(xb_ld(&bar[XB_TOPGEN]) == tg, bar);
;             __builtin_amdgcn_fence(__ATOMIC_ACQUIRE, "agent");
;             xb_add(&bar[XB_XGEN(b.x)], 1u);
;             asm volatile("s_waitcnt vmcnt(0)" ::: "memory");
;         } else {
;             XB_SPIN(xb_ld(&bar[XB_XGEN(b.x)]) == gen, bar);
.LBB0_528:
	s_andn2_saveexec_b64 s[8:9], s[8:9]
	s_cbranch_execz .LBB0_548
	s_mov_b64 s[8:9], exec
	s_add_i32 s98, s36, -1
	s_lshr_b32 s98, 0x1ffffffe, s98
	s_bitcmp1_b32 s98, 0
	s_cbranch_scc0 .Lxb_global
	v_mov_b32_e32 v1, 0x20048
	ds_read_b32 v1, v1
	s_waitcnt lgkmcnt(0)
	v_readfirstlane_b32 s98, v1
	s_cmp_lg_u32 s98, 0
	s_cbranch_scc0 .Lxb_global
	s_add_i32 s98, s36, -1
	s_lshr_b32 s98, 0x102040, s98
	s_bitcmp1_b32 s98, 0
	s_cbranch_scc0 .LBB0_545
	buffer_wbl2 sc1
	s_waitcnt vmcnt(0)
	v_mov_b32_e32 v1, 0x2c0
	v_mov_b32_e32 v2, 1
	v_readlane_b32 s98, v254, 2
	v_readlane_b32 s99, v254, 3
	s_nop 4
	global_atomic_add v1, v2, s[98:99]
	s_branch .LBB0_545

; #define XBAR() do { XcdBarrier xb_; xb_.bar = (unsigned*)(p.ws + OFF_BAR); xb_.x = xb_xcc_id(); xb_.st = (volatile LAS unsigned*)&xb_words; xcd_barrier(xb_, g_wave); } while (0)
; DI void xcd_barrier(const XcdBarrier& b, const int gw) {
;     ...
;     __syncthreads();
; __global__ void __launch_bounds__(NTHREADS) fwd_kernel(Params p) {
;     ...
;         if (ph + 1 < p.ph_hi) { if (p.ph_hi < 0) grid.sync(); else XBAR(); }
.Lrdy_done:
.LBB0_549:
	s_mov_b64 s[4:5], 0
	s_waitcnt lgkmcnt(0)
	s_barrier
	s_add_i32 s98, s36, -1
	s_lshr_b32 s98, 0x1ffffffe, s98
	s_bitcmp1_b32 s98, 0
	s_cbranch_scc1 .Lnostag
	s_and_b32 s98, s2, 7
	s_mul_i32 s98, s98, 1
	s_cmp_eq_u32 s98, 0
	s_cbranch_scc1 .Lnostag
.Lstag:
	s_sleep 127
	s_sub_u32 s98, s98, 1
	s_cmp_lg_u32 s98, 0
	s_cbranch_scc1 .Lstag
